# GEMM MFMA segments: the back-to-back s_setprio 0 / s_setprio 1 pair between the two 16-MFMA clusters removed (96 pairs); outer raise/drop kept
# baseline (speedup 1.0000x reference)
; #define PG8_STAGE(bufoff, gbase, voff) do { _Pragma("unroll") for (int _i = 0; _i < 2; ++_i) \
;         __builtin_amdgcn_global_load_lds((const unsigned*)((const char*)(gbase) + (voff)[_i]), (LAS unsigned*)(lds + (bufoff) + ldsw + _i * 8192), 16, 0, 0); } while (0)
; #define PG8_LDA(dst, b, h) do { _Pragma("unroll") for (int m = 0; m < 4; ++m) _Pragma("unroll") for (int k = 0; k < 2; ++k) dst[m][k] = *(const LAS bf16x8*)(lds + PG8_SA(b, h) + aoff + m * 2048 + k * 1024); } while (0)
; #define PG8_LDB(dst, b, h) do { _Pragma("unroll") for (int n = 0; n < 2; ++n) _Pragma("unroll") for (int k = 0; k < 2; ++k) dst[n][k] = *(const LAS bf16x8*)(lds + PG8_SB(b, h) + boff + n * 2048 + k * 1024); } while (0)
; #define PG8_MMA(ai, bj, At, Bt) do { __builtin_amdgcn_s_setprio(1); _Pragma("unroll") for (int m = 0; m < 4; ++m) _Pragma("unroll") for (int n = 0; n < 2; ++n) _Pragma("unroll") for (int k = 0; k < 2; ++k) \
;         acc[ai][bj][m][n] = __builtin_amdgcn_mfma_f32_16x16x32_bf16(Bt[n][k], At[m][k], acc[ai][bj][m][n], 0, 0, 0); __builtin_amdgcn_s_setprio(0); } while (0)
; #define PG8_BAR __builtin_amdgcn_s_barrier()
; template <class Epi>
; __device__ __forceinline__ void gemm_phase(LAS unsigned char* lds, const Gemm g, const StaticOrder& S, const Epi& E) {
;     ...
;         const bool has_next = S.next(ui + 1, nxt);
;         const char* nA = has_next ? (const char*)g.A + (size_t)nxt.pm * tstepA : cA; const char* nB = has_next ? (const char*)g.Bt + (size_t)nxt.pn * tstepB : cB;
; #pragma nounroll
;         for (int t = 0; t < nt; t += 2) {
;             const bool last = (t == nt - 2);
;             const char* a1 = cA + (size_t)(t + 1) * kstep;
;             const char* a2 = last ? nA : cA + (size_t)(t + 2) * kstep; const char* b2 = last ? nB : cB + (size_t)(t + 2) * kstep;
;             const char* a3 = a2 + kstep; const char* b3 = b2 + kstep;
;             PG8_LDB(B0, 0, 0); PG8_LDB(B1, 0, 1); PG8_SCHED; PG8_LDA(At, 0, 0); PG8_STAGE(PG8_SA(1, 1), a1 + hstepA, voffA);
;             PG8_WAIT_V(8); PG8_WAIT_L(0); PG8_BAR; PG8_MMA(0, 0, At, B0); PG8_MMA(0, 1, At, B1); PG8_BAR; PG8_SCHED;
;             PG8_LDA(At, 0, 1); PG8_STAGE(PG8_SB(0, 0), b2, voffB); PG8_STAGE(PG8_SB(0, 1), b2 + hstepB, voffB); PG8_STAGE(PG8_SA(0, 0), a2, voffA);
;             PG8_WAIT_V(8); PG8_WAIT_L(0); PG8_BAR; PG8_MMA(1, 0, At, B0); PG8_MMA(1, 1, At, B1); PG8_BAR; PG8_SCHED;
.LBB0_191:
	s_ashr_i32 s65, s64, 31
	s_lshl_b64 s[68:69], s[64:65], 19
	s_add_u32 s68, s24, s68
	s_addc_u32 s69, s25, s69
	s_and_b64 s[70:71], s[4:5], exec
	s_cselect_b32 s7, s69, s75
	s_cselect_b32 s65, s68, s74
	s_ashr_i32 s63, s62, 31
	s_lshl_b64 s[70:71], s[62:63], 19
	s_add_u32 s70, s10, s70
	s_addc_u32 s71, s11, s71
	s_and_b64 s[78:79], s[4:5], exec
	s_cselect_b32 s63, s71, s77
	s_cselect_b32 s73, s70, s76
	s_add_u32 s74, s74, 0x40080
	s_addc_u32 s75, s75, 0
	s_add_u32 s87, s76, 0x100
	s_addc_u32 s88, s77, 0
	s_mov_b32 s89, -2
	v_lshl_add_u32 v248, s72, 8, v150
	v_add_u32_e32 v248, s41, v248
	v_ashrrev_i32_e32 v249, 31, v248
	v_lshl_add_u64 v[248:249], v[248:249], 2, s[50:51]
	global_load_dword v240, v[248:249], off
	global_load_dword v241, v[248:249], off offset:64
	global_load_dword v242, v[248:249], off offset:128
	global_load_dword v243, v[248:249], off offset:192
	global_load_dword v244, v[248:249], off offset:512
	global_load_dword v245, v[248:249], off offset:576
	global_load_dword v246, v[248:249], off offset:640
	global_load_dword v247, v[248:249], off offset:704
	ds_read_b128 v[144:147], v153
	ds_read_b128 v[158:161], v153 offset:1024
	ds_read_b128 v[162:165], v153 offset:2048
	ds_read_b128 v[166:169], v153 offset:3072
	ds_read_b128 v[170:173], v154
	ds_read_b128 v[178:181], v154 offset:1024
	ds_read_b128 v[182:185], v154 offset:2048
	ds_read_b128 v[186:189], v154 offset:3072
	s_add_u32 s76, s74, 0xfffc0080
	s_addc_u32 s77, s75, -1
	s_cmp_eq_u32 s89, 12
	s_cselect_b32 s79, s7, s77
	s_cselect_b32 s78, s65, s76
	s_cselect_b32 s77, s63, s88
	s_cselect_b32 s76, s73, s87
	v_lshl_add_u64 v[148:149], s[74:75], 0, v[136:137]
	s_add_i32 m0, s19, 0xc000
	ds_read_b128 v[190:193], v155
	ds_read_b128 v[194:197], v155 offset:1024
	ds_read_b128 v[198:201], v155 offset:2048
	ds_read_b128 v[202:205], v155 offset:3072
	ds_read_b128 v[206:209], v155 offset:4096
	ds_read_b128 v[210:213], v155 offset:5120
	ds_read_b128 v[214:217], v155 offset:6144
	ds_read_b128 v[218:221], v155 offset:7168
	global_load_lds_dwordx4 v[148:149], off
	v_lshl_add_u64 v[148:149], s[74:75], 0, v[138:139]
	s_add_i32 m0, s19, 0xe000
	s_nop 0
	global_load_lds_dwordx4 v[148:149], off
	s_waitcnt vmcnt(8)
	s_waitcnt lgkmcnt(0)
	s_barrier
	s_setprio 1
	s_waitcnt lgkmcnt(0)
	v_mfma_f32_16x16x32_bf16 v[124:127], v[144:147], v[190:193], 0
	v_mfma_f32_16x16x32_bf16 v[120:123], v[162:165], v[190:193], 0
	v_mfma_f32_16x16x32_bf16 v[108:111], v[144:147], v[198:201], 0
	v_mfma_f32_16x16x32_bf16 v[104:107], v[162:165], v[198:201], 0
	v_mfma_f32_16x16x32_bf16 v[92:95], v[144:147], v[206:209], 0
	v_mfma_f32_16x16x32_bf16 v[88:91], v[162:165], v[206:209], 0
	v_mfma_f32_16x16x32_bf16 v[76:79], v[144:147], v[214:217], 0
	v_mfma_f32_16x16x32_bf16 v[72:75], v[162:165], v[214:217], 0
	v_mfma_f32_16x16x32_bf16 v[124:127], v[158:161], v[194:197], v[124:127]
	v_mfma_f32_16x16x32_bf16 v[120:123], v[166:169], v[194:197], v[120:123]
	v_mfma_f32_16x16x32_bf16 v[108:111], v[158:161], v[202:205], v[108:111]
	v_mfma_f32_16x16x32_bf16 v[104:107], v[166:169], v[202:205], v[104:107]
	v_mfma_f32_16x16x32_bf16 v[92:95], v[158:161], v[210:213], v[92:95]
	v_mfma_f32_16x16x32_bf16 v[88:91], v[166:169], v[210:213], v[88:91]
	v_mfma_f32_16x16x32_bf16 v[76:79], v[158:161], v[218:221], v[76:79]
	v_mfma_f32_16x16x32_bf16 v[72:75], v[166:169], v[218:221], v[72:75]
	v_mfma_f32_16x16x32_bf16 v[116:119], v[170:173], v[190:193], 0
	v_mfma_f32_16x16x32_bf16 v[112:115], v[182:185], v[190:193], 0
	v_mfma_f32_16x16x32_bf16 v[100:103], v[170:173], v[198:201], 0
	v_mfma_f32_16x16x32_bf16 v[96:99], v[182:185], v[198:201], 0
	v_mfma_f32_16x16x32_bf16 v[84:87], v[170:173], v[206:209], 0
	v_mfma_f32_16x16x32_bf16 v[80:83], v[182:185], v[206:209], 0
	v_mfma_f32_16x16x32_bf16 v[68:71], v[170:173], v[214:217], 0
	v_mfma_f32_16x16x32_bf16 v[64:67], v[182:185], v[214:217], 0
	v_mfma_f32_16x16x32_bf16 v[116:119], v[178:181], v[194:197], v[116:119]
	v_mfma_f32_16x16x32_bf16 v[112:115], v[186:189], v[194:197], v[112:115]
	v_mfma_f32_16x16x32_bf16 v[100:103], v[178:181], v[202:205], v[100:103]
	v_mfma_f32_16x16x32_bf16 v[96:99], v[186:189], v[202:205], v[96:99]
	v_mfma_f32_16x16x32_bf16 v[84:87], v[178:181], v[210:213], v[84:87]
	v_mfma_f32_16x16x32_bf16 v[80:83], v[186:189], v[210:213], v[80:83]
	v_mfma_f32_16x16x32_bf16 v[68:71], v[178:181], v[218:221], v[68:71]
	v_mfma_f32_16x16x32_bf16 v[64:67], v[186:189], v[218:221], v[64:67]
	s_setprio 0
	s_barrier
	s_add_i32 s90, s84, s3
	v_lshl_add_u64 v[148:149], s[76:77], 0, v[130:131]
	s_mov_b32 m0, s90
	ds_read_b128 v[190:193], v155 offset:16384
	ds_read_b128 v[194:197], v155 offset:17408
	ds_read_b128 v[198:201], v155 offset:18432
	ds_read_b128 v[202:205], v155 offset:19456
	ds_read_b128 v[206:209], v155 offset:20480
	ds_read_b128 v[210:213], v155 offset:21504
	ds_read_b128 v[214:217], v155 offset:22528
	ds_read_b128 v[218:221], v155 offset:23552
	global_load_lds_dwordx4 v[148:149], off
	s_add_i32 m0, s90, 0x2000
	s_add_u32 s90, s76, 0x40000
	v_lshl_add_u64 v[174:175], s[76:77], 0, v[134:135]
	s_addc_u32 s91, s77, 0
	s_add_i32 s92, s85, s3
	global_load_lds_dwordx4 v[174:175], off
	v_lshl_add_u64 v[222:223], s[90:91], 0, v[130:131]
	s_mov_b32 m0, s92
	v_lshl_add_u64 v[226:227], s[78:79], 0, v[132:133]
	global_load_lds_dwordx4 v[222:223], off
	v_lshl_add_u64 v[222:223], s[90:91], 0, v[134:135]
	s_add_i32 m0, s92, 0x2000
	s_nop 0
	global_load_lds_dwordx4 v[222:223], off
	v_lshl_add_u64 v[222:223], s[78:79], 0, v[128:129]
	s_mov_b32 m0, s19
	s_nop 0
	global_load_lds_dwordx4 v[222:223], off
	s_mov_b32 m0, s23
	s_nop 0
	global_load_lds_dwordx4 v[226:227], off
	s_waitcnt vmcnt(8)
	s_waitcnt lgkmcnt(0)
	s_barrier
; #define PG8_STAGE(bufoff, gbase, voff) do { _Pragma("unroll") for (int _i = 0; _i < 2; ++_i) \
;         __builtin_amdgcn_global_load_lds((const unsigned*)((const char*)(gbase) + (voff)[_i]), (LAS unsigned*)(lds + (bufoff) + ldsw + _i * 8192), 16, 0, 0); } while (0)
; #define PG8_LDA(dst, b, h) do { _Pragma("unroll") for (int m = 0; m < 4; ++m) _Pragma("unroll") for (int k = 0; k < 2; ++k) dst[m][k] = *(const LAS bf16x8*)(lds + PG8_SA(b, h) + aoff + m * 2048 + k * 1024); } while (0)
; #define PG8_LDB(dst, b, h) do { _Pragma("unroll") for (int n = 0; n < 2; ++n) _Pragma("unroll") for (int k = 0; k < 2; ++k) dst[n][k] = *(const LAS bf16x8*)(lds + PG8_SB(b, h) + boff + n * 2048 + k * 1024); } while (0)
; #define PG8_MMA(ai, bj, At, Bt) do { __builtin_amdgcn_s_setprio(1); _Pragma("unroll") for (int m = 0; m < 4; ++m) _Pragma("unroll") for (int n = 0; n < 2; ++n) _Pragma("unroll") for (int k = 0; k < 2; ++k) \
;         acc[ai][bj][m][n] = __builtin_amdgcn_mfma_f32_16x16x32_bf16(Bt[n][k], At[m][k], acc[ai][bj][m][n], 0, 0, 0); __builtin_amdgcn_s_setprio(0); } while (0)
; #define PG8_WAIT_V(n) asm volatile("s_waitcnt vmcnt(" #n ")" ::: "memory")
; #define PG8_WAIT_L(n) asm volatile("s_waitcnt lgkmcnt(" #n ")" ::: "memory")
; #define PG8_BAR __builtin_amdgcn_s_barrier()
; #define PG8_SCHED __builtin_amdgcn_sched_barrier(0)
; template <class Epi>
; __device__ __forceinline__ void gemm_phase(LAS unsigned char* lds, const Gemm g, const StaticOrder& S, const Epi& E) {
;     ...
;             PG8_WAIT_V(8); PG8_WAIT_L(0); PG8_BAR; PG8_MMA(1, 0, At, B0); PG8_MMA(1, 1, At, B1); PG8_BAR; PG8_SCHED;
;             PG8_LDB(B0, 1, 0); PG8_LDB(B1, 1, 1); PG8_SCHED; PG8_LDA(At, 1, 0); PG8_STAGE(PG8_SA(0, 1), a2 + hstepA, voffA);
;             PG8_WAIT_V(8); PG8_WAIT_L(0); PG8_BAR; PG8_MMA(0, 0, At, B0); PG8_MMA(0, 1, At, B1); PG8_BAR; PG8_SCHED;
	s_setprio 1
	s_waitcnt lgkmcnt(0)
	v_mfma_f32_16x16x32_bf16 v[60:63], v[144:147], v[190:193], 0
	v_mfma_f32_16x16x32_bf16 v[56:59], v[162:165], v[190:193], 0
	v_mfma_f32_16x16x32_bf16 v[44:47], v[144:147], v[198:201], 0
	v_mfma_f32_16x16x32_bf16 v[40:43], v[162:165], v[198:201], 0
	v_mfma_f32_16x16x32_bf16 v[28:31], v[144:147], v[206:209], 0
	v_mfma_f32_16x16x32_bf16 v[24:27], v[162:165], v[206:209], 0
	v_mfma_f32_16x16x32_bf16 v[12:15], v[144:147], v[214:217], 0
	v_mfma_f32_16x16x32_bf16 v[8:11], v[162:165], v[214:217], 0
	v_mfma_f32_16x16x32_bf16 v[60:63], v[158:161], v[194:197], v[60:63]
	v_mfma_f32_16x16x32_bf16 v[56:59], v[166:169], v[194:197], v[56:59]
	v_mfma_f32_16x16x32_bf16 v[44:47], v[158:161], v[202:205], v[44:47]
	v_mfma_f32_16x16x32_bf16 v[40:43], v[166:169], v[202:205], v[40:43]
	v_mfma_f32_16x16x32_bf16 v[28:31], v[158:161], v[210:213], v[28:31]
	v_mfma_f32_16x16x32_bf16 v[24:27], v[166:169], v[210:213], v[24:27]
	v_mfma_f32_16x16x32_bf16 v[12:15], v[158:161], v[218:221], v[12:15]
	v_mfma_f32_16x16x32_bf16 v[8:11], v[166:169], v[218:221], v[8:11]
	v_mfma_f32_16x16x32_bf16 v[52:55], v[170:173], v[190:193], 0
	v_mfma_f32_16x16x32_bf16 v[48:51], v[182:185], v[190:193], 0
	v_mfma_f32_16x16x32_bf16 v[36:39], v[170:173], v[198:201], 0
	v_mfma_f32_16x16x32_bf16 v[32:35], v[182:185], v[198:201], 0
	v_mfma_f32_16x16x32_bf16 v[20:23], v[170:173], v[206:209], 0
	v_mfma_f32_16x16x32_bf16 v[16:19], v[182:185], v[206:209], 0
	v_mfma_f32_16x16x32_bf16 v[4:7], v[170:173], v[214:217], 0
	v_mfma_f32_16x16x32_bf16 v[0:3], v[182:185], v[214:217], 0
	v_mfma_f32_16x16x32_bf16 v[52:55], v[178:181], v[194:197], v[52:55]
	v_mfma_f32_16x16x32_bf16 v[48:51], v[186:189], v[194:197], v[48:51]
	v_mfma_f32_16x16x32_bf16 v[36:39], v[178:181], v[202:205], v[36:39]
	v_mfma_f32_16x16x32_bf16 v[32:35], v[186:189], v[202:205], v[32:35]
	v_mfma_f32_16x16x32_bf16 v[20:23], v[178:181], v[210:213], v[20:23]
	v_mfma_f32_16x16x32_bf16 v[16:19], v[186:189], v[210:213], v[16:19]
	v_mfma_f32_16x16x32_bf16 v[4:7], v[178:181], v[218:221], v[4:7]
	v_mfma_f32_16x16x32_bf16 v[0:3], v[186:189], v[218:221], v[0:3]
	s_setprio 0
	s_barrier
	s_add_i32 s90, 0, 0x18000
	v_add_u32_e32 v157, s90, v152
	s_add_i32 s91, 0, 0x1c000
	ds_read_b128 v[144:147], v157
	ds_read_b128 v[158:161], v157 offset:1024
	ds_read_b128 v[162:165], v157 offset:2048
	ds_read_b128 v[166:169], v157 offset:3072
	v_add_u32_e32 v157, s91, v152
	ds_read_b128 v[170:173], v157
	ds_read_b128 v[178:181], v157 offset:1024
	ds_read_b128 v[182:185], v157 offset:2048
	ds_read_b128 v[186:189], v157 offset:3072
	s_add_u32 s78, s78, 0x40000
	s_addc_u32 s79, s79, 0
	s_mov_b32 m0, s33
	v_lshl_add_u64 v[228:229], s[78:79], 0, v[128:129]
	ds_read_b128 v[190:193], v155 offset:32768
	ds_read_b128 v[194:197], v155 offset:33792
	ds_read_b128 v[198:201], v155 offset:34816
	ds_read_b128 v[202:205], v155 offset:35840
	ds_read_b128 v[206:209], v155 offset:36864
	ds_read_b128 v[210:213], v155 offset:37888
	ds_read_b128 v[214:217], v155 offset:38912
	ds_read_b128 v[218:221], v155 offset:39936
	global_load_lds_dwordx4 v[228:229], off
	v_lshl_add_u64 v[228:229], s[78:79], 0, v[132:133]
	s_mov_b32 m0, s35
	s_nop 0
	global_load_lds_dwordx4 v[228:229], off
	s_waitcnt vmcnt(8)
	s_waitcnt lgkmcnt(0)
	s_barrier
	s_setprio 1
	s_waitcnt lgkmcnt(0)
	v_mfma_f32_16x16x32_bf16 v[124:127], v[144:147], v[190:193], v[124:127]
	v_mfma_f32_16x16x32_bf16 v[120:123], v[162:165], v[190:193], v[120:123]
	v_mfma_f32_16x16x32_bf16 v[108:111], v[144:147], v[198:201], v[108:111]
	v_mfma_f32_16x16x32_bf16 v[104:107], v[162:165], v[198:201], v[104:107]
	v_mfma_f32_16x16x32_bf16 v[92:95], v[144:147], v[206:209], v[92:95]
	v_mfma_f32_16x16x32_bf16 v[88:91], v[162:165], v[206:209], v[88:91]
	v_mfma_f32_16x16x32_bf16 v[76:79], v[144:147], v[214:217], v[76:79]
	v_mfma_f32_16x16x32_bf16 v[72:75], v[162:165], v[214:217], v[72:75]
	v_mfma_f32_16x16x32_bf16 v[124:127], v[158:161], v[194:197], v[124:127]
	v_mfma_f32_16x16x32_bf16 v[120:123], v[166:169], v[194:197], v[120:123]
	v_mfma_f32_16x16x32_bf16 v[108:111], v[158:161], v[202:205], v[108:111]
	v_mfma_f32_16x16x32_bf16 v[104:107], v[166:169], v[202:205], v[104:107]
	v_mfma_f32_16x16x32_bf16 v[92:95], v[158:161], v[210:213], v[92:95]
	v_mfma_f32_16x16x32_bf16 v[88:91], v[166:169], v[210:213], v[88:91]
	v_mfma_f32_16x16x32_bf16 v[76:79], v[158:161], v[218:221], v[76:79]
	v_mfma_f32_16x16x32_bf16 v[72:75], v[166:169], v[218:221], v[72:75]
	v_mfma_f32_16x16x32_bf16 v[116:119], v[170:173], v[190:193], v[116:119]
	v_mfma_f32_16x16x32_bf16 v[112:115], v[182:185], v[190:193], v[112:115]
	v_mfma_f32_16x16x32_bf16 v[100:103], v[170:173], v[198:201], v[100:103]
	v_mfma_f32_16x16x32_bf16 v[96:99], v[182:185], v[198:201], v[96:99]
	v_mfma_f32_16x16x32_bf16 v[84:87], v[170:173], v[206:209], v[84:87]
	v_mfma_f32_16x16x32_bf16 v[80:83], v[182:185], v[206:209], v[80:83]
	v_mfma_f32_16x16x32_bf16 v[68:71], v[170:173], v[214:217], v[68:71]
	v_mfma_f32_16x16x32_bf16 v[64:67], v[182:185], v[214:217], v[64:67]
	v_mfma_f32_16x16x32_bf16 v[116:119], v[178:181], v[194:197], v[116:119]
	v_mfma_f32_16x16x32_bf16 v[112:115], v[186:189], v[194:197], v[112:115]
	v_mfma_f32_16x16x32_bf16 v[100:103], v[178:181], v[202:205], v[100:103]
	v_mfma_f32_16x16x32_bf16 v[96:99], v[186:189], v[202:205], v[96:99]
	v_mfma_f32_16x16x32_bf16 v[84:87], v[178:181], v[210:213], v[84:87]
	v_mfma_f32_16x16x32_bf16 v[80:83], v[186:189], v[210:213], v[80:83]
	v_mfma_f32_16x16x32_bf16 v[68:71], v[178:181], v[218:221], v[68:71]
	v_mfma_f32_16x16x32_bf16 v[64:67], v[186:189], v[218:221], v[64:67]
	s_setprio 0
	s_barrier
; #define PG8_STAGE(bufoff, gbase, voff) do { _Pragma("unroll") for (int _i = 0; _i < 2; ++_i) \
;         __builtin_amdgcn_global_load_lds((const unsigned*)((const char*)(gbase) + (voff)[_i]), (LAS unsigned*)(lds + (bufoff) + ldsw + _i * 8192), 16, 0, 0); } while (0)
; #define PG8_LDA(dst, b, h) do { _Pragma("unroll") for (int m = 0; m < 4; ++m) _Pragma("unroll") for (int k = 0; k < 2; ++k) dst[m][k] = *(const LAS bf16x8*)(lds + PG8_SA(b, h) + aoff + m * 2048 + k * 1024); } while (0)
; #define PG8_LDB(dst, b, h) do { _Pragma("unroll") for (int n = 0; n < 2; ++n) _Pragma("unroll") for (int k = 0; k < 2; ++k) dst[n][k] = *(const LAS bf16x8*)(lds + PG8_SB(b, h) + boff + n * 2048 + k * 1024); } while (0)
; #define PG8_WAIT_V(n) asm volatile("s_waitcnt vmcnt(" #n ")" ::: "memory")
; #define PG8_WAIT_L(n) asm volatile("s_waitcnt lgkmcnt(" #n ")" ::: "memory")
; template <class Epi>
; __device__ __forceinline__ void gemm_phase(LAS unsigned char* lds, const Gemm g, const StaticOrder& S, const Epi& E) {
;     ...
;         for (int t = 0; t < nt; t += 2) {
;             const bool last = (t == nt - 2);
;             const char* a1 = cA + (size_t)(t + 1) * kstep;
;             const char* a2 = last ? nA : cA + (size_t)(t + 2) * kstep; const char* b2 = last ? nB : cB + (size_t)(t + 2) * kstep;
;             const char* a3 = a2 + kstep; const char* b3 = b2 + kstep;
;             PG8_LDB(B0, 0, 0); PG8_LDB(B1, 0, 1); PG8_SCHED; PG8_LDA(At, 0, 0); PG8_STAGE(PG8_SA(1, 1), a1 + hstepA, voffA);
;             PG8_WAIT_V(8); PG8_WAIT_L(0); PG8_BAR; PG8_MMA(0, 0, At, B0); PG8_MMA(0, 1, At, B1); PG8_BAR; PG8_SCHED;
;             PG8_LDA(At, 0, 1); PG8_STAGE(PG8_SB(0, 0), b2, voffB); PG8_STAGE(PG8_SB(0, 1), b2 + hstepB, voffB); PG8_STAGE(PG8_SA(0, 0), a2, voffA);
;             PG8_WAIT_V(8); PG8_WAIT_L(0); PG8_BAR; PG8_MMA(1, 0, At, B0); PG8_MMA(1, 1, At, B1); PG8_BAR; PG8_SCHED;
;             PG8_LDB(B0, 1, 0); PG8_LDB(B1, 1, 1); PG8_SCHED; PG8_LDA(At, 1, 0); PG8_STAGE(PG8_SA(0, 1), a2 + hstepA, voffA);
;             PG8_WAIT_V(8); PG8_WAIT_L(0); PG8_BAR; PG8_MMA(0, 0, At, B0); PG8_MMA(0, 1, At, B1); PG8_BAR; PG8_SCHED;
;             PG8_LDA(At, 1, 1); PG8_STAGE(PG8_SB(1, 0), b3, voffB); PG8_STAGE(PG8_SB(1, 1), b3 + hstepB, voffB); PG8_STAGE(PG8_SA(1, 0), a3, voffA);
;             PG8_WAIT_V(8); PG8_WAIT_L(0); PG8_BAR; PG8_MMA(1, 0, At, B0); PG8_MMA(1, 1, At, B1); PG8_BAR; PG8_SCHED;
	s_add_i32 s78, s90, s3
	v_lshl_add_u64 v[148:149], v[148:149], 0, s[12:13]
	s_mov_b32 m0, s78
	ds_read_b128 v[190:193], v155 offset:49152
	ds_read_b128 v[194:197], v155 offset:50176
	ds_read_b128 v[198:201], v155 offset:51200
	ds_read_b128 v[202:205], v155 offset:52224
	ds_read_b128 v[206:209], v155 offset:53248
	ds_read_b128 v[210:213], v155 offset:54272
	ds_read_b128 v[214:217], v155 offset:55296
	ds_read_b128 v[218:221], v155 offset:56320
	global_load_lds_dwordx4 v[148:149], off
	s_add_i32 m0, s78, 0x2000
	s_add_u32 s76, s76, 0x40080
	v_lshl_add_u64 v[148:149], v[174:175], 0, s[12:13]
	s_addc_u32 s77, s77, 0
	s_add_i32 s78, s91, s3
	global_load_lds_dwordx4 v[148:149], off
	v_lshl_add_u64 v[148:149], s[76:77], 0, v[130:131]
	s_mov_b32 m0, s78
	s_nop 0
	global_load_lds_dwordx4 v[148:149], off
	v_lshl_add_u64 v[148:149], s[76:77], 0, v[134:135]
	s_add_i32 m0, s78, 0x2000
	s_nop 0
	global_load_lds_dwordx4 v[148:149], off
	v_lshl_add_u64 v[148:149], v[222:223], 0, s[12:13]
	s_mov_b32 m0, s57
	s_nop 0
	global_load_lds_dwordx4 v[148:149], off
	v_lshl_add_u64 v[148:149], v[226:227], 0, s[12:13]
	s_mov_b32 m0, s80
	s_nop 0
	global_load_lds_dwordx4 v[148:149], off
	s_waitcnt vmcnt(8)
	s_waitcnt lgkmcnt(0)
	s_barrier
	s_setprio 1
	s_waitcnt lgkmcnt(0)
	v_mfma_f32_16x16x32_bf16 v[60:63], v[144:147], v[190:193], v[60:63]
	v_mfma_f32_16x16x32_bf16 v[56:59], v[162:165], v[190:193], v[56:59]
	v_mfma_f32_16x16x32_bf16 v[44:47], v[144:147], v[198:201], v[44:47]
	v_mfma_f32_16x16x32_bf16 v[40:43], v[162:165], v[198:201], v[40:43]
	v_mfma_f32_16x16x32_bf16 v[28:31], v[144:147], v[206:209], v[28:31]
	v_mfma_f32_16x16x32_bf16 v[24:27], v[162:165], v[206:209], v[24:27]
	v_mfma_f32_16x16x32_bf16 v[12:15], v[144:147], v[214:217], v[12:15]
	v_mfma_f32_16x16x32_bf16 v[8:11], v[162:165], v[214:217], v[8:11]
	v_mfma_f32_16x16x32_bf16 v[60:63], v[158:161], v[194:197], v[60:63]
	v_mfma_f32_16x16x32_bf16 v[56:59], v[166:169], v[194:197], v[56:59]
	v_mfma_f32_16x16x32_bf16 v[44:47], v[158:161], v[202:205], v[44:47]
	v_mfma_f32_16x16x32_bf16 v[40:43], v[166:169], v[202:205], v[40:43]
	v_mfma_f32_16x16x32_bf16 v[28:31], v[158:161], v[210:213], v[28:31]
	v_mfma_f32_16x16x32_bf16 v[24:27], v[166:169], v[210:213], v[24:27]
	v_mfma_f32_16x16x32_bf16 v[12:15], v[158:161], v[218:221], v[12:15]
	v_mfma_f32_16x16x32_bf16 v[8:11], v[166:169], v[218:221], v[8:11]
	v_mfma_f32_16x16x32_bf16 v[52:55], v[170:173], v[190:193], v[52:55]
	v_mfma_f32_16x16x32_bf16 v[48:51], v[182:185], v[190:193], v[48:51]
	v_mfma_f32_16x16x32_bf16 v[36:39], v[170:173], v[198:201], v[36:39]
	v_mfma_f32_16x16x32_bf16 v[32:35], v[182:185], v[198:201], v[32:35]
	v_mfma_f32_16x16x32_bf16 v[20:23], v[170:173], v[206:209], v[20:23]
	v_mfma_f32_16x16x32_bf16 v[16:19], v[182:185], v[206:209], v[16:19]
	v_mfma_f32_16x16x32_bf16 v[4:7], v[170:173], v[214:217], v[4:7]
	v_mfma_f32_16x16x32_bf16 v[0:3], v[182:185], v[214:217], v[0:3]
	v_mfma_f32_16x16x32_bf16 v[52:55], v[178:181], v[194:197], v[52:55]
	v_mfma_f32_16x16x32_bf16 v[48:51], v[186:189], v[194:197], v[48:51]
	v_mfma_f32_16x16x32_bf16 v[36:39], v[178:181], v[202:205], v[36:39]
	v_mfma_f32_16x16x32_bf16 v[32:35], v[186:189], v[202:205], v[32:35]
	v_mfma_f32_16x16x32_bf16 v[20:23], v[178:181], v[210:213], v[20:23]
	v_mfma_f32_16x16x32_bf16 v[16:19], v[186:189], v[210:213], v[16:19]
	v_mfma_f32_16x16x32_bf16 v[4:7], v[178:181], v[218:221], v[4:7]
	v_mfma_f32_16x16x32_bf16 v[0:3], v[186:189], v[218:221], v[0:3]
	s_setprio 0
	s_barrier
	s_add_i32 s89, s89, 2
	s_add_u32 s74, s74, 0x100
	s_addc_u32 s75, s75, 0
	s_add_u32 s87, s87, 0x100
	s_addc_u32 s88, s88, 0
	s_cmp_gt_u32 s89, 13
.LBB0_192:
	ds_read_b128 v[144:147], v153
	ds_read_b128 v[158:161], v153 offset:1024
	ds_read_b128 v[162:165], v153 offset:2048
	ds_read_b128 v[166:169], v153 offset:3072
	ds_read_b128 v[170:173], v154
	ds_read_b128 v[178:181], v154 offset:1024
	ds_read_b128 v[182:185], v154 offset:2048
	ds_read_b128 v[186:189], v154 offset:3072
	s_add_u32 s76, s74, 0xfffc0080
	s_addc_u32 s77, s75, -1
	s_cmp_eq_u32 s89, 12
	s_cselect_b32 s79, s7, s77
	s_cselect_b32 s78, s65, s76
	s_cselect_b32 s77, s63, s88
	s_cselect_b32 s76, s73, s87
	v_lshl_add_u64 v[148:149], s[74:75], 0, v[136:137]
	s_add_i32 m0, s19, 0xc000
	ds_read_b128 v[190:193], v155
	ds_read_b128 v[194:197], v155 offset:1024
	ds_read_b128 v[198:201], v155 offset:2048
	ds_read_b128 v[202:205], v155 offset:3072
	ds_read_b128 v[206:209], v155 offset:4096
	ds_read_b128 v[210:213], v155 offset:5120
	ds_read_b128 v[214:217], v155 offset:6144
	ds_read_b128 v[218:221], v155 offset:7168
	global_load_lds_dwordx4 v[148:149], off
	v_lshl_add_u64 v[148:149], s[74:75], 0, v[138:139]
	s_add_i32 m0, s19, 0xe000
	s_nop 0
	global_load_lds_dwordx4 v[148:149], off
	s_waitcnt vmcnt(8)
	s_waitcnt lgkmcnt(0)
	s_barrier
; #define PG8_STAGE(bufoff, gbase, voff) do { _Pragma("unroll") for (int _i = 0; _i < 2; ++_i) \
;         __builtin_amdgcn_global_load_lds((const unsigned*)((const char*)(gbase) + (voff)[_i]), (LAS unsigned*)(lds + (bufoff) + ldsw + _i * 8192), 16, 0, 0); } while (0)
; #define PG8_LDA(dst, b, h) do { _Pragma("unroll") for (int m = 0; m < 4; ++m) _Pragma("unroll") for (int k = 0; k < 2; ++k) dst[m][k] = *(const LAS bf16x8*)(lds + PG8_SA(b, h) + aoff + m * 2048 + k * 1024); } while (0)
; #define PG8_MMA(ai, bj, At, Bt) do { __builtin_amdgcn_s_setprio(1); _Pragma("unroll") for (int m = 0; m < 4; ++m) _Pragma("unroll") for (int n = 0; n < 2; ++n) _Pragma("unroll") for (int k = 0; k < 2; ++k) \
;         acc[ai][bj][m][n] = __builtin_amdgcn_mfma_f32_16x16x32_bf16(Bt[n][k], At[m][k], acc[ai][bj][m][n], 0, 0, 0); __builtin_amdgcn_s_setprio(0); } while (0)
; #define PG8_WAIT_V(n) asm volatile("s_waitcnt vmcnt(" #n ")" ::: "memory")
; #define PG8_WAIT_L(n) asm volatile("s_waitcnt lgkmcnt(" #n ")" ::: "memory")
; #define PG8_BAR __builtin_amdgcn_s_barrier()
; #define PG8_SCHED __builtin_amdgcn_sched_barrier(0)
; template <class Epi>
; __device__ __forceinline__ void gemm_phase(LAS unsigned char* lds, const Gemm g, const StaticOrder& S, const Epi& E) {
;     ...
;             PG8_WAIT_V(8); PG8_WAIT_L(0); PG8_BAR; PG8_MMA(0, 0, At, B0); PG8_MMA(0, 1, At, B1); PG8_BAR; PG8_SCHED;
;             PG8_LDA(At, 0, 1); PG8_STAGE(PG8_SB(0, 0), b2, voffB); PG8_STAGE(PG8_SB(0, 1), b2 + hstepB, voffB); PG8_STAGE(PG8_SA(0, 0), a2, voffA);
;             PG8_WAIT_V(8); PG8_WAIT_L(0); PG8_BAR; PG8_MMA(1, 0, At, B0); PG8_MMA(1, 1, At, B1); PG8_BAR; PG8_SCHED;
	s_setprio 1
	s_waitcnt lgkmcnt(0)
	v_mfma_f32_16x16x32_bf16 v[124:127], v[144:147], v[190:193], v[124:127]
	v_mfma_f32_16x16x32_bf16 v[120:123], v[162:165], v[190:193], v[120:123]
	v_mfma_f32_16x16x32_bf16 v[108:111], v[144:147], v[198:201], v[108:111]
	v_mfma_f32_16x16x32_bf16 v[104:107], v[162:165], v[198:201], v[104:107]
	v_mfma_f32_16x16x32_bf16 v[92:95], v[144:147], v[206:209], v[92:95]
	v_mfma_f32_16x16x32_bf16 v[88:91], v[162:165], v[206:209], v[88:91]
	v_mfma_f32_16x16x32_bf16 v[76:79], v[144:147], v[214:217], v[76:79]
	v_mfma_f32_16x16x32_bf16 v[72:75], v[162:165], v[214:217], v[72:75]
	v_mfma_f32_16x16x32_bf16 v[124:127], v[158:161], v[194:197], v[124:127]
	v_mfma_f32_16x16x32_bf16 v[120:123], v[166:169], v[194:197], v[120:123]
	v_mfma_f32_16x16x32_bf16 v[108:111], v[158:161], v[202:205], v[108:111]
	v_mfma_f32_16x16x32_bf16 v[104:107], v[166:169], v[202:205], v[104:107]
	v_mfma_f32_16x16x32_bf16 v[92:95], v[158:161], v[210:213], v[92:95]
	v_mfma_f32_16x16x32_bf16 v[88:91], v[166:169], v[210:213], v[88:91]
	v_mfma_f32_16x16x32_bf16 v[76:79], v[158:161], v[218:221], v[76:79]
	v_mfma_f32_16x16x32_bf16 v[72:75], v[166:169], v[218:221], v[72:75]
	v_mfma_f32_16x16x32_bf16 v[116:119], v[170:173], v[190:193], v[116:119]
	v_mfma_f32_16x16x32_bf16 v[112:115], v[182:185], v[190:193], v[112:115]
	v_mfma_f32_16x16x32_bf16 v[100:103], v[170:173], v[198:201], v[100:103]
	v_mfma_f32_16x16x32_bf16 v[96:99], v[182:185], v[198:201], v[96:99]
	v_mfma_f32_16x16x32_bf16 v[84:87], v[170:173], v[206:209], v[84:87]
	v_mfma_f32_16x16x32_bf16 v[80:83], v[182:185], v[206:209], v[80:83]
	v_mfma_f32_16x16x32_bf16 v[68:71], v[170:173], v[214:217], v[68:71]
	v_mfma_f32_16x16x32_bf16 v[64:67], v[182:185], v[214:217], v[64:67]
	v_mfma_f32_16x16x32_bf16 v[116:119], v[178:181], v[194:197], v[116:119]
	v_mfma_f32_16x16x32_bf16 v[112:115], v[186:189], v[194:197], v[112:115]
	v_mfma_f32_16x16x32_bf16 v[100:103], v[178:181], v[202:205], v[100:103]
	v_mfma_f32_16x16x32_bf16 v[96:99], v[186:189], v[202:205], v[96:99]
	v_mfma_f32_16x16x32_bf16 v[84:87], v[178:181], v[210:213], v[84:87]
	v_mfma_f32_16x16x32_bf16 v[80:83], v[186:189], v[210:213], v[80:83]
	v_mfma_f32_16x16x32_bf16 v[68:71], v[178:181], v[218:221], v[68:71]
	v_mfma_f32_16x16x32_bf16 v[64:67], v[186:189], v[218:221], v[64:67]
	s_setprio 0
	s_barrier
	s_add_i32 s90, s84, s3
	v_lshl_add_u64 v[148:149], s[76:77], 0, v[130:131]
	s_mov_b32 m0, s90
	ds_read_b128 v[190:193], v155 offset:16384
	ds_read_b128 v[194:197], v155 offset:17408
	ds_read_b128 v[198:201], v155 offset:18432
	ds_read_b128 v[202:205], v155 offset:19456
	ds_read_b128 v[206:209], v155 offset:20480
	ds_read_b128 v[210:213], v155 offset:21504
	ds_read_b128 v[214:217], v155 offset:22528
	ds_read_b128 v[218:221], v155 offset:23552
	global_load_lds_dwordx4 v[148:149], off
	s_add_i32 m0, s90, 0x2000
	s_add_u32 s90, s76, 0x40000
	v_lshl_add_u64 v[174:175], s[76:77], 0, v[134:135]
	s_addc_u32 s91, s77, 0
	s_add_i32 s92, s85, s3
	global_load_lds_dwordx4 v[174:175], off
	v_lshl_add_u64 v[222:223], s[90:91], 0, v[130:131]
	s_mov_b32 m0, s92
	v_lshl_add_u64 v[226:227], s[78:79], 0, v[132:133]
	global_load_lds_dwordx4 v[222:223], off
	v_lshl_add_u64 v[222:223], s[90:91], 0, v[134:135]
	s_add_i32 m0, s92, 0x2000
	s_nop 0
	global_load_lds_dwordx4 v[222:223], off
	v_lshl_add_u64 v[222:223], s[78:79], 0, v[128:129]
	s_mov_b32 m0, s19
	s_nop 0
	global_load_lds_dwordx4 v[222:223], off
	s_mov_b32 m0, s23
	s_nop 0
	global_load_lds_dwordx4 v[226:227], off
	s_waitcnt vmcnt(8)
	s_waitcnt lgkmcnt(0)
	s_barrier
	s_setprio 1
	s_waitcnt lgkmcnt(0)
	v_mfma_f32_16x16x32_bf16 v[60:63], v[144:147], v[190:193], v[60:63]
	v_mfma_f32_16x16x32_bf16 v[56:59], v[162:165], v[190:193], v[56:59]
	v_mfma_f32_16x16x32_bf16 v[44:47], v[144:147], v[198:201], v[44:47]
	v_mfma_f32_16x16x32_bf16 v[40:43], v[162:165], v[198:201], v[40:43]
	v_mfma_f32_16x16x32_bf16 v[28:31], v[144:147], v[206:209], v[28:31]
	v_mfma_f32_16x16x32_bf16 v[24:27], v[162:165], v[206:209], v[24:27]
	v_mfma_f32_16x16x32_bf16 v[12:15], v[144:147], v[214:217], v[12:15]
	v_mfma_f32_16x16x32_bf16 v[8:11], v[162:165], v[214:217], v[8:11]
	v_mfma_f32_16x16x32_bf16 v[60:63], v[158:161], v[194:197], v[60:63]
	v_mfma_f32_16x16x32_bf16 v[56:59], v[166:169], v[194:197], v[56:59]
	v_mfma_f32_16x16x32_bf16 v[44:47], v[158:161], v[202:205], v[44:47]
	v_mfma_f32_16x16x32_bf16 v[40:43], v[166:169], v[202:205], v[40:43]
	v_mfma_f32_16x16x32_bf16 v[28:31], v[158:161], v[210:213], v[28:31]
	v_mfma_f32_16x16x32_bf16 v[24:27], v[166:169], v[210:213], v[24:27]
	v_mfma_f32_16x16x32_bf16 v[12:15], v[158:161], v[218:221], v[12:15]
	v_mfma_f32_16x16x32_bf16 v[8:11], v[166:169], v[218:221], v[8:11]
	v_mfma_f32_16x16x32_bf16 v[52:55], v[170:173], v[190:193], v[52:55]
	v_mfma_f32_16x16x32_bf16 v[48:51], v[182:185], v[190:193], v[48:51]
	v_mfma_f32_16x16x32_bf16 v[36:39], v[170:173], v[198:201], v[36:39]
	v_mfma_f32_16x16x32_bf16 v[32:35], v[182:185], v[198:201], v[32:35]
	v_mfma_f32_16x16x32_bf16 v[20:23], v[170:173], v[206:209], v[20:23]
	v_mfma_f32_16x16x32_bf16 v[16:19], v[182:185], v[206:209], v[16:19]
	v_mfma_f32_16x16x32_bf16 v[4:7], v[170:173], v[214:217], v[4:7]
	v_mfma_f32_16x16x32_bf16 v[0:3], v[182:185], v[214:217], v[0:3]
	v_mfma_f32_16x16x32_bf16 v[52:55], v[178:181], v[194:197], v[52:55]
	v_mfma_f32_16x16x32_bf16 v[48:51], v[186:189], v[194:197], v[48:51]
	v_mfma_f32_16x16x32_bf16 v[36:39], v[178:181], v[202:205], v[36:39]
	v_mfma_f32_16x16x32_bf16 v[32:35], v[186:189], v[202:205], v[32:35]
	v_mfma_f32_16x16x32_bf16 v[20:23], v[178:181], v[210:213], v[20:23]
	v_mfma_f32_16x16x32_bf16 v[16:19], v[186:189], v[210:213], v[16:19]
	v_mfma_f32_16x16x32_bf16 v[4:7], v[178:181], v[218:221], v[4:7]
	v_mfma_f32_16x16x32_bf16 v[0:3], v[186:189], v[218:221], v[0:3]
	s_setprio 0
	s_barrier
; #define PG8_STAGE(bufoff, gbase, voff) do { _Pragma("unroll") for (int _i = 0; _i < 2; ++_i) \
;         __builtin_amdgcn_global_load_lds((const unsigned*)((const char*)(gbase) + (voff)[_i]), (LAS unsigned*)(lds + (bufoff) + ldsw + _i * 8192), 16, 0, 0); } while (0)
; #define PG8_LDA(dst, b, h) do { _Pragma("unroll") for (int m = 0; m < 4; ++m) _Pragma("unroll") for (int k = 0; k < 2; ++k) dst[m][k] = *(const LAS bf16x8*)(lds + PG8_SA(b, h) + aoff + m * 2048 + k * 1024); } while (0)
; #define PG8_LDB(dst, b, h) do { _Pragma("unroll") for (int n = 0; n < 2; ++n) _Pragma("unroll") for (int k = 0; k < 2; ++k) dst[n][k] = *(const LAS bf16x8*)(lds + PG8_SB(b, h) + boff + n * 2048 + k * 1024); } while (0)
; #define PG8_MMA(ai, bj, At, Bt) do { __builtin_amdgcn_s_setprio(1); _Pragma("unroll") for (int m = 0; m < 4; ++m) _Pragma("unroll") for (int n = 0; n < 2; ++n) _Pragma("unroll") for (int k = 0; k < 2; ++k) \
;         acc[ai][bj][m][n] = __builtin_amdgcn_mfma_f32_16x16x32_bf16(Bt[n][k], At[m][k], acc[ai][bj][m][n], 0, 0, 0); __builtin_amdgcn_s_setprio(0); } while (0)
; #define PG8_WAIT_V(n) asm volatile("s_waitcnt vmcnt(" #n ")" ::: "memory")
; #define PG8_WAIT_L(n) asm volatile("s_waitcnt lgkmcnt(" #n ")" ::: "memory")
; #define PG8_BAR __builtin_amdgcn_s_barrier()
; #define PG8_SCHED __builtin_amdgcn_sched_barrier(0)
; template <class Epi>
; __device__ __forceinline__ void gemm_phase(LAS unsigned char* lds, const Gemm g, const StaticOrder& S, const Epi& E) {
;     ...
;             PG8_LDB(B0, 1, 0); PG8_LDB(B1, 1, 1); PG8_SCHED; PG8_LDA(At, 1, 0); PG8_STAGE(PG8_SA(0, 1), a2 + hstepA, voffA);
;             PG8_WAIT_V(8); PG8_WAIT_L(0); PG8_BAR; PG8_MMA(0, 0, At, B0); PG8_MMA(0, 1, At, B1); PG8_BAR; PG8_SCHED;
	s_add_i32 s90, 0, 0x18000
	v_add_u32_e32 v157, s90, v152
	s_add_i32 s91, 0, 0x1c000
	ds_read_b128 v[144:147], v157
	ds_read_b128 v[158:161], v157 offset:1024
	ds_read_b128 v[162:165], v157 offset:2048
	ds_read_b128 v[166:169], v157 offset:3072
	v_add_u32_e32 v157, s91, v152
	ds_read_b128 v[170:173], v157
	ds_read_b128 v[178:181], v157 offset:1024
	ds_read_b128 v[182:185], v157 offset:2048
	ds_read_b128 v[186:189], v157 offset:3072
	s_add_u32 s78, s78, 0x40000
	s_addc_u32 s79, s79, 0
	s_mov_b32 m0, s33
	v_lshl_add_u64 v[228:229], s[78:79], 0, v[128:129]
	ds_read_b128 v[190:193], v155 offset:32768
	ds_read_b128 v[194:197], v155 offset:33792
	ds_read_b128 v[198:201], v155 offset:34816
	ds_read_b128 v[202:205], v155 offset:35840
	ds_read_b128 v[206:209], v155 offset:36864
	ds_read_b128 v[210:213], v155 offset:37888
	ds_read_b128 v[214:217], v155 offset:38912
	ds_read_b128 v[218:221], v155 offset:39936
	global_load_lds_dwordx4 v[228:229], off
	v_lshl_add_u64 v[228:229], s[78:79], 0, v[132:133]
	s_mov_b32 m0, s35
	s_nop 0
	global_load_lds_dwordx4 v[228:229], off
	s_waitcnt vmcnt(8)
	s_waitcnt lgkmcnt(0)
	s_barrier
	s_setprio 1
	s_waitcnt lgkmcnt(0)
	v_mfma_f32_16x16x32_bf16 v[124:127], v[144:147], v[190:193], v[124:127]
	v_mfma_f32_16x16x32_bf16 v[120:123], v[162:165], v[190:193], v[120:123]
	v_mfma_f32_16x16x32_bf16 v[108:111], v[144:147], v[198:201], v[108:111]
	v_mfma_f32_16x16x32_bf16 v[104:107], v[162:165], v[198:201], v[104:107]
	v_mfma_f32_16x16x32_bf16 v[92:95], v[144:147], v[206:209], v[92:95]
	v_mfma_f32_16x16x32_bf16 v[88:91], v[162:165], v[206:209], v[88:91]
	v_mfma_f32_16x16x32_bf16 v[76:79], v[144:147], v[214:217], v[76:79]
	v_mfma_f32_16x16x32_bf16 v[72:75], v[162:165], v[214:217], v[72:75]
	v_mfma_f32_16x16x32_bf16 v[124:127], v[158:161], v[194:197], v[124:127]
	v_mfma_f32_16x16x32_bf16 v[120:123], v[166:169], v[194:197], v[120:123]
	v_mfma_f32_16x16x32_bf16 v[108:111], v[158:161], v[202:205], v[108:111]
	v_mfma_f32_16x16x32_bf16 v[104:107], v[166:169], v[202:205], v[104:107]
	v_mfma_f32_16x16x32_bf16 v[92:95], v[158:161], v[210:213], v[92:95]
	v_mfma_f32_16x16x32_bf16 v[88:91], v[166:169], v[210:213], v[88:91]
	v_mfma_f32_16x16x32_bf16 v[76:79], v[158:161], v[218:221], v[76:79]
	v_mfma_f32_16x16x32_bf16 v[72:75], v[166:169], v[218:221], v[72:75]
	v_mfma_f32_16x16x32_bf16 v[116:119], v[170:173], v[190:193], v[116:119]
	v_mfma_f32_16x16x32_bf16 v[112:115], v[182:185], v[190:193], v[112:115]
	v_mfma_f32_16x16x32_bf16 v[100:103], v[170:173], v[198:201], v[100:103]
	v_mfma_f32_16x16x32_bf16 v[96:99], v[182:185], v[198:201], v[96:99]
	v_mfma_f32_16x16x32_bf16 v[84:87], v[170:173], v[206:209], v[84:87]
	v_mfma_f32_16x16x32_bf16 v[80:83], v[182:185], v[206:209], v[80:83]
	v_mfma_f32_16x16x32_bf16 v[68:71], v[170:173], v[214:217], v[68:71]
	v_mfma_f32_16x16x32_bf16 v[64:67], v[182:185], v[214:217], v[64:67]
	v_mfma_f32_16x16x32_bf16 v[116:119], v[178:181], v[194:197], v[116:119]
	v_mfma_f32_16x16x32_bf16 v[112:115], v[186:189], v[194:197], v[112:115]
	v_mfma_f32_16x16x32_bf16 v[100:103], v[178:181], v[202:205], v[100:103]
	v_mfma_f32_16x16x32_bf16 v[96:99], v[186:189], v[202:205], v[96:99]
	v_mfma_f32_16x16x32_bf16 v[84:87], v[178:181], v[210:213], v[84:87]
	v_mfma_f32_16x16x32_bf16 v[80:83], v[186:189], v[210:213], v[80:83]
	v_mfma_f32_16x16x32_bf16 v[68:71], v[178:181], v[218:221], v[68:71]
	v_mfma_f32_16x16x32_bf16 v[64:67], v[186:189], v[218:221], v[64:67]
	s_setprio 0
	s_barrier
; #define PG8_STAGE(bufoff, gbase, voff) do { _Pragma("unroll") for (int _i = 0; _i < 2; ++_i) \
;         __builtin_amdgcn_global_load_lds((const unsigned*)((const char*)(gbase) + (voff)[_i]), (LAS unsigned*)(lds + (bufoff) + ldsw + _i * 8192), 16, 0, 0); } while (0)
; #define PG8_LDA(dst, b, h) do { _Pragma("unroll") for (int m = 0; m < 4; ++m) _Pragma("unroll") for (int k = 0; k < 2; ++k) dst[m][k] = *(const LAS bf16x8*)(lds + PG8_SA(b, h) + aoff + m * 2048 + k * 1024); } while (0)
; #define PG8_MMA(ai, bj, At, Bt) do { __builtin_amdgcn_s_setprio(1); _Pragma("unroll") for (int m = 0; m < 4; ++m) _Pragma("unroll") for (int n = 0; n < 2; ++n) _Pragma("unroll") for (int k = 0; k < 2; ++k) \
;         acc[ai][bj][m][n] = __builtin_amdgcn_mfma_f32_16x16x32_bf16(Bt[n][k], At[m][k], acc[ai][bj][m][n], 0, 0, 0); __builtin_amdgcn_s_setprio(0); } while (0)
; #define PG8_WAIT_V(n) asm volatile("s_waitcnt vmcnt(" #n ")" ::: "memory")
; #define PG8_WAIT_L(n) asm volatile("s_waitcnt lgkmcnt(" #n ")" ::: "memory")
; #define PG8_BAR __builtin_amdgcn_s_barrier()
; #define PG8_SCHED __builtin_amdgcn_sched_barrier(0)
; template <class Epi>
; __device__ __forceinline__ void gemm_phase(LAS unsigned char* lds, const Gemm g, const StaticOrder& S, const Epi& E) {
;     ...
;             PG8_LDA(At, 1, 1); PG8_STAGE(PG8_SB(1, 0), b3, voffB); PG8_STAGE(PG8_SB(1, 1), b3 + hstepB, voffB); PG8_STAGE(PG8_SA(1, 0), a3, voffA);
;             PG8_WAIT_V(8); PG8_WAIT_L(0); PG8_BAR; PG8_MMA(1, 0, At, B0); PG8_MMA(1, 1, At, B1); PG8_BAR; PG8_SCHED;
;         }
;         if (wr == 0) PG8_BAR;
	s_add_i32 s78, s90, s3
	v_lshl_add_u64 v[148:149], v[148:149], 0, s[12:13]
	s_mov_b32 m0, s78
	ds_read_b128 v[190:193], v155 offset:49152
	ds_read_b128 v[194:197], v155 offset:50176
	ds_read_b128 v[198:201], v155 offset:51200
	ds_read_b128 v[202:205], v155 offset:52224
	ds_read_b128 v[206:209], v155 offset:53248
	ds_read_b128 v[210:213], v155 offset:54272
	ds_read_b128 v[214:217], v155 offset:55296
	ds_read_b128 v[218:221], v155 offset:56320
	global_load_lds_dwordx4 v[148:149], off
	s_add_i32 m0, s78, 0x2000
	s_add_u32 s76, s76, 0x40080
	v_lshl_add_u64 v[148:149], v[174:175], 0, s[12:13]
	s_addc_u32 s77, s77, 0
	s_add_i32 s78, s91, s3
	global_load_lds_dwordx4 v[148:149], off
	v_lshl_add_u64 v[148:149], s[76:77], 0, v[130:131]
	s_mov_b32 m0, s78
	s_nop 0
	global_load_lds_dwordx4 v[148:149], off
	v_lshl_add_u64 v[148:149], s[76:77], 0, v[134:135]
	s_add_i32 m0, s78, 0x2000
	s_nop 0
	global_load_lds_dwordx4 v[148:149], off
	v_lshl_add_u64 v[148:149], v[222:223], 0, s[12:13]
	s_mov_b32 m0, s57
	s_nop 0
	global_load_lds_dwordx4 v[148:149], off
	v_lshl_add_u64 v[148:149], v[226:227], 0, s[12:13]
	s_mov_b32 m0, s80
	s_nop 0
	global_load_lds_dwordx4 v[148:149], off
	s_waitcnt vmcnt(8)
	s_waitcnt lgkmcnt(0)
	s_barrier
	s_setprio 1
	s_waitcnt lgkmcnt(0)
	v_mfma_f32_16x16x32_bf16 v[60:63], v[144:147], v[190:193], v[60:63]
	v_mfma_f32_16x16x32_bf16 v[56:59], v[162:165], v[190:193], v[56:59]
	v_mfma_f32_16x16x32_bf16 v[44:47], v[144:147], v[198:201], v[44:47]
	v_mfma_f32_16x16x32_bf16 v[40:43], v[162:165], v[198:201], v[40:43]
	v_mfma_f32_16x16x32_bf16 v[28:31], v[144:147], v[206:209], v[28:31]
	v_mfma_f32_16x16x32_bf16 v[24:27], v[162:165], v[206:209], v[24:27]
	v_mfma_f32_16x16x32_bf16 v[12:15], v[144:147], v[214:217], v[12:15]
	v_mfma_f32_16x16x32_bf16 v[8:11], v[162:165], v[214:217], v[8:11]
	v_mfma_f32_16x16x32_bf16 v[60:63], v[158:161], v[194:197], v[60:63]
	v_mfma_f32_16x16x32_bf16 v[56:59], v[166:169], v[194:197], v[56:59]
	v_mfma_f32_16x16x32_bf16 v[44:47], v[158:161], v[202:205], v[44:47]
	v_mfma_f32_16x16x32_bf16 v[40:43], v[166:169], v[202:205], v[40:43]
	v_mfma_f32_16x16x32_bf16 v[28:31], v[158:161], v[210:213], v[28:31]
	v_mfma_f32_16x16x32_bf16 v[24:27], v[166:169], v[210:213], v[24:27]
	v_mfma_f32_16x16x32_bf16 v[12:15], v[158:161], v[218:221], v[12:15]
	v_mfma_f32_16x16x32_bf16 v[8:11], v[166:169], v[218:221], v[8:11]
	v_mfma_f32_16x16x32_bf16 v[52:55], v[170:173], v[190:193], v[52:55]
	v_mfma_f32_16x16x32_bf16 v[48:51], v[182:185], v[190:193], v[48:51]
	v_mfma_f32_16x16x32_bf16 v[36:39], v[170:173], v[198:201], v[36:39]
	v_mfma_f32_16x16x32_bf16 v[32:35], v[182:185], v[198:201], v[32:35]
	v_mfma_f32_16x16x32_bf16 v[20:23], v[170:173], v[206:209], v[20:23]
	v_mfma_f32_16x16x32_bf16 v[16:19], v[182:185], v[206:209], v[16:19]
	v_mfma_f32_16x16x32_bf16 v[4:7], v[170:173], v[214:217], v[4:7]
	v_mfma_f32_16x16x32_bf16 v[0:3], v[182:185], v[214:217], v[0:3]
	v_mfma_f32_16x16x32_bf16 v[52:55], v[178:181], v[194:197], v[52:55]
	v_mfma_f32_16x16x32_bf16 v[48:51], v[186:189], v[194:197], v[48:51]
	v_mfma_f32_16x16x32_bf16 v[36:39], v[178:181], v[202:205], v[36:39]
	v_mfma_f32_16x16x32_bf16 v[32:35], v[186:189], v[202:205], v[32:35]
	v_mfma_f32_16x16x32_bf16 v[20:23], v[178:181], v[210:213], v[20:23]
	v_mfma_f32_16x16x32_bf16 v[16:19], v[186:189], v[210:213], v[16:19]
	v_mfma_f32_16x16x32_bf16 v[4:7], v[178:181], v[218:221], v[4:7]
	v_mfma_f32_16x16x32_bf16 v[0:3], v[186:189], v[218:221], v[0:3]
	s_setprio 0
	s_barrier
	s_add_i32 s89, s89, 2
	s_add_u32 s74, s74, 0x100
	s_addc_u32 s75, s75, 0
	s_add_u32 s87, s87, 0x100
	s_addc_u32 s88, s88, 0
	s_cmp_gt_u32 s89, 13
	s_cbranch_scc0 .LBB0_192
	s_and_b64 vcc, exec, s[14:15]
	s_cbranch_vccz .LBB0_195
	s_barrier

; #define PG8_STAGE(bufoff, gbase, voff) do { _Pragma("unroll") for (int _i = 0; _i < 2; ++_i) \
;         __builtin_amdgcn_global_load_lds((const unsigned*)((const char*)(gbase) + (voff)[_i]), (LAS unsigned*)(lds + (bufoff) + ldsw + _i * 8192), 16, 0, 0); } while (0)
; #define PG8_LDA(dst, b, h) do { _Pragma("unroll") for (int m = 0; m < 4; ++m) _Pragma("unroll") for (int k = 0; k < 2; ++k) dst[m][k] = *(const LAS bf16x8*)(lds + PG8_SA(b, h) + aoff + m * 2048 + k * 1024); } while (0)
; #define PG8_LDB(dst, b, h) do { _Pragma("unroll") for (int n = 0; n < 2; ++n) _Pragma("unroll") for (int k = 0; k < 2; ++k) dst[n][k] = *(const LAS bf16x8*)(lds + PG8_SB(b, h) + boff + n * 2048 + k * 1024); } while (0)
; #define PG8_MMA(ai, bj, At, Bt) do { __builtin_amdgcn_s_setprio(1); _Pragma("unroll") for (int m = 0; m < 4; ++m) _Pragma("unroll") for (int n = 0; n < 2; ++n) _Pragma("unroll") for (int k = 0; k < 2; ++k) \
;         acc[ai][bj][m][n] = __builtin_amdgcn_mfma_f32_16x16x32_bf16(Bt[n][k], At[m][k], acc[ai][bj][m][n], 0, 0, 0); __builtin_amdgcn_s_setprio(0); } while (0)
; #define PG8_BAR __builtin_amdgcn_s_barrier()
; template <class Epi>
; __device__ __forceinline__ void gemm_phase(LAS unsigned char* lds, const Gemm g, const StaticOrder& S, const Epi& E) {
;     ...
;         const bool has_next = S.next(ui + 1, nxt);
;         const char* nA = has_next ? (const char*)g.A + (size_t)nxt.pm * tstepA : cA; const char* nB = has_next ? (const char*)g.Bt + (size_t)nxt.pn * tstepB : cB;
; #pragma nounroll
;         for (int t = 0; t < nt; t += 2) {
;             const bool last = (t == nt - 2);
;             const char* a1 = cA + (size_t)(t + 1) * kstep;
;             const char* a2 = last ? nA : cA + (size_t)(t + 2) * kstep; const char* b2 = last ? nB : cB + (size_t)(t + 2) * kstep;
;             const char* a3 = a2 + kstep; const char* b3 = b2 + kstep;
;             PG8_LDB(B0, 0, 0); PG8_LDB(B1, 0, 1); PG8_SCHED; PG8_LDA(At, 0, 0); PG8_STAGE(PG8_SA(1, 1), a1 + hstepA, voffA);
;             PG8_WAIT_V(8); PG8_WAIT_L(0); PG8_BAR; PG8_MMA(0, 0, At, B0); PG8_MMA(0, 1, At, B1); PG8_BAR; PG8_SCHED;
;             PG8_LDA(At, 0, 1); PG8_STAGE(PG8_SB(0, 0), b2, voffB); PG8_STAGE(PG8_SB(0, 1), b2 + hstepB, voffB); PG8_STAGE(PG8_SA(0, 0), a2, voffA);
;             PG8_WAIT_V(8); PG8_WAIT_L(0); PG8_BAR; PG8_MMA(1, 0, At, B0); PG8_MMA(1, 1, At, B1); PG8_BAR; PG8_SCHED;
.LBB0_456:
	s_ashr_i32 s23, s22, 31
	s_lshl_b64 s[28:29], s[22:23], 19
	s_add_u32 s28, s40, s28
	s_addc_u32 s29, s41, s29
	s_and_b64 s[30:31], s[4:5], exec
	s_cselect_b32 s1, s29, s39
	s_cselect_b32 s23, s28, s38
	s_ashr_i32 s19, s18, 31
	s_lshl_b64 s[30:31], s[18:19], 19
	s_add_u32 s30, s3, s30
	s_addc_u32 s31, s33, s31
	s_and_b64 s[52:53], s[4:5], exec
	s_cselect_b32 s19, s31, s43
	s_cselect_b32 s74, s30, s42
	s_add_u32 s38, s38, 0x40080
	s_addc_u32 s39, s39, 0
	s_add_u32 s75, s42, 0x100
	s_addc_u32 s76, s43, 0
	s_mov_b32 s77, -2
	s_waitcnt lgkmcnt(0)
	s_nop 0
	ds_read_b128 v[128:131], v173
	ds_read_b128 v[132:135], v173 offset:1024
	ds_read_b128 v[136:139], v173 offset:2048
	ds_read_b128 v[140:143], v173 offset:3072
	ds_read_b128 v[160:163], v174
	ds_read_b128 v[164:167], v174 offset:1024
	ds_read_b128 v[178:181], v174 offset:2048
	ds_read_b128 v[182:185], v174 offset:3072
	s_add_u32 s42, s38, 0xfffc0080
	s_addc_u32 s43, s39, -1
	s_cmp_eq_u32 s77, 12
	s_cselect_b32 s53, s1, s43
	s_cselect_b32 s52, s23, s42
	s_cselect_b32 s43, s19, s76
	s_cselect_b32 s42, s74, s75
	v_lshl_add_u64 v[168:169], s[38:39], 0, v[152:153]
	s_add_i32 m0, s35, 0xc000
	ds_read_b128 v[186:189], v175
	ds_read_b128 v[190:193], v175 offset:1024
	ds_read_b128 v[194:197], v175 offset:2048
	ds_read_b128 v[198:201], v175 offset:3072
	ds_read_b128 v[202:205], v175 offset:4096
	ds_read_b128 v[206:209], v175 offset:5120
	ds_read_b128 v[210:213], v175 offset:6144
	ds_read_b128 v[214:217], v175 offset:7168
	global_load_lds_dwordx4 v[168:169], off
	v_lshl_add_u64 v[168:169], s[38:39], 0, v[154:155]
	s_add_i32 m0, s35, 0xe000
	s_nop 0
	global_load_lds_dwordx4 v[168:169], off
	s_waitcnt vmcnt(8)
	s_waitcnt lgkmcnt(0)
	s_barrier
	s_setprio 1
	s_waitcnt lgkmcnt(0)
	v_mfma_f32_16x16x32_bf16 v[124:127], v[128:131], v[186:189], 0
	v_mfma_f32_16x16x32_bf16 v[120:123], v[136:139], v[186:189], 0
	v_mfma_f32_16x16x32_bf16 v[108:111], v[128:131], v[194:197], 0
	v_mfma_f32_16x16x32_bf16 v[104:107], v[136:139], v[194:197], 0
	v_mfma_f32_16x16x32_bf16 v[92:95], v[128:131], v[202:205], 0
	v_mfma_f32_16x16x32_bf16 v[88:91], v[136:139], v[202:205], 0
	v_mfma_f32_16x16x32_bf16 v[76:79], v[128:131], v[210:213], 0
	v_mfma_f32_16x16x32_bf16 v[72:75], v[136:139], v[210:213], 0
	v_mfma_f32_16x16x32_bf16 v[124:127], v[132:135], v[190:193], v[124:127]
	v_mfma_f32_16x16x32_bf16 v[120:123], v[140:143], v[190:193], v[120:123]
	v_mfma_f32_16x16x32_bf16 v[108:111], v[132:135], v[198:201], v[108:111]
	v_mfma_f32_16x16x32_bf16 v[104:107], v[140:143], v[198:201], v[104:107]
	v_mfma_f32_16x16x32_bf16 v[92:95], v[132:135], v[206:209], v[92:95]
	v_mfma_f32_16x16x32_bf16 v[88:91], v[140:143], v[206:209], v[88:91]
	v_mfma_f32_16x16x32_bf16 v[76:79], v[132:135], v[214:217], v[76:79]
	v_mfma_f32_16x16x32_bf16 v[72:75], v[140:143], v[214:217], v[72:75]
	v_mfma_f32_16x16x32_bf16 v[116:119], v[160:163], v[186:189], 0
	v_mfma_f32_16x16x32_bf16 v[112:115], v[178:181], v[186:189], 0
	v_mfma_f32_16x16x32_bf16 v[100:103], v[160:163], v[194:197], 0
	v_mfma_f32_16x16x32_bf16 v[96:99], v[178:181], v[194:197], 0
	v_mfma_f32_16x16x32_bf16 v[84:87], v[160:163], v[202:205], 0
	v_mfma_f32_16x16x32_bf16 v[80:83], v[178:181], v[202:205], 0
	v_mfma_f32_16x16x32_bf16 v[68:71], v[160:163], v[210:213], 0
	v_mfma_f32_16x16x32_bf16 v[64:67], v[178:181], v[210:213], 0
	v_mfma_f32_16x16x32_bf16 v[116:119], v[164:167], v[190:193], v[116:119]
	v_mfma_f32_16x16x32_bf16 v[112:115], v[182:185], v[190:193], v[112:115]
	v_mfma_f32_16x16x32_bf16 v[100:103], v[164:167], v[198:201], v[100:103]
	v_mfma_f32_16x16x32_bf16 v[96:99], v[182:185], v[198:201], v[96:99]
	v_mfma_f32_16x16x32_bf16 v[84:87], v[164:167], v[206:209], v[84:87]
	v_mfma_f32_16x16x32_bf16 v[80:83], v[182:185], v[206:209], v[80:83]
	v_mfma_f32_16x16x32_bf16 v[68:71], v[164:167], v[214:217], v[68:71]
	v_mfma_f32_16x16x32_bf16 v[64:67], v[182:185], v[214:217], v[64:67]
	s_setprio 0
	s_barrier
	s_add_i32 s78, s72, s54
	v_lshl_add_u64 v[168:169], s[42:43], 0, v[146:147]
	s_mov_b32 m0, s78
	ds_read_b128 v[186:189], v175 offset:16384
	ds_read_b128 v[190:193], v175 offset:17408
	ds_read_b128 v[194:197], v175 offset:18432
	ds_read_b128 v[198:201], v175 offset:19456
	ds_read_b128 v[202:205], v175 offset:20480
	ds_read_b128 v[206:209], v175 offset:21504
	ds_read_b128 v[210:213], v175 offset:22528
	ds_read_b128 v[214:217], v175 offset:23552
	global_load_lds_dwordx4 v[168:169], off
	s_add_i32 m0, s78, 0x2000
	s_add_u32 s78, s42, 0x40000
	v_lshl_add_u64 v[218:219], s[42:43], 0, v[150:151]
	s_addc_u32 s79, s43, 0
	s_add_i32 s80, s73, s54
	global_load_lds_dwordx4 v[218:219], off
	v_lshl_add_u64 v[220:221], s[78:79], 0, v[146:147]
	s_mov_b32 m0, s80
	v_lshl_add_u64 v[222:223], s[52:53], 0, v[148:149]
	global_load_lds_dwordx4 v[220:221], off
	v_lshl_add_u64 v[220:221], s[78:79], 0, v[150:151]
	s_add_i32 m0, s80, 0x2000
	s_nop 0
	global_load_lds_dwordx4 v[220:221], off
	v_lshl_add_u64 v[220:221], s[52:53], 0, v[144:145]
	s_mov_b32 m0, s35
	s_nop 0
	global_load_lds_dwordx4 v[220:221], off
	s_mov_b32 m0, s55
	s_nop 0
	global_load_lds_dwordx4 v[222:223], off
	s_waitcnt vmcnt(8)
	s_waitcnt lgkmcnt(0)
	s_barrier
; #define PG8_STAGE(bufoff, gbase, voff) do { _Pragma("unroll") for (int _i = 0; _i < 2; ++_i) \
;         __builtin_amdgcn_global_load_lds((const unsigned*)((const char*)(gbase) + (voff)[_i]), (LAS unsigned*)(lds + (bufoff) + ldsw + _i * 8192), 16, 0, 0); } while (0)
; #define PG8_LDA(dst, b, h) do { _Pragma("unroll") for (int m = 0; m < 4; ++m) _Pragma("unroll") for (int k = 0; k < 2; ++k) dst[m][k] = *(const LAS bf16x8*)(lds + PG8_SA(b, h) + aoff + m * 2048 + k * 1024); } while (0)
; #define PG8_LDB(dst, b, h) do { _Pragma("unroll") for (int n = 0; n < 2; ++n) _Pragma("unroll") for (int k = 0; k < 2; ++k) dst[n][k] = *(const LAS bf16x8*)(lds + PG8_SB(b, h) + boff + n * 2048 + k * 1024); } while (0)
; #define PG8_MMA(ai, bj, At, Bt) do { __builtin_amdgcn_s_setprio(1); _Pragma("unroll") for (int m = 0; m < 4; ++m) _Pragma("unroll") for (int n = 0; n < 2; ++n) _Pragma("unroll") for (int k = 0; k < 2; ++k) \
;         acc[ai][bj][m][n] = __builtin_amdgcn_mfma_f32_16x16x32_bf16(Bt[n][k], At[m][k], acc[ai][bj][m][n], 0, 0, 0); __builtin_amdgcn_s_setprio(0); } while (0)
; #define PG8_WAIT_V(n) asm volatile("s_waitcnt vmcnt(" #n ")" ::: "memory")
; #define PG8_WAIT_L(n) asm volatile("s_waitcnt lgkmcnt(" #n ")" ::: "memory")
; #define PG8_BAR __builtin_amdgcn_s_barrier()
; #define PG8_SCHED __builtin_amdgcn_sched_barrier(0)
; template <class Epi>
; __device__ __forceinline__ void gemm_phase(LAS unsigned char* lds, const Gemm g, const StaticOrder& S, const Epi& E) {
;     ...
;             PG8_WAIT_V(8); PG8_WAIT_L(0); PG8_BAR; PG8_MMA(1, 0, At, B0); PG8_MMA(1, 1, At, B1); PG8_BAR; PG8_SCHED;
;             PG8_LDB(B0, 1, 0); PG8_LDB(B1, 1, 1); PG8_SCHED; PG8_LDA(At, 1, 0); PG8_STAGE(PG8_SA(0, 1), a2 + hstepA, voffA);
;             PG8_WAIT_V(8); PG8_WAIT_L(0); PG8_BAR; PG8_MMA(0, 0, At, B0); PG8_MMA(0, 1, At, B1); PG8_BAR; PG8_SCHED;
	s_setprio 1
	s_waitcnt lgkmcnt(0)
	v_mfma_f32_16x16x32_bf16 v[60:63], v[128:131], v[186:189], 0
	v_mfma_f32_16x16x32_bf16 v[56:59], v[136:139], v[186:189], 0
	v_mfma_f32_16x16x32_bf16 v[44:47], v[128:131], v[194:197], 0
	v_mfma_f32_16x16x32_bf16 v[40:43], v[136:139], v[194:197], 0
	v_mfma_f32_16x16x32_bf16 v[28:31], v[128:131], v[202:205], 0
	v_mfma_f32_16x16x32_bf16 v[24:27], v[136:139], v[202:205], 0
	v_mfma_f32_16x16x32_bf16 v[12:15], v[128:131], v[210:213], 0
	v_mfma_f32_16x16x32_bf16 v[8:11], v[136:139], v[210:213], 0
	v_mfma_f32_16x16x32_bf16 v[60:63], v[132:135], v[190:193], v[60:63]
	v_mfma_f32_16x16x32_bf16 v[56:59], v[140:143], v[190:193], v[56:59]
	v_mfma_f32_16x16x32_bf16 v[44:47], v[132:135], v[198:201], v[44:47]
	v_mfma_f32_16x16x32_bf16 v[40:43], v[140:143], v[198:201], v[40:43]
	v_mfma_f32_16x16x32_bf16 v[28:31], v[132:135], v[206:209], v[28:31]
	v_mfma_f32_16x16x32_bf16 v[24:27], v[140:143], v[206:209], v[24:27]
	v_mfma_f32_16x16x32_bf16 v[12:15], v[132:135], v[214:217], v[12:15]
	v_mfma_f32_16x16x32_bf16 v[8:11], v[140:143], v[214:217], v[8:11]
	v_mfma_f32_16x16x32_bf16 v[52:55], v[160:163], v[186:189], 0
	v_mfma_f32_16x16x32_bf16 v[48:51], v[178:181], v[186:189], 0
	v_mfma_f32_16x16x32_bf16 v[36:39], v[160:163], v[194:197], 0
	v_mfma_f32_16x16x32_bf16 v[32:35], v[178:181], v[194:197], 0
	v_mfma_f32_16x16x32_bf16 v[20:23], v[160:163], v[202:205], 0
	v_mfma_f32_16x16x32_bf16 v[16:19], v[178:181], v[202:205], 0
	v_mfma_f32_16x16x32_bf16 v[4:7], v[160:163], v[210:213], 0
	v_mfma_f32_16x16x32_bf16 v[0:3], v[178:181], v[210:213], 0
	v_mfma_f32_16x16x32_bf16 v[52:55], v[164:167], v[190:193], v[52:55]
	v_mfma_f32_16x16x32_bf16 v[48:51], v[182:185], v[190:193], v[48:51]
	v_mfma_f32_16x16x32_bf16 v[36:39], v[164:167], v[198:201], v[36:39]
	v_mfma_f32_16x16x32_bf16 v[32:35], v[182:185], v[198:201], v[32:35]
	v_mfma_f32_16x16x32_bf16 v[20:23], v[164:167], v[206:209], v[20:23]
	v_mfma_f32_16x16x32_bf16 v[16:19], v[182:185], v[206:209], v[16:19]
	v_mfma_f32_16x16x32_bf16 v[4:7], v[164:167], v[214:217], v[4:7]
	v_mfma_f32_16x16x32_bf16 v[0:3], v[182:185], v[214:217], v[0:3]
	s_setprio 0
	s_barrier
	s_add_i32 s78, 0, 0x18000
	s_add_i32 s79, 0, 0x1c000
	v_add_u32_e32 v140, s78, v172
	v_add_u32_e32 v182, s79, v172
	ds_read_b128 v[128:131], v140
	ds_read_b128 v[132:135], v140 offset:1024
	ds_read_b128 v[136:139], v140 offset:2048
	ds_read_b128 v[140:143], v140 offset:3072
	ds_read_b128 v[160:163], v182
	ds_read_b128 v[164:167], v182 offset:1024
	ds_read_b128 v[178:181], v182 offset:2048
	ds_read_b128 v[182:185], v182 offset:3072
	s_add_u32 s52, s52, 0x40000
	s_addc_u32 s53, s53, 0
	s_mov_b32 m0, s56
	v_lshl_add_u64 v[226:227], s[52:53], 0, v[144:145]
	ds_read_b128 v[186:189], v175 offset:32768
	ds_read_b128 v[190:193], v175 offset:33792
	ds_read_b128 v[194:197], v175 offset:34816
	ds_read_b128 v[198:201], v175 offset:35840
	ds_read_b128 v[202:205], v175 offset:36864
	ds_read_b128 v[206:209], v175 offset:37888
	ds_read_b128 v[210:213], v175 offset:38912
	ds_read_b128 v[214:217], v175 offset:39936
	global_load_lds_dwordx4 v[226:227], off
	v_lshl_add_u64 v[226:227], s[52:53], 0, v[148:149]
	s_mov_b32 m0, s57
	s_nop 0
	global_load_lds_dwordx4 v[226:227], off
	s_waitcnt vmcnt(8)
	s_waitcnt lgkmcnt(0)
	s_barrier
	s_setprio 1
	s_waitcnt lgkmcnt(0)
	v_mfma_f32_16x16x32_bf16 v[124:127], v[128:131], v[186:189], v[124:127]
	v_mfma_f32_16x16x32_bf16 v[120:123], v[136:139], v[186:189], v[120:123]
	v_mfma_f32_16x16x32_bf16 v[108:111], v[128:131], v[194:197], v[108:111]
	v_mfma_f32_16x16x32_bf16 v[104:107], v[136:139], v[194:197], v[104:107]
	v_mfma_f32_16x16x32_bf16 v[92:95], v[128:131], v[202:205], v[92:95]
	v_mfma_f32_16x16x32_bf16 v[88:91], v[136:139], v[202:205], v[88:91]
	v_mfma_f32_16x16x32_bf16 v[76:79], v[128:131], v[210:213], v[76:79]
	v_mfma_f32_16x16x32_bf16 v[72:75], v[136:139], v[210:213], v[72:75]
	v_mfma_f32_16x16x32_bf16 v[124:127], v[132:135], v[190:193], v[124:127]
	v_mfma_f32_16x16x32_bf16 v[120:123], v[140:143], v[190:193], v[120:123]
	v_mfma_f32_16x16x32_bf16 v[108:111], v[132:135], v[198:201], v[108:111]
	v_mfma_f32_16x16x32_bf16 v[104:107], v[140:143], v[198:201], v[104:107]
	v_mfma_f32_16x16x32_bf16 v[92:95], v[132:135], v[206:209], v[92:95]
	v_mfma_f32_16x16x32_bf16 v[88:91], v[140:143], v[206:209], v[88:91]
	v_mfma_f32_16x16x32_bf16 v[76:79], v[132:135], v[214:217], v[76:79]
	v_mfma_f32_16x16x32_bf16 v[72:75], v[140:143], v[214:217], v[72:75]
	v_mfma_f32_16x16x32_bf16 v[116:119], v[160:163], v[186:189], v[116:119]
	v_mfma_f32_16x16x32_bf16 v[112:115], v[178:181], v[186:189], v[112:115]
	v_mfma_f32_16x16x32_bf16 v[100:103], v[160:163], v[194:197], v[100:103]
	v_mfma_f32_16x16x32_bf16 v[96:99], v[178:181], v[194:197], v[96:99]
	v_mfma_f32_16x16x32_bf16 v[84:87], v[160:163], v[202:205], v[84:87]
	v_mfma_f32_16x16x32_bf16 v[80:83], v[178:181], v[202:205], v[80:83]
	v_mfma_f32_16x16x32_bf16 v[68:71], v[160:163], v[210:213], v[68:71]
	v_mfma_f32_16x16x32_bf16 v[64:67], v[178:181], v[210:213], v[64:67]
	v_mfma_f32_16x16x32_bf16 v[116:119], v[164:167], v[190:193], v[116:119]
	v_mfma_f32_16x16x32_bf16 v[112:115], v[182:185], v[190:193], v[112:115]
	v_mfma_f32_16x16x32_bf16 v[100:103], v[164:167], v[198:201], v[100:103]
	v_mfma_f32_16x16x32_bf16 v[96:99], v[182:185], v[198:201], v[96:99]
	v_mfma_f32_16x16x32_bf16 v[84:87], v[164:167], v[206:209], v[84:87]
	v_mfma_f32_16x16x32_bf16 v[80:83], v[182:185], v[206:209], v[80:83]
	v_mfma_f32_16x16x32_bf16 v[68:71], v[164:167], v[214:217], v[68:71]
	v_mfma_f32_16x16x32_bf16 v[64:67], v[182:185], v[214:217], v[64:67]
	s_setprio 0
	s_barrier
; #define PG8_STAGE(bufoff, gbase, voff) do { _Pragma("unroll") for (int _i = 0; _i < 2; ++_i) \
;         __builtin_amdgcn_global_load_lds((const unsigned*)((const char*)(gbase) + (voff)[_i]), (LAS unsigned*)(lds + (bufoff) + ldsw + _i * 8192), 16, 0, 0); } while (0)
; #define PG8_LDA(dst, b, h) do { _Pragma("unroll") for (int m = 0; m < 4; ++m) _Pragma("unroll") for (int k = 0; k < 2; ++k) dst[m][k] = *(const LAS bf16x8*)(lds + PG8_SA(b, h) + aoff + m * 2048 + k * 1024); } while (0)
; #define PG8_LDB(dst, b, h) do { _Pragma("unroll") for (int n = 0; n < 2; ++n) _Pragma("unroll") for (int k = 0; k < 2; ++k) dst[n][k] = *(const LAS bf16x8*)(lds + PG8_SB(b, h) + boff + n * 2048 + k * 1024); } while (0)
; #define PG8_WAIT_V(n) asm volatile("s_waitcnt vmcnt(" #n ")" ::: "memory")
; #define PG8_WAIT_L(n) asm volatile("s_waitcnt lgkmcnt(" #n ")" ::: "memory")
; template <class Epi>
; __device__ __forceinline__ void gemm_phase(LAS unsigned char* lds, const Gemm g, const StaticOrder& S, const Epi& E) {
;     ...
;         for (int t = 0; t < nt; t += 2) {
;             const bool last = (t == nt - 2);
;             const char* a1 = cA + (size_t)(t + 1) * kstep;
;             const char* a2 = last ? nA : cA + (size_t)(t + 2) * kstep; const char* b2 = last ? nB : cB + (size_t)(t + 2) * kstep;
;             const char* a3 = a2 + kstep; const char* b3 = b2 + kstep;
;             PG8_LDB(B0, 0, 0); PG8_LDB(B1, 0, 1); PG8_SCHED; PG8_LDA(At, 0, 0); PG8_STAGE(PG8_SA(1, 1), a1 + hstepA, voffA);
;             PG8_WAIT_V(8); PG8_WAIT_L(0); PG8_BAR; PG8_MMA(0, 0, At, B0); PG8_MMA(0, 1, At, B1); PG8_BAR; PG8_SCHED;
;             PG8_LDA(At, 0, 1); PG8_STAGE(PG8_SB(0, 0), b2, voffB); PG8_STAGE(PG8_SB(0, 1), b2 + hstepB, voffB); PG8_STAGE(PG8_SA(0, 0), a2, voffA);
;             PG8_WAIT_V(8); PG8_WAIT_L(0); PG8_BAR; PG8_MMA(1, 0, At, B0); PG8_MMA(1, 1, At, B1); PG8_BAR; PG8_SCHED;
;             PG8_LDB(B0, 1, 0); PG8_LDB(B1, 1, 1); PG8_SCHED; PG8_LDA(At, 1, 0); PG8_STAGE(PG8_SA(0, 1), a2 + hstepA, voffA);
;             PG8_WAIT_V(8); PG8_WAIT_L(0); PG8_BAR; PG8_MMA(0, 0, At, B0); PG8_MMA(0, 1, At, B1); PG8_BAR; PG8_SCHED;
;             PG8_LDA(At, 1, 1); PG8_STAGE(PG8_SB(1, 0), b3, voffB); PG8_STAGE(PG8_SB(1, 1), b3 + hstepB, voffB); PG8_STAGE(PG8_SA(1, 0), a3, voffA);
;             PG8_WAIT_V(8); PG8_WAIT_L(0); PG8_BAR; PG8_MMA(1, 0, At, B0); PG8_MMA(1, 1, At, B1); PG8_BAR; PG8_SCHED;
	s_add_i32 s52, s78, s54
	v_lshl_add_u64 v[168:169], v[168:169], 0, s[12:13]
	s_mov_b32 m0, s52
	ds_read_b128 v[186:189], v175 offset:49152
	ds_read_b128 v[190:193], v175 offset:50176
	ds_read_b128 v[194:197], v175 offset:51200
	ds_read_b128 v[198:201], v175 offset:52224
	ds_read_b128 v[202:205], v175 offset:53248
	ds_read_b128 v[206:209], v175 offset:54272
	ds_read_b128 v[210:213], v175 offset:55296
	ds_read_b128 v[214:217], v175 offset:56320
	global_load_lds_dwordx4 v[168:169], off
	s_add_i32 m0, s52, 0x2000
	s_add_u32 s42, s42, 0x40080
	v_lshl_add_u64 v[168:169], v[218:219], 0, s[12:13]
	s_addc_u32 s43, s43, 0
	s_add_i32 s52, s79, s54
	global_load_lds_dwordx4 v[168:169], off
	v_lshl_add_u64 v[168:169], s[42:43], 0, v[146:147]
	s_mov_b32 m0, s52
	s_nop 0
	global_load_lds_dwordx4 v[168:169], off
	v_lshl_add_u64 v[168:169], s[42:43], 0, v[150:151]
	s_add_i32 m0, s52, 0x2000
	s_nop 0
	global_load_lds_dwordx4 v[168:169], off
	v_lshl_add_u64 v[168:169], v[220:221], 0, s[12:13]
	s_mov_b32 m0, s65
	s_nop 0
	global_load_lds_dwordx4 v[168:169], off
	v_lshl_add_u64 v[168:169], v[222:223], 0, s[12:13]
	s_mov_b32 m0, s68
	s_nop 0
	global_load_lds_dwordx4 v[168:169], off
	s_waitcnt vmcnt(8)
	s_waitcnt lgkmcnt(0)
	s_barrier
	s_setprio 1
	s_waitcnt lgkmcnt(0)
	v_mfma_f32_16x16x32_bf16 v[60:63], v[128:131], v[186:189], v[60:63]
	v_mfma_f32_16x16x32_bf16 v[56:59], v[136:139], v[186:189], v[56:59]
	v_mfma_f32_16x16x32_bf16 v[44:47], v[128:131], v[194:197], v[44:47]
	v_mfma_f32_16x16x32_bf16 v[40:43], v[136:139], v[194:197], v[40:43]
	v_mfma_f32_16x16x32_bf16 v[28:31], v[128:131], v[202:205], v[28:31]
	v_mfma_f32_16x16x32_bf16 v[24:27], v[136:139], v[202:205], v[24:27]
	v_mfma_f32_16x16x32_bf16 v[12:15], v[128:131], v[210:213], v[12:15]
	v_mfma_f32_16x16x32_bf16 v[8:11], v[136:139], v[210:213], v[8:11]
	v_mfma_f32_16x16x32_bf16 v[60:63], v[132:135], v[190:193], v[60:63]
	v_mfma_f32_16x16x32_bf16 v[56:59], v[140:143], v[190:193], v[56:59]
	v_mfma_f32_16x16x32_bf16 v[44:47], v[132:135], v[198:201], v[44:47]
	v_mfma_f32_16x16x32_bf16 v[40:43], v[140:143], v[198:201], v[40:43]
	v_mfma_f32_16x16x32_bf16 v[28:31], v[132:135], v[206:209], v[28:31]
	v_mfma_f32_16x16x32_bf16 v[24:27], v[140:143], v[206:209], v[24:27]
	v_mfma_f32_16x16x32_bf16 v[12:15], v[132:135], v[214:217], v[12:15]
	v_mfma_f32_16x16x32_bf16 v[8:11], v[140:143], v[214:217], v[8:11]
	v_mfma_f32_16x16x32_bf16 v[52:55], v[160:163], v[186:189], v[52:55]
	v_mfma_f32_16x16x32_bf16 v[48:51], v[178:181], v[186:189], v[48:51]
	v_mfma_f32_16x16x32_bf16 v[36:39], v[160:163], v[194:197], v[36:39]
	v_mfma_f32_16x16x32_bf16 v[32:35], v[178:181], v[194:197], v[32:35]
	v_mfma_f32_16x16x32_bf16 v[20:23], v[160:163], v[202:205], v[20:23]
	v_mfma_f32_16x16x32_bf16 v[16:19], v[178:181], v[202:205], v[16:19]
	v_mfma_f32_16x16x32_bf16 v[4:7], v[160:163], v[210:213], v[4:7]
	v_mfma_f32_16x16x32_bf16 v[0:3], v[178:181], v[210:213], v[0:3]
	v_mfma_f32_16x16x32_bf16 v[52:55], v[164:167], v[190:193], v[52:55]
	v_mfma_f32_16x16x32_bf16 v[48:51], v[182:185], v[190:193], v[48:51]
	v_mfma_f32_16x16x32_bf16 v[36:39], v[164:167], v[198:201], v[36:39]
	v_mfma_f32_16x16x32_bf16 v[32:35], v[182:185], v[198:201], v[32:35]
	v_mfma_f32_16x16x32_bf16 v[20:23], v[164:167], v[206:209], v[20:23]
	v_mfma_f32_16x16x32_bf16 v[16:19], v[182:185], v[206:209], v[16:19]
	v_mfma_f32_16x16x32_bf16 v[4:7], v[164:167], v[214:217], v[4:7]
	v_mfma_f32_16x16x32_bf16 v[0:3], v[182:185], v[214:217], v[0:3]
	s_setprio 0
	s_barrier
	s_add_i32 s77, s77, 2
	s_add_u32 s38, s38, 0x100
	s_addc_u32 s39, s39, 0
	s_add_u32 s75, s75, 0x100
	s_addc_u32 s76, s76, 0
	s_cmp_gt_u32 s77, 13
.LBB0_457:
	ds_read_b128 v[128:131], v173
	ds_read_b128 v[132:135], v173 offset:1024
	ds_read_b128 v[136:139], v173 offset:2048
	ds_read_b128 v[140:143], v173 offset:3072
	ds_read_b128 v[160:163], v174
	ds_read_b128 v[164:167], v174 offset:1024
	ds_read_b128 v[178:181], v174 offset:2048
	ds_read_b128 v[182:185], v174 offset:3072
	s_add_u32 s42, s38, 0xfffc0080
	s_addc_u32 s43, s39, -1
	s_cmp_eq_u32 s77, 12
	s_cselect_b32 s53, s1, s43
	s_cselect_b32 s52, s23, s42
	s_cselect_b32 s43, s19, s76
	s_cselect_b32 s42, s74, s75
	v_lshl_add_u64 v[168:169], s[38:39], 0, v[152:153]
	s_add_i32 m0, s35, 0xc000
	ds_read_b128 v[186:189], v175
	ds_read_b128 v[190:193], v175 offset:1024
	ds_read_b128 v[194:197], v175 offset:2048
	ds_read_b128 v[198:201], v175 offset:3072
	ds_read_b128 v[202:205], v175 offset:4096
	ds_read_b128 v[206:209], v175 offset:5120
	ds_read_b128 v[210:213], v175 offset:6144
	ds_read_b128 v[214:217], v175 offset:7168
	global_load_lds_dwordx4 v[168:169], off
	v_lshl_add_u64 v[168:169], s[38:39], 0, v[154:155]
	s_add_i32 m0, s35, 0xe000
	s_nop 0
	global_load_lds_dwordx4 v[168:169], off
	s_waitcnt vmcnt(8)
	s_waitcnt lgkmcnt(0)
	s_barrier
; #define PG8_STAGE(bufoff, gbase, voff) do { _Pragma("unroll") for (int _i = 0; _i < 2; ++_i) \
;         __builtin_amdgcn_global_load_lds((const unsigned*)((const char*)(gbase) + (voff)[_i]), (LAS unsigned*)(lds + (bufoff) + ldsw + _i * 8192), 16, 0, 0); } while (0)
; #define PG8_LDA(dst, b, h) do { _Pragma("unroll") for (int m = 0; m < 4; ++m) _Pragma("unroll") for (int k = 0; k < 2; ++k) dst[m][k] = *(const LAS bf16x8*)(lds + PG8_SA(b, h) + aoff + m * 2048 + k * 1024); } while (0)
; #define PG8_MMA(ai, bj, At, Bt) do { __builtin_amdgcn_s_setprio(1); _Pragma("unroll") for (int m = 0; m < 4; ++m) _Pragma("unroll") for (int n = 0; n < 2; ++n) _Pragma("unroll") for (int k = 0; k < 2; ++k) \
;         acc[ai][bj][m][n] = __builtin_amdgcn_mfma_f32_16x16x32_bf16(Bt[n][k], At[m][k], acc[ai][bj][m][n], 0, 0, 0); __builtin_amdgcn_s_setprio(0); } while (0)
; #define PG8_WAIT_V(n) asm volatile("s_waitcnt vmcnt(" #n ")" ::: "memory")
; #define PG8_WAIT_L(n) asm volatile("s_waitcnt lgkmcnt(" #n ")" ::: "memory")
; #define PG8_BAR __builtin_amdgcn_s_barrier()
; #define PG8_SCHED __builtin_amdgcn_sched_barrier(0)
; template <class Epi>
; __device__ __forceinline__ void gemm_phase(LAS unsigned char* lds, const Gemm g, const StaticOrder& S, const Epi& E) {
;     ...
;             PG8_WAIT_V(8); PG8_WAIT_L(0); PG8_BAR; PG8_MMA(0, 0, At, B0); PG8_MMA(0, 1, At, B1); PG8_BAR; PG8_SCHED;
;             PG8_LDA(At, 0, 1); PG8_STAGE(PG8_SB(0, 0), b2, voffB); PG8_STAGE(PG8_SB(0, 1), b2 + hstepB, voffB); PG8_STAGE(PG8_SA(0, 0), a2, voffA);
;             PG8_WAIT_V(8); PG8_WAIT_L(0); PG8_BAR; PG8_MMA(1, 0, At, B0); PG8_MMA(1, 1, At, B1); PG8_BAR; PG8_SCHED;
	s_setprio 1
	s_waitcnt lgkmcnt(0)
	v_mfma_f32_16x16x32_bf16 v[124:127], v[128:131], v[186:189], v[124:127]
	v_mfma_f32_16x16x32_bf16 v[120:123], v[136:139], v[186:189], v[120:123]
	v_mfma_f32_16x16x32_bf16 v[108:111], v[128:131], v[194:197], v[108:111]
	v_mfma_f32_16x16x32_bf16 v[104:107], v[136:139], v[194:197], v[104:107]
	v_mfma_f32_16x16x32_bf16 v[92:95], v[128:131], v[202:205], v[92:95]
	v_mfma_f32_16x16x32_bf16 v[88:91], v[136:139], v[202:205], v[88:91]
	v_mfma_f32_16x16x32_bf16 v[76:79], v[128:131], v[210:213], v[76:79]
	v_mfma_f32_16x16x32_bf16 v[72:75], v[136:139], v[210:213], v[72:75]
	v_mfma_f32_16x16x32_bf16 v[124:127], v[132:135], v[190:193], v[124:127]
	v_mfma_f32_16x16x32_bf16 v[120:123], v[140:143], v[190:193], v[120:123]
	v_mfma_f32_16x16x32_bf16 v[108:111], v[132:135], v[198:201], v[108:111]
	v_mfma_f32_16x16x32_bf16 v[104:107], v[140:143], v[198:201], v[104:107]
	v_mfma_f32_16x16x32_bf16 v[92:95], v[132:135], v[206:209], v[92:95]
	v_mfma_f32_16x16x32_bf16 v[88:91], v[140:143], v[206:209], v[88:91]
	v_mfma_f32_16x16x32_bf16 v[76:79], v[132:135], v[214:217], v[76:79]
	v_mfma_f32_16x16x32_bf16 v[72:75], v[140:143], v[214:217], v[72:75]
	v_mfma_f32_16x16x32_bf16 v[116:119], v[160:163], v[186:189], v[116:119]
	v_mfma_f32_16x16x32_bf16 v[112:115], v[178:181], v[186:189], v[112:115]
	v_mfma_f32_16x16x32_bf16 v[100:103], v[160:163], v[194:197], v[100:103]
	v_mfma_f32_16x16x32_bf16 v[96:99], v[178:181], v[194:197], v[96:99]
	v_mfma_f32_16x16x32_bf16 v[84:87], v[160:163], v[202:205], v[84:87]
	v_mfma_f32_16x16x32_bf16 v[80:83], v[178:181], v[202:205], v[80:83]
	v_mfma_f32_16x16x32_bf16 v[68:71], v[160:163], v[210:213], v[68:71]
	v_mfma_f32_16x16x32_bf16 v[64:67], v[178:181], v[210:213], v[64:67]
	v_mfma_f32_16x16x32_bf16 v[116:119], v[164:167], v[190:193], v[116:119]
	v_mfma_f32_16x16x32_bf16 v[112:115], v[182:185], v[190:193], v[112:115]
	v_mfma_f32_16x16x32_bf16 v[100:103], v[164:167], v[198:201], v[100:103]
	v_mfma_f32_16x16x32_bf16 v[96:99], v[182:185], v[198:201], v[96:99]
	v_mfma_f32_16x16x32_bf16 v[84:87], v[164:167], v[206:209], v[84:87]
	v_mfma_f32_16x16x32_bf16 v[80:83], v[182:185], v[206:209], v[80:83]
	v_mfma_f32_16x16x32_bf16 v[68:71], v[164:167], v[214:217], v[68:71]
	v_mfma_f32_16x16x32_bf16 v[64:67], v[182:185], v[214:217], v[64:67]
	s_setprio 0
	s_barrier
	s_add_i32 s78, s72, s54
	v_lshl_add_u64 v[168:169], s[42:43], 0, v[146:147]
	s_mov_b32 m0, s78
	ds_read_b128 v[186:189], v175 offset:16384
	ds_read_b128 v[190:193], v175 offset:17408
	ds_read_b128 v[194:197], v175 offset:18432
	ds_read_b128 v[198:201], v175 offset:19456
	ds_read_b128 v[202:205], v175 offset:20480
	ds_read_b128 v[206:209], v175 offset:21504
	ds_read_b128 v[210:213], v175 offset:22528
	ds_read_b128 v[214:217], v175 offset:23552
	global_load_lds_dwordx4 v[168:169], off
	s_add_i32 m0, s78, 0x2000
	s_add_u32 s78, s42, 0x40000
	v_lshl_add_u64 v[218:219], s[42:43], 0, v[150:151]
	s_addc_u32 s79, s43, 0
	s_add_i32 s80, s73, s54
	global_load_lds_dwordx4 v[218:219], off
	v_lshl_add_u64 v[220:221], s[78:79], 0, v[146:147]
	s_mov_b32 m0, s80
	v_lshl_add_u64 v[222:223], s[52:53], 0, v[148:149]
	global_load_lds_dwordx4 v[220:221], off
	v_lshl_add_u64 v[220:221], s[78:79], 0, v[150:151]
	s_add_i32 m0, s80, 0x2000
	s_nop 0
	global_load_lds_dwordx4 v[220:221], off
	v_lshl_add_u64 v[220:221], s[52:53], 0, v[144:145]
	s_mov_b32 m0, s35
	s_nop 0
	global_load_lds_dwordx4 v[220:221], off
	s_mov_b32 m0, s55
	s_nop 0
	global_load_lds_dwordx4 v[222:223], off
	s_waitcnt vmcnt(8)
	s_waitcnt lgkmcnt(0)
	s_barrier
	s_setprio 1
	s_waitcnt lgkmcnt(0)
	v_mfma_f32_16x16x32_bf16 v[60:63], v[128:131], v[186:189], v[60:63]
	v_mfma_f32_16x16x32_bf16 v[56:59], v[136:139], v[186:189], v[56:59]
	v_mfma_f32_16x16x32_bf16 v[44:47], v[128:131], v[194:197], v[44:47]
	v_mfma_f32_16x16x32_bf16 v[40:43], v[136:139], v[194:197], v[40:43]
	v_mfma_f32_16x16x32_bf16 v[28:31], v[128:131], v[202:205], v[28:31]
	v_mfma_f32_16x16x32_bf16 v[24:27], v[136:139], v[202:205], v[24:27]
	v_mfma_f32_16x16x32_bf16 v[12:15], v[128:131], v[210:213], v[12:15]
	v_mfma_f32_16x16x32_bf16 v[8:11], v[136:139], v[210:213], v[8:11]
	v_mfma_f32_16x16x32_bf16 v[60:63], v[132:135], v[190:193], v[60:63]
	v_mfma_f32_16x16x32_bf16 v[56:59], v[140:143], v[190:193], v[56:59]
	v_mfma_f32_16x16x32_bf16 v[44:47], v[132:135], v[198:201], v[44:47]
	v_mfma_f32_16x16x32_bf16 v[40:43], v[140:143], v[198:201], v[40:43]
	v_mfma_f32_16x16x32_bf16 v[28:31], v[132:135], v[206:209], v[28:31]
	v_mfma_f32_16x16x32_bf16 v[24:27], v[140:143], v[206:209], v[24:27]
	v_mfma_f32_16x16x32_bf16 v[12:15], v[132:135], v[214:217], v[12:15]
	v_mfma_f32_16x16x32_bf16 v[8:11], v[140:143], v[214:217], v[8:11]
	v_mfma_f32_16x16x32_bf16 v[52:55], v[160:163], v[186:189], v[52:55]
	v_mfma_f32_16x16x32_bf16 v[48:51], v[178:181], v[186:189], v[48:51]
	v_mfma_f32_16x16x32_bf16 v[36:39], v[160:163], v[194:197], v[36:39]
	v_mfma_f32_16x16x32_bf16 v[32:35], v[178:181], v[194:197], v[32:35]
	v_mfma_f32_16x16x32_bf16 v[20:23], v[160:163], v[202:205], v[20:23]
	v_mfma_f32_16x16x32_bf16 v[16:19], v[178:181], v[202:205], v[16:19]
	v_mfma_f32_16x16x32_bf16 v[4:7], v[160:163], v[210:213], v[4:7]
	v_mfma_f32_16x16x32_bf16 v[0:3], v[178:181], v[210:213], v[0:3]
	v_mfma_f32_16x16x32_bf16 v[52:55], v[164:167], v[190:193], v[52:55]
	v_mfma_f32_16x16x32_bf16 v[48:51], v[182:185], v[190:193], v[48:51]
	v_mfma_f32_16x16x32_bf16 v[36:39], v[164:167], v[198:201], v[36:39]
	v_mfma_f32_16x16x32_bf16 v[32:35], v[182:185], v[198:201], v[32:35]
	v_mfma_f32_16x16x32_bf16 v[20:23], v[164:167], v[206:209], v[20:23]
	v_mfma_f32_16x16x32_bf16 v[16:19], v[182:185], v[206:209], v[16:19]
	v_mfma_f32_16x16x32_bf16 v[4:7], v[164:167], v[214:217], v[4:7]
	v_mfma_f32_16x16x32_bf16 v[0:3], v[182:185], v[214:217], v[0:3]
	s_setprio 0
	s_barrier
; #define PG8_STAGE(bufoff, gbase, voff) do { _Pragma("unroll") for (int _i = 0; _i < 2; ++_i) \
;         __builtin_amdgcn_global_load_lds((const unsigned*)((const char*)(gbase) + (voff)[_i]), (LAS unsigned*)(lds + (bufoff) + ldsw + _i * 8192), 16, 0, 0); } while (0)
; #define PG8_LDA(dst, b, h) do { _Pragma("unroll") for (int m = 0; m < 4; ++m) _Pragma("unroll") for (int k = 0; k < 2; ++k) dst[m][k] = *(const LAS bf16x8*)(lds + PG8_SA(b, h) + aoff + m * 2048 + k * 1024); } while (0)
; #define PG8_LDB(dst, b, h) do { _Pragma("unroll") for (int n = 0; n < 2; ++n) _Pragma("unroll") for (int k = 0; k < 2; ++k) dst[n][k] = *(const LAS bf16x8*)(lds + PG8_SB(b, h) + boff + n * 2048 + k * 1024); } while (0)
; #define PG8_MMA(ai, bj, At, Bt) do { __builtin_amdgcn_s_setprio(1); _Pragma("unroll") for (int m = 0; m < 4; ++m) _Pragma("unroll") for (int n = 0; n < 2; ++n) _Pragma("unroll") for (int k = 0; k < 2; ++k) \
;         acc[ai][bj][m][n] = __builtin_amdgcn_mfma_f32_16x16x32_bf16(Bt[n][k], At[m][k], acc[ai][bj][m][n], 0, 0, 0); __builtin_amdgcn_s_setprio(0); } while (0)
; #define PG8_WAIT_V(n) asm volatile("s_waitcnt vmcnt(" #n ")" ::: "memory")
; #define PG8_WAIT_L(n) asm volatile("s_waitcnt lgkmcnt(" #n ")" ::: "memory")
; #define PG8_BAR __builtin_amdgcn_s_barrier()
; #define PG8_SCHED __builtin_amdgcn_sched_barrier(0)
; template <class Epi>
; __device__ __forceinline__ void gemm_phase(LAS unsigned char* lds, const Gemm g, const StaticOrder& S, const Epi& E) {
;     ...
;             PG8_LDB(B0, 1, 0); PG8_LDB(B1, 1, 1); PG8_SCHED; PG8_LDA(At, 1, 0); PG8_STAGE(PG8_SA(0, 1), a2 + hstepA, voffA);
;             PG8_WAIT_V(8); PG8_WAIT_L(0); PG8_BAR; PG8_MMA(0, 0, At, B0); PG8_MMA(0, 1, At, B1); PG8_BAR; PG8_SCHED;
	s_add_i32 s78, 0, 0x18000
	s_add_i32 s79, 0, 0x1c000
	v_add_u32_e32 v140, s78, v172
	v_add_u32_e32 v182, s79, v172
	ds_read_b128 v[128:131], v140
	ds_read_b128 v[132:135], v140 offset:1024
	ds_read_b128 v[136:139], v140 offset:2048
	ds_read_b128 v[140:143], v140 offset:3072
	ds_read_b128 v[160:163], v182
	ds_read_b128 v[164:167], v182 offset:1024
	ds_read_b128 v[178:181], v182 offset:2048
	ds_read_b128 v[182:185], v182 offset:3072
	s_add_u32 s52, s52, 0x40000
	s_addc_u32 s53, s53, 0
	s_mov_b32 m0, s56
	v_lshl_add_u64 v[226:227], s[52:53], 0, v[144:145]
	ds_read_b128 v[186:189], v175 offset:32768
	ds_read_b128 v[190:193], v175 offset:33792
	ds_read_b128 v[194:197], v175 offset:34816
	ds_read_b128 v[198:201], v175 offset:35840
	ds_read_b128 v[202:205], v175 offset:36864
	ds_read_b128 v[206:209], v175 offset:37888
	ds_read_b128 v[210:213], v175 offset:38912
	ds_read_b128 v[214:217], v175 offset:39936
	global_load_lds_dwordx4 v[226:227], off
	v_lshl_add_u64 v[226:227], s[52:53], 0, v[148:149]
	s_mov_b32 m0, s57
	s_nop 0
	global_load_lds_dwordx4 v[226:227], off
	s_waitcnt vmcnt(8)
	s_waitcnt lgkmcnt(0)
	s_barrier
	s_setprio 1
	s_waitcnt lgkmcnt(0)
	v_mfma_f32_16x16x32_bf16 v[124:127], v[128:131], v[186:189], v[124:127]
	v_mfma_f32_16x16x32_bf16 v[120:123], v[136:139], v[186:189], v[120:123]
	v_mfma_f32_16x16x32_bf16 v[108:111], v[128:131], v[194:197], v[108:111]
	v_mfma_f32_16x16x32_bf16 v[104:107], v[136:139], v[194:197], v[104:107]
	v_mfma_f32_16x16x32_bf16 v[92:95], v[128:131], v[202:205], v[92:95]
	v_mfma_f32_16x16x32_bf16 v[88:91], v[136:139], v[202:205], v[88:91]
	v_mfma_f32_16x16x32_bf16 v[76:79], v[128:131], v[210:213], v[76:79]
	v_mfma_f32_16x16x32_bf16 v[72:75], v[136:139], v[210:213], v[72:75]
	v_mfma_f32_16x16x32_bf16 v[124:127], v[132:135], v[190:193], v[124:127]
	v_mfma_f32_16x16x32_bf16 v[120:123], v[140:143], v[190:193], v[120:123]
	v_mfma_f32_16x16x32_bf16 v[108:111], v[132:135], v[198:201], v[108:111]
	v_mfma_f32_16x16x32_bf16 v[104:107], v[140:143], v[198:201], v[104:107]
	v_mfma_f32_16x16x32_bf16 v[92:95], v[132:135], v[206:209], v[92:95]
	v_mfma_f32_16x16x32_bf16 v[88:91], v[140:143], v[206:209], v[88:91]
	v_mfma_f32_16x16x32_bf16 v[76:79], v[132:135], v[214:217], v[76:79]
	v_mfma_f32_16x16x32_bf16 v[72:75], v[140:143], v[214:217], v[72:75]
	v_mfma_f32_16x16x32_bf16 v[116:119], v[160:163], v[186:189], v[116:119]
	v_mfma_f32_16x16x32_bf16 v[112:115], v[178:181], v[186:189], v[112:115]
	v_mfma_f32_16x16x32_bf16 v[100:103], v[160:163], v[194:197], v[100:103]
	v_mfma_f32_16x16x32_bf16 v[96:99], v[178:181], v[194:197], v[96:99]
	v_mfma_f32_16x16x32_bf16 v[84:87], v[160:163], v[202:205], v[84:87]
	v_mfma_f32_16x16x32_bf16 v[80:83], v[178:181], v[202:205], v[80:83]
	v_mfma_f32_16x16x32_bf16 v[68:71], v[160:163], v[210:213], v[68:71]
	v_mfma_f32_16x16x32_bf16 v[64:67], v[178:181], v[210:213], v[64:67]
	v_mfma_f32_16x16x32_bf16 v[116:119], v[164:167], v[190:193], v[116:119]
	v_mfma_f32_16x16x32_bf16 v[112:115], v[182:185], v[190:193], v[112:115]
	v_mfma_f32_16x16x32_bf16 v[100:103], v[164:167], v[198:201], v[100:103]
	v_mfma_f32_16x16x32_bf16 v[96:99], v[182:185], v[198:201], v[96:99]
	v_mfma_f32_16x16x32_bf16 v[84:87], v[164:167], v[206:209], v[84:87]
	v_mfma_f32_16x16x32_bf16 v[80:83], v[182:185], v[206:209], v[80:83]
	v_mfma_f32_16x16x32_bf16 v[68:71], v[164:167], v[214:217], v[68:71]
	v_mfma_f32_16x16x32_bf16 v[64:67], v[182:185], v[214:217], v[64:67]
	s_setprio 0
	s_barrier
; #define PG8_STAGE(bufoff, gbase, voff) do { _Pragma("unroll") for (int _i = 0; _i < 2; ++_i) \
;         __builtin_amdgcn_global_load_lds((const unsigned*)((const char*)(gbase) + (voff)[_i]), (LAS unsigned*)(lds + (bufoff) + ldsw + _i * 8192), 16, 0, 0); } while (0)
; #define PG8_LDA(dst, b, h) do { _Pragma("unroll") for (int m = 0; m < 4; ++m) _Pragma("unroll") for (int k = 0; k < 2; ++k) dst[m][k] = *(const LAS bf16x8*)(lds + PG8_SA(b, h) + aoff + m * 2048 + k * 1024); } while (0)
; #define PG8_MMA(ai, bj, At, Bt) do { __builtin_amdgcn_s_setprio(1); _Pragma("unroll") for (int m = 0; m < 4; ++m) _Pragma("unroll") for (int n = 0; n < 2; ++n) _Pragma("unroll") for (int k = 0; k < 2; ++k) \
;         acc[ai][bj][m][n] = __builtin_amdgcn_mfma_f32_16x16x32_bf16(Bt[n][k], At[m][k], acc[ai][bj][m][n], 0, 0, 0); __builtin_amdgcn_s_setprio(0); } while (0)
; #define PG8_WAIT_V(n) asm volatile("s_waitcnt vmcnt(" #n ")" ::: "memory")
; #define PG8_WAIT_L(n) asm volatile("s_waitcnt lgkmcnt(" #n ")" ::: "memory")
; #define PG8_BAR __builtin_amdgcn_s_barrier()
; #define PG8_SCHED __builtin_amdgcn_sched_barrier(0)
; template <class Epi>
; __device__ __forceinline__ void gemm_phase(LAS unsigned char* lds, const Gemm g, const StaticOrder& S, const Epi& E) {
;     ...
;             PG8_LDA(At, 1, 1); PG8_STAGE(PG8_SB(1, 0), b3, voffB); PG8_STAGE(PG8_SB(1, 1), b3 + hstepB, voffB); PG8_STAGE(PG8_SA(1, 0), a3, voffA);
;             PG8_WAIT_V(8); PG8_WAIT_L(0); PG8_BAR; PG8_MMA(1, 0, At, B0); PG8_MMA(1, 1, At, B1); PG8_BAR; PG8_SCHED;
;         }
;         if (wr == 0) PG8_BAR;
	s_add_i32 s52, s78, s54
	v_lshl_add_u64 v[168:169], v[168:169], 0, s[12:13]
	s_mov_b32 m0, s52
	ds_read_b128 v[186:189], v175 offset:49152
	ds_read_b128 v[190:193], v175 offset:50176
	ds_read_b128 v[194:197], v175 offset:51200
	ds_read_b128 v[198:201], v175 offset:52224
	ds_read_b128 v[202:205], v175 offset:53248
	ds_read_b128 v[206:209], v175 offset:54272
	ds_read_b128 v[210:213], v175 offset:55296
	ds_read_b128 v[214:217], v175 offset:56320
	global_load_lds_dwordx4 v[168:169], off
	s_add_i32 m0, s52, 0x2000
	s_add_u32 s42, s42, 0x40080
	v_lshl_add_u64 v[168:169], v[218:219], 0, s[12:13]
	s_addc_u32 s43, s43, 0
	s_add_i32 s52, s79, s54
	global_load_lds_dwordx4 v[168:169], off
	v_lshl_add_u64 v[168:169], s[42:43], 0, v[146:147]
	s_mov_b32 m0, s52
	s_nop 0
	global_load_lds_dwordx4 v[168:169], off
	v_lshl_add_u64 v[168:169], s[42:43], 0, v[150:151]
	s_add_i32 m0, s52, 0x2000
	s_nop 0
	global_load_lds_dwordx4 v[168:169], off
	v_lshl_add_u64 v[168:169], v[220:221], 0, s[12:13]
	s_mov_b32 m0, s65
	s_nop 0
	global_load_lds_dwordx4 v[168:169], off
	v_lshl_add_u64 v[168:169], v[222:223], 0, s[12:13]
	s_mov_b32 m0, s68
	s_nop 0
	global_load_lds_dwordx4 v[168:169], off
	s_waitcnt vmcnt(8)
	s_waitcnt lgkmcnt(0)
	s_barrier
	s_setprio 1
	s_waitcnt lgkmcnt(0)
	v_mfma_f32_16x16x32_bf16 v[60:63], v[128:131], v[186:189], v[60:63]
	v_mfma_f32_16x16x32_bf16 v[56:59], v[136:139], v[186:189], v[56:59]
	v_mfma_f32_16x16x32_bf16 v[44:47], v[128:131], v[194:197], v[44:47]
	v_mfma_f32_16x16x32_bf16 v[40:43], v[136:139], v[194:197], v[40:43]
	v_mfma_f32_16x16x32_bf16 v[28:31], v[128:131], v[202:205], v[28:31]
	v_mfma_f32_16x16x32_bf16 v[24:27], v[136:139], v[202:205], v[24:27]
	v_mfma_f32_16x16x32_bf16 v[12:15], v[128:131], v[210:213], v[12:15]
	v_mfma_f32_16x16x32_bf16 v[8:11], v[136:139], v[210:213], v[8:11]
	v_mfma_f32_16x16x32_bf16 v[60:63], v[132:135], v[190:193], v[60:63]
	v_mfma_f32_16x16x32_bf16 v[56:59], v[140:143], v[190:193], v[56:59]
	v_mfma_f32_16x16x32_bf16 v[44:47], v[132:135], v[198:201], v[44:47]
	v_mfma_f32_16x16x32_bf16 v[40:43], v[140:143], v[198:201], v[40:43]
	v_mfma_f32_16x16x32_bf16 v[28:31], v[132:135], v[206:209], v[28:31]
	v_mfma_f32_16x16x32_bf16 v[24:27], v[140:143], v[206:209], v[24:27]
	v_mfma_f32_16x16x32_bf16 v[12:15], v[132:135], v[214:217], v[12:15]
	v_mfma_f32_16x16x32_bf16 v[8:11], v[140:143], v[214:217], v[8:11]
	v_mfma_f32_16x16x32_bf16 v[52:55], v[160:163], v[186:189], v[52:55]
	v_mfma_f32_16x16x32_bf16 v[48:51], v[178:181], v[186:189], v[48:51]
	v_mfma_f32_16x16x32_bf16 v[36:39], v[160:163], v[194:197], v[36:39]
	v_mfma_f32_16x16x32_bf16 v[32:35], v[178:181], v[194:197], v[32:35]
	v_mfma_f32_16x16x32_bf16 v[20:23], v[160:163], v[202:205], v[20:23]
	v_mfma_f32_16x16x32_bf16 v[16:19], v[178:181], v[202:205], v[16:19]
	v_mfma_f32_16x16x32_bf16 v[4:7], v[160:163], v[210:213], v[4:7]
	v_mfma_f32_16x16x32_bf16 v[0:3], v[178:181], v[210:213], v[0:3]
	v_mfma_f32_16x16x32_bf16 v[52:55], v[164:167], v[190:193], v[52:55]
	v_mfma_f32_16x16x32_bf16 v[48:51], v[182:185], v[190:193], v[48:51]
	v_mfma_f32_16x16x32_bf16 v[36:39], v[164:167], v[198:201], v[36:39]
	v_mfma_f32_16x16x32_bf16 v[32:35], v[182:185], v[198:201], v[32:35]
	v_mfma_f32_16x16x32_bf16 v[20:23], v[164:167], v[206:209], v[20:23]
	v_mfma_f32_16x16x32_bf16 v[16:19], v[182:185], v[206:209], v[16:19]
	v_mfma_f32_16x16x32_bf16 v[4:7], v[164:167], v[214:217], v[4:7]
	v_mfma_f32_16x16x32_bf16 v[0:3], v[182:185], v[214:217], v[0:3]
	s_setprio 0
	s_barrier
	s_add_i32 s77, s77, 2
	s_add_u32 s38, s38, 0x100
	s_addc_u32 s39, s39, 0
	s_add_u32 s75, s75, 0x100
	s_addc_u32 s76, s76, 0
	s_cmp_gt_u32 s77, 13
	s_cbranch_scc0 .LBB0_457
	s_and_b64 vcc, exec, s[14:15]
	s_cbranch_vccz .LBB0_460
	s_barrier

; #define PG8_STAGE(bufoff, gbase, voff) do { _Pragma("unroll") for (int _i = 0; _i < 2; ++_i) \
;         __builtin_amdgcn_global_load_lds((const unsigned*)((const char*)(gbase) + (voff)[_i]), (LAS unsigned*)(lds + (bufoff) + ldsw + _i * 8192), 16, 0, 0); } while (0)
; #define PG8_LDA(dst, b, h) do { _Pragma("unroll") for (int m = 0; m < 4; ++m) _Pragma("unroll") for (int k = 0; k < 2; ++k) dst[m][k] = *(const LAS bf16x8*)(lds + PG8_SA(b, h) + aoff + m * 2048 + k * 1024); } while (0)
; #define PG8_LDB(dst, b, h) do { _Pragma("unroll") for (int n = 0; n < 2; ++n) _Pragma("unroll") for (int k = 0; k < 2; ++k) dst[n][k] = *(const LAS bf16x8*)(lds + PG8_SB(b, h) + boff + n * 2048 + k * 1024); } while (0)
; #define PG8_MMA(ai, bj, At, Bt) do { __builtin_amdgcn_s_setprio(1); _Pragma("unroll") for (int m = 0; m < 4; ++m) _Pragma("unroll") for (int n = 0; n < 2; ++n) _Pragma("unroll") for (int k = 0; k < 2; ++k) \
;         acc[ai][bj][m][n] = __builtin_amdgcn_mfma_f32_16x16x32_bf16(Bt[n][k], At[m][k], acc[ai][bj][m][n], 0, 0, 0); __builtin_amdgcn_s_setprio(0); } while (0)
; #define PG8_BAR __builtin_amdgcn_s_barrier()
; template <class Epi>
; __device__ __forceinline__ void gemm_phase(LAS unsigned char* lds, const Gemm g, const StaticOrder& S, const Epi& E) {
;     ...
;         const bool has_next = S.next(ui + 1, nxt);
;         const char* nA = has_next ? (const char*)g.A + (size_t)nxt.pm * tstepA : cA; const char* nB = has_next ? (const char*)g.Bt + (size_t)nxt.pn * tstepB : cB;
; #pragma nounroll
;         for (int t = 0; t < nt; t += 2) {
;             const bool last = (t == nt - 2);
;             const char* a1 = cA + (size_t)(t + 1) * kstep;
;             const char* a2 = last ? nA : cA + (size_t)(t + 2) * kstep; const char* b2 = last ? nB : cB + (size_t)(t + 2) * kstep;
;             const char* a3 = a2 + kstep; const char* b3 = b2 + kstep;
;             PG8_LDB(B0, 0, 0); PG8_LDB(B1, 0, 1); PG8_SCHED; PG8_LDA(At, 0, 0); PG8_STAGE(PG8_SA(1, 1), a1 + hstepA, voffA);
;             PG8_WAIT_V(8); PG8_WAIT_L(0); PG8_BAR; PG8_MMA(0, 0, At, B0); PG8_MMA(0, 1, At, B1); PG8_BAR; PG8_SCHED;
;             PG8_LDA(At, 0, 1); PG8_STAGE(PG8_SB(0, 0), b2, voffB); PG8_STAGE(PG8_SB(0, 1), b2 + hstepB, voffB); PG8_STAGE(PG8_SA(0, 0), a2, voffA);
;             PG8_WAIT_V(8); PG8_WAIT_L(0); PG8_BAR; PG8_MMA(1, 0, At, B0); PG8_MMA(1, 1, At, B1); PG8_BAR; PG8_SCHED;
.LBB0_545:
	s_ashr_i32 s71, s70, 31
	s_lshl_b64 s[12:13], s[70:71], 19
	s_add_u32 s72, s24, s12
	s_addc_u32 s73, s25, s13
	s_and_b64 s[12:13], s[4:5], exec
	s_cselect_b32 s1, s73, s9
	s_cselect_b32 s7, s72, s8
	s_ashr_i32 s69, s68, 31
	s_lshl_b64 s[12:13], s[68:69], 19
	s_add_u32 s74, s3, s12
	s_addc_u32 s75, s33, s13
	s_and_b64 s[12:13], s[4:5], exec
	s_cselect_b32 s69, s75, s11
	s_cselect_b32 s71, s74, s10
	s_add_u32 s8, s8, 0x40080
	s_addc_u32 s9, s9, 0
	s_add_u32 s76, s10, 0x100
	s_addc_u32 s77, s11, 0
	s_mov_b32 s89, -2
	s_nop 0
	v_lshl_add_u32 v248, s6, 8, v151
	v_add_u32_e32 v248, s65, v248
	v_ashrrev_i32_e32 v249, 31, v248
	v_lshl_add_u64 v[248:249], v[248:249], 2, s[22:23]
	global_load_dword v240, v[248:249], off
	global_load_dword v241, v[248:249], off offset:64
	global_load_dword v242, v[248:249], off offset:128
	global_load_dword v243, v[248:249], off offset:192
	global_load_dword v244, v[248:249], off offset:512
	global_load_dword v245, v[248:249], off offset:576
	global_load_dword v246, v[248:249], off offset:640
	global_load_dword v247, v[248:249], off offset:704
	ds_read_b128 v[146:149], v162
	ds_read_b128 v[166:169], v162 offset:1024
	ds_read_b128 v[170:173], v162 offset:2048
	ds_read_b128 v[178:181], v162 offset:3072
	ds_read_b128 v[182:185], v163
	ds_read_b128 v[186:189], v163 offset:1024
	ds_read_b128 v[190:193], v163 offset:2048
	ds_read_b128 v[194:197], v163 offset:3072
	s_add_u32 s10, s8, 0xfffc0080
	s_addc_u32 s11, s9, -1
	s_cmp_eq_u32 s89, 12
	s_cselect_b32 s13, s1, s11
	s_cselect_b32 s12, s7, s10
	s_cselect_b32 s11, s69, s77
	s_cselect_b32 s10, s71, s76
	v_lshl_add_u64 v[174:175], s[8:9], 0, v[138:139]
	s_add_i32 m0, s43, 0xc000
	ds_read_b128 v[198:201], v164
	ds_read_b128 v[202:205], v164 offset:1024
	ds_read_b128 v[206:209], v164 offset:2048
	ds_read_b128 v[210:213], v164 offset:3072
	ds_read_b128 v[214:217], v164 offset:4096
	ds_read_b128 v[218:221], v164 offset:5120
	ds_read_b128 v[226:229], v164 offset:6144
	ds_read_b128 v[230:233], v164 offset:7168
	global_load_lds_dwordx4 v[174:175], off
	v_lshl_add_u64 v[174:175], s[8:9], 0, v[140:141]
	s_add_i32 m0, s43, 0xe000
	s_nop 0
	global_load_lds_dwordx4 v[174:175], off
	s_waitcnt vmcnt(8)
	s_waitcnt lgkmcnt(0)
	s_barrier
	s_setprio 1
	s_waitcnt lgkmcnt(0)
	v_mfma_f32_16x16x32_bf16 v[124:127], v[146:149], v[198:201], 0
	v_mfma_f32_16x16x32_bf16 v[120:123], v[170:173], v[198:201], 0
	v_mfma_f32_16x16x32_bf16 v[112:115], v[146:149], v[206:209], 0
	v_mfma_f32_16x16x32_bf16 v[104:107], v[170:173], v[206:209], 0
	v_mfma_f32_16x16x32_bf16 v[100:103], v[146:149], v[214:217], 0
	v_mfma_f32_16x16x32_bf16 v[92:95], v[170:173], v[214:217], 0
	v_mfma_f32_16x16x32_bf16 v[84:87], v[146:149], v[226:229], 0
	v_mfma_f32_16x16x32_bf16 v[76:79], v[170:173], v[226:229], 0
	v_mfma_f32_16x16x32_bf16 v[124:127], v[166:169], v[202:205], v[124:127]
	v_mfma_f32_16x16x32_bf16 v[120:123], v[178:181], v[202:205], v[120:123]
	v_mfma_f32_16x16x32_bf16 v[112:115], v[166:169], v[210:213], v[112:115]
	v_mfma_f32_16x16x32_bf16 v[104:107], v[178:181], v[210:213], v[104:107]
	v_mfma_f32_16x16x32_bf16 v[100:103], v[166:169], v[218:221], v[100:103]
	v_mfma_f32_16x16x32_bf16 v[92:95], v[178:181], v[218:221], v[92:95]
	v_mfma_f32_16x16x32_bf16 v[84:87], v[166:169], v[230:233], v[84:87]
	v_mfma_f32_16x16x32_bf16 v[76:79], v[178:181], v[230:233], v[76:79]
	v_mfma_f32_16x16x32_bf16 v[116:119], v[182:185], v[198:201], 0
	v_mfma_f32_16x16x32_bf16 v[108:111], v[190:193], v[198:201], 0
	v_mfma_f32_16x16x32_bf16 v[96:99], v[182:185], v[206:209], 0
	v_mfma_f32_16x16x32_bf16 v[88:91], v[190:193], v[206:209], 0
	v_mfma_f32_16x16x32_bf16 v[80:83], v[182:185], v[214:217], 0
	v_mfma_f32_16x16x32_bf16 v[72:75], v[190:193], v[214:217], 0
	v_mfma_f32_16x16x32_bf16 v[68:71], v[182:185], v[226:229], 0
	v_mfma_f32_16x16x32_bf16 v[64:67], v[190:193], v[226:229], 0
	v_mfma_f32_16x16x32_bf16 v[116:119], v[186:189], v[202:205], v[116:119]
	v_mfma_f32_16x16x32_bf16 v[108:111], v[194:197], v[202:205], v[108:111]
	v_mfma_f32_16x16x32_bf16 v[96:99], v[186:189], v[210:213], v[96:99]
	v_mfma_f32_16x16x32_bf16 v[88:91], v[194:197], v[210:213], v[88:91]
	v_mfma_f32_16x16x32_bf16 v[80:83], v[186:189], v[218:221], v[80:83]
	v_mfma_f32_16x16x32_bf16 v[72:75], v[194:197], v[218:221], v[72:75]
	v_mfma_f32_16x16x32_bf16 v[68:71], v[186:189], v[230:233], v[68:71]
	v_mfma_f32_16x16x32_bf16 v[64:67], v[194:197], v[230:233], v[64:67]
	s_setprio 0
	s_barrier
	s_add_i32 s90, s85, s39
	v_lshl_add_u64 v[174:175], s[10:11], 0, v[130:131]
	s_mov_b32 m0, s90
	ds_read_b128 v[198:201], v164 offset:16384
	ds_read_b128 v[202:205], v164 offset:17408
	ds_read_b128 v[206:209], v164 offset:18432
	ds_read_b128 v[210:213], v164 offset:19456
	ds_read_b128 v[214:217], v164 offset:20480
	ds_read_b128 v[218:221], v164 offset:21504
	ds_read_b128 v[226:229], v164 offset:22528
	ds_read_b128 v[230:233], v164 offset:23552
	global_load_lds_dwordx4 v[174:175], off
	s_add_i32 m0, s90, 0x2000
	s_add_u32 s90, s10, 0x40000
	v_lshl_add_u64 v[222:223], s[10:11], 0, v[134:135]
	s_addc_u32 s91, s11, 0
	s_add_i32 s92, s86, s39
	global_load_lds_dwordx4 v[222:223], off
	v_lshl_add_u64 v[234:235], s[90:91], 0, v[130:131]
	s_mov_b32 m0, s92
	v_lshl_add_u64 v[236:237], s[12:13], 0, v[132:133]
	global_load_lds_dwordx4 v[234:235], off
	v_lshl_add_u64 v[234:235], s[90:91], 0, v[134:135]
	s_add_i32 m0, s92, 0x2000
	s_nop 0
	global_load_lds_dwordx4 v[234:235], off
	v_lshl_add_u64 v[234:235], s[12:13], 0, v[128:129]
	s_mov_b32 m0, s43
	s_nop 0
	global_load_lds_dwordx4 v[234:235], off
	s_mov_b32 m0, s53
	s_nop 0
	global_load_lds_dwordx4 v[236:237], off
	s_waitcnt vmcnt(8)
	s_waitcnt lgkmcnt(0)
	s_barrier
; #define PG8_STAGE(bufoff, gbase, voff) do { _Pragma("unroll") for (int _i = 0; _i < 2; ++_i) \
;         __builtin_amdgcn_global_load_lds((const unsigned*)((const char*)(gbase) + (voff)[_i]), (LAS unsigned*)(lds + (bufoff) + ldsw + _i * 8192), 16, 0, 0); } while (0)
; #define PG8_LDA(dst, b, h) do { _Pragma("unroll") for (int m = 0; m < 4; ++m) _Pragma("unroll") for (int k = 0; k < 2; ++k) dst[m][k] = *(const LAS bf16x8*)(lds + PG8_SA(b, h) + aoff + m * 2048 + k * 1024); } while (0)
; #define PG8_LDB(dst, b, h) do { _Pragma("unroll") for (int n = 0; n < 2; ++n) _Pragma("unroll") for (int k = 0; k < 2; ++k) dst[n][k] = *(const LAS bf16x8*)(lds + PG8_SB(b, h) + boff + n * 2048 + k * 1024); } while (0)
; #define PG8_MMA(ai, bj, At, Bt) do { __builtin_amdgcn_s_setprio(1); _Pragma("unroll") for (int m = 0; m < 4; ++m) _Pragma("unroll") for (int n = 0; n < 2; ++n) _Pragma("unroll") for (int k = 0; k < 2; ++k) \
;         acc[ai][bj][m][n] = __builtin_amdgcn_mfma_f32_16x16x32_bf16(Bt[n][k], At[m][k], acc[ai][bj][m][n], 0, 0, 0); __builtin_amdgcn_s_setprio(0); } while (0)
; #define PG8_WAIT_V(n) asm volatile("s_waitcnt vmcnt(" #n ")" ::: "memory")
; #define PG8_WAIT_L(n) asm volatile("s_waitcnt lgkmcnt(" #n ")" ::: "memory")
; #define PG8_BAR __builtin_amdgcn_s_barrier()
; #define PG8_SCHED __builtin_amdgcn_sched_barrier(0)
; template <class Epi>
; __device__ __forceinline__ void gemm_phase(LAS unsigned char* lds, const Gemm g, const StaticOrder& S, const Epi& E) {
;     ...
;             PG8_WAIT_V(8); PG8_WAIT_L(0); PG8_BAR; PG8_MMA(1, 0, At, B0); PG8_MMA(1, 1, At, B1); PG8_BAR; PG8_SCHED;
;             PG8_LDB(B0, 1, 0); PG8_LDB(B1, 1, 1); PG8_SCHED; PG8_LDA(At, 1, 0); PG8_STAGE(PG8_SA(0, 1), a2 + hstepA, voffA);
;             PG8_WAIT_V(8); PG8_WAIT_L(0); PG8_BAR; PG8_MMA(0, 0, At, B0); PG8_MMA(0, 1, At, B1); PG8_BAR; PG8_SCHED;
	s_setprio 1
	s_waitcnt lgkmcnt(0)
	v_mfma_f32_16x16x32_bf16 v[60:63], v[146:149], v[198:201], 0
	v_mfma_f32_16x16x32_bf16 v[56:59], v[170:173], v[198:201], 0
	v_mfma_f32_16x16x32_bf16 v[52:55], v[146:149], v[206:209], 0
	v_mfma_f32_16x16x32_bf16 v[44:47], v[170:173], v[206:209], 0
	v_mfma_f32_16x16x32_bf16 v[36:39], v[146:149], v[214:217], 0
	v_mfma_f32_16x16x32_bf16 v[28:31], v[170:173], v[214:217], 0
	v_mfma_f32_16x16x32_bf16 v[20:23], v[146:149], v[226:229], 0
	v_mfma_f32_16x16x32_bf16 v[12:15], v[170:173], v[226:229], 0
	v_mfma_f32_16x16x32_bf16 v[60:63], v[166:169], v[202:205], v[60:63]
	v_mfma_f32_16x16x32_bf16 v[56:59], v[178:181], v[202:205], v[56:59]
	v_mfma_f32_16x16x32_bf16 v[52:55], v[166:169], v[210:213], v[52:55]
	v_mfma_f32_16x16x32_bf16 v[44:47], v[178:181], v[210:213], v[44:47]
	v_mfma_f32_16x16x32_bf16 v[36:39], v[166:169], v[218:221], v[36:39]
	v_mfma_f32_16x16x32_bf16 v[28:31], v[178:181], v[218:221], v[28:31]
	v_mfma_f32_16x16x32_bf16 v[20:23], v[166:169], v[230:233], v[20:23]
	v_mfma_f32_16x16x32_bf16 v[12:15], v[178:181], v[230:233], v[12:15]
	v_mfma_f32_16x16x32_bf16 v[48:51], v[182:185], v[198:201], 0
	v_mfma_f32_16x16x32_bf16 v[40:43], v[190:193], v[198:201], 0
	v_mfma_f32_16x16x32_bf16 v[32:35], v[182:185], v[206:209], 0
	v_mfma_f32_16x16x32_bf16 v[24:27], v[190:193], v[206:209], 0
	v_mfma_f32_16x16x32_bf16 v[16:19], v[182:185], v[214:217], 0
	v_mfma_f32_16x16x32_bf16 v[8:11], v[190:193], v[214:217], 0
	v_mfma_f32_16x16x32_bf16 v[4:7], v[182:185], v[226:229], 0
	v_mfma_f32_16x16x32_bf16 v[0:3], v[190:193], v[226:229], 0
	v_mfma_f32_16x16x32_bf16 v[48:51], v[186:189], v[202:205], v[48:51]
	v_mfma_f32_16x16x32_bf16 v[40:43], v[194:197], v[202:205], v[40:43]
	v_mfma_f32_16x16x32_bf16 v[32:35], v[186:189], v[210:213], v[32:35]
	v_mfma_f32_16x16x32_bf16 v[24:27], v[194:197], v[210:213], v[24:27]
	v_mfma_f32_16x16x32_bf16 v[16:19], v[186:189], v[218:221], v[16:19]
	v_mfma_f32_16x16x32_bf16 v[8:11], v[194:197], v[218:221], v[8:11]
	v_mfma_f32_16x16x32_bf16 v[4:7], v[186:189], v[230:233], v[4:7]
	v_mfma_f32_16x16x32_bf16 v[0:3], v[194:197], v[230:233], v[0:3]
	s_setprio 0
	s_barrier
	s_add_i32 s90, 0, 0x18000
	v_add_u32_e32 v136, s90, v161
	s_add_i32 s91, 0, 0x1c000
	ds_read_b128 v[146:149], v136
	ds_read_b128 v[166:169], v136 offset:1024
	ds_read_b128 v[170:173], v136 offset:2048
	ds_read_b128 v[178:181], v136 offset:3072
	v_add_u32_e32 v136, s91, v161
	ds_read_b128 v[182:185], v136
	ds_read_b128 v[186:189], v136 offset:1024
	ds_read_b128 v[190:193], v136 offset:2048
	ds_read_b128 v[194:197], v136 offset:3072
	s_add_u32 s12, s12, 0x40000
	s_addc_u32 s13, s13, 0
	s_mov_b32 m0, s55
	v_lshl_add_u64 v[238:239], s[12:13], 0, v[128:129]
	ds_read_b128 v[198:201], v164 offset:32768
	ds_read_b128 v[202:205], v164 offset:33792
	ds_read_b128 v[206:209], v164 offset:34816
	ds_read_b128 v[210:213], v164 offset:35840
	ds_read_b128 v[214:217], v164 offset:36864
	ds_read_b128 v[218:221], v164 offset:37888
	ds_read_b128 v[226:229], v164 offset:38912
	ds_read_b128 v[230:233], v164 offset:39936
	global_load_lds_dwordx4 v[238:239], off
	v_lshl_add_u64 v[238:239], s[12:13], 0, v[132:133]
	s_mov_b32 m0, s57
	s_nop 0
	global_load_lds_dwordx4 v[238:239], off
	s_waitcnt vmcnt(8)
	s_waitcnt lgkmcnt(0)
	s_barrier
	s_setprio 1
	s_waitcnt lgkmcnt(0)
	v_mfma_f32_16x16x32_bf16 v[124:127], v[146:149], v[198:201], v[124:127]
	v_mfma_f32_16x16x32_bf16 v[120:123], v[170:173], v[198:201], v[120:123]
	v_mfma_f32_16x16x32_bf16 v[112:115], v[146:149], v[206:209], v[112:115]
	v_mfma_f32_16x16x32_bf16 v[104:107], v[170:173], v[206:209], v[104:107]
	v_mfma_f32_16x16x32_bf16 v[100:103], v[146:149], v[214:217], v[100:103]
	v_mfma_f32_16x16x32_bf16 v[92:95], v[170:173], v[214:217], v[92:95]
	v_mfma_f32_16x16x32_bf16 v[84:87], v[146:149], v[226:229], v[84:87]
	v_mfma_f32_16x16x32_bf16 v[76:79], v[170:173], v[226:229], v[76:79]
	v_mfma_f32_16x16x32_bf16 v[124:127], v[166:169], v[202:205], v[124:127]
	v_mfma_f32_16x16x32_bf16 v[120:123], v[178:181], v[202:205], v[120:123]
	v_mfma_f32_16x16x32_bf16 v[112:115], v[166:169], v[210:213], v[112:115]
	v_mfma_f32_16x16x32_bf16 v[104:107], v[178:181], v[210:213], v[104:107]
	v_mfma_f32_16x16x32_bf16 v[100:103], v[166:169], v[218:221], v[100:103]
	v_mfma_f32_16x16x32_bf16 v[92:95], v[178:181], v[218:221], v[92:95]
	v_mfma_f32_16x16x32_bf16 v[84:87], v[166:169], v[230:233], v[84:87]
	v_mfma_f32_16x16x32_bf16 v[76:79], v[178:181], v[230:233], v[76:79]
	v_mfma_f32_16x16x32_bf16 v[116:119], v[182:185], v[198:201], v[116:119]
	v_mfma_f32_16x16x32_bf16 v[108:111], v[190:193], v[198:201], v[108:111]
	v_mfma_f32_16x16x32_bf16 v[96:99], v[182:185], v[206:209], v[96:99]
	v_mfma_f32_16x16x32_bf16 v[88:91], v[190:193], v[206:209], v[88:91]
	v_mfma_f32_16x16x32_bf16 v[80:83], v[182:185], v[214:217], v[80:83]
	v_mfma_f32_16x16x32_bf16 v[72:75], v[190:193], v[214:217], v[72:75]
	v_mfma_f32_16x16x32_bf16 v[68:71], v[182:185], v[226:229], v[68:71]
	v_mfma_f32_16x16x32_bf16 v[64:67], v[190:193], v[226:229], v[64:67]
	v_mfma_f32_16x16x32_bf16 v[116:119], v[186:189], v[202:205], v[116:119]
	v_mfma_f32_16x16x32_bf16 v[108:111], v[194:197], v[202:205], v[108:111]
	v_mfma_f32_16x16x32_bf16 v[96:99], v[186:189], v[210:213], v[96:99]
	v_mfma_f32_16x16x32_bf16 v[88:91], v[194:197], v[210:213], v[88:91]
	v_mfma_f32_16x16x32_bf16 v[80:83], v[186:189], v[218:221], v[80:83]
	v_mfma_f32_16x16x32_bf16 v[72:75], v[194:197], v[218:221], v[72:75]
	v_mfma_f32_16x16x32_bf16 v[68:71], v[186:189], v[230:233], v[68:71]
	v_mfma_f32_16x16x32_bf16 v[64:67], v[194:197], v[230:233], v[64:67]
	s_setprio 0
	s_barrier
; #define PG8_STAGE(bufoff, gbase, voff) do { _Pragma("unroll") for (int _i = 0; _i < 2; ++_i) \
;         __builtin_amdgcn_global_load_lds((const unsigned*)((const char*)(gbase) + (voff)[_i]), (LAS unsigned*)(lds + (bufoff) + ldsw + _i * 8192), 16, 0, 0); } while (0)
; #define PG8_LDA(dst, b, h) do { _Pragma("unroll") for (int m = 0; m < 4; ++m) _Pragma("unroll") for (int k = 0; k < 2; ++k) dst[m][k] = *(const LAS bf16x8*)(lds + PG8_SA(b, h) + aoff + m * 2048 + k * 1024); } while (0)
; #define PG8_LDB(dst, b, h) do { _Pragma("unroll") for (int n = 0; n < 2; ++n) _Pragma("unroll") for (int k = 0; k < 2; ++k) dst[n][k] = *(const LAS bf16x8*)(lds + PG8_SB(b, h) + boff + n * 2048 + k * 1024); } while (0)
; #define PG8_WAIT_V(n) asm volatile("s_waitcnt vmcnt(" #n ")" ::: "memory")
; #define PG8_WAIT_L(n) asm volatile("s_waitcnt lgkmcnt(" #n ")" ::: "memory")
; template <class Epi>
; __device__ __forceinline__ void gemm_phase(LAS unsigned char* lds, const Gemm g, const StaticOrder& S, const Epi& E) {
;     ...
;         for (int t = 0; t < nt; t += 2) {
;             const bool last = (t == nt - 2);
;             const char* a1 = cA + (size_t)(t + 1) * kstep;
;             const char* a2 = last ? nA : cA + (size_t)(t + 2) * kstep; const char* b2 = last ? nB : cB + (size_t)(t + 2) * kstep;
;             const char* a3 = a2 + kstep; const char* b3 = b2 + kstep;
;             PG8_LDB(B0, 0, 0); PG8_LDB(B1, 0, 1); PG8_SCHED; PG8_LDA(At, 0, 0); PG8_STAGE(PG8_SA(1, 1), a1 + hstepA, voffA);
;             PG8_WAIT_V(8); PG8_WAIT_L(0); PG8_BAR; PG8_MMA(0, 0, At, B0); PG8_MMA(0, 1, At, B1); PG8_BAR; PG8_SCHED;
;             PG8_LDA(At, 0, 1); PG8_STAGE(PG8_SB(0, 0), b2, voffB); PG8_STAGE(PG8_SB(0, 1), b2 + hstepB, voffB); PG8_STAGE(PG8_SA(0, 0), a2, voffA);
;             PG8_WAIT_V(8); PG8_WAIT_L(0); PG8_BAR; PG8_MMA(1, 0, At, B0); PG8_MMA(1, 1, At, B1); PG8_BAR; PG8_SCHED;
;             PG8_LDB(B0, 1, 0); PG8_LDB(B1, 1, 1); PG8_SCHED; PG8_LDA(At, 1, 0); PG8_STAGE(PG8_SA(0, 1), a2 + hstepA, voffA);
;             PG8_WAIT_V(8); PG8_WAIT_L(0); PG8_BAR; PG8_MMA(0, 0, At, B0); PG8_MMA(0, 1, At, B1); PG8_BAR; PG8_SCHED;
;             PG8_LDA(At, 1, 1); PG8_STAGE(PG8_SB(1, 0), b3, voffB); PG8_STAGE(PG8_SB(1, 1), b3 + hstepB, voffB); PG8_STAGE(PG8_SA(1, 0), a3, voffA);
;             PG8_WAIT_V(8); PG8_WAIT_L(0); PG8_BAR; PG8_MMA(1, 0, At, B0); PG8_MMA(1, 1, At, B1); PG8_BAR; PG8_SCHED;
	s_add_i32 s12, s90, s39
	v_lshl_add_u64 v[174:175], v[174:175], 0, s[30:31]
	s_mov_b32 m0, s12
	ds_read_b128 v[198:201], v164 offset:49152
	ds_read_b128 v[202:205], v164 offset:50176
	ds_read_b128 v[206:209], v164 offset:51200
	ds_read_b128 v[210:213], v164 offset:52224
	ds_read_b128 v[214:217], v164 offset:53248
	ds_read_b128 v[218:221], v164 offset:54272
	ds_read_b128 v[226:229], v164 offset:55296
	ds_read_b128 v[230:233], v164 offset:56320
	global_load_lds_dwordx4 v[174:175], off
	s_add_i32 m0, s12, 0x2000
	s_add_u32 s10, s10, 0x40080
	v_lshl_add_u64 v[174:175], v[222:223], 0, s[30:31]
	s_addc_u32 s11, s11, 0
	s_add_i32 s12, s91, s39
	global_load_lds_dwordx4 v[174:175], off
	v_lshl_add_u64 v[174:175], s[10:11], 0, v[130:131]
	s_mov_b32 m0, s12
	s_nop 0
	global_load_lds_dwordx4 v[174:175], off
	v_lshl_add_u64 v[174:175], s[10:11], 0, v[134:135]
	s_add_i32 m0, s12, 0x2000
	s_nop 0
	global_load_lds_dwordx4 v[174:175], off
	v_lshl_add_u64 v[174:175], v[234:235], 0, s[30:31]
	s_mov_b32 m0, s79
	s_nop 0
	global_load_lds_dwordx4 v[174:175], off
	v_lshl_add_u64 v[174:175], v[236:237], 0, s[30:31]
	s_mov_b32 m0, s80
	s_nop 0
	global_load_lds_dwordx4 v[174:175], off
	s_waitcnt vmcnt(8)
	s_waitcnt lgkmcnt(0)
	s_barrier
	s_setprio 1
	s_waitcnt lgkmcnt(0)
	v_mfma_f32_16x16x32_bf16 v[60:63], v[146:149], v[198:201], v[60:63]
	v_mfma_f32_16x16x32_bf16 v[56:59], v[170:173], v[198:201], v[56:59]
	v_mfma_f32_16x16x32_bf16 v[52:55], v[146:149], v[206:209], v[52:55]
	v_mfma_f32_16x16x32_bf16 v[44:47], v[170:173], v[206:209], v[44:47]
	v_mfma_f32_16x16x32_bf16 v[36:39], v[146:149], v[214:217], v[36:39]
	v_mfma_f32_16x16x32_bf16 v[28:31], v[170:173], v[214:217], v[28:31]
	v_mfma_f32_16x16x32_bf16 v[20:23], v[146:149], v[226:229], v[20:23]
	v_mfma_f32_16x16x32_bf16 v[12:15], v[170:173], v[226:229], v[12:15]
	v_mfma_f32_16x16x32_bf16 v[60:63], v[166:169], v[202:205], v[60:63]
	v_mfma_f32_16x16x32_bf16 v[56:59], v[178:181], v[202:205], v[56:59]
	v_mfma_f32_16x16x32_bf16 v[52:55], v[166:169], v[210:213], v[52:55]
	v_mfma_f32_16x16x32_bf16 v[44:47], v[178:181], v[210:213], v[44:47]
	v_mfma_f32_16x16x32_bf16 v[36:39], v[166:169], v[218:221], v[36:39]
	v_mfma_f32_16x16x32_bf16 v[28:31], v[178:181], v[218:221], v[28:31]
	v_mfma_f32_16x16x32_bf16 v[20:23], v[166:169], v[230:233], v[20:23]
	v_mfma_f32_16x16x32_bf16 v[12:15], v[178:181], v[230:233], v[12:15]
	v_mfma_f32_16x16x32_bf16 v[48:51], v[182:185], v[198:201], v[48:51]
	v_mfma_f32_16x16x32_bf16 v[40:43], v[190:193], v[198:201], v[40:43]
	v_mfma_f32_16x16x32_bf16 v[32:35], v[182:185], v[206:209], v[32:35]
	v_mfma_f32_16x16x32_bf16 v[24:27], v[190:193], v[206:209], v[24:27]
	v_mfma_f32_16x16x32_bf16 v[16:19], v[182:185], v[214:217], v[16:19]
	v_mfma_f32_16x16x32_bf16 v[8:11], v[190:193], v[214:217], v[8:11]
	v_mfma_f32_16x16x32_bf16 v[4:7], v[182:185], v[226:229], v[4:7]
	v_mfma_f32_16x16x32_bf16 v[0:3], v[190:193], v[226:229], v[0:3]
	v_mfma_f32_16x16x32_bf16 v[48:51], v[186:189], v[202:205], v[48:51]
	v_mfma_f32_16x16x32_bf16 v[40:43], v[194:197], v[202:205], v[40:43]
	v_mfma_f32_16x16x32_bf16 v[32:35], v[186:189], v[210:213], v[32:35]
	v_mfma_f32_16x16x32_bf16 v[24:27], v[194:197], v[210:213], v[24:27]
	v_mfma_f32_16x16x32_bf16 v[16:19], v[186:189], v[218:221], v[16:19]
	v_mfma_f32_16x16x32_bf16 v[8:11], v[194:197], v[218:221], v[8:11]
	v_mfma_f32_16x16x32_bf16 v[4:7], v[186:189], v[230:233], v[4:7]
	v_mfma_f32_16x16x32_bf16 v[0:3], v[194:197], v[230:233], v[0:3]
	s_setprio 0
	s_barrier
	s_add_i32 s89, s89, 2
	s_add_u32 s8, s8, 0x100
	s_addc_u32 s9, s9, 0
	s_add_u32 s76, s76, 0x100
	s_addc_u32 s77, s77, 0
	s_cmp_gt_u32 s89, 13
.LBB0_546:
	ds_read_b128 v[146:149], v162
	ds_read_b128 v[166:169], v162 offset:1024
	ds_read_b128 v[170:173], v162 offset:2048
	ds_read_b128 v[178:181], v162 offset:3072
	ds_read_b128 v[182:185], v163
	ds_read_b128 v[186:189], v163 offset:1024
	ds_read_b128 v[190:193], v163 offset:2048
	ds_read_b128 v[194:197], v163 offset:3072
	s_add_u32 s10, s8, 0xfffc0080
	s_addc_u32 s11, s9, -1
	s_cmp_eq_u32 s89, 12
	s_cselect_b32 s13, s1, s11
	s_cselect_b32 s12, s7, s10
	s_cselect_b32 s11, s69, s77
	s_cselect_b32 s10, s71, s76
	v_lshl_add_u64 v[174:175], s[8:9], 0, v[138:139]
	s_add_i32 m0, s43, 0xc000
	ds_read_b128 v[198:201], v164
	ds_read_b128 v[202:205], v164 offset:1024
	ds_read_b128 v[206:209], v164 offset:2048
	ds_read_b128 v[210:213], v164 offset:3072
	ds_read_b128 v[214:217], v164 offset:4096
	ds_read_b128 v[218:221], v164 offset:5120
	ds_read_b128 v[226:229], v164 offset:6144
	ds_read_b128 v[230:233], v164 offset:7168
	global_load_lds_dwordx4 v[174:175], off
	v_lshl_add_u64 v[174:175], s[8:9], 0, v[140:141]
	s_add_i32 m0, s43, 0xe000
	s_nop 0
	global_load_lds_dwordx4 v[174:175], off
	s_waitcnt vmcnt(8)
	s_waitcnt lgkmcnt(0)
	s_barrier
; #define PG8_STAGE(bufoff, gbase, voff) do { _Pragma("unroll") for (int _i = 0; _i < 2; ++_i) \
;         __builtin_amdgcn_global_load_lds((const unsigned*)((const char*)(gbase) + (voff)[_i]), (LAS unsigned*)(lds + (bufoff) + ldsw + _i * 8192), 16, 0, 0); } while (0)
; #define PG8_LDA(dst, b, h) do { _Pragma("unroll") for (int m = 0; m < 4; ++m) _Pragma("unroll") for (int k = 0; k < 2; ++k) dst[m][k] = *(const LAS bf16x8*)(lds + PG8_SA(b, h) + aoff + m * 2048 + k * 1024); } while (0)
; #define PG8_MMA(ai, bj, At, Bt) do { __builtin_amdgcn_s_setprio(1); _Pragma("unroll") for (int m = 0; m < 4; ++m) _Pragma("unroll") for (int n = 0; n < 2; ++n) _Pragma("unroll") for (int k = 0; k < 2; ++k) \
;         acc[ai][bj][m][n] = __builtin_amdgcn_mfma_f32_16x16x32_bf16(Bt[n][k], At[m][k], acc[ai][bj][m][n], 0, 0, 0); __builtin_amdgcn_s_setprio(0); } while (0)
; #define PG8_WAIT_V(n) asm volatile("s_waitcnt vmcnt(" #n ")" ::: "memory")
; #define PG8_WAIT_L(n) asm volatile("s_waitcnt lgkmcnt(" #n ")" ::: "memory")
; #define PG8_BAR __builtin_amdgcn_s_barrier()
; #define PG8_SCHED __builtin_amdgcn_sched_barrier(0)
; template <class Epi>
; __device__ __forceinline__ void gemm_phase(LAS unsigned char* lds, const Gemm g, const StaticOrder& S, const Epi& E) {
;     ...
;             PG8_WAIT_V(8); PG8_WAIT_L(0); PG8_BAR; PG8_MMA(0, 0, At, B0); PG8_MMA(0, 1, At, B1); PG8_BAR; PG8_SCHED;
;             PG8_LDA(At, 0, 1); PG8_STAGE(PG8_SB(0, 0), b2, voffB); PG8_STAGE(PG8_SB(0, 1), b2 + hstepB, voffB); PG8_STAGE(PG8_SA(0, 0), a2, voffA);
;             PG8_WAIT_V(8); PG8_WAIT_L(0); PG8_BAR; PG8_MMA(1, 0, At, B0); PG8_MMA(1, 1, At, B1); PG8_BAR; PG8_SCHED;
	s_setprio 1
	s_waitcnt lgkmcnt(0)
	v_mfma_f32_16x16x32_bf16 v[124:127], v[146:149], v[198:201], v[124:127]
	v_mfma_f32_16x16x32_bf16 v[120:123], v[170:173], v[198:201], v[120:123]
	v_mfma_f32_16x16x32_bf16 v[112:115], v[146:149], v[206:209], v[112:115]
	v_mfma_f32_16x16x32_bf16 v[104:107], v[170:173], v[206:209], v[104:107]
	v_mfma_f32_16x16x32_bf16 v[100:103], v[146:149], v[214:217], v[100:103]
	v_mfma_f32_16x16x32_bf16 v[92:95], v[170:173], v[214:217], v[92:95]
	v_mfma_f32_16x16x32_bf16 v[84:87], v[146:149], v[226:229], v[84:87]
	v_mfma_f32_16x16x32_bf16 v[76:79], v[170:173], v[226:229], v[76:79]
	v_mfma_f32_16x16x32_bf16 v[124:127], v[166:169], v[202:205], v[124:127]
	v_mfma_f32_16x16x32_bf16 v[120:123], v[178:181], v[202:205], v[120:123]
	v_mfma_f32_16x16x32_bf16 v[112:115], v[166:169], v[210:213], v[112:115]
	v_mfma_f32_16x16x32_bf16 v[104:107], v[178:181], v[210:213], v[104:107]
	v_mfma_f32_16x16x32_bf16 v[100:103], v[166:169], v[218:221], v[100:103]
	v_mfma_f32_16x16x32_bf16 v[92:95], v[178:181], v[218:221], v[92:95]
	v_mfma_f32_16x16x32_bf16 v[84:87], v[166:169], v[230:233], v[84:87]
	v_mfma_f32_16x16x32_bf16 v[76:79], v[178:181], v[230:233], v[76:79]
	v_mfma_f32_16x16x32_bf16 v[116:119], v[182:185], v[198:201], v[116:119]
	v_mfma_f32_16x16x32_bf16 v[108:111], v[190:193], v[198:201], v[108:111]
	v_mfma_f32_16x16x32_bf16 v[96:99], v[182:185], v[206:209], v[96:99]
	v_mfma_f32_16x16x32_bf16 v[88:91], v[190:193], v[206:209], v[88:91]
	v_mfma_f32_16x16x32_bf16 v[80:83], v[182:185], v[214:217], v[80:83]
	v_mfma_f32_16x16x32_bf16 v[72:75], v[190:193], v[214:217], v[72:75]
	v_mfma_f32_16x16x32_bf16 v[68:71], v[182:185], v[226:229], v[68:71]
	v_mfma_f32_16x16x32_bf16 v[64:67], v[190:193], v[226:229], v[64:67]
	v_mfma_f32_16x16x32_bf16 v[116:119], v[186:189], v[202:205], v[116:119]
	v_mfma_f32_16x16x32_bf16 v[108:111], v[194:197], v[202:205], v[108:111]
	v_mfma_f32_16x16x32_bf16 v[96:99], v[186:189], v[210:213], v[96:99]
	v_mfma_f32_16x16x32_bf16 v[88:91], v[194:197], v[210:213], v[88:91]
	v_mfma_f32_16x16x32_bf16 v[80:83], v[186:189], v[218:221], v[80:83]
	v_mfma_f32_16x16x32_bf16 v[72:75], v[194:197], v[218:221], v[72:75]
	v_mfma_f32_16x16x32_bf16 v[68:71], v[186:189], v[230:233], v[68:71]
	v_mfma_f32_16x16x32_bf16 v[64:67], v[194:197], v[230:233], v[64:67]
	s_setprio 0
	s_barrier
	s_add_i32 s90, s85, s39
	v_lshl_add_u64 v[174:175], s[10:11], 0, v[130:131]
	s_mov_b32 m0, s90
	ds_read_b128 v[198:201], v164 offset:16384
	ds_read_b128 v[202:205], v164 offset:17408
	ds_read_b128 v[206:209], v164 offset:18432
	ds_read_b128 v[210:213], v164 offset:19456
	ds_read_b128 v[214:217], v164 offset:20480
	ds_read_b128 v[218:221], v164 offset:21504
	ds_read_b128 v[226:229], v164 offset:22528
	ds_read_b128 v[230:233], v164 offset:23552
	global_load_lds_dwordx4 v[174:175], off
	s_add_i32 m0, s90, 0x2000
	s_add_u32 s90, s10, 0x40000
	v_lshl_add_u64 v[222:223], s[10:11], 0, v[134:135]
	s_addc_u32 s91, s11, 0
	s_add_i32 s92, s86, s39
	global_load_lds_dwordx4 v[222:223], off
	v_lshl_add_u64 v[234:235], s[90:91], 0, v[130:131]
	s_mov_b32 m0, s92
	v_lshl_add_u64 v[236:237], s[12:13], 0, v[132:133]
	global_load_lds_dwordx4 v[234:235], off
	v_lshl_add_u64 v[234:235], s[90:91], 0, v[134:135]
	s_add_i32 m0, s92, 0x2000
	s_nop 0
	global_load_lds_dwordx4 v[234:235], off
	v_lshl_add_u64 v[234:235], s[12:13], 0, v[128:129]
	s_mov_b32 m0, s43
	s_nop 0
	global_load_lds_dwordx4 v[234:235], off
	s_mov_b32 m0, s53
	s_nop 0
	global_load_lds_dwordx4 v[236:237], off
	s_waitcnt vmcnt(8)
	s_waitcnt lgkmcnt(0)
	s_barrier
	s_setprio 1
	s_waitcnt lgkmcnt(0)
	v_mfma_f32_16x16x32_bf16 v[60:63], v[146:149], v[198:201], v[60:63]
	v_mfma_f32_16x16x32_bf16 v[56:59], v[170:173], v[198:201], v[56:59]
	v_mfma_f32_16x16x32_bf16 v[52:55], v[146:149], v[206:209], v[52:55]
	v_mfma_f32_16x16x32_bf16 v[44:47], v[170:173], v[206:209], v[44:47]
	v_mfma_f32_16x16x32_bf16 v[36:39], v[146:149], v[214:217], v[36:39]
	v_mfma_f32_16x16x32_bf16 v[28:31], v[170:173], v[214:217], v[28:31]
	v_mfma_f32_16x16x32_bf16 v[20:23], v[146:149], v[226:229], v[20:23]
	v_mfma_f32_16x16x32_bf16 v[12:15], v[170:173], v[226:229], v[12:15]
	v_mfma_f32_16x16x32_bf16 v[60:63], v[166:169], v[202:205], v[60:63]
	v_mfma_f32_16x16x32_bf16 v[56:59], v[178:181], v[202:205], v[56:59]
	v_mfma_f32_16x16x32_bf16 v[52:55], v[166:169], v[210:213], v[52:55]
	v_mfma_f32_16x16x32_bf16 v[44:47], v[178:181], v[210:213], v[44:47]
	v_mfma_f32_16x16x32_bf16 v[36:39], v[166:169], v[218:221], v[36:39]
	v_mfma_f32_16x16x32_bf16 v[28:31], v[178:181], v[218:221], v[28:31]
	v_mfma_f32_16x16x32_bf16 v[20:23], v[166:169], v[230:233], v[20:23]
	v_mfma_f32_16x16x32_bf16 v[12:15], v[178:181], v[230:233], v[12:15]
	v_mfma_f32_16x16x32_bf16 v[48:51], v[182:185], v[198:201], v[48:51]
	v_mfma_f32_16x16x32_bf16 v[40:43], v[190:193], v[198:201], v[40:43]
	v_mfma_f32_16x16x32_bf16 v[32:35], v[182:185], v[206:209], v[32:35]
	v_mfma_f32_16x16x32_bf16 v[24:27], v[190:193], v[206:209], v[24:27]
	v_mfma_f32_16x16x32_bf16 v[16:19], v[182:185], v[214:217], v[16:19]
	v_mfma_f32_16x16x32_bf16 v[8:11], v[190:193], v[214:217], v[8:11]
	v_mfma_f32_16x16x32_bf16 v[4:7], v[182:185], v[226:229], v[4:7]
	v_mfma_f32_16x16x32_bf16 v[0:3], v[190:193], v[226:229], v[0:3]
	v_mfma_f32_16x16x32_bf16 v[48:51], v[186:189], v[202:205], v[48:51]
	v_mfma_f32_16x16x32_bf16 v[40:43], v[194:197], v[202:205], v[40:43]
	v_mfma_f32_16x16x32_bf16 v[32:35], v[186:189], v[210:213], v[32:35]
	v_mfma_f32_16x16x32_bf16 v[24:27], v[194:197], v[210:213], v[24:27]
	v_mfma_f32_16x16x32_bf16 v[16:19], v[186:189], v[218:221], v[16:19]
	v_mfma_f32_16x16x32_bf16 v[8:11], v[194:197], v[218:221], v[8:11]
	v_mfma_f32_16x16x32_bf16 v[4:7], v[186:189], v[230:233], v[4:7]
	v_mfma_f32_16x16x32_bf16 v[0:3], v[194:197], v[230:233], v[0:3]
	s_setprio 0
	s_barrier
; #define PG8_STAGE(bufoff, gbase, voff) do { _Pragma("unroll") for (int _i = 0; _i < 2; ++_i) \
;         __builtin_amdgcn_global_load_lds((const unsigned*)((const char*)(gbase) + (voff)[_i]), (LAS unsigned*)(lds + (bufoff) + ldsw + _i * 8192), 16, 0, 0); } while (0)
; #define PG8_LDA(dst, b, h) do { _Pragma("unroll") for (int m = 0; m < 4; ++m) _Pragma("unroll") for (int k = 0; k < 2; ++k) dst[m][k] = *(const LAS bf16x8*)(lds + PG8_SA(b, h) + aoff + m * 2048 + k * 1024); } while (0)
; #define PG8_LDB(dst, b, h) do { _Pragma("unroll") for (int n = 0; n < 2; ++n) _Pragma("unroll") for (int k = 0; k < 2; ++k) dst[n][k] = *(const LAS bf16x8*)(lds + PG8_SB(b, h) + boff + n * 2048 + k * 1024); } while (0)
; #define PG8_MMA(ai, bj, At, Bt) do { __builtin_amdgcn_s_setprio(1); _Pragma("unroll") for (int m = 0; m < 4; ++m) _Pragma("unroll") for (int n = 0; n < 2; ++n) _Pragma("unroll") for (int k = 0; k < 2; ++k) \
;         acc[ai][bj][m][n] = __builtin_amdgcn_mfma_f32_16x16x32_bf16(Bt[n][k], At[m][k], acc[ai][bj][m][n], 0, 0, 0); __builtin_amdgcn_s_setprio(0); } while (0)
; #define PG8_WAIT_V(n) asm volatile("s_waitcnt vmcnt(" #n ")" ::: "memory")
; #define PG8_WAIT_L(n) asm volatile("s_waitcnt lgkmcnt(" #n ")" ::: "memory")
; #define PG8_BAR __builtin_amdgcn_s_barrier()
; #define PG8_SCHED __builtin_amdgcn_sched_barrier(0)
; template <class Epi>
; __device__ __forceinline__ void gemm_phase(LAS unsigned char* lds, const Gemm g, const StaticOrder& S, const Epi& E) {
;     ...
;             PG8_LDB(B0, 1, 0); PG8_LDB(B1, 1, 1); PG8_SCHED; PG8_LDA(At, 1, 0); PG8_STAGE(PG8_SA(0, 1), a2 + hstepA, voffA);
;             PG8_WAIT_V(8); PG8_WAIT_L(0); PG8_BAR; PG8_MMA(0, 0, At, B0); PG8_MMA(0, 1, At, B1); PG8_BAR; PG8_SCHED;
	s_add_i32 s90, 0, 0x18000
	v_add_u32_e32 v136, s90, v161
	s_add_i32 s91, 0, 0x1c000
	ds_read_b128 v[146:149], v136
	ds_read_b128 v[166:169], v136 offset:1024
	ds_read_b128 v[170:173], v136 offset:2048
	ds_read_b128 v[178:181], v136 offset:3072
	v_add_u32_e32 v136, s91, v161
	ds_read_b128 v[182:185], v136
	ds_read_b128 v[186:189], v136 offset:1024
	ds_read_b128 v[190:193], v136 offset:2048
	ds_read_b128 v[194:197], v136 offset:3072
	s_add_u32 s12, s12, 0x40000
	s_addc_u32 s13, s13, 0
	s_mov_b32 m0, s55
	v_lshl_add_u64 v[238:239], s[12:13], 0, v[128:129]
	ds_read_b128 v[198:201], v164 offset:32768
	ds_read_b128 v[202:205], v164 offset:33792
	ds_read_b128 v[206:209], v164 offset:34816
	ds_read_b128 v[210:213], v164 offset:35840
	ds_read_b128 v[214:217], v164 offset:36864
	ds_read_b128 v[218:221], v164 offset:37888
	ds_read_b128 v[226:229], v164 offset:38912
	ds_read_b128 v[230:233], v164 offset:39936
	global_load_lds_dwordx4 v[238:239], off
	v_lshl_add_u64 v[238:239], s[12:13], 0, v[132:133]
	s_mov_b32 m0, s57
	s_nop 0
	global_load_lds_dwordx4 v[238:239], off
	s_waitcnt vmcnt(8)
	s_waitcnt lgkmcnt(0)
	s_barrier
	s_setprio 1
	s_waitcnt lgkmcnt(0)
	v_mfma_f32_16x16x32_bf16 v[124:127], v[146:149], v[198:201], v[124:127]
	v_mfma_f32_16x16x32_bf16 v[120:123], v[170:173], v[198:201], v[120:123]
	v_mfma_f32_16x16x32_bf16 v[112:115], v[146:149], v[206:209], v[112:115]
	v_mfma_f32_16x16x32_bf16 v[104:107], v[170:173], v[206:209], v[104:107]
	v_mfma_f32_16x16x32_bf16 v[100:103], v[146:149], v[214:217], v[100:103]
	v_mfma_f32_16x16x32_bf16 v[92:95], v[170:173], v[214:217], v[92:95]
	v_mfma_f32_16x16x32_bf16 v[84:87], v[146:149], v[226:229], v[84:87]
	v_mfma_f32_16x16x32_bf16 v[76:79], v[170:173], v[226:229], v[76:79]
	v_mfma_f32_16x16x32_bf16 v[124:127], v[166:169], v[202:205], v[124:127]
	v_mfma_f32_16x16x32_bf16 v[120:123], v[178:181], v[202:205], v[120:123]
	v_mfma_f32_16x16x32_bf16 v[112:115], v[166:169], v[210:213], v[112:115]
	v_mfma_f32_16x16x32_bf16 v[104:107], v[178:181], v[210:213], v[104:107]
	v_mfma_f32_16x16x32_bf16 v[100:103], v[166:169], v[218:221], v[100:103]
	v_mfma_f32_16x16x32_bf16 v[92:95], v[178:181], v[218:221], v[92:95]
	v_mfma_f32_16x16x32_bf16 v[84:87], v[166:169], v[230:233], v[84:87]
	v_mfma_f32_16x16x32_bf16 v[76:79], v[178:181], v[230:233], v[76:79]
	v_mfma_f32_16x16x32_bf16 v[116:119], v[182:185], v[198:201], v[116:119]
	v_mfma_f32_16x16x32_bf16 v[108:111], v[190:193], v[198:201], v[108:111]
	v_mfma_f32_16x16x32_bf16 v[96:99], v[182:185], v[206:209], v[96:99]
	v_mfma_f32_16x16x32_bf16 v[88:91], v[190:193], v[206:209], v[88:91]
	v_mfma_f32_16x16x32_bf16 v[80:83], v[182:185], v[214:217], v[80:83]
	v_mfma_f32_16x16x32_bf16 v[72:75], v[190:193], v[214:217], v[72:75]
	v_mfma_f32_16x16x32_bf16 v[68:71], v[182:185], v[226:229], v[68:71]
	v_mfma_f32_16x16x32_bf16 v[64:67], v[190:193], v[226:229], v[64:67]
	v_mfma_f32_16x16x32_bf16 v[116:119], v[186:189], v[202:205], v[116:119]
	v_mfma_f32_16x16x32_bf16 v[108:111], v[194:197], v[202:205], v[108:111]
	v_mfma_f32_16x16x32_bf16 v[96:99], v[186:189], v[210:213], v[96:99]
	v_mfma_f32_16x16x32_bf16 v[88:91], v[194:197], v[210:213], v[88:91]
	v_mfma_f32_16x16x32_bf16 v[80:83], v[186:189], v[218:221], v[80:83]
	v_mfma_f32_16x16x32_bf16 v[72:75], v[194:197], v[218:221], v[72:75]
	v_mfma_f32_16x16x32_bf16 v[68:71], v[186:189], v[230:233], v[68:71]
	v_mfma_f32_16x16x32_bf16 v[64:67], v[194:197], v[230:233], v[64:67]
	s_setprio 0
	s_barrier
; #define PG8_STAGE(bufoff, gbase, voff) do { _Pragma("unroll") for (int _i = 0; _i < 2; ++_i) \
;         __builtin_amdgcn_global_load_lds((const unsigned*)((const char*)(gbase) + (voff)[_i]), (LAS unsigned*)(lds + (bufoff) + ldsw + _i * 8192), 16, 0, 0); } while (0)
; #define PG8_LDA(dst, b, h) do { _Pragma("unroll") for (int m = 0; m < 4; ++m) _Pragma("unroll") for (int k = 0; k < 2; ++k) dst[m][k] = *(const LAS bf16x8*)(lds + PG8_SA(b, h) + aoff + m * 2048 + k * 1024); } while (0)
; #define PG8_MMA(ai, bj, At, Bt) do { __builtin_amdgcn_s_setprio(1); _Pragma("unroll") for (int m = 0; m < 4; ++m) _Pragma("unroll") for (int n = 0; n < 2; ++n) _Pragma("unroll") for (int k = 0; k < 2; ++k) \
;         acc[ai][bj][m][n] = __builtin_amdgcn_mfma_f32_16x16x32_bf16(Bt[n][k], At[m][k], acc[ai][bj][m][n], 0, 0, 0); __builtin_amdgcn_s_setprio(0); } while (0)
; #define PG8_WAIT_V(n) asm volatile("s_waitcnt vmcnt(" #n ")" ::: "memory")
; #define PG8_WAIT_L(n) asm volatile("s_waitcnt lgkmcnt(" #n ")" ::: "memory")
; #define PG8_BAR __builtin_amdgcn_s_barrier()
; #define PG8_SCHED __builtin_amdgcn_sched_barrier(0)
; template <class Epi>
; __device__ __forceinline__ void gemm_phase(LAS unsigned char* lds, const Gemm g, const StaticOrder& S, const Epi& E) {
;     ...
;             PG8_LDA(At, 1, 1); PG8_STAGE(PG8_SB(1, 0), b3, voffB); PG8_STAGE(PG8_SB(1, 1), b3 + hstepB, voffB); PG8_STAGE(PG8_SA(1, 0), a3, voffA);
;             PG8_WAIT_V(8); PG8_WAIT_L(0); PG8_BAR; PG8_MMA(1, 0, At, B0); PG8_MMA(1, 1, At, B1); PG8_BAR; PG8_SCHED;
;         }
;         if (wr == 0) PG8_BAR;
	s_add_i32 s12, s90, s39
	v_lshl_add_u64 v[174:175], v[174:175], 0, s[30:31]
	s_mov_b32 m0, s12
	ds_read_b128 v[198:201], v164 offset:49152
	ds_read_b128 v[202:205], v164 offset:50176
	ds_read_b128 v[206:209], v164 offset:51200
	ds_read_b128 v[210:213], v164 offset:52224
	ds_read_b128 v[214:217], v164 offset:53248
	ds_read_b128 v[218:221], v164 offset:54272
	ds_read_b128 v[226:229], v164 offset:55296
	ds_read_b128 v[230:233], v164 offset:56320
	global_load_lds_dwordx4 v[174:175], off
	s_add_i32 m0, s12, 0x2000
	s_add_u32 s10, s10, 0x40080
	v_lshl_add_u64 v[174:175], v[222:223], 0, s[30:31]
	s_addc_u32 s11, s11, 0
	s_add_i32 s12, s91, s39
	global_load_lds_dwordx4 v[174:175], off
	v_lshl_add_u64 v[174:175], s[10:11], 0, v[130:131]
	s_mov_b32 m0, s12
	s_nop 0
	global_load_lds_dwordx4 v[174:175], off
	v_lshl_add_u64 v[174:175], s[10:11], 0, v[134:135]
	s_add_i32 m0, s12, 0x2000
	s_nop 0
	global_load_lds_dwordx4 v[174:175], off
	v_lshl_add_u64 v[174:175], v[234:235], 0, s[30:31]
	s_mov_b32 m0, s79
	s_nop 0
	global_load_lds_dwordx4 v[174:175], off
	v_lshl_add_u64 v[174:175], v[236:237], 0, s[30:31]
	s_mov_b32 m0, s80
	s_nop 0
	global_load_lds_dwordx4 v[174:175], off
	s_waitcnt vmcnt(8)
	s_waitcnt lgkmcnt(0)
	s_barrier
	s_setprio 1
	s_waitcnt lgkmcnt(0)
	v_mfma_f32_16x16x32_bf16 v[60:63], v[146:149], v[198:201], v[60:63]
	v_mfma_f32_16x16x32_bf16 v[56:59], v[170:173], v[198:201], v[56:59]
	v_mfma_f32_16x16x32_bf16 v[52:55], v[146:149], v[206:209], v[52:55]
	v_mfma_f32_16x16x32_bf16 v[44:47], v[170:173], v[206:209], v[44:47]
	v_mfma_f32_16x16x32_bf16 v[36:39], v[146:149], v[214:217], v[36:39]
	v_mfma_f32_16x16x32_bf16 v[28:31], v[170:173], v[214:217], v[28:31]
	v_mfma_f32_16x16x32_bf16 v[20:23], v[146:149], v[226:229], v[20:23]
	v_mfma_f32_16x16x32_bf16 v[12:15], v[170:173], v[226:229], v[12:15]
	v_mfma_f32_16x16x32_bf16 v[60:63], v[166:169], v[202:205], v[60:63]
	v_mfma_f32_16x16x32_bf16 v[56:59], v[178:181], v[202:205], v[56:59]
	v_mfma_f32_16x16x32_bf16 v[52:55], v[166:169], v[210:213], v[52:55]
	v_mfma_f32_16x16x32_bf16 v[44:47], v[178:181], v[210:213], v[44:47]
	v_mfma_f32_16x16x32_bf16 v[36:39], v[166:169], v[218:221], v[36:39]
	v_mfma_f32_16x16x32_bf16 v[28:31], v[178:181], v[218:221], v[28:31]
	v_mfma_f32_16x16x32_bf16 v[20:23], v[166:169], v[230:233], v[20:23]
	v_mfma_f32_16x16x32_bf16 v[12:15], v[178:181], v[230:233], v[12:15]
	v_mfma_f32_16x16x32_bf16 v[48:51], v[182:185], v[198:201], v[48:51]
	v_mfma_f32_16x16x32_bf16 v[40:43], v[190:193], v[198:201], v[40:43]
	v_mfma_f32_16x16x32_bf16 v[32:35], v[182:185], v[206:209], v[32:35]
	v_mfma_f32_16x16x32_bf16 v[24:27], v[190:193], v[206:209], v[24:27]
	v_mfma_f32_16x16x32_bf16 v[16:19], v[182:185], v[214:217], v[16:19]
	v_mfma_f32_16x16x32_bf16 v[8:11], v[190:193], v[214:217], v[8:11]
	v_mfma_f32_16x16x32_bf16 v[4:7], v[182:185], v[226:229], v[4:7]
	v_mfma_f32_16x16x32_bf16 v[0:3], v[190:193], v[226:229], v[0:3]
	v_mfma_f32_16x16x32_bf16 v[48:51], v[186:189], v[202:205], v[48:51]
	v_mfma_f32_16x16x32_bf16 v[40:43], v[194:197], v[202:205], v[40:43]
	v_mfma_f32_16x16x32_bf16 v[32:35], v[186:189], v[210:213], v[32:35]
	v_mfma_f32_16x16x32_bf16 v[24:27], v[194:197], v[210:213], v[24:27]
	v_mfma_f32_16x16x32_bf16 v[16:19], v[186:189], v[218:221], v[16:19]
	v_mfma_f32_16x16x32_bf16 v[8:11], v[194:197], v[218:221], v[8:11]
	v_mfma_f32_16x16x32_bf16 v[4:7], v[186:189], v[230:233], v[4:7]
	v_mfma_f32_16x16x32_bf16 v[0:3], v[194:197], v[230:233], v[0:3]
	s_setprio 0
	s_barrier
	s_add_i32 s89, s89, 2
	s_add_u32 s8, s8, 0x100
	s_addc_u32 s9, s9, 0
	s_add_u32 s76, s76, 0x100
	s_addc_u32 s77, s77, 0
	s_cmp_gt_u32 s89, 13
	s_cbranch_scc0 .LBB0_546
	s_and_b64 vcc, exec, s[34:35]
	s_cbranch_vccz .LBB0_549
	s_barrier

; #define PG8_STAGE(bufoff, gbase, voff) do { _Pragma("unroll") for (int _i = 0; _i < 2; ++_i) \
;         __builtin_amdgcn_global_load_lds((const unsigned*)((const char*)(gbase) + (voff)[_i]), (LAS unsigned*)(lds + (bufoff) + ldsw + _i * 8192), 16, 0, 0); } while (0)
; #define PG8_LDA(dst, b, h) do { _Pragma("unroll") for (int m = 0; m < 4; ++m) _Pragma("unroll") for (int k = 0; k < 2; ++k) dst[m][k] = *(const LAS bf16x8*)(lds + PG8_SA(b, h) + aoff + m * 2048 + k * 1024); } while (0)
; #define PG8_LDB(dst, b, h) do { _Pragma("unroll") for (int n = 0; n < 2; ++n) _Pragma("unroll") for (int k = 0; k < 2; ++k) dst[n][k] = *(const LAS bf16x8*)(lds + PG8_SB(b, h) + boff + n * 2048 + k * 1024); } while (0)
; #define PG8_MMA(ai, bj, At, Bt) do { __builtin_amdgcn_s_setprio(1); _Pragma("unroll") for (int m = 0; m < 4; ++m) _Pragma("unroll") for (int n = 0; n < 2; ++n) _Pragma("unroll") for (int k = 0; k < 2; ++k) \
;         acc[ai][bj][m][n] = __builtin_amdgcn_mfma_f32_16x16x32_bf16(Bt[n][k], At[m][k], acc[ai][bj][m][n], 0, 0, 0); __builtin_amdgcn_s_setprio(0); } while (0)
; #define PG8_WAIT_V(n) asm volatile("s_waitcnt vmcnt(" #n ")" ::: "memory")
; #define PG8_WAIT_L(n) asm volatile("s_waitcnt lgkmcnt(" #n ")" ::: "memory")
; #define PG8_BAR __builtin_amdgcn_s_barrier()
; #define PG8_SCHED __builtin_amdgcn_sched_barrier(0)
; template <class Epi>
; __device__ __forceinline__ void gemm_phase(LAS unsigned char* lds, const Gemm g, const StaticOrder& S, const Epi& E) {
;     ...
;         for (int t = 0; t < nt; t += 2) {
;             const bool last = (t == nt - 2);
;             const char* a1 = cA + (size_t)(t + 1) * kstep;
;             const char* a2 = last ? nA : cA + (size_t)(t + 2) * kstep; const char* b2 = last ? nB : cB + (size_t)(t + 2) * kstep;
;             const char* a3 = a2 + kstep; const char* b3 = b2 + kstep;
;             PG8_LDB(B0, 0, 0); PG8_LDB(B1, 0, 1); PG8_SCHED; PG8_LDA(At, 0, 0); PG8_STAGE(PG8_SA(1, 1), a1 + hstepA, voffA);
;             PG8_WAIT_V(8); PG8_WAIT_L(0); PG8_BAR; PG8_MMA(0, 0, At, B0); PG8_MMA(0, 1, At, B1); PG8_BAR; PG8_SCHED;
;             PG8_LDA(At, 0, 1); PG8_STAGE(PG8_SB(0, 0), b2, voffB); PG8_STAGE(PG8_SB(0, 1), b2 + hstepB, voffB); PG8_STAGE(PG8_SA(0, 0), a2, voffA);
;             PG8_WAIT_V(8); PG8_WAIT_L(0); PG8_BAR; PG8_MMA(1, 0, At, B0); PG8_MMA(1, 1, At, B1); PG8_BAR; PG8_SCHED;
.LBB0_612:
	s_add_u32 s68, s42, s56
	s_addc_u32 s69, s43, s57
	s_add_u32 s64, s68, 0x100
	s_addc_u32 s65, s69, 0
	s_and_b64 s[62:63], s[54:55], exec
	s_cselect_b32 s63, s1, s65
	s_cselect_b32 s62, s19, s64
	s_add_u32 s56, s38, s56
	s_addc_u32 s57, s39, s57
	s_add_u32 s56, s56, 0x100
	s_addc_u32 s57, s57, 0
	s_and_b64 s[54:55], s[54:55], exec
	s_cselect_b32 s65, s13, s57
	s_cselect_b32 s64, s88, s56
	s_add_u32 s70, s68, 0x10080
	ds_read_b128 v[140:143], v145
	ds_read_b128 v[154:157], v145 offset:1024
	ds_read_b128 v[158:161], v145 offset:2048
	ds_read_b128 v[162:165], v145 offset:3072
	ds_read_b128 v[166:169], v146
	ds_read_b128 v[170:173], v146 offset:1024
	ds_read_b128 v[178:181], v146 offset:2048
	ds_read_b128 v[182:185], v146 offset:3072
	s_addc_u32 s71, s69, 0
	s_add_i32 vcc_lo, s86, s72
	s_add_i32 m0, s35, 0xc000
	s_add_i32 vcc_hi, s35, 0xe000
	s_add_i32 s95, vcc_lo, 0x2000
	s_add_u32 s68, s64, 0x10000
	s_addc_u32 s69, s65, 0
	s_add_i32 s97, s87, s72
	s_add_i32 s96, s97, 0x2000
	s_add_i32 s94, 0, 0x18000
	s_add_i32 s93, 0, 0x1c000
	s_add_u32 s56, s62, 0x10000
	s_addc_u32 s57, s63, 0
	s_add_i32 s92, s94, s72
	s_add_i32 s90, s92, 0x2000
	s_add_u32 s54, s64, 0x10080
	s_addc_u32 s55, s65, 0
	s_add_i32 s91, s93, s72
	s_add_i32 s89, s91, 0x2000
	v_lshl_add_u64 v[174:175], s[70:71], 0, v[128:129]
	ds_read_b128 v[186:189], v147
	ds_read_b128 v[190:193], v147 offset:1024
	ds_read_b128 v[194:197], v147 offset:2048
	ds_read_b128 v[198:201], v147 offset:3072
	ds_read_b128 v[202:205], v147 offset:4096
	ds_read_b128 v[206:209], v147 offset:5120
	ds_read_b128 v[210:213], v147 offset:6144
	ds_read_b128 v[214:217], v147 offset:7168
	global_load_lds_dwordx4 v[174:175], off
	v_lshl_add_u64 v[174:175], s[70:71], 0, v[132:133]
	s_mov_b32 m0, vcc_hi
	s_nop 0
	global_load_lds_dwordx4 v[174:175], off
	s_waitcnt vmcnt(8)
	s_waitcnt lgkmcnt(0)
	s_barrier
	s_setprio 1
	s_waitcnt lgkmcnt(0)
	v_mfma_f32_16x16x32_bf16 v[124:127], v[140:143], v[186:189], v[124:127]
	v_mfma_f32_16x16x32_bf16 v[120:123], v[158:161], v[186:189], v[120:123]
	v_mfma_f32_16x16x32_bf16 v[108:111], v[140:143], v[194:197], v[108:111]
	v_mfma_f32_16x16x32_bf16 v[104:107], v[158:161], v[194:197], v[104:107]
	v_mfma_f32_16x16x32_bf16 v[92:95], v[140:143], v[202:205], v[92:95]
	v_mfma_f32_16x16x32_bf16 v[88:91], v[158:161], v[202:205], v[88:91]
	v_mfma_f32_16x16x32_bf16 v[76:79], v[140:143], v[210:213], v[76:79]
	v_mfma_f32_16x16x32_bf16 v[72:75], v[158:161], v[210:213], v[72:75]
	v_mfma_f32_16x16x32_bf16 v[124:127], v[154:157], v[190:193], v[124:127]
	v_mfma_f32_16x16x32_bf16 v[120:123], v[162:165], v[190:193], v[120:123]
	v_mfma_f32_16x16x32_bf16 v[108:111], v[154:157], v[198:201], v[108:111]
	v_mfma_f32_16x16x32_bf16 v[104:107], v[162:165], v[198:201], v[104:107]
	v_mfma_f32_16x16x32_bf16 v[92:95], v[154:157], v[206:209], v[92:95]
	v_mfma_f32_16x16x32_bf16 v[88:91], v[162:165], v[206:209], v[88:91]
	v_mfma_f32_16x16x32_bf16 v[76:79], v[154:157], v[214:217], v[76:79]
	v_mfma_f32_16x16x32_bf16 v[72:75], v[162:165], v[214:217], v[72:75]
	v_mfma_f32_16x16x32_bf16 v[116:119], v[166:169], v[186:189], v[116:119]
	v_mfma_f32_16x16x32_bf16 v[112:115], v[178:181], v[186:189], v[112:115]
	v_mfma_f32_16x16x32_bf16 v[100:103], v[166:169], v[194:197], v[100:103]
	v_mfma_f32_16x16x32_bf16 v[96:99], v[178:181], v[194:197], v[96:99]
	v_mfma_f32_16x16x32_bf16 v[84:87], v[166:169], v[202:205], v[84:87]
	v_mfma_f32_16x16x32_bf16 v[80:83], v[178:181], v[202:205], v[80:83]
	v_mfma_f32_16x16x32_bf16 v[68:71], v[166:169], v[210:213], v[68:71]
	v_mfma_f32_16x16x32_bf16 v[64:67], v[178:181], v[210:213], v[64:67]
	v_mfma_f32_16x16x32_bf16 v[116:119], v[170:173], v[190:193], v[116:119]
	v_mfma_f32_16x16x32_bf16 v[112:115], v[182:185], v[190:193], v[112:115]
	v_mfma_f32_16x16x32_bf16 v[100:103], v[170:173], v[198:201], v[100:103]
	v_mfma_f32_16x16x32_bf16 v[96:99], v[182:185], v[198:201], v[96:99]
	v_mfma_f32_16x16x32_bf16 v[84:87], v[170:173], v[206:209], v[84:87]
	v_mfma_f32_16x16x32_bf16 v[80:83], v[182:185], v[206:209], v[80:83]
	v_mfma_f32_16x16x32_bf16 v[68:71], v[170:173], v[214:217], v[68:71]
	v_mfma_f32_16x16x32_bf16 v[64:67], v[182:185], v[214:217], v[64:67]
	s_setprio 0
	s_barrier
	s_mov_b32 m0, vcc_lo
	v_lshl_add_u64 v[174:175], s[64:65], 0, v[130:131]
	ds_read_b128 v[186:189], v147 offset:16384
	ds_read_b128 v[190:193], v147 offset:17408
	ds_read_b128 v[194:197], v147 offset:18432
	ds_read_b128 v[198:201], v147 offset:19456
	ds_read_b128 v[202:205], v147 offset:20480
	ds_read_b128 v[206:209], v147 offset:21504
	ds_read_b128 v[210:213], v147 offset:22528
	ds_read_b128 v[214:217], v147 offset:23552
	global_load_lds_dwordx4 v[174:175], off
	v_lshl_add_u64 v[218:219], s[64:65], 0, v[134:135]
	s_mov_b32 m0, s95
	v_lshl_add_u64 v[220:221], s[68:69], 0, v[130:131]
	global_load_lds_dwordx4 v[218:219], off
	s_mov_b32 m0, s97
	v_lshl_add_u64 v[222:223], s[62:63], 0, v[132:133]
	global_load_lds_dwordx4 v[220:221], off
	v_lshl_add_u64 v[220:221], s[68:69], 0, v[134:135]
	s_mov_b32 m0, s96
	s_nop 0
	global_load_lds_dwordx4 v[220:221], off
	v_lshl_add_u64 v[220:221], s[62:63], 0, v[128:129]
	s_mov_b32 m0, s35
	s_nop 0
	global_load_lds_dwordx4 v[220:221], off
	s_mov_b32 m0, s75
	s_nop 0
	global_load_lds_dwordx4 v[222:223], off
	s_waitcnt vmcnt(8)
	s_waitcnt lgkmcnt(0)
	s_barrier
; #define PG8_STAGE(bufoff, gbase, voff) do { _Pragma("unroll") for (int _i = 0; _i < 2; ++_i) \
;         __builtin_amdgcn_global_load_lds((const unsigned*)((const char*)(gbase) + (voff)[_i]), (LAS unsigned*)(lds + (bufoff) + ldsw + _i * 8192), 16, 0, 0); } while (0)
; #define PG8_LDA(dst, b, h) do { _Pragma("unroll") for (int m = 0; m < 4; ++m) _Pragma("unroll") for (int k = 0; k < 2; ++k) dst[m][k] = *(const LAS bf16x8*)(lds + PG8_SA(b, h) + aoff + m * 2048 + k * 1024); } while (0)
; #define PG8_LDB(dst, b, h) do { _Pragma("unroll") for (int n = 0; n < 2; ++n) _Pragma("unroll") for (int k = 0; k < 2; ++k) dst[n][k] = *(const LAS bf16x8*)(lds + PG8_SB(b, h) + boff + n * 2048 + k * 1024); } while (0)
; #define PG8_MMA(ai, bj, At, Bt) do { __builtin_amdgcn_s_setprio(1); _Pragma("unroll") for (int m = 0; m < 4; ++m) _Pragma("unroll") for (int n = 0; n < 2; ++n) _Pragma("unroll") for (int k = 0; k < 2; ++k) \
;         acc[ai][bj][m][n] = __builtin_amdgcn_mfma_f32_16x16x32_bf16(Bt[n][k], At[m][k], acc[ai][bj][m][n], 0, 0, 0); __builtin_amdgcn_s_setprio(0); } while (0)
; #define PG8_WAIT_V(n) asm volatile("s_waitcnt vmcnt(" #n ")" ::: "memory")
; #define PG8_WAIT_L(n) asm volatile("s_waitcnt lgkmcnt(" #n ")" ::: "memory")
; #define PG8_BAR __builtin_amdgcn_s_barrier()
; #define PG8_SCHED __builtin_amdgcn_sched_barrier(0)
; template <class Epi>
; __device__ __forceinline__ void gemm_phase(LAS unsigned char* lds, const Gemm g, const StaticOrder& S, const Epi& E) {
;     ...
;             PG8_WAIT_V(8); PG8_WAIT_L(0); PG8_BAR; PG8_MMA(1, 0, At, B0); PG8_MMA(1, 1, At, B1); PG8_BAR; PG8_SCHED;
;             PG8_LDB(B0, 1, 0); PG8_LDB(B1, 1, 1); PG8_SCHED; PG8_LDA(At, 1, 0); PG8_STAGE(PG8_SA(0, 1), a2 + hstepA, voffA);
;             PG8_WAIT_V(8); PG8_WAIT_L(0); PG8_BAR; PG8_MMA(0, 0, At, B0); PG8_MMA(0, 1, At, B1); PG8_BAR; PG8_SCHED;
	s_setprio 1
	s_waitcnt lgkmcnt(0)
	v_mfma_f32_16x16x32_bf16 v[60:63], v[140:143], v[186:189], v[60:63]
	v_mfma_f32_16x16x32_bf16 v[56:59], v[158:161], v[186:189], v[56:59]
	v_mfma_f32_16x16x32_bf16 v[44:47], v[140:143], v[194:197], v[44:47]
	v_mfma_f32_16x16x32_bf16 v[40:43], v[158:161], v[194:197], v[40:43]
	v_mfma_f32_16x16x32_bf16 v[28:31], v[140:143], v[202:205], v[28:31]
	v_mfma_f32_16x16x32_bf16 v[24:27], v[158:161], v[202:205], v[24:27]
	v_mfma_f32_16x16x32_bf16 v[12:15], v[140:143], v[210:213], v[12:15]
	v_mfma_f32_16x16x32_bf16 v[8:11], v[158:161], v[210:213], v[8:11]
	v_mfma_f32_16x16x32_bf16 v[60:63], v[154:157], v[190:193], v[60:63]
	v_mfma_f32_16x16x32_bf16 v[56:59], v[162:165], v[190:193], v[56:59]
	v_mfma_f32_16x16x32_bf16 v[44:47], v[154:157], v[198:201], v[44:47]
	v_mfma_f32_16x16x32_bf16 v[40:43], v[162:165], v[198:201], v[40:43]
	v_mfma_f32_16x16x32_bf16 v[28:31], v[154:157], v[206:209], v[28:31]
	v_mfma_f32_16x16x32_bf16 v[24:27], v[162:165], v[206:209], v[24:27]
	v_mfma_f32_16x16x32_bf16 v[12:15], v[154:157], v[214:217], v[12:15]
	v_mfma_f32_16x16x32_bf16 v[8:11], v[162:165], v[214:217], v[8:11]
	v_mfma_f32_16x16x32_bf16 v[52:55], v[166:169], v[186:189], v[52:55]
	v_mfma_f32_16x16x32_bf16 v[48:51], v[178:181], v[186:189], v[48:51]
	v_mfma_f32_16x16x32_bf16 v[36:39], v[166:169], v[194:197], v[36:39]
	v_mfma_f32_16x16x32_bf16 v[32:35], v[178:181], v[194:197], v[32:35]
	v_mfma_f32_16x16x32_bf16 v[20:23], v[166:169], v[202:205], v[20:23]
	v_mfma_f32_16x16x32_bf16 v[16:19], v[178:181], v[202:205], v[16:19]
	v_mfma_f32_16x16x32_bf16 v[4:7], v[166:169], v[210:213], v[4:7]
	v_mfma_f32_16x16x32_bf16 v[0:3], v[178:181], v[210:213], v[0:3]
	v_mfma_f32_16x16x32_bf16 v[52:55], v[170:173], v[190:193], v[52:55]
	v_mfma_f32_16x16x32_bf16 v[48:51], v[182:185], v[190:193], v[48:51]
	v_mfma_f32_16x16x32_bf16 v[36:39], v[170:173], v[198:201], v[36:39]
	v_mfma_f32_16x16x32_bf16 v[32:35], v[182:185], v[198:201], v[32:35]
	v_mfma_f32_16x16x32_bf16 v[20:23], v[170:173], v[206:209], v[20:23]
	v_mfma_f32_16x16x32_bf16 v[16:19], v[182:185], v[206:209], v[16:19]
	v_mfma_f32_16x16x32_bf16 v[4:7], v[170:173], v[214:217], v[4:7]
	v_mfma_f32_16x16x32_bf16 v[0:3], v[182:185], v[214:217], v[0:3]
	s_setprio 0
	s_barrier
	v_add_u32_e32 v149, s94, v144
	ds_read_b128 v[140:143], v149
	ds_read_b128 v[154:157], v149 offset:1024
	ds_read_b128 v[158:161], v149 offset:2048
	ds_read_b128 v[162:165], v149 offset:3072
	v_add_u32_e32 v149, s93, v144
	ds_read_b128 v[166:169], v149
	ds_read_b128 v[170:173], v149 offset:1024
	ds_read_b128 v[178:181], v149 offset:2048
	ds_read_b128 v[182:185], v149 offset:3072
	s_mov_b32 m0, s76
	v_lshl_add_u64 v[226:227], s[56:57], 0, v[128:129]
	ds_read_b128 v[186:189], v147 offset:32768
	ds_read_b128 v[190:193], v147 offset:33792
	ds_read_b128 v[194:197], v147 offset:34816
	ds_read_b128 v[198:201], v147 offset:35840
	ds_read_b128 v[202:205], v147 offset:36864
	ds_read_b128 v[206:209], v147 offset:37888
	ds_read_b128 v[210:213], v147 offset:38912
	ds_read_b128 v[214:217], v147 offset:39936
	global_load_lds_dwordx4 v[226:227], off
	v_lshl_add_u64 v[226:227], s[56:57], 0, v[132:133]
	s_mov_b32 m0, s77
	s_nop 0
	global_load_lds_dwordx4 v[226:227], off
	s_waitcnt vmcnt(8)
	s_waitcnt lgkmcnt(0)
	s_barrier
	s_setprio 1
	s_waitcnt lgkmcnt(0)
	v_mfma_f32_16x16x32_bf16 v[124:127], v[140:143], v[186:189], v[124:127]
	v_mfma_f32_16x16x32_bf16 v[120:123], v[158:161], v[186:189], v[120:123]
	v_mfma_f32_16x16x32_bf16 v[108:111], v[140:143], v[194:197], v[108:111]
	v_mfma_f32_16x16x32_bf16 v[104:107], v[158:161], v[194:197], v[104:107]
	v_mfma_f32_16x16x32_bf16 v[92:95], v[140:143], v[202:205], v[92:95]
	v_mfma_f32_16x16x32_bf16 v[88:91], v[158:161], v[202:205], v[88:91]
	v_mfma_f32_16x16x32_bf16 v[76:79], v[140:143], v[210:213], v[76:79]
	v_mfma_f32_16x16x32_bf16 v[72:75], v[158:161], v[210:213], v[72:75]
	v_mfma_f32_16x16x32_bf16 v[124:127], v[154:157], v[190:193], v[124:127]
	v_mfma_f32_16x16x32_bf16 v[120:123], v[162:165], v[190:193], v[120:123]
	v_mfma_f32_16x16x32_bf16 v[108:111], v[154:157], v[198:201], v[108:111]
	v_mfma_f32_16x16x32_bf16 v[104:107], v[162:165], v[198:201], v[104:107]
	v_mfma_f32_16x16x32_bf16 v[92:95], v[154:157], v[206:209], v[92:95]
	v_mfma_f32_16x16x32_bf16 v[88:91], v[162:165], v[206:209], v[88:91]
	v_mfma_f32_16x16x32_bf16 v[76:79], v[154:157], v[214:217], v[76:79]
	v_mfma_f32_16x16x32_bf16 v[72:75], v[162:165], v[214:217], v[72:75]
	v_mfma_f32_16x16x32_bf16 v[116:119], v[166:169], v[186:189], v[116:119]
	v_mfma_f32_16x16x32_bf16 v[112:115], v[178:181], v[186:189], v[112:115]
	v_mfma_f32_16x16x32_bf16 v[100:103], v[166:169], v[194:197], v[100:103]
	v_mfma_f32_16x16x32_bf16 v[96:99], v[178:181], v[194:197], v[96:99]
	v_mfma_f32_16x16x32_bf16 v[84:87], v[166:169], v[202:205], v[84:87]
	v_mfma_f32_16x16x32_bf16 v[80:83], v[178:181], v[202:205], v[80:83]
	v_mfma_f32_16x16x32_bf16 v[68:71], v[166:169], v[210:213], v[68:71]
	v_mfma_f32_16x16x32_bf16 v[64:67], v[178:181], v[210:213], v[64:67]
	v_mfma_f32_16x16x32_bf16 v[116:119], v[170:173], v[190:193], v[116:119]
	v_mfma_f32_16x16x32_bf16 v[112:115], v[182:185], v[190:193], v[112:115]
	v_mfma_f32_16x16x32_bf16 v[100:103], v[170:173], v[198:201], v[100:103]
	v_mfma_f32_16x16x32_bf16 v[96:99], v[182:185], v[198:201], v[96:99]
	v_mfma_f32_16x16x32_bf16 v[84:87], v[170:173], v[206:209], v[84:87]
	v_mfma_f32_16x16x32_bf16 v[80:83], v[182:185], v[206:209], v[80:83]
	v_mfma_f32_16x16x32_bf16 v[68:71], v[170:173], v[214:217], v[68:71]
	v_mfma_f32_16x16x32_bf16 v[64:67], v[182:185], v[214:217], v[64:67]
	s_setprio 0
	s_barrier
; #define PG8_STAGE(bufoff, gbase, voff) do { _Pragma("unroll") for (int _i = 0; _i < 2; ++_i) \
;         __builtin_amdgcn_global_load_lds((const unsigned*)((const char*)(gbase) + (voff)[_i]), (LAS unsigned*)(lds + (bufoff) + ldsw + _i * 8192), 16, 0, 0); } while (0)
; #define PG8_LDA(dst, b, h) do { _Pragma("unroll") for (int m = 0; m < 4; ++m) _Pragma("unroll") for (int k = 0; k < 2; ++k) dst[m][k] = *(const LAS bf16x8*)(lds + PG8_SA(b, h) + aoff + m * 2048 + k * 1024); } while (0)
; #define PG8_MMA(ai, bj, At, Bt) do { __builtin_amdgcn_s_setprio(1); _Pragma("unroll") for (int m = 0; m < 4; ++m) _Pragma("unroll") for (int n = 0; n < 2; ++n) _Pragma("unroll") for (int k = 0; k < 2; ++k) \
;         acc[ai][bj][m][n] = __builtin_amdgcn_mfma_f32_16x16x32_bf16(Bt[n][k], At[m][k], acc[ai][bj][m][n], 0, 0, 0); __builtin_amdgcn_s_setprio(0); } while (0)
; #define PG8_WAIT_V(n) asm volatile("s_waitcnt vmcnt(" #n ")" ::: "memory")
; #define PG8_WAIT_L(n) asm volatile("s_waitcnt lgkmcnt(" #n ")" ::: "memory")
; #define PG8_BAR __builtin_amdgcn_s_barrier()
; #define PG8_SCHED __builtin_amdgcn_sched_barrier(0)
; template <class Epi>
; __device__ __forceinline__ void gemm_phase(LAS unsigned char* lds, const Gemm g, const StaticOrder& S, const Epi& E) {
;     ...
;             PG8_LDA(At, 1, 1); PG8_STAGE(PG8_SB(1, 0), b3, voffB); PG8_STAGE(PG8_SB(1, 1), b3 + hstepB, voffB); PG8_STAGE(PG8_SA(1, 0), a3, voffA);
;             PG8_WAIT_V(8); PG8_WAIT_L(0); PG8_BAR; PG8_MMA(1, 0, At, B0); PG8_MMA(1, 1, At, B1); PG8_BAR; PG8_SCHED;
;         }
;         if (wr == 0) PG8_BAR;
	s_mov_b32 m0, s92
	v_lshl_add_u64 v[174:175], v[174:175], 0, s[8:9]
	ds_read_b128 v[186:189], v147 offset:49152
	ds_read_b128 v[190:193], v147 offset:50176
	ds_read_b128 v[194:197], v147 offset:51200
	ds_read_b128 v[198:201], v147 offset:52224
	ds_read_b128 v[202:205], v147 offset:53248
	ds_read_b128 v[206:209], v147 offset:54272
	ds_read_b128 v[210:213], v147 offset:55296
	ds_read_b128 v[214:217], v147 offset:56320
	global_load_lds_dwordx4 v[174:175], off
	v_lshl_add_u64 v[174:175], v[218:219], 0, s[8:9]
	s_mov_b32 m0, s90
	s_nop 0
	global_load_lds_dwordx4 v[174:175], off
	v_lshl_add_u64 v[174:175], s[54:55], 0, v[130:131]
	s_mov_b32 m0, s91
	s_nop 0
	global_load_lds_dwordx4 v[174:175], off
	v_lshl_add_u64 v[174:175], s[54:55], 0, v[134:135]
	s_mov_b32 m0, s89
	s_nop 0
	global_load_lds_dwordx4 v[174:175], off
	v_lshl_add_u64 v[174:175], v[220:221], 0, s[8:9]
	s_mov_b32 m0, s81
	s_nop 0
	global_load_lds_dwordx4 v[174:175], off
	v_lshl_add_u64 v[174:175], v[222:223], 0, s[8:9]
	s_mov_b32 m0, s82
	s_nop 0
	global_load_lds_dwordx4 v[174:175], off
	s_waitcnt vmcnt(8)
	s_waitcnt lgkmcnt(0)
	s_barrier
	s_setprio 1
	s_waitcnt lgkmcnt(0)
	v_mfma_f32_16x16x32_bf16 v[60:63], v[140:143], v[186:189], v[60:63]
	v_mfma_f32_16x16x32_bf16 v[56:59], v[158:161], v[186:189], v[56:59]
	v_mfma_f32_16x16x32_bf16 v[44:47], v[140:143], v[194:197], v[44:47]
	v_mfma_f32_16x16x32_bf16 v[40:43], v[158:161], v[194:197], v[40:43]
	v_mfma_f32_16x16x32_bf16 v[28:31], v[140:143], v[202:205], v[28:31]
	v_mfma_f32_16x16x32_bf16 v[24:27], v[158:161], v[202:205], v[24:27]
	v_mfma_f32_16x16x32_bf16 v[12:15], v[140:143], v[210:213], v[12:15]
	v_mfma_f32_16x16x32_bf16 v[8:11], v[158:161], v[210:213], v[8:11]
	v_mfma_f32_16x16x32_bf16 v[60:63], v[154:157], v[190:193], v[60:63]
	v_mfma_f32_16x16x32_bf16 v[56:59], v[162:165], v[190:193], v[56:59]
	v_mfma_f32_16x16x32_bf16 v[44:47], v[154:157], v[198:201], v[44:47]
	v_mfma_f32_16x16x32_bf16 v[40:43], v[162:165], v[198:201], v[40:43]
	v_mfma_f32_16x16x32_bf16 v[28:31], v[154:157], v[206:209], v[28:31]
	v_mfma_f32_16x16x32_bf16 v[24:27], v[162:165], v[206:209], v[24:27]
	v_mfma_f32_16x16x32_bf16 v[12:15], v[154:157], v[214:217], v[12:15]
	v_mfma_f32_16x16x32_bf16 v[8:11], v[162:165], v[214:217], v[8:11]
	v_mfma_f32_16x16x32_bf16 v[52:55], v[166:169], v[186:189], v[52:55]
	v_mfma_f32_16x16x32_bf16 v[48:51], v[178:181], v[186:189], v[48:51]
	v_mfma_f32_16x16x32_bf16 v[36:39], v[166:169], v[194:197], v[36:39]
	v_mfma_f32_16x16x32_bf16 v[32:35], v[178:181], v[194:197], v[32:35]
	v_mfma_f32_16x16x32_bf16 v[20:23], v[166:169], v[202:205], v[20:23]
	v_mfma_f32_16x16x32_bf16 v[16:19], v[178:181], v[202:205], v[16:19]
	v_mfma_f32_16x16x32_bf16 v[4:7], v[166:169], v[210:213], v[4:7]
	v_mfma_f32_16x16x32_bf16 v[0:3], v[178:181], v[210:213], v[0:3]
	v_mfma_f32_16x16x32_bf16 v[52:55], v[170:173], v[190:193], v[52:55]
	v_mfma_f32_16x16x32_bf16 v[48:51], v[182:185], v[190:193], v[48:51]
	v_mfma_f32_16x16x32_bf16 v[36:39], v[170:173], v[198:201], v[36:39]
	v_mfma_f32_16x16x32_bf16 v[32:35], v[182:185], v[198:201], v[32:35]
	v_mfma_f32_16x16x32_bf16 v[20:23], v[170:173], v[206:209], v[20:23]
	v_mfma_f32_16x16x32_bf16 v[16:19], v[182:185], v[206:209], v[16:19]
	v_mfma_f32_16x16x32_bf16 v[4:7], v[170:173], v[214:217], v[4:7]
	v_mfma_f32_16x16x32_bf16 v[0:3], v[182:185], v[214:217], v[0:3]
	s_setprio 0
	s_barrier
	s_andn2_b64 vcc, exec, s[52:53]
	s_mov_b64 s[54:55], -1
	s_mov_b64 s[52:53], 0
	s_mov_b64 s[56:57], 0x100
	s_cbranch_vccz .LBB0_612
	s_and_b64 vcc, exec, s[10:11]
	s_cbranch_vccz .LBB0_615
	s_barrier

; #define PG8_STAGE(bufoff, gbase, voff) do { _Pragma("unroll") for (int _i = 0; _i < 2; ++_i) \
;         __builtin_amdgcn_global_load_lds((const unsigned*)((const char*)(gbase) + (voff)[_i]), (LAS unsigned*)(lds + (bufoff) + ldsw + _i * 8192), 16, 0, 0); } while (0)
; #define PG8_LDA(dst, b, h) do { _Pragma("unroll") for (int m = 0; m < 4; ++m) _Pragma("unroll") for (int k = 0; k < 2; ++k) dst[m][k] = *(const LAS bf16x8*)(lds + PG8_SA(b, h) + aoff + m * 2048 + k * 1024); } while (0)
; #define PG8_LDB(dst, b, h) do { _Pragma("unroll") for (int n = 0; n < 2; ++n) _Pragma("unroll") for (int k = 0; k < 2; ++k) dst[n][k] = *(const LAS bf16x8*)(lds + PG8_SB(b, h) + boff + n * 2048 + k * 1024); } while (0)
; #define PG8_MMA(ai, bj, At, Bt) do { __builtin_amdgcn_s_setprio(1); _Pragma("unroll") for (int m = 0; m < 4; ++m) _Pragma("unroll") for (int n = 0; n < 2; ++n) _Pragma("unroll") for (int k = 0; k < 2; ++k) \
;         acc[ai][bj][m][n] = __builtin_amdgcn_mfma_f32_16x16x32_bf16(Bt[n][k], At[m][k], acc[ai][bj][m][n], 0, 0, 0); __builtin_amdgcn_s_setprio(0); } while (0)
; #define PG8_BAR __builtin_amdgcn_s_barrier()
; template <class Epi>
; __device__ __forceinline__ void gemm_phase(LAS unsigned char* lds, const Gemm g, const StaticOrder& S, const Epi& E) {
;     ...
;         const bool has_next = S.next(ui + 1, nxt);
;         const char* nA = has_next ? (const char*)g.A + (size_t)nxt.pm * tstepA : cA; const char* nB = has_next ? (const char*)g.Bt + (size_t)nxt.pn * tstepB : cB;
; #pragma nounroll
;         for (int t = 0; t < nt; t += 2) {
;             const bool last = (t == nt - 2);
;             const char* a1 = cA + (size_t)(t + 1) * kstep;
;             const char* a2 = last ? nA : cA + (size_t)(t + 2) * kstep; const char* b2 = last ? nB : cB + (size_t)(t + 2) * kstep;
;             const char* a3 = a2 + kstep; const char* b3 = b2 + kstep;
;             PG8_LDB(B0, 0, 0); PG8_LDB(B1, 0, 1); PG8_SCHED; PG8_LDA(At, 0, 0); PG8_STAGE(PG8_SA(1, 1), a1 + hstepA, voffA);
;             PG8_WAIT_V(8); PG8_WAIT_L(0); PG8_BAR; PG8_MMA(0, 0, At, B0); PG8_MMA(0, 1, At, B1); PG8_BAR; PG8_SCHED;
;             PG8_LDA(At, 0, 1); PG8_STAGE(PG8_SB(0, 0), b2, voffB); PG8_STAGE(PG8_SB(0, 1), b2 + hstepB, voffB); PG8_STAGE(PG8_SA(0, 0), a2, voffA);
;             PG8_WAIT_V(8); PG8_WAIT_L(0); PG8_BAR; PG8_MMA(1, 0, At, B0); PG8_MMA(1, 1, At, B1); PG8_BAR; PG8_SCHED;
.LBB0_791:
	s_add_u32 s0, s0, 0xb0080
	s_addc_u32 s1, s1, 0
	s_add_u32 s75, s34, 0x100
	s_addc_u32 s76, s35, 0
	s_mov_b32 s77, -2
	s_waitcnt lgkmcnt(0)
	s_nop 0
	ds_read_b128 v[128:131], v182
	ds_read_b128 v[132:135], v182 offset:1024
	ds_read_b128 v[136:139], v182 offset:2048
	ds_read_b128 v[140:143], v182 offset:3072
	ds_read_b128 v[160:163], v183
	ds_read_b128 v[164:167], v183 offset:1024
	ds_read_b128 v[168:171], v183 offset:2048
	ds_read_b128 v[172:175], v183 offset:3072
	s_add_u32 s34, s0, 0xfff50080
	s_addc_u32 s35, s1, -1
	s_cmp_eq_u32 s77, 40
	s_cselect_b32 s39, s7, s35
	s_cselect_b32 s38, s6, s34
	s_cselect_b32 s35, s23, s76
	s_cselect_b32 s34, s22, s75
	v_lshl_add_u64 v[178:179], s[0:1], 0, v[152:153]
	s_add_i32 m0, s43, 0xc000
	ds_read_b128 v[186:189], v184
	ds_read_b128 v[190:193], v184 offset:1024
	ds_read_b128 v[194:197], v184 offset:2048
	ds_read_b128 v[198:201], v184 offset:3072
	ds_read_b128 v[202:205], v184 offset:4096
	ds_read_b128 v[206:209], v184 offset:5120
	ds_read_b128 v[210:213], v184 offset:6144
	ds_read_b128 v[214:217], v184 offset:7168
	global_load_lds_dwordx4 v[178:179], off
	v_lshl_add_u64 v[178:179], s[0:1], 0, v[154:155]
	s_add_i32 m0, s43, 0xe000
	s_nop 0
	global_load_lds_dwordx4 v[178:179], off
	s_waitcnt vmcnt(8)
	s_waitcnt lgkmcnt(0)
	s_barrier
	s_setprio 1
	s_waitcnt lgkmcnt(0)
	v_mfma_f32_16x16x32_bf16 v[124:127], v[128:131], v[186:189], 0
	v_mfma_f32_16x16x32_bf16 v[120:123], v[136:139], v[186:189], 0
	v_mfma_f32_16x16x32_bf16 v[108:111], v[128:131], v[194:197], 0
	v_mfma_f32_16x16x32_bf16 v[104:107], v[136:139], v[194:197], 0
	v_mfma_f32_16x16x32_bf16 v[92:95], v[128:131], v[202:205], 0
	v_mfma_f32_16x16x32_bf16 v[88:91], v[136:139], v[202:205], 0
	v_mfma_f32_16x16x32_bf16 v[76:79], v[128:131], v[210:213], 0
	v_mfma_f32_16x16x32_bf16 v[72:75], v[136:139], v[210:213], 0
	v_mfma_f32_16x16x32_bf16 v[124:127], v[132:135], v[190:193], v[124:127]
	v_mfma_f32_16x16x32_bf16 v[120:123], v[140:143], v[190:193], v[120:123]
	v_mfma_f32_16x16x32_bf16 v[108:111], v[132:135], v[198:201], v[108:111]
	v_mfma_f32_16x16x32_bf16 v[104:107], v[140:143], v[198:201], v[104:107]
	v_mfma_f32_16x16x32_bf16 v[92:95], v[132:135], v[206:209], v[92:95]
	v_mfma_f32_16x16x32_bf16 v[88:91], v[140:143], v[206:209], v[88:91]
	v_mfma_f32_16x16x32_bf16 v[76:79], v[132:135], v[214:217], v[76:79]
	v_mfma_f32_16x16x32_bf16 v[72:75], v[140:143], v[214:217], v[72:75]
	v_mfma_f32_16x16x32_bf16 v[116:119], v[160:163], v[186:189], 0
	v_mfma_f32_16x16x32_bf16 v[112:115], v[168:171], v[186:189], 0
	v_mfma_f32_16x16x32_bf16 v[100:103], v[160:163], v[194:197], 0
	v_mfma_f32_16x16x32_bf16 v[96:99], v[168:171], v[194:197], 0
	v_mfma_f32_16x16x32_bf16 v[84:87], v[160:163], v[202:205], 0
	v_mfma_f32_16x16x32_bf16 v[80:83], v[168:171], v[202:205], 0
	v_mfma_f32_16x16x32_bf16 v[68:71], v[160:163], v[210:213], 0
	v_mfma_f32_16x16x32_bf16 v[64:67], v[168:171], v[210:213], 0
	v_mfma_f32_16x16x32_bf16 v[116:119], v[164:167], v[190:193], v[116:119]
	v_mfma_f32_16x16x32_bf16 v[112:115], v[172:175], v[190:193], v[112:115]
	v_mfma_f32_16x16x32_bf16 v[100:103], v[164:167], v[198:201], v[100:103]
	v_mfma_f32_16x16x32_bf16 v[96:99], v[172:175], v[198:201], v[96:99]
	v_mfma_f32_16x16x32_bf16 v[84:87], v[164:167], v[206:209], v[84:87]
	v_mfma_f32_16x16x32_bf16 v[80:83], v[172:175], v[206:209], v[80:83]
	v_mfma_f32_16x16x32_bf16 v[68:71], v[164:167], v[214:217], v[68:71]
	v_mfma_f32_16x16x32_bf16 v[64:67], v[172:175], v[214:217], v[64:67]
	s_setprio 0
	s_barrier
	s_add_i32 s78, s69, s42
	v_lshl_add_u64 v[178:179], s[34:35], 0, v[146:147]
	s_mov_b32 m0, s78
	ds_read_b128 v[186:189], v184 offset:16384
	ds_read_b128 v[190:193], v184 offset:17408
	ds_read_b128 v[194:197], v184 offset:18432
	ds_read_b128 v[198:201], v184 offset:19456
	ds_read_b128 v[202:205], v184 offset:20480
	ds_read_b128 v[206:209], v184 offset:21504
	ds_read_b128 v[210:213], v184 offset:22528
	ds_read_b128 v[214:217], v184 offset:23552
	global_load_lds_dwordx4 v[178:179], off
	s_add_i32 m0, s78, 0x2000
	s_add_u32 s78, s34, 0xb0000
	v_lshl_add_u64 v[218:219], s[34:35], 0, v[150:151]
	s_addc_u32 s79, s35, 0
	s_add_i32 s80, s70, s42
	global_load_lds_dwordx4 v[218:219], off
	v_lshl_add_u64 v[220:221], s[78:79], 0, v[146:147]
	s_mov_b32 m0, s80
	v_lshl_add_u64 v[222:223], s[38:39], 0, v[148:149]
	global_load_lds_dwordx4 v[220:221], off
	v_lshl_add_u64 v[220:221], s[78:79], 0, v[150:151]
	s_add_i32 m0, s80, 0x2000
	s_nop 0
	global_load_lds_dwordx4 v[220:221], off
	v_lshl_add_u64 v[220:221], s[38:39], 0, v[144:145]
	s_mov_b32 m0, s43
	s_nop 0
	global_load_lds_dwordx4 v[220:221], off
	s_mov_b32 m0, s52
	s_nop 0
	global_load_lds_dwordx4 v[222:223], off
	s_waitcnt vmcnt(8)
	s_waitcnt lgkmcnt(0)
	s_barrier
; #define PG8_STAGE(bufoff, gbase, voff) do { _Pragma("unroll") for (int _i = 0; _i < 2; ++_i) \
;         __builtin_amdgcn_global_load_lds((const unsigned*)((const char*)(gbase) + (voff)[_i]), (LAS unsigned*)(lds + (bufoff) + ldsw + _i * 8192), 16, 0, 0); } while (0)
; #define PG8_LDA(dst, b, h) do { _Pragma("unroll") for (int m = 0; m < 4; ++m) _Pragma("unroll") for (int k = 0; k < 2; ++k) dst[m][k] = *(const LAS bf16x8*)(lds + PG8_SA(b, h) + aoff + m * 2048 + k * 1024); } while (0)
; #define PG8_LDB(dst, b, h) do { _Pragma("unroll") for (int n = 0; n < 2; ++n) _Pragma("unroll") for (int k = 0; k < 2; ++k) dst[n][k] = *(const LAS bf16x8*)(lds + PG8_SB(b, h) + boff + n * 2048 + k * 1024); } while (0)
; #define PG8_MMA(ai, bj, At, Bt) do { __builtin_amdgcn_s_setprio(1); _Pragma("unroll") for (int m = 0; m < 4; ++m) _Pragma("unroll") for (int n = 0; n < 2; ++n) _Pragma("unroll") for (int k = 0; k < 2; ++k) \
;         acc[ai][bj][m][n] = __builtin_amdgcn_mfma_f32_16x16x32_bf16(Bt[n][k], At[m][k], acc[ai][bj][m][n], 0, 0, 0); __builtin_amdgcn_s_setprio(0); } while (0)
; #define PG8_WAIT_V(n) asm volatile("s_waitcnt vmcnt(" #n ")" ::: "memory")
; #define PG8_WAIT_L(n) asm volatile("s_waitcnt lgkmcnt(" #n ")" ::: "memory")
; #define PG8_BAR __builtin_amdgcn_s_barrier()
; #define PG8_SCHED __builtin_amdgcn_sched_barrier(0)
; template <class Epi>
; __device__ __forceinline__ void gemm_phase(LAS unsigned char* lds, const Gemm g, const StaticOrder& S, const Epi& E) {
;     ...
;             PG8_WAIT_V(8); PG8_WAIT_L(0); PG8_BAR; PG8_MMA(1, 0, At, B0); PG8_MMA(1, 1, At, B1); PG8_BAR; PG8_SCHED;
;             PG8_LDB(B0, 1, 0); PG8_LDB(B1, 1, 1); PG8_SCHED; PG8_LDA(At, 1, 0); PG8_STAGE(PG8_SA(0, 1), a2 + hstepA, voffA);
;             PG8_WAIT_V(8); PG8_WAIT_L(0); PG8_BAR; PG8_MMA(0, 0, At, B0); PG8_MMA(0, 1, At, B1); PG8_BAR; PG8_SCHED;
	s_setprio 1
	s_waitcnt lgkmcnt(0)
	v_mfma_f32_16x16x32_bf16 v[60:63], v[128:131], v[186:189], 0
	v_mfma_f32_16x16x32_bf16 v[56:59], v[136:139], v[186:189], 0
	v_mfma_f32_16x16x32_bf16 v[44:47], v[128:131], v[194:197], 0
	v_mfma_f32_16x16x32_bf16 v[40:43], v[136:139], v[194:197], 0
	v_mfma_f32_16x16x32_bf16 v[28:31], v[128:131], v[202:205], 0
	v_mfma_f32_16x16x32_bf16 v[24:27], v[136:139], v[202:205], 0
	v_mfma_f32_16x16x32_bf16 v[12:15], v[128:131], v[210:213], 0
	v_mfma_f32_16x16x32_bf16 v[8:11], v[136:139], v[210:213], 0
	v_mfma_f32_16x16x32_bf16 v[60:63], v[132:135], v[190:193], v[60:63]
	v_mfma_f32_16x16x32_bf16 v[56:59], v[140:143], v[190:193], v[56:59]
	v_mfma_f32_16x16x32_bf16 v[44:47], v[132:135], v[198:201], v[44:47]
	v_mfma_f32_16x16x32_bf16 v[40:43], v[140:143], v[198:201], v[40:43]
	v_mfma_f32_16x16x32_bf16 v[28:31], v[132:135], v[206:209], v[28:31]
	v_mfma_f32_16x16x32_bf16 v[24:27], v[140:143], v[206:209], v[24:27]
	v_mfma_f32_16x16x32_bf16 v[12:15], v[132:135], v[214:217], v[12:15]
	v_mfma_f32_16x16x32_bf16 v[8:11], v[140:143], v[214:217], v[8:11]
	v_mfma_f32_16x16x32_bf16 v[52:55], v[160:163], v[186:189], 0
	v_mfma_f32_16x16x32_bf16 v[48:51], v[168:171], v[186:189], 0
	v_mfma_f32_16x16x32_bf16 v[36:39], v[160:163], v[194:197], 0
	v_mfma_f32_16x16x32_bf16 v[32:35], v[168:171], v[194:197], 0
	v_mfma_f32_16x16x32_bf16 v[20:23], v[160:163], v[202:205], 0
	v_mfma_f32_16x16x32_bf16 v[16:19], v[168:171], v[202:205], 0
	v_mfma_f32_16x16x32_bf16 v[4:7], v[160:163], v[210:213], 0
	v_mfma_f32_16x16x32_bf16 v[0:3], v[168:171], v[210:213], 0
	v_mfma_f32_16x16x32_bf16 v[52:55], v[164:167], v[190:193], v[52:55]
	v_mfma_f32_16x16x32_bf16 v[48:51], v[172:175], v[190:193], v[48:51]
	v_mfma_f32_16x16x32_bf16 v[36:39], v[164:167], v[198:201], v[36:39]
	v_mfma_f32_16x16x32_bf16 v[32:35], v[172:175], v[198:201], v[32:35]
	v_mfma_f32_16x16x32_bf16 v[20:23], v[164:167], v[206:209], v[20:23]
	v_mfma_f32_16x16x32_bf16 v[16:19], v[172:175], v[206:209], v[16:19]
	v_mfma_f32_16x16x32_bf16 v[4:7], v[164:167], v[214:217], v[4:7]
	v_mfma_f32_16x16x32_bf16 v[0:3], v[172:175], v[214:217], v[0:3]
	s_setprio 0
	s_barrier
	s_add_i32 s78, 0, 0x18000
	s_add_i32 s79, 0, 0x1c000
	v_add_u32_e32 v140, s78, v181
	v_add_u32_e32 v172, s79, v181
	ds_read_b128 v[128:131], v140
	ds_read_b128 v[132:135], v140 offset:1024
	ds_read_b128 v[136:139], v140 offset:2048
	ds_read_b128 v[140:143], v140 offset:3072
	ds_read_b128 v[160:163], v172
	ds_read_b128 v[164:167], v172 offset:1024
	ds_read_b128 v[168:171], v172 offset:2048
	ds_read_b128 v[172:175], v172 offset:3072
	s_add_u32 s38, s38, 0xb0000
	s_addc_u32 s39, s39, 0
	s_mov_b32 m0, s53
	v_lshl_add_u64 v[226:227], s[38:39], 0, v[144:145]
	ds_read_b128 v[186:189], v184 offset:32768
	ds_read_b128 v[190:193], v184 offset:33792
	ds_read_b128 v[194:197], v184 offset:34816
	ds_read_b128 v[198:201], v184 offset:35840
	ds_read_b128 v[202:205], v184 offset:36864
	ds_read_b128 v[206:209], v184 offset:37888
	ds_read_b128 v[210:213], v184 offset:38912
	ds_read_b128 v[214:217], v184 offset:39936
	global_load_lds_dwordx4 v[226:227], off
	v_lshl_add_u64 v[226:227], s[38:39], 0, v[148:149]
	s_mov_b32 m0, s54
	s_nop 0
	global_load_lds_dwordx4 v[226:227], off
	s_waitcnt vmcnt(8)
	s_waitcnt lgkmcnt(0)
	s_barrier
	s_setprio 1
	s_waitcnt lgkmcnt(0)
	v_mfma_f32_16x16x32_bf16 v[124:127], v[128:131], v[186:189], v[124:127]
	v_mfma_f32_16x16x32_bf16 v[120:123], v[136:139], v[186:189], v[120:123]
	v_mfma_f32_16x16x32_bf16 v[108:111], v[128:131], v[194:197], v[108:111]
	v_mfma_f32_16x16x32_bf16 v[104:107], v[136:139], v[194:197], v[104:107]
	v_mfma_f32_16x16x32_bf16 v[92:95], v[128:131], v[202:205], v[92:95]
	v_mfma_f32_16x16x32_bf16 v[88:91], v[136:139], v[202:205], v[88:91]
	v_mfma_f32_16x16x32_bf16 v[76:79], v[128:131], v[210:213], v[76:79]
	v_mfma_f32_16x16x32_bf16 v[72:75], v[136:139], v[210:213], v[72:75]
	v_mfma_f32_16x16x32_bf16 v[124:127], v[132:135], v[190:193], v[124:127]
	v_mfma_f32_16x16x32_bf16 v[120:123], v[140:143], v[190:193], v[120:123]
	v_mfma_f32_16x16x32_bf16 v[108:111], v[132:135], v[198:201], v[108:111]
	v_mfma_f32_16x16x32_bf16 v[104:107], v[140:143], v[198:201], v[104:107]
	v_mfma_f32_16x16x32_bf16 v[92:95], v[132:135], v[206:209], v[92:95]
	v_mfma_f32_16x16x32_bf16 v[88:91], v[140:143], v[206:209], v[88:91]
	v_mfma_f32_16x16x32_bf16 v[76:79], v[132:135], v[214:217], v[76:79]
	v_mfma_f32_16x16x32_bf16 v[72:75], v[140:143], v[214:217], v[72:75]
	v_mfma_f32_16x16x32_bf16 v[116:119], v[160:163], v[186:189], v[116:119]
	v_mfma_f32_16x16x32_bf16 v[112:115], v[168:171], v[186:189], v[112:115]
	v_mfma_f32_16x16x32_bf16 v[100:103], v[160:163], v[194:197], v[100:103]
	v_mfma_f32_16x16x32_bf16 v[96:99], v[168:171], v[194:197], v[96:99]
	v_mfma_f32_16x16x32_bf16 v[84:87], v[160:163], v[202:205], v[84:87]
	v_mfma_f32_16x16x32_bf16 v[80:83], v[168:171], v[202:205], v[80:83]
	v_mfma_f32_16x16x32_bf16 v[68:71], v[160:163], v[210:213], v[68:71]
	v_mfma_f32_16x16x32_bf16 v[64:67], v[168:171], v[210:213], v[64:67]
	v_mfma_f32_16x16x32_bf16 v[116:119], v[164:167], v[190:193], v[116:119]
	v_mfma_f32_16x16x32_bf16 v[112:115], v[172:175], v[190:193], v[112:115]
	v_mfma_f32_16x16x32_bf16 v[100:103], v[164:167], v[198:201], v[100:103]
	v_mfma_f32_16x16x32_bf16 v[96:99], v[172:175], v[198:201], v[96:99]
	v_mfma_f32_16x16x32_bf16 v[84:87], v[164:167], v[206:209], v[84:87]
	v_mfma_f32_16x16x32_bf16 v[80:83], v[172:175], v[206:209], v[80:83]
	v_mfma_f32_16x16x32_bf16 v[68:71], v[164:167], v[214:217], v[68:71]
	v_mfma_f32_16x16x32_bf16 v[64:67], v[172:175], v[214:217], v[64:67]
	s_setprio 0
	s_barrier
; #define PG8_STAGE(bufoff, gbase, voff) do { _Pragma("unroll") for (int _i = 0; _i < 2; ++_i) \
;         __builtin_amdgcn_global_load_lds((const unsigned*)((const char*)(gbase) + (voff)[_i]), (LAS unsigned*)(lds + (bufoff) + ldsw + _i * 8192), 16, 0, 0); } while (0)
; #define PG8_LDA(dst, b, h) do { _Pragma("unroll") for (int m = 0; m < 4; ++m) _Pragma("unroll") for (int k = 0; k < 2; ++k) dst[m][k] = *(const LAS bf16x8*)(lds + PG8_SA(b, h) + aoff + m * 2048 + k * 1024); } while (0)
; #define PG8_LDB(dst, b, h) do { _Pragma("unroll") for (int n = 0; n < 2; ++n) _Pragma("unroll") for (int k = 0; k < 2; ++k) dst[n][k] = *(const LAS bf16x8*)(lds + PG8_SB(b, h) + boff + n * 2048 + k * 1024); } while (0)
; #define PG8_MMA(ai, bj, At, Bt) do { __builtin_amdgcn_s_setprio(1); _Pragma("unroll") for (int m = 0; m < 4; ++m) _Pragma("unroll") for (int n = 0; n < 2; ++n) _Pragma("unroll") for (int k = 0; k < 2; ++k) \
;         acc[ai][bj][m][n] = __builtin_amdgcn_mfma_f32_16x16x32_bf16(Bt[n][k], At[m][k], acc[ai][bj][m][n], 0, 0, 0); __builtin_amdgcn_s_setprio(0); } while (0)
; #define PG8_WAIT_V(n) asm volatile("s_waitcnt vmcnt(" #n ")" ::: "memory")
; #define PG8_BAR __builtin_amdgcn_s_barrier()
; template <class Epi>
; __device__ __forceinline__ void gemm_phase(LAS unsigned char* lds, const Gemm g, const StaticOrder& S, const Epi& E) {
;     ...
;             PG8_LDB(B0, 0, 0); PG8_LDB(B1, 0, 1); PG8_SCHED; PG8_LDA(At, 0, 0); PG8_STAGE(PG8_SA(1, 1), a1 + hstepA, voffA);
;             PG8_WAIT_V(8); PG8_WAIT_L(0); PG8_BAR; PG8_MMA(0, 0, At, B0); PG8_MMA(0, 1, At, B1); PG8_BAR; PG8_SCHED;
;             PG8_LDA(At, 0, 1); PG8_STAGE(PG8_SB(0, 0), b2, voffB); PG8_STAGE(PG8_SB(0, 1), b2 + hstepB, voffB); PG8_STAGE(PG8_SA(0, 0), a2, voffA);
;             PG8_WAIT_V(8); PG8_WAIT_L(0); PG8_BAR; PG8_MMA(1, 0, At, B0); PG8_MMA(1, 1, At, B1); PG8_BAR; PG8_SCHED;
;             PG8_LDB(B0, 1, 0); PG8_LDB(B1, 1, 1); PG8_SCHED; PG8_LDA(At, 1, 0); PG8_STAGE(PG8_SA(0, 1), a2 + hstepA, voffA);
;             PG8_WAIT_V(8); PG8_WAIT_L(0); PG8_BAR; PG8_MMA(0, 0, At, B0); PG8_MMA(0, 1, At, B1); PG8_BAR; PG8_SCHED;
;             PG8_LDA(At, 1, 1); PG8_STAGE(PG8_SB(1, 0), b3, voffB); PG8_STAGE(PG8_SB(1, 1), b3 + hstepB, voffB); PG8_STAGE(PG8_SA(1, 0), a3, voffA);
;             PG8_WAIT_V(8); PG8_WAIT_L(0); PG8_BAR; PG8_MMA(1, 0, At, B0); PG8_MMA(1, 1, At, B1); PG8_BAR; PG8_SCHED;
	s_add_i32 s38, s78, s42
	v_lshl_add_u64 v[178:179], v[178:179], 0, s[16:17]
	s_mov_b32 m0, s38
	ds_read_b128 v[186:189], v184 offset:49152
	ds_read_b128 v[190:193], v184 offset:50176
	ds_read_b128 v[194:197], v184 offset:51200
	ds_read_b128 v[198:201], v184 offset:52224
	ds_read_b128 v[202:205], v184 offset:53248
	ds_read_b128 v[206:209], v184 offset:54272
	ds_read_b128 v[210:213], v184 offset:55296
	ds_read_b128 v[214:217], v184 offset:56320
	global_load_lds_dwordx4 v[178:179], off
	s_add_i32 m0, s38, 0x2000
	s_add_u32 s34, s34, 0xb0080
	v_lshl_add_u64 v[178:179], v[218:219], 0, s[16:17]
	s_addc_u32 s35, s35, 0
	s_add_i32 s38, s79, s42
	global_load_lds_dwordx4 v[178:179], off
	v_lshl_add_u64 v[178:179], s[34:35], 0, v[146:147]
	s_mov_b32 m0, s38
	s_nop 0
	global_load_lds_dwordx4 v[178:179], off
	v_lshl_add_u64 v[178:179], s[34:35], 0, v[150:151]
	s_add_i32 m0, s38, 0x2000
	s_nop 0
	global_load_lds_dwordx4 v[178:179], off
	v_lshl_add_u64 v[178:179], v[220:221], 0, s[16:17]
	s_mov_b32 m0, s62
	s_nop 0
	global_load_lds_dwordx4 v[178:179], off
	v_lshl_add_u64 v[178:179], v[222:223], 0, s[16:17]
	s_mov_b32 m0, s63
	s_nop 0
	global_load_lds_dwordx4 v[178:179], off
	s_waitcnt vmcnt(8)
	s_waitcnt lgkmcnt(0)
	s_barrier
	s_setprio 1
	s_waitcnt lgkmcnt(0)
	v_mfma_f32_16x16x32_bf16 v[60:63], v[128:131], v[186:189], v[60:63]
	v_mfma_f32_16x16x32_bf16 v[56:59], v[136:139], v[186:189], v[56:59]
	v_mfma_f32_16x16x32_bf16 v[44:47], v[128:131], v[194:197], v[44:47]
	v_mfma_f32_16x16x32_bf16 v[40:43], v[136:139], v[194:197], v[40:43]
	v_mfma_f32_16x16x32_bf16 v[28:31], v[128:131], v[202:205], v[28:31]
	v_mfma_f32_16x16x32_bf16 v[24:27], v[136:139], v[202:205], v[24:27]
	v_mfma_f32_16x16x32_bf16 v[12:15], v[128:131], v[210:213], v[12:15]
	v_mfma_f32_16x16x32_bf16 v[8:11], v[136:139], v[210:213], v[8:11]
	v_mfma_f32_16x16x32_bf16 v[60:63], v[132:135], v[190:193], v[60:63]
	v_mfma_f32_16x16x32_bf16 v[56:59], v[140:143], v[190:193], v[56:59]
	v_mfma_f32_16x16x32_bf16 v[44:47], v[132:135], v[198:201], v[44:47]
	v_mfma_f32_16x16x32_bf16 v[40:43], v[140:143], v[198:201], v[40:43]
	v_mfma_f32_16x16x32_bf16 v[28:31], v[132:135], v[206:209], v[28:31]
	v_mfma_f32_16x16x32_bf16 v[24:27], v[140:143], v[206:209], v[24:27]
	v_mfma_f32_16x16x32_bf16 v[12:15], v[132:135], v[214:217], v[12:15]
	v_mfma_f32_16x16x32_bf16 v[8:11], v[140:143], v[214:217], v[8:11]
	v_mfma_f32_16x16x32_bf16 v[52:55], v[160:163], v[186:189], v[52:55]
	v_mfma_f32_16x16x32_bf16 v[48:51], v[168:171], v[186:189], v[48:51]
	v_mfma_f32_16x16x32_bf16 v[36:39], v[160:163], v[194:197], v[36:39]
	v_mfma_f32_16x16x32_bf16 v[32:35], v[168:171], v[194:197], v[32:35]
	v_mfma_f32_16x16x32_bf16 v[20:23], v[160:163], v[202:205], v[20:23]
	v_mfma_f32_16x16x32_bf16 v[16:19], v[168:171], v[202:205], v[16:19]
	v_mfma_f32_16x16x32_bf16 v[4:7], v[160:163], v[210:213], v[4:7]
	v_mfma_f32_16x16x32_bf16 v[0:3], v[168:171], v[210:213], v[0:3]
	v_mfma_f32_16x16x32_bf16 v[52:55], v[164:167], v[190:193], v[52:55]
	v_mfma_f32_16x16x32_bf16 v[48:51], v[172:175], v[190:193], v[48:51]
	v_mfma_f32_16x16x32_bf16 v[36:39], v[164:167], v[198:201], v[36:39]
	v_mfma_f32_16x16x32_bf16 v[32:35], v[172:175], v[198:201], v[32:35]
	v_mfma_f32_16x16x32_bf16 v[20:23], v[164:167], v[206:209], v[20:23]
	v_mfma_f32_16x16x32_bf16 v[16:19], v[172:175], v[206:209], v[16:19]
	v_mfma_f32_16x16x32_bf16 v[4:7], v[164:167], v[214:217], v[4:7]
	v_mfma_f32_16x16x32_bf16 v[0:3], v[172:175], v[214:217], v[0:3]
	s_setprio 0
	s_barrier
	s_add_i32 s77, s77, 2
	s_add_u32 s0, s0, 0x100
	s_addc_u32 s1, s1, 0
	s_add_u32 s75, s75, 0x100
	s_addc_u32 s76, s76, 0
	s_cmp_gt_u32 s77, 41
.LBB0_792:
	ds_read_b128 v[128:131], v182
	ds_read_b128 v[132:135], v182 offset:1024
	ds_read_b128 v[136:139], v182 offset:2048
	ds_read_b128 v[140:143], v182 offset:3072
	ds_read_b128 v[160:163], v183
	ds_read_b128 v[164:167], v183 offset:1024
	ds_read_b128 v[168:171], v183 offset:2048
	ds_read_b128 v[172:175], v183 offset:3072
	s_add_u32 s34, s0, 0xfff50080
	s_addc_u32 s35, s1, -1
	s_cmp_eq_u32 s77, 40
	s_cselect_b32 s39, s7, s35
	s_cselect_b32 s38, s6, s34
	s_cselect_b32 s35, s23, s76
	s_cselect_b32 s34, s22, s75
	v_lshl_add_u64 v[178:179], s[0:1], 0, v[152:153]
	s_add_i32 m0, s43, 0xc000
	ds_read_b128 v[186:189], v184
	ds_read_b128 v[190:193], v184 offset:1024
	ds_read_b128 v[194:197], v184 offset:2048
	ds_read_b128 v[198:201], v184 offset:3072
	ds_read_b128 v[202:205], v184 offset:4096
	ds_read_b128 v[206:209], v184 offset:5120
	ds_read_b128 v[210:213], v184 offset:6144
	ds_read_b128 v[214:217], v184 offset:7168
	global_load_lds_dwordx4 v[178:179], off
	v_lshl_add_u64 v[178:179], s[0:1], 0, v[154:155]
	s_add_i32 m0, s43, 0xe000
	s_nop 0
	global_load_lds_dwordx4 v[178:179], off
	s_waitcnt vmcnt(8)
	s_waitcnt lgkmcnt(0)
	s_barrier
; #define PG8_STAGE(bufoff, gbase, voff) do { _Pragma("unroll") for (int _i = 0; _i < 2; ++_i) \
;         __builtin_amdgcn_global_load_lds((const unsigned*)((const char*)(gbase) + (voff)[_i]), (LAS unsigned*)(lds + (bufoff) + ldsw + _i * 8192), 16, 0, 0); } while (0)
; #define PG8_LDA(dst, b, h) do { _Pragma("unroll") for (int m = 0; m < 4; ++m) _Pragma("unroll") for (int k = 0; k < 2; ++k) dst[m][k] = *(const LAS bf16x8*)(lds + PG8_SA(b, h) + aoff + m * 2048 + k * 1024); } while (0)
; #define PG8_MMA(ai, bj, At, Bt) do { __builtin_amdgcn_s_setprio(1); _Pragma("unroll") for (int m = 0; m < 4; ++m) _Pragma("unroll") for (int n = 0; n < 2; ++n) _Pragma("unroll") for (int k = 0; k < 2; ++k) \
;         acc[ai][bj][m][n] = __builtin_amdgcn_mfma_f32_16x16x32_bf16(Bt[n][k], At[m][k], acc[ai][bj][m][n], 0, 0, 0); __builtin_amdgcn_s_setprio(0); } while (0)
; #define PG8_WAIT_V(n) asm volatile("s_waitcnt vmcnt(" #n ")" ::: "memory")
; #define PG8_WAIT_L(n) asm volatile("s_waitcnt lgkmcnt(" #n ")" ::: "memory")
; #define PG8_BAR __builtin_amdgcn_s_barrier()
; #define PG8_SCHED __builtin_amdgcn_sched_barrier(0)
; template <class Epi>
; __device__ __forceinline__ void gemm_phase(LAS unsigned char* lds, const Gemm g, const StaticOrder& S, const Epi& E) {
;     ...
;             PG8_WAIT_V(8); PG8_WAIT_L(0); PG8_BAR; PG8_MMA(0, 0, At, B0); PG8_MMA(0, 1, At, B1); PG8_BAR; PG8_SCHED;
;             PG8_LDA(At, 0, 1); PG8_STAGE(PG8_SB(0, 0), b2, voffB); PG8_STAGE(PG8_SB(0, 1), b2 + hstepB, voffB); PG8_STAGE(PG8_SA(0, 0), a2, voffA);
;             PG8_WAIT_V(8); PG8_WAIT_L(0); PG8_BAR; PG8_MMA(1, 0, At, B0); PG8_MMA(1, 1, At, B1); PG8_BAR; PG8_SCHED;
	s_setprio 1
	s_waitcnt lgkmcnt(0)
	v_mfma_f32_16x16x32_bf16 v[124:127], v[128:131], v[186:189], v[124:127]
	v_mfma_f32_16x16x32_bf16 v[120:123], v[136:139], v[186:189], v[120:123]
	v_mfma_f32_16x16x32_bf16 v[108:111], v[128:131], v[194:197], v[108:111]
	v_mfma_f32_16x16x32_bf16 v[104:107], v[136:139], v[194:197], v[104:107]
	v_mfma_f32_16x16x32_bf16 v[92:95], v[128:131], v[202:205], v[92:95]
	v_mfma_f32_16x16x32_bf16 v[88:91], v[136:139], v[202:205], v[88:91]
	v_mfma_f32_16x16x32_bf16 v[76:79], v[128:131], v[210:213], v[76:79]
	v_mfma_f32_16x16x32_bf16 v[72:75], v[136:139], v[210:213], v[72:75]
	v_mfma_f32_16x16x32_bf16 v[124:127], v[132:135], v[190:193], v[124:127]
	v_mfma_f32_16x16x32_bf16 v[120:123], v[140:143], v[190:193], v[120:123]
	v_mfma_f32_16x16x32_bf16 v[108:111], v[132:135], v[198:201], v[108:111]
	v_mfma_f32_16x16x32_bf16 v[104:107], v[140:143], v[198:201], v[104:107]
	v_mfma_f32_16x16x32_bf16 v[92:95], v[132:135], v[206:209], v[92:95]
	v_mfma_f32_16x16x32_bf16 v[88:91], v[140:143], v[206:209], v[88:91]
	v_mfma_f32_16x16x32_bf16 v[76:79], v[132:135], v[214:217], v[76:79]
	v_mfma_f32_16x16x32_bf16 v[72:75], v[140:143], v[214:217], v[72:75]
	v_mfma_f32_16x16x32_bf16 v[116:119], v[160:163], v[186:189], v[116:119]
	v_mfma_f32_16x16x32_bf16 v[112:115], v[168:171], v[186:189], v[112:115]
	v_mfma_f32_16x16x32_bf16 v[100:103], v[160:163], v[194:197], v[100:103]
	v_mfma_f32_16x16x32_bf16 v[96:99], v[168:171], v[194:197], v[96:99]
	v_mfma_f32_16x16x32_bf16 v[84:87], v[160:163], v[202:205], v[84:87]
	v_mfma_f32_16x16x32_bf16 v[80:83], v[168:171], v[202:205], v[80:83]
	v_mfma_f32_16x16x32_bf16 v[68:71], v[160:163], v[210:213], v[68:71]
	v_mfma_f32_16x16x32_bf16 v[64:67], v[168:171], v[210:213], v[64:67]
	v_mfma_f32_16x16x32_bf16 v[116:119], v[164:167], v[190:193], v[116:119]
	v_mfma_f32_16x16x32_bf16 v[112:115], v[172:175], v[190:193], v[112:115]
	v_mfma_f32_16x16x32_bf16 v[100:103], v[164:167], v[198:201], v[100:103]
	v_mfma_f32_16x16x32_bf16 v[96:99], v[172:175], v[198:201], v[96:99]
	v_mfma_f32_16x16x32_bf16 v[84:87], v[164:167], v[206:209], v[84:87]
	v_mfma_f32_16x16x32_bf16 v[80:83], v[172:175], v[206:209], v[80:83]
	v_mfma_f32_16x16x32_bf16 v[68:71], v[164:167], v[214:217], v[68:71]
	v_mfma_f32_16x16x32_bf16 v[64:67], v[172:175], v[214:217], v[64:67]
	s_setprio 0
	s_barrier
	s_add_i32 s78, s69, s42
	v_lshl_add_u64 v[178:179], s[34:35], 0, v[146:147]
	s_mov_b32 m0, s78
	ds_read_b128 v[186:189], v184 offset:16384
	ds_read_b128 v[190:193], v184 offset:17408
	ds_read_b128 v[194:197], v184 offset:18432
	ds_read_b128 v[198:201], v184 offset:19456
	ds_read_b128 v[202:205], v184 offset:20480
	ds_read_b128 v[206:209], v184 offset:21504
	ds_read_b128 v[210:213], v184 offset:22528
	ds_read_b128 v[214:217], v184 offset:23552
	global_load_lds_dwordx4 v[178:179], off
	s_add_i32 m0, s78, 0x2000
	s_add_u32 s78, s34, 0xb0000
	v_lshl_add_u64 v[218:219], s[34:35], 0, v[150:151]
	s_addc_u32 s79, s35, 0
	s_add_i32 s80, s70, s42
	global_load_lds_dwordx4 v[218:219], off
	v_lshl_add_u64 v[220:221], s[78:79], 0, v[146:147]
	s_mov_b32 m0, s80
	v_lshl_add_u64 v[222:223], s[38:39], 0, v[148:149]
	global_load_lds_dwordx4 v[220:221], off
	v_lshl_add_u64 v[220:221], s[78:79], 0, v[150:151]
	s_add_i32 m0, s80, 0x2000
	s_nop 0
	global_load_lds_dwordx4 v[220:221], off
	v_lshl_add_u64 v[220:221], s[38:39], 0, v[144:145]
	s_mov_b32 m0, s43
	s_nop 0
	global_load_lds_dwordx4 v[220:221], off
	s_mov_b32 m0, s52
	s_nop 0
	global_load_lds_dwordx4 v[222:223], off
	s_waitcnt vmcnt(8)
	s_waitcnt lgkmcnt(0)
	s_barrier
	s_setprio 1
	s_waitcnt lgkmcnt(0)
	v_mfma_f32_16x16x32_bf16 v[60:63], v[128:131], v[186:189], v[60:63]
	v_mfma_f32_16x16x32_bf16 v[56:59], v[136:139], v[186:189], v[56:59]
	v_mfma_f32_16x16x32_bf16 v[44:47], v[128:131], v[194:197], v[44:47]
	v_mfma_f32_16x16x32_bf16 v[40:43], v[136:139], v[194:197], v[40:43]
	v_mfma_f32_16x16x32_bf16 v[28:31], v[128:131], v[202:205], v[28:31]
	v_mfma_f32_16x16x32_bf16 v[24:27], v[136:139], v[202:205], v[24:27]
	v_mfma_f32_16x16x32_bf16 v[12:15], v[128:131], v[210:213], v[12:15]
	v_mfma_f32_16x16x32_bf16 v[8:11], v[136:139], v[210:213], v[8:11]
	v_mfma_f32_16x16x32_bf16 v[60:63], v[132:135], v[190:193], v[60:63]
	v_mfma_f32_16x16x32_bf16 v[56:59], v[140:143], v[190:193], v[56:59]
	v_mfma_f32_16x16x32_bf16 v[44:47], v[132:135], v[198:201], v[44:47]
	v_mfma_f32_16x16x32_bf16 v[40:43], v[140:143], v[198:201], v[40:43]
	v_mfma_f32_16x16x32_bf16 v[28:31], v[132:135], v[206:209], v[28:31]
	v_mfma_f32_16x16x32_bf16 v[24:27], v[140:143], v[206:209], v[24:27]
	v_mfma_f32_16x16x32_bf16 v[12:15], v[132:135], v[214:217], v[12:15]
	v_mfma_f32_16x16x32_bf16 v[8:11], v[140:143], v[214:217], v[8:11]
	v_mfma_f32_16x16x32_bf16 v[52:55], v[160:163], v[186:189], v[52:55]
	v_mfma_f32_16x16x32_bf16 v[48:51], v[168:171], v[186:189], v[48:51]
	v_mfma_f32_16x16x32_bf16 v[36:39], v[160:163], v[194:197], v[36:39]
	v_mfma_f32_16x16x32_bf16 v[32:35], v[168:171], v[194:197], v[32:35]
	v_mfma_f32_16x16x32_bf16 v[20:23], v[160:163], v[202:205], v[20:23]
	v_mfma_f32_16x16x32_bf16 v[16:19], v[168:171], v[202:205], v[16:19]
	v_mfma_f32_16x16x32_bf16 v[4:7], v[160:163], v[210:213], v[4:7]
	v_mfma_f32_16x16x32_bf16 v[0:3], v[168:171], v[210:213], v[0:3]
	v_mfma_f32_16x16x32_bf16 v[52:55], v[164:167], v[190:193], v[52:55]
	v_mfma_f32_16x16x32_bf16 v[48:51], v[172:175], v[190:193], v[48:51]
	v_mfma_f32_16x16x32_bf16 v[36:39], v[164:167], v[198:201], v[36:39]
	v_mfma_f32_16x16x32_bf16 v[32:35], v[172:175], v[198:201], v[32:35]
	v_mfma_f32_16x16x32_bf16 v[20:23], v[164:167], v[206:209], v[20:23]
	v_mfma_f32_16x16x32_bf16 v[16:19], v[172:175], v[206:209], v[16:19]
	v_mfma_f32_16x16x32_bf16 v[4:7], v[164:167], v[214:217], v[4:7]
	v_mfma_f32_16x16x32_bf16 v[0:3], v[172:175], v[214:217], v[0:3]
	s_setprio 0
	s_barrier
; #define PG8_STAGE(bufoff, gbase, voff) do { _Pragma("unroll") for (int _i = 0; _i < 2; ++_i) \
;         __builtin_amdgcn_global_load_lds((const unsigned*)((const char*)(gbase) + (voff)[_i]), (LAS unsigned*)(lds + (bufoff) + ldsw + _i * 8192), 16, 0, 0); } while (0)
; #define PG8_LDA(dst, b, h) do { _Pragma("unroll") for (int m = 0; m < 4; ++m) _Pragma("unroll") for (int k = 0; k < 2; ++k) dst[m][k] = *(const LAS bf16x8*)(lds + PG8_SA(b, h) + aoff + m * 2048 + k * 1024); } while (0)
; #define PG8_LDB(dst, b, h) do { _Pragma("unroll") for (int n = 0; n < 2; ++n) _Pragma("unroll") for (int k = 0; k < 2; ++k) dst[n][k] = *(const LAS bf16x8*)(lds + PG8_SB(b, h) + boff + n * 2048 + k * 1024); } while (0)
; #define PG8_MMA(ai, bj, At, Bt) do { __builtin_amdgcn_s_setprio(1); _Pragma("unroll") for (int m = 0; m < 4; ++m) _Pragma("unroll") for (int n = 0; n < 2; ++n) _Pragma("unroll") for (int k = 0; k < 2; ++k) \
;         acc[ai][bj][m][n] = __builtin_amdgcn_mfma_f32_16x16x32_bf16(Bt[n][k], At[m][k], acc[ai][bj][m][n], 0, 0, 0); __builtin_amdgcn_s_setprio(0); } while (0)
; #define PG8_WAIT_V(n) asm volatile("s_waitcnt vmcnt(" #n ")" ::: "memory")
; #define PG8_WAIT_L(n) asm volatile("s_waitcnt lgkmcnt(" #n ")" ::: "memory")
; #define PG8_BAR __builtin_amdgcn_s_barrier()
; #define PG8_SCHED __builtin_amdgcn_sched_barrier(0)
; template <class Epi>
; __device__ __forceinline__ void gemm_phase(LAS unsigned char* lds, const Gemm g, const StaticOrder& S, const Epi& E) {
;     ...
;             PG8_LDB(B0, 1, 0); PG8_LDB(B1, 1, 1); PG8_SCHED; PG8_LDA(At, 1, 0); PG8_STAGE(PG8_SA(0, 1), a2 + hstepA, voffA);
;             PG8_WAIT_V(8); PG8_WAIT_L(0); PG8_BAR; PG8_MMA(0, 0, At, B0); PG8_MMA(0, 1, At, B1); PG8_BAR; PG8_SCHED;
	s_add_i32 s78, 0, 0x18000
	s_add_i32 s79, 0, 0x1c000
	v_add_u32_e32 v140, s78, v181
	v_add_u32_e32 v172, s79, v181
	ds_read_b128 v[128:131], v140
	ds_read_b128 v[132:135], v140 offset:1024
	ds_read_b128 v[136:139], v140 offset:2048
	ds_read_b128 v[140:143], v140 offset:3072
	ds_read_b128 v[160:163], v172
	ds_read_b128 v[164:167], v172 offset:1024
	ds_read_b128 v[168:171], v172 offset:2048
	ds_read_b128 v[172:175], v172 offset:3072
	s_add_u32 s38, s38, 0xb0000
	s_addc_u32 s39, s39, 0
	s_mov_b32 m0, s53
	v_lshl_add_u64 v[226:227], s[38:39], 0, v[144:145]
	ds_read_b128 v[186:189], v184 offset:32768
	ds_read_b128 v[190:193], v184 offset:33792
	ds_read_b128 v[194:197], v184 offset:34816
	ds_read_b128 v[198:201], v184 offset:35840
	ds_read_b128 v[202:205], v184 offset:36864
	ds_read_b128 v[206:209], v184 offset:37888
	ds_read_b128 v[210:213], v184 offset:38912
	ds_read_b128 v[214:217], v184 offset:39936
	global_load_lds_dwordx4 v[226:227], off
	v_lshl_add_u64 v[226:227], s[38:39], 0, v[148:149]
	s_mov_b32 m0, s54
	s_nop 0
	global_load_lds_dwordx4 v[226:227], off
	s_waitcnt vmcnt(8)
	s_waitcnt lgkmcnt(0)
	s_barrier
	s_setprio 1
	s_waitcnt lgkmcnt(0)
	v_mfma_f32_16x16x32_bf16 v[124:127], v[128:131], v[186:189], v[124:127]
	v_mfma_f32_16x16x32_bf16 v[120:123], v[136:139], v[186:189], v[120:123]
	v_mfma_f32_16x16x32_bf16 v[108:111], v[128:131], v[194:197], v[108:111]
	v_mfma_f32_16x16x32_bf16 v[104:107], v[136:139], v[194:197], v[104:107]
	v_mfma_f32_16x16x32_bf16 v[92:95], v[128:131], v[202:205], v[92:95]
	v_mfma_f32_16x16x32_bf16 v[88:91], v[136:139], v[202:205], v[88:91]
	v_mfma_f32_16x16x32_bf16 v[76:79], v[128:131], v[210:213], v[76:79]
	v_mfma_f32_16x16x32_bf16 v[72:75], v[136:139], v[210:213], v[72:75]
	v_mfma_f32_16x16x32_bf16 v[124:127], v[132:135], v[190:193], v[124:127]
	v_mfma_f32_16x16x32_bf16 v[120:123], v[140:143], v[190:193], v[120:123]
	v_mfma_f32_16x16x32_bf16 v[108:111], v[132:135], v[198:201], v[108:111]
	v_mfma_f32_16x16x32_bf16 v[104:107], v[140:143], v[198:201], v[104:107]
	v_mfma_f32_16x16x32_bf16 v[92:95], v[132:135], v[206:209], v[92:95]
	v_mfma_f32_16x16x32_bf16 v[88:91], v[140:143], v[206:209], v[88:91]
	v_mfma_f32_16x16x32_bf16 v[76:79], v[132:135], v[214:217], v[76:79]
	v_mfma_f32_16x16x32_bf16 v[72:75], v[140:143], v[214:217], v[72:75]
	v_mfma_f32_16x16x32_bf16 v[116:119], v[160:163], v[186:189], v[116:119]
	v_mfma_f32_16x16x32_bf16 v[112:115], v[168:171], v[186:189], v[112:115]
	v_mfma_f32_16x16x32_bf16 v[100:103], v[160:163], v[194:197], v[100:103]
	v_mfma_f32_16x16x32_bf16 v[96:99], v[168:171], v[194:197], v[96:99]
	v_mfma_f32_16x16x32_bf16 v[84:87], v[160:163], v[202:205], v[84:87]
	v_mfma_f32_16x16x32_bf16 v[80:83], v[168:171], v[202:205], v[80:83]
	v_mfma_f32_16x16x32_bf16 v[68:71], v[160:163], v[210:213], v[68:71]
	v_mfma_f32_16x16x32_bf16 v[64:67], v[168:171], v[210:213], v[64:67]
	v_mfma_f32_16x16x32_bf16 v[116:119], v[164:167], v[190:193], v[116:119]
	v_mfma_f32_16x16x32_bf16 v[112:115], v[172:175], v[190:193], v[112:115]
	v_mfma_f32_16x16x32_bf16 v[100:103], v[164:167], v[198:201], v[100:103]
	v_mfma_f32_16x16x32_bf16 v[96:99], v[172:175], v[198:201], v[96:99]
	v_mfma_f32_16x16x32_bf16 v[84:87], v[164:167], v[206:209], v[84:87]
	v_mfma_f32_16x16x32_bf16 v[80:83], v[172:175], v[206:209], v[80:83]
	v_mfma_f32_16x16x32_bf16 v[68:71], v[164:167], v[214:217], v[68:71]
	v_mfma_f32_16x16x32_bf16 v[64:67], v[172:175], v[214:217], v[64:67]
	s_setprio 0
	s_barrier
; #define PG8_STAGE(bufoff, gbase, voff) do { _Pragma("unroll") for (int _i = 0; _i < 2; ++_i) \
;         __builtin_amdgcn_global_load_lds((const unsigned*)((const char*)(gbase) + (voff)[_i]), (LAS unsigned*)(lds + (bufoff) + ldsw + _i * 8192), 16, 0, 0); } while (0)
; #define PG8_LDA(dst, b, h) do { _Pragma("unroll") for (int m = 0; m < 4; ++m) _Pragma("unroll") for (int k = 0; k < 2; ++k) dst[m][k] = *(const LAS bf16x8*)(lds + PG8_SA(b, h) + aoff + m * 2048 + k * 1024); } while (0)
; #define PG8_MMA(ai, bj, At, Bt) do { __builtin_amdgcn_s_setprio(1); _Pragma("unroll") for (int m = 0; m < 4; ++m) _Pragma("unroll") for (int n = 0; n < 2; ++n) _Pragma("unroll") for (int k = 0; k < 2; ++k) \
;         acc[ai][bj][m][n] = __builtin_amdgcn_mfma_f32_16x16x32_bf16(Bt[n][k], At[m][k], acc[ai][bj][m][n], 0, 0, 0); __builtin_amdgcn_s_setprio(0); } while (0)
; #define PG8_WAIT_V(n) asm volatile("s_waitcnt vmcnt(" #n ")" ::: "memory")
; #define PG8_WAIT_L(n) asm volatile("s_waitcnt lgkmcnt(" #n ")" ::: "memory")
; #define PG8_BAR __builtin_amdgcn_s_barrier()
; #define PG8_SCHED __builtin_amdgcn_sched_barrier(0)
; template <class Epi>
; __device__ __forceinline__ void gemm_phase(LAS unsigned char* lds, const Gemm g, const StaticOrder& S, const Epi& E) {
;     ...
;             PG8_LDA(At, 1, 1); PG8_STAGE(PG8_SB(1, 0), b3, voffB); PG8_STAGE(PG8_SB(1, 1), b3 + hstepB, voffB); PG8_STAGE(PG8_SA(1, 0), a3, voffA);
;             PG8_WAIT_V(8); PG8_WAIT_L(0); PG8_BAR; PG8_MMA(1, 0, At, B0); PG8_MMA(1, 1, At, B1); PG8_BAR; PG8_SCHED;
;         }
;         if (wr == 0) PG8_BAR;
	s_add_i32 s38, s78, s42
	v_lshl_add_u64 v[178:179], v[178:179], 0, s[16:17]
	s_mov_b32 m0, s38
	ds_read_b128 v[186:189], v184 offset:49152
	ds_read_b128 v[190:193], v184 offset:50176
	ds_read_b128 v[194:197], v184 offset:51200
	ds_read_b128 v[198:201], v184 offset:52224
	ds_read_b128 v[202:205], v184 offset:53248
	ds_read_b128 v[206:209], v184 offset:54272
	ds_read_b128 v[210:213], v184 offset:55296
	ds_read_b128 v[214:217], v184 offset:56320
	global_load_lds_dwordx4 v[178:179], off
	s_add_i32 m0, s38, 0x2000
	s_add_u32 s34, s34, 0xb0080
	v_lshl_add_u64 v[178:179], v[218:219], 0, s[16:17]
	s_addc_u32 s35, s35, 0
	s_add_i32 s38, s79, s42
	global_load_lds_dwordx4 v[178:179], off
	v_lshl_add_u64 v[178:179], s[34:35], 0, v[146:147]
	s_mov_b32 m0, s38
	s_nop 0
	global_load_lds_dwordx4 v[178:179], off
	v_lshl_add_u64 v[178:179], s[34:35], 0, v[150:151]
	s_add_i32 m0, s38, 0x2000
	s_nop 0
	global_load_lds_dwordx4 v[178:179], off
	v_lshl_add_u64 v[178:179], v[220:221], 0, s[16:17]
	s_mov_b32 m0, s62
	s_nop 0
	global_load_lds_dwordx4 v[178:179], off
	v_lshl_add_u64 v[178:179], v[222:223], 0, s[16:17]
	s_mov_b32 m0, s63
	s_nop 0
	global_load_lds_dwordx4 v[178:179], off
	s_waitcnt vmcnt(8)
	s_waitcnt lgkmcnt(0)
	s_barrier
	s_setprio 1
	s_waitcnt lgkmcnt(0)
	v_mfma_f32_16x16x32_bf16 v[60:63], v[128:131], v[186:189], v[60:63]
	v_mfma_f32_16x16x32_bf16 v[56:59], v[136:139], v[186:189], v[56:59]
	v_mfma_f32_16x16x32_bf16 v[44:47], v[128:131], v[194:197], v[44:47]
	v_mfma_f32_16x16x32_bf16 v[40:43], v[136:139], v[194:197], v[40:43]
	v_mfma_f32_16x16x32_bf16 v[28:31], v[128:131], v[202:205], v[28:31]
	v_mfma_f32_16x16x32_bf16 v[24:27], v[136:139], v[202:205], v[24:27]
	v_mfma_f32_16x16x32_bf16 v[12:15], v[128:131], v[210:213], v[12:15]
	v_mfma_f32_16x16x32_bf16 v[8:11], v[136:139], v[210:213], v[8:11]
	v_mfma_f32_16x16x32_bf16 v[60:63], v[132:135], v[190:193], v[60:63]
	v_mfma_f32_16x16x32_bf16 v[56:59], v[140:143], v[190:193], v[56:59]
	v_mfma_f32_16x16x32_bf16 v[44:47], v[132:135], v[198:201], v[44:47]
	v_mfma_f32_16x16x32_bf16 v[40:43], v[140:143], v[198:201], v[40:43]
	v_mfma_f32_16x16x32_bf16 v[28:31], v[132:135], v[206:209], v[28:31]
	v_mfma_f32_16x16x32_bf16 v[24:27], v[140:143], v[206:209], v[24:27]
	v_mfma_f32_16x16x32_bf16 v[12:15], v[132:135], v[214:217], v[12:15]
	v_mfma_f32_16x16x32_bf16 v[8:11], v[140:143], v[214:217], v[8:11]
	v_mfma_f32_16x16x32_bf16 v[52:55], v[160:163], v[186:189], v[52:55]
	v_mfma_f32_16x16x32_bf16 v[48:51], v[168:171], v[186:189], v[48:51]
	v_mfma_f32_16x16x32_bf16 v[36:39], v[160:163], v[194:197], v[36:39]
	v_mfma_f32_16x16x32_bf16 v[32:35], v[168:171], v[194:197], v[32:35]
	v_mfma_f32_16x16x32_bf16 v[20:23], v[160:163], v[202:205], v[20:23]
	v_mfma_f32_16x16x32_bf16 v[16:19], v[168:171], v[202:205], v[16:19]
	v_mfma_f32_16x16x32_bf16 v[4:7], v[160:163], v[210:213], v[4:7]
	v_mfma_f32_16x16x32_bf16 v[0:3], v[168:171], v[210:213], v[0:3]
	v_mfma_f32_16x16x32_bf16 v[52:55], v[164:167], v[190:193], v[52:55]
	v_mfma_f32_16x16x32_bf16 v[48:51], v[172:175], v[190:193], v[48:51]
	v_mfma_f32_16x16x32_bf16 v[36:39], v[164:167], v[198:201], v[36:39]
	v_mfma_f32_16x16x32_bf16 v[32:35], v[172:175], v[198:201], v[32:35]
	v_mfma_f32_16x16x32_bf16 v[20:23], v[164:167], v[206:209], v[20:23]
	v_mfma_f32_16x16x32_bf16 v[16:19], v[172:175], v[206:209], v[16:19]
	v_mfma_f32_16x16x32_bf16 v[4:7], v[164:167], v[214:217], v[4:7]
	v_mfma_f32_16x16x32_bf16 v[0:3], v[172:175], v[214:217], v[0:3]
	s_setprio 0
	s_barrier
	s_add_i32 s77, s77, 2
	s_add_u32 s0, s0, 0x100
	s_addc_u32 s1, s1, 0
	s_add_u32 s75, s75, 0x100
	s_addc_u32 s76, s76, 0
	s_cmp_gt_u32 s77, 41
	s_cbranch_scc0 .LBB0_792
	s_and_b64 vcc, exec, s[18:19]
	s_cbranch_vccz .LBB0_795
	s_barrier

; #define PG8_STAGE(bufoff, gbase, voff) do { _Pragma("unroll") for (int _i = 0; _i < 2; ++_i) \
;         __builtin_amdgcn_global_load_lds((const unsigned*)((const char*)(gbase) + (voff)[_i]), (LAS unsigned*)(lds + (bufoff) + ldsw + _i * 8192), 16, 0, 0); } while (0)
; #define PG8_LDA(dst, b, h) do { _Pragma("unroll") for (int m = 0; m < 4; ++m) _Pragma("unroll") for (int k = 0; k < 2; ++k) dst[m][k] = *(const LAS bf16x8*)(lds + PG8_SA(b, h) + aoff + m * 2048 + k * 1024); } while (0)
; #define PG8_LDB(dst, b, h) do { _Pragma("unroll") for (int n = 0; n < 2; ++n) _Pragma("unroll") for (int k = 0; k < 2; ++k) dst[n][k] = *(const LAS bf16x8*)(lds + PG8_SB(b, h) + boff + n * 2048 + k * 1024); } while (0)
; #define PG8_MMA(ai, bj, At, Bt) do { __builtin_amdgcn_s_setprio(1); _Pragma("unroll") for (int m = 0; m < 4; ++m) _Pragma("unroll") for (int n = 0; n < 2; ++n) _Pragma("unroll") for (int k = 0; k < 2; ++k) \
;         acc[ai][bj][m][n] = __builtin_amdgcn_mfma_f32_16x16x32_bf16(Bt[n][k], At[m][k], acc[ai][bj][m][n], 0, 0, 0); __builtin_amdgcn_s_setprio(0); } while (0)
; #define PG8_BAR __builtin_amdgcn_s_barrier()
; template <class Epi>
; __device__ __forceinline__ void gemm_phase(LAS unsigned char* lds, const Gemm g, const StaticOrder& S, const Epi& E) {
;     ...
;         const bool has_next = S.next(ui + 1, nxt);
;         const char* nA = has_next ? (const char*)g.A + (size_t)nxt.pm * tstepA : cA; const char* nB = has_next ? (const char*)g.Bt + (size_t)nxt.pn * tstepB : cB;
; #pragma nounroll
;         for (int t = 0; t < nt; t += 2) {
;             const bool last = (t == nt - 2);
;             const char* a1 = cA + (size_t)(t + 1) * kstep;
;             const char* a2 = last ? nA : cA + (size_t)(t + 2) * kstep; const char* b2 = last ? nB : cB + (size_t)(t + 2) * kstep;
;             const char* a3 = a2 + kstep; const char* b3 = b2 + kstep;
;             PG8_LDB(B0, 0, 0); PG8_LDB(B1, 0, 1); PG8_SCHED; PG8_LDA(At, 0, 0); PG8_STAGE(PG8_SA(1, 1), a1 + hstepA, voffA);
;             PG8_WAIT_V(8); PG8_WAIT_L(0); PG8_BAR; PG8_MMA(0, 0, At, B0); PG8_MMA(0, 1, At, B1); PG8_BAR; PG8_SCHED;
;             PG8_LDA(At, 0, 1); PG8_STAGE(PG8_SB(0, 0), b2, voffB); PG8_STAGE(PG8_SB(0, 1), b2 + hstepB, voffB); PG8_STAGE(PG8_SA(0, 0), a2, voffA);
;             PG8_WAIT_V(8); PG8_WAIT_L(0); PG8_BAR; PG8_MMA(1, 0, At, B0); PG8_MMA(1, 1, At, B1); PG8_BAR; PG8_SCHED;
.LBB0_888:
	s_ashr_i32 s43, s42, 31
	s_lshl_b64 s[52:53], s[42:43], 19
	s_add_u32 s52, s30, s52
	s_addc_u32 s53, s31, s53
	s_and_b64 s[54:55], s[4:5], exec
	s_cselect_b32 s7, s53, s57
	s_cselect_b32 s9, s52, s56
	s_ashr_i32 s39, s38, 31
	s_lshl_b64 s[54:55], s[38:39], 19
	s_add_u32 s54, s3, s54
	s_addc_u32 s55, s33, s55
	s_and_b64 s[64:65], s[4:5], exec
	s_cselect_b32 s39, s55, s63
	s_cselect_b32 s43, s54, s62
	s_add_u32 s56, s56, 0x40080
	s_addc_u32 s57, s57, 0
	s_add_u32 s83, s62, 0x100
	s_addc_u32 s84, s63, 0
	s_mov_b32 s85, -2
	s_waitcnt lgkmcnt(0)
	s_nop 0
	ds_read_b128 v[40:43], v208
	ds_read_b128 v[44:47], v208 offset:1024
	ds_read_b128 v[56:59], v208 offset:2048
	ds_read_b128 v[60:63], v208 offset:3072
	ds_read_b128 v[144:147], v209
	ds_read_b128 v[148:151], v209 offset:1024
	ds_read_b128 v[152:155], v209 offset:2048
	ds_read_b128 v[156:159], v209 offset:3072
	s_add_u32 s62, s56, 0xfffc0080
	s_addc_u32 s63, s57, -1
	s_cmp_eq_u32 s85, 12
	s_cselect_b32 s65, s7, s63
	s_cselect_b32 s64, s9, s62
	s_cselect_b32 s63, s39, s84
	s_cselect_b32 s62, s43, s83
	v_lshl_add_u64 v[218:219], s[56:57], 0, v[178:179]
	s_add_i32 m0, s69, 0xc000
	ds_read_b128 v[160:163], v210
	ds_read_b128 v[164:167], v210 offset:1024
	ds_read_b128 v[186:189], v210 offset:2048
	ds_read_b128 v[190:193], v210 offset:3072
	ds_read_b128 v[194:197], v210 offset:4096
	ds_read_b128 v[198:201], v210 offset:5120
	ds_read_b128 v[202:205], v210 offset:6144
	ds_read_b128 v[214:217], v210 offset:7168
	global_load_lds_dwordx4 v[218:219], off
	v_lshl_add_u64 v[218:219], s[56:57], 0, v[180:181]
	s_add_i32 m0, s69, 0xe000
	s_nop 0
	global_load_lds_dwordx4 v[218:219], off
	s_waitcnt vmcnt(8)
	s_waitcnt lgkmcnt(0)
	s_barrier
	s_setprio 1
	s_waitcnt lgkmcnt(0)
	v_mfma_f32_16x16x32_bf16 v[140:143], v[40:43], v[160:163], 0
	v_mfma_f32_16x16x32_bf16 v[136:139], v[56:59], v[160:163], 0
	v_mfma_f32_16x16x32_bf16 v[124:127], v[40:43], v[186:189], 0
	v_mfma_f32_16x16x32_bf16 v[120:123], v[56:59], v[186:189], 0
	v_mfma_f32_16x16x32_bf16 v[108:111], v[40:43], v[194:197], 0
	v_mfma_f32_16x16x32_bf16 v[104:107], v[56:59], v[194:197], 0
	v_mfma_f32_16x16x32_bf16 v[92:95], v[40:43], v[202:205], 0
	v_mfma_f32_16x16x32_bf16 v[88:91], v[56:59], v[202:205], 0
	v_mfma_f32_16x16x32_bf16 v[140:143], v[44:47], v[164:167], v[140:143]
	v_mfma_f32_16x16x32_bf16 v[136:139], v[60:63], v[164:167], v[136:139]
	v_mfma_f32_16x16x32_bf16 v[124:127], v[44:47], v[190:193], v[124:127]
	v_mfma_f32_16x16x32_bf16 v[120:123], v[60:63], v[190:193], v[120:123]
	v_mfma_f32_16x16x32_bf16 v[108:111], v[44:47], v[198:201], v[108:111]
	v_mfma_f32_16x16x32_bf16 v[104:107], v[60:63], v[198:201], v[104:107]
	v_mfma_f32_16x16x32_bf16 v[92:95], v[44:47], v[214:217], v[92:95]
	v_mfma_f32_16x16x32_bf16 v[88:91], v[60:63], v[214:217], v[88:91]
	v_mfma_f32_16x16x32_bf16 v[132:135], v[144:147], v[160:163], 0
	v_mfma_f32_16x16x32_bf16 v[128:131], v[152:155], v[160:163], 0
	v_mfma_f32_16x16x32_bf16 v[116:119], v[144:147], v[186:189], 0
	v_mfma_f32_16x16x32_bf16 v[112:115], v[152:155], v[186:189], 0
	v_mfma_f32_16x16x32_bf16 v[100:103], v[144:147], v[194:197], 0
	v_mfma_f32_16x16x32_bf16 v[96:99], v[152:155], v[194:197], 0
	v_mfma_f32_16x16x32_bf16 v[84:87], v[144:147], v[202:205], 0
	v_mfma_f32_16x16x32_bf16 v[80:83], v[152:155], v[202:205], 0
	v_mfma_f32_16x16x32_bf16 v[132:135], v[148:151], v[164:167], v[132:135]
	v_mfma_f32_16x16x32_bf16 v[128:131], v[156:159], v[164:167], v[128:131]
	v_mfma_f32_16x16x32_bf16 v[116:119], v[148:151], v[190:193], v[116:119]
	v_mfma_f32_16x16x32_bf16 v[112:115], v[156:159], v[190:193], v[112:115]
	v_mfma_f32_16x16x32_bf16 v[100:103], v[148:151], v[198:201], v[100:103]
	v_mfma_f32_16x16x32_bf16 v[96:99], v[156:159], v[198:201], v[96:99]
	v_mfma_f32_16x16x32_bf16 v[84:87], v[148:151], v[214:217], v[84:87]
	v_mfma_f32_16x16x32_bf16 v[80:83], v[156:159], v[214:217], v[80:83]
	s_setprio 0
	s_barrier
	s_add_i32 s86, s81, s68
	v_lshl_add_u64 v[218:219], s[62:63], 0, v[170:171]
	s_mov_b32 m0, s86
	ds_read_b128 v[160:163], v210 offset:16384
	ds_read_b128 v[164:167], v210 offset:17408
	ds_read_b128 v[186:189], v210 offset:18432
	ds_read_b128 v[190:193], v210 offset:19456
	ds_read_b128 v[194:197], v210 offset:20480
	ds_read_b128 v[198:201], v210 offset:21504
	ds_read_b128 v[202:205], v210 offset:22528
	ds_read_b128 v[214:217], v210 offset:23552
	global_load_lds_dwordx4 v[218:219], off
	s_add_i32 m0, s86, 0x2000
	s_add_u32 s86, s62, 0x40000
	v_lshl_add_u64 v[220:221], s[62:63], 0, v[174:175]
	s_addc_u32 s87, s63, 0
	s_add_i32 s88, s82, s68
	global_load_lds_dwordx4 v[220:221], off
	v_lshl_add_u64 v[222:223], s[86:87], 0, v[170:171]
	s_mov_b32 m0, s88
	v_lshl_add_u64 v[226:227], s[64:65], 0, v[172:173]
	global_load_lds_dwordx4 v[222:223], off
	v_lshl_add_u64 v[222:223], s[86:87], 0, v[174:175]
	s_add_i32 m0, s88, 0x2000
	s_nop 0
	global_load_lds_dwordx4 v[222:223], off
	v_lshl_add_u64 v[222:223], s[64:65], 0, v[168:169]
	s_mov_b32 m0, s69
	s_nop 0
	global_load_lds_dwordx4 v[222:223], off
	s_mov_b32 m0, s70
	s_nop 0
	global_load_lds_dwordx4 v[226:227], off
	s_waitcnt vmcnt(8)
	s_waitcnt lgkmcnt(0)
	s_barrier
; #define PG8_STAGE(bufoff, gbase, voff) do { _Pragma("unroll") for (int _i = 0; _i < 2; ++_i) \
;         __builtin_amdgcn_global_load_lds((const unsigned*)((const char*)(gbase) + (voff)[_i]), (LAS unsigned*)(lds + (bufoff) + ldsw + _i * 8192), 16, 0, 0); } while (0)
; #define PG8_LDA(dst, b, h) do { _Pragma("unroll") for (int m = 0; m < 4; ++m) _Pragma("unroll") for (int k = 0; k < 2; ++k) dst[m][k] = *(const LAS bf16x8*)(lds + PG8_SA(b, h) + aoff + m * 2048 + k * 1024); } while (0)
; #define PG8_LDB(dst, b, h) do { _Pragma("unroll") for (int n = 0; n < 2; ++n) _Pragma("unroll") for (int k = 0; k < 2; ++k) dst[n][k] = *(const LAS bf16x8*)(lds + PG8_SB(b, h) + boff + n * 2048 + k * 1024); } while (0)
; #define PG8_MMA(ai, bj, At, Bt) do { __builtin_amdgcn_s_setprio(1); _Pragma("unroll") for (int m = 0; m < 4; ++m) _Pragma("unroll") for (int n = 0; n < 2; ++n) _Pragma("unroll") for (int k = 0; k < 2; ++k) \
;         acc[ai][bj][m][n] = __builtin_amdgcn_mfma_f32_16x16x32_bf16(Bt[n][k], At[m][k], acc[ai][bj][m][n], 0, 0, 0); __builtin_amdgcn_s_setprio(0); } while (0)
; #define PG8_WAIT_V(n) asm volatile("s_waitcnt vmcnt(" #n ")" ::: "memory")
; #define PG8_WAIT_L(n) asm volatile("s_waitcnt lgkmcnt(" #n ")" ::: "memory")
; #define PG8_BAR __builtin_amdgcn_s_barrier()
; #define PG8_SCHED __builtin_amdgcn_sched_barrier(0)
; template <class Epi>
; __device__ __forceinline__ void gemm_phase(LAS unsigned char* lds, const Gemm g, const StaticOrder& S, const Epi& E) {
;     ...
;             PG8_WAIT_V(8); PG8_WAIT_L(0); PG8_BAR; PG8_MMA(1, 0, At, B0); PG8_MMA(1, 1, At, B1); PG8_BAR; PG8_SCHED;
;             PG8_LDB(B0, 1, 0); PG8_LDB(B1, 1, 1); PG8_SCHED; PG8_LDA(At, 1, 0); PG8_STAGE(PG8_SA(0, 1), a2 + hstepA, voffA);
;             PG8_WAIT_V(8); PG8_WAIT_L(0); PG8_BAR; PG8_MMA(0, 0, At, B0); PG8_MMA(0, 1, At, B1); PG8_BAR; PG8_SCHED;
	s_setprio 1
	s_waitcnt lgkmcnt(0)
	v_mfma_f32_16x16x32_bf16 v[76:79], v[40:43], v[160:163], 0
	v_mfma_f32_16x16x32_bf16 v[72:75], v[56:59], v[160:163], 0
	v_mfma_f32_16x16x32_bf16 v[52:55], v[40:43], v[186:189], 0
	v_mfma_f32_16x16x32_bf16 v[48:51], v[56:59], v[186:189], 0
	v_mfma_f32_16x16x32_bf16 v[28:31], v[40:43], v[194:197], 0
	v_mfma_f32_16x16x32_bf16 v[24:27], v[56:59], v[194:197], 0
	v_mfma_f32_16x16x32_bf16 v[12:15], v[40:43], v[202:205], 0
	v_mfma_f32_16x16x32_bf16 v[8:11], v[56:59], v[202:205], 0
	v_mfma_f32_16x16x32_bf16 v[76:79], v[44:47], v[164:167], v[76:79]
	v_mfma_f32_16x16x32_bf16 v[72:75], v[60:63], v[164:167], v[72:75]
	v_mfma_f32_16x16x32_bf16 v[52:55], v[44:47], v[190:193], v[52:55]
	v_mfma_f32_16x16x32_bf16 v[48:51], v[60:63], v[190:193], v[48:51]
	v_mfma_f32_16x16x32_bf16 v[28:31], v[44:47], v[198:201], v[28:31]
	v_mfma_f32_16x16x32_bf16 v[24:27], v[60:63], v[198:201], v[24:27]
	v_mfma_f32_16x16x32_bf16 v[12:15], v[44:47], v[214:217], v[12:15]
	v_mfma_f32_16x16x32_bf16 v[8:11], v[60:63], v[214:217], v[8:11]
	v_mfma_f32_16x16x32_bf16 v[36:39], v[144:147], v[186:189], 0
	v_mfma_f32_16x16x32_bf16 v[32:35], v[152:155], v[186:189], 0
	v_mfma_f32_16x16x32_bf16 v[20:23], v[144:147], v[194:197], 0
	v_mfma_f32_16x16x32_bf16 v[16:19], v[152:155], v[194:197], 0
	v_mfma_f32_16x16x32_bf16 v[4:7], v[144:147], v[202:205], 0
	v_mfma_f32_16x16x32_bf16 v[0:3], v[152:155], v[202:205], 0
	v_mfma_f32_16x16x32_bf16 v[40:43], v[144:147], v[160:163], 0
	v_mfma_f32_16x16x32_bf16 v[44:47], v[152:155], v[160:163], 0
	v_mfma_f32_16x16x32_bf16 v[36:39], v[148:151], v[190:193], v[36:39]
	v_mfma_f32_16x16x32_bf16 v[32:35], v[156:159], v[190:193], v[32:35]
	v_mfma_f32_16x16x32_bf16 v[20:23], v[148:151], v[198:201], v[20:23]
	v_mfma_f32_16x16x32_bf16 v[16:19], v[156:159], v[198:201], v[16:19]
	v_mfma_f32_16x16x32_bf16 v[4:7], v[148:151], v[214:217], v[4:7]
	v_mfma_f32_16x16x32_bf16 v[0:3], v[156:159], v[214:217], v[0:3]
	v_mfma_f32_16x16x32_bf16 v[40:43], v[148:151], v[164:167], v[40:43]
	v_mfma_f32_16x16x32_bf16 v[44:47], v[156:159], v[164:167], v[44:47]
	s_setprio 0
	s_barrier
	s_add_i32 s86, 0, 0x18000
	s_add_i32 s87, 0, 0x1c000
	v_add_u32_e32 v68, s86, v207
	v_add_u32_e32 v156, s87, v207
	ds_read_b128 v[56:59], v68
	ds_read_b128 v[60:63], v68 offset:1024
	ds_read_b128 v[64:67], v68 offset:2048
	ds_read_b128 v[68:71], v68 offset:3072
	ds_read_b128 v[144:147], v156
	ds_read_b128 v[148:151], v156 offset:1024
	ds_read_b128 v[152:155], v156 offset:2048
	ds_read_b128 v[156:159], v156 offset:3072
	s_add_u32 s64, s64, 0x40000
	s_addc_u32 s65, s65, 0
	s_mov_b32 m0, s71
	v_lshl_add_u64 v[228:229], s[64:65], 0, v[168:169]
	ds_read_b128 v[160:163], v210 offset:32768
	ds_read_b128 v[164:167], v210 offset:33792
	ds_read_b128 v[186:189], v210 offset:34816
	ds_read_b128 v[190:193], v210 offset:35840
	ds_read_b128 v[194:197], v210 offset:36864
	ds_read_b128 v[198:201], v210 offset:37888
	ds_read_b128 v[202:205], v210 offset:38912
	ds_read_b128 v[214:217], v210 offset:39936
	global_load_lds_dwordx4 v[228:229], off
	v_lshl_add_u64 v[228:229], s[64:65], 0, v[172:173]
	s_mov_b32 m0, s72
	s_nop 0
	global_load_lds_dwordx4 v[228:229], off
	s_waitcnt vmcnt(8)
	s_waitcnt lgkmcnt(0)
	s_barrier
	s_setprio 1
	s_waitcnt lgkmcnt(0)
	v_mfma_f32_16x16x32_bf16 v[140:143], v[56:59], v[160:163], v[140:143]
	v_mfma_f32_16x16x32_bf16 v[136:139], v[64:67], v[160:163], v[136:139]
	v_mfma_f32_16x16x32_bf16 v[124:127], v[56:59], v[186:189], v[124:127]
	v_mfma_f32_16x16x32_bf16 v[120:123], v[64:67], v[186:189], v[120:123]
	v_mfma_f32_16x16x32_bf16 v[108:111], v[56:59], v[194:197], v[108:111]
	v_mfma_f32_16x16x32_bf16 v[104:107], v[64:67], v[194:197], v[104:107]
	v_mfma_f32_16x16x32_bf16 v[92:95], v[56:59], v[202:205], v[92:95]
	v_mfma_f32_16x16x32_bf16 v[88:91], v[64:67], v[202:205], v[88:91]
	v_mfma_f32_16x16x32_bf16 v[140:143], v[60:63], v[164:167], v[140:143]
	v_mfma_f32_16x16x32_bf16 v[136:139], v[68:71], v[164:167], v[136:139]
	v_mfma_f32_16x16x32_bf16 v[124:127], v[60:63], v[190:193], v[124:127]
	v_mfma_f32_16x16x32_bf16 v[120:123], v[68:71], v[190:193], v[120:123]
	v_mfma_f32_16x16x32_bf16 v[108:111], v[60:63], v[198:201], v[108:111]
	v_mfma_f32_16x16x32_bf16 v[104:107], v[68:71], v[198:201], v[104:107]
	v_mfma_f32_16x16x32_bf16 v[92:95], v[60:63], v[214:217], v[92:95]
	v_mfma_f32_16x16x32_bf16 v[88:91], v[68:71], v[214:217], v[88:91]
	v_mfma_f32_16x16x32_bf16 v[132:135], v[144:147], v[160:163], v[132:135]
	v_mfma_f32_16x16x32_bf16 v[128:131], v[152:155], v[160:163], v[128:131]
	v_mfma_f32_16x16x32_bf16 v[116:119], v[144:147], v[186:189], v[116:119]
	v_mfma_f32_16x16x32_bf16 v[112:115], v[152:155], v[186:189], v[112:115]
	v_mfma_f32_16x16x32_bf16 v[100:103], v[144:147], v[194:197], v[100:103]
	v_mfma_f32_16x16x32_bf16 v[96:99], v[152:155], v[194:197], v[96:99]
	v_mfma_f32_16x16x32_bf16 v[84:87], v[144:147], v[202:205], v[84:87]
	v_mfma_f32_16x16x32_bf16 v[80:83], v[152:155], v[202:205], v[80:83]
	v_mfma_f32_16x16x32_bf16 v[132:135], v[148:151], v[164:167], v[132:135]
	v_mfma_f32_16x16x32_bf16 v[128:131], v[156:159], v[164:167], v[128:131]
	v_mfma_f32_16x16x32_bf16 v[116:119], v[148:151], v[190:193], v[116:119]
	v_mfma_f32_16x16x32_bf16 v[112:115], v[156:159], v[190:193], v[112:115]
	v_mfma_f32_16x16x32_bf16 v[100:103], v[148:151], v[198:201], v[100:103]
	v_mfma_f32_16x16x32_bf16 v[96:99], v[156:159], v[198:201], v[96:99]
	v_mfma_f32_16x16x32_bf16 v[84:87], v[148:151], v[214:217], v[84:87]
	v_mfma_f32_16x16x32_bf16 v[80:83], v[156:159], v[214:217], v[80:83]
	s_setprio 0
	s_barrier
; #define PG8_STAGE(bufoff, gbase, voff) do { _Pragma("unroll") for (int _i = 0; _i < 2; ++_i) \
;         __builtin_amdgcn_global_load_lds((const unsigned*)((const char*)(gbase) + (voff)[_i]), (LAS unsigned*)(lds + (bufoff) + ldsw + _i * 8192), 16, 0, 0); } while (0)
; #define PG8_LDA(dst, b, h) do { _Pragma("unroll") for (int m = 0; m < 4; ++m) _Pragma("unroll") for (int k = 0; k < 2; ++k) dst[m][k] = *(const LAS bf16x8*)(lds + PG8_SA(b, h) + aoff + m * 2048 + k * 1024); } while (0)
; #define PG8_LDB(dst, b, h) do { _Pragma("unroll") for (int n = 0; n < 2; ++n) _Pragma("unroll") for (int k = 0; k < 2; ++k) dst[n][k] = *(const LAS bf16x8*)(lds + PG8_SB(b, h) + boff + n * 2048 + k * 1024); } while (0)
; #define PG8_MMA(ai, bj, At, Bt) do { __builtin_amdgcn_s_setprio(1); _Pragma("unroll") for (int m = 0; m < 4; ++m) _Pragma("unroll") for (int n = 0; n < 2; ++n) _Pragma("unroll") for (int k = 0; k < 2; ++k) \
;         acc[ai][bj][m][n] = __builtin_amdgcn_mfma_f32_16x16x32_bf16(Bt[n][k], At[m][k], acc[ai][bj][m][n], 0, 0, 0); __builtin_amdgcn_s_setprio(0); } while (0)
; #define PG8_WAIT_V(n) asm volatile("s_waitcnt vmcnt(" #n ")" ::: "memory")
; #define PG8_WAIT_L(n) asm volatile("s_waitcnt lgkmcnt(" #n ")" ::: "memory")
; #define PG8_BAR __builtin_amdgcn_s_barrier()
; #define PG8_SCHED __builtin_amdgcn_sched_barrier(0)
; template <class Epi>
; __device__ __forceinline__ void gemm_phase(LAS unsigned char* lds, const Gemm g, const StaticOrder& S, const Epi& E) {
;     ...
;             PG8_LDB(B0, 0, 0); PG8_LDB(B1, 0, 1); PG8_SCHED; PG8_LDA(At, 0, 0); PG8_STAGE(PG8_SA(1, 1), a1 + hstepA, voffA);
;     ...
;             PG8_LDA(At, 1, 1); PG8_STAGE(PG8_SB(1, 0), b3, voffB); PG8_STAGE(PG8_SB(1, 1), b3 + hstepB, voffB); PG8_STAGE(PG8_SA(1, 0), a3, voffA);
;             PG8_WAIT_V(8); PG8_WAIT_L(0); PG8_BAR; PG8_MMA(1, 0, At, B0); PG8_MMA(1, 1, At, B1); PG8_BAR; PG8_SCHED;
	s_add_i32 s64, s86, s68
	v_lshl_add_u64 v[218:219], v[218:219], 0, s[18:19]
	s_mov_b32 m0, s64
	ds_read_b128 v[160:163], v210 offset:49152
	ds_read_b128 v[164:167], v210 offset:50176
	ds_read_b128 v[186:189], v210 offset:51200
	ds_read_b128 v[190:193], v210 offset:52224
	ds_read_b128 v[194:197], v210 offset:53248
	ds_read_b128 v[198:201], v210 offset:54272
	ds_read_b128 v[202:205], v210 offset:55296
	ds_read_b128 v[214:217], v210 offset:56320
	global_load_lds_dwordx4 v[218:219], off
	s_add_i32 m0, s64, 0x2000
	s_add_u32 s62, s62, 0x40080
	v_lshl_add_u64 v[218:219], v[220:221], 0, s[18:19]
	s_addc_u32 s63, s63, 0
	s_add_i32 s64, s87, s68
	global_load_lds_dwordx4 v[218:219], off
	v_lshl_add_u64 v[218:219], s[62:63], 0, v[170:171]
	s_mov_b32 m0, s64
	s_nop 0
	global_load_lds_dwordx4 v[218:219], off
	v_lshl_add_u64 v[218:219], s[62:63], 0, v[174:175]
	s_add_i32 m0, s64, 0x2000
	s_nop 0
	global_load_lds_dwordx4 v[218:219], off
	v_lshl_add_u64 v[218:219], v[222:223], 0, s[18:19]
	s_mov_b32 m0, s76
	s_nop 0
	global_load_lds_dwordx4 v[218:219], off
	v_lshl_add_u64 v[218:219], v[226:227], 0, s[18:19]
	s_mov_b32 m0, s77
	s_nop 0
	global_load_lds_dwordx4 v[218:219], off
	s_waitcnt vmcnt(8)
	s_waitcnt lgkmcnt(0)
	s_barrier
	s_setprio 1
	s_waitcnt lgkmcnt(0)
	v_mfma_f32_16x16x32_bf16 v[76:79], v[56:59], v[160:163], v[76:79]
	v_mfma_f32_16x16x32_bf16 v[72:75], v[64:67], v[160:163], v[72:75]
	v_mfma_f32_16x16x32_bf16 v[52:55], v[56:59], v[186:189], v[52:55]
	v_mfma_f32_16x16x32_bf16 v[48:51], v[64:67], v[186:189], v[48:51]
	v_mfma_f32_16x16x32_bf16 v[28:31], v[56:59], v[194:197], v[28:31]
	v_mfma_f32_16x16x32_bf16 v[24:27], v[64:67], v[194:197], v[24:27]
	v_mfma_f32_16x16x32_bf16 v[12:15], v[56:59], v[202:205], v[12:15]
	v_mfma_f32_16x16x32_bf16 v[8:11], v[64:67], v[202:205], v[8:11]
	v_mfma_f32_16x16x32_bf16 v[76:79], v[60:63], v[164:167], v[76:79]
	v_mfma_f32_16x16x32_bf16 v[72:75], v[68:71], v[164:167], v[72:75]
	v_mfma_f32_16x16x32_bf16 v[52:55], v[60:63], v[190:193], v[52:55]
	v_mfma_f32_16x16x32_bf16 v[48:51], v[68:71], v[190:193], v[48:51]
	v_mfma_f32_16x16x32_bf16 v[28:31], v[60:63], v[198:201], v[28:31]
	v_mfma_f32_16x16x32_bf16 v[24:27], v[68:71], v[198:201], v[24:27]
	v_mfma_f32_16x16x32_bf16 v[12:15], v[60:63], v[214:217], v[12:15]
	v_mfma_f32_16x16x32_bf16 v[8:11], v[68:71], v[214:217], v[8:11]
	v_mfma_f32_16x16x32_bf16 v[40:43], v[144:147], v[160:163], v[40:43]
	v_mfma_f32_16x16x32_bf16 v[68:71], v[148:151], v[164:167], v[40:43]
	v_mfma_f32_16x16x32_bf16 v[40:43], v[152:155], v[160:163], v[44:47]
	v_mfma_f32_16x16x32_bf16 v[36:39], v[144:147], v[186:189], v[36:39]
	v_mfma_f32_16x16x32_bf16 v[32:35], v[152:155], v[186:189], v[32:35]
	v_mfma_f32_16x16x32_bf16 v[20:23], v[144:147], v[194:197], v[20:23]
	v_mfma_f32_16x16x32_bf16 v[16:19], v[152:155], v[194:197], v[16:19]
	v_mfma_f32_16x16x32_bf16 v[4:7], v[144:147], v[202:205], v[4:7]
	v_mfma_f32_16x16x32_bf16 v[0:3], v[152:155], v[202:205], v[0:3]
	v_mfma_f32_16x16x32_bf16 v[64:67], v[156:159], v[164:167], v[40:43]
	v_mfma_f32_16x16x32_bf16 v[36:39], v[148:151], v[190:193], v[36:39]
	v_mfma_f32_16x16x32_bf16 v[32:35], v[156:159], v[190:193], v[32:35]
	v_mfma_f32_16x16x32_bf16 v[20:23], v[148:151], v[198:201], v[20:23]
	v_mfma_f32_16x16x32_bf16 v[16:19], v[156:159], v[198:201], v[16:19]
	v_mfma_f32_16x16x32_bf16 v[4:7], v[148:151], v[214:217], v[4:7]
	v_mfma_f32_16x16x32_bf16 v[0:3], v[156:159], v[214:217], v[0:3]
	s_setprio 0
	s_barrier
	s_add_i32 s85, s85, 2
	s_add_u32 s56, s56, 0x100
	s_addc_u32 s57, s57, 0
	s_add_u32 s83, s83, 0x100
	s_addc_u32 s84, s84, 0
	s_cmp_gt_u32 s85, 13
.LBB0_889:
	ds_read_b128 v[40:43], v208
	ds_read_b128 v[44:47], v208 offset:1024
	ds_read_b128 v[56:59], v208 offset:2048
	ds_read_b128 v[60:63], v208 offset:3072
	ds_read_b128 v[144:147], v209
	ds_read_b128 v[148:151], v209 offset:1024
	ds_read_b128 v[152:155], v209 offset:2048
	ds_read_b128 v[156:159], v209 offset:3072
	s_add_u32 s62, s56, 0xfffc0080
	s_addc_u32 s63, s57, -1
	s_cmp_eq_u32 s85, 12
	s_cselect_b32 s65, s7, s63
	s_cselect_b32 s64, s9, s62
	s_cselect_b32 s63, s39, s84
	s_cselect_b32 s62, s43, s83
	v_lshl_add_u64 v[218:219], s[56:57], 0, v[178:179]
	s_add_i32 m0, s69, 0xc000
	ds_read_b128 v[160:163], v210
	ds_read_b128 v[164:167], v210 offset:1024
	ds_read_b128 v[186:189], v210 offset:2048
	ds_read_b128 v[190:193], v210 offset:3072
	ds_read_b128 v[194:197], v210 offset:4096
	ds_read_b128 v[198:201], v210 offset:5120
	ds_read_b128 v[202:205], v210 offset:6144
	ds_read_b128 v[214:217], v210 offset:7168
	global_load_lds_dwordx4 v[218:219], off
	v_lshl_add_u64 v[218:219], s[56:57], 0, v[180:181]
	s_add_i32 m0, s69, 0xe000
	s_nop 0
	global_load_lds_dwordx4 v[218:219], off
	s_waitcnt vmcnt(8)
	s_waitcnt lgkmcnt(0)
	s_barrier
; #define PG8_STAGE(bufoff, gbase, voff) do { _Pragma("unroll") for (int _i = 0; _i < 2; ++_i) \
;         __builtin_amdgcn_global_load_lds((const unsigned*)((const char*)(gbase) + (voff)[_i]), (LAS unsigned*)(lds + (bufoff) + ldsw + _i * 8192), 16, 0, 0); } while (0)
; #define PG8_LDA(dst, b, h) do { _Pragma("unroll") for (int m = 0; m < 4; ++m) _Pragma("unroll") for (int k = 0; k < 2; ++k) dst[m][k] = *(const LAS bf16x8*)(lds + PG8_SA(b, h) + aoff + m * 2048 + k * 1024); } while (0)
; #define PG8_MMA(ai, bj, At, Bt) do { __builtin_amdgcn_s_setprio(1); _Pragma("unroll") for (int m = 0; m < 4; ++m) _Pragma("unroll") for (int n = 0; n < 2; ++n) _Pragma("unroll") for (int k = 0; k < 2; ++k) \
;         acc[ai][bj][m][n] = __builtin_amdgcn_mfma_f32_16x16x32_bf16(Bt[n][k], At[m][k], acc[ai][bj][m][n], 0, 0, 0); __builtin_amdgcn_s_setprio(0); } while (0)
; #define PG8_WAIT_V(n) asm volatile("s_waitcnt vmcnt(" #n ")" ::: "memory")
; #define PG8_WAIT_L(n) asm volatile("s_waitcnt lgkmcnt(" #n ")" ::: "memory")
; #define PG8_BAR __builtin_amdgcn_s_barrier()
; #define PG8_SCHED __builtin_amdgcn_sched_barrier(0)
; template <class Epi>
; __device__ __forceinline__ void gemm_phase(LAS unsigned char* lds, const Gemm g, const StaticOrder& S, const Epi& E) {
;     ...
;             PG8_WAIT_V(8); PG8_WAIT_L(0); PG8_BAR; PG8_MMA(0, 0, At, B0); PG8_MMA(0, 1, At, B1); PG8_BAR; PG8_SCHED;
;             PG8_LDA(At, 0, 1); PG8_STAGE(PG8_SB(0, 0), b2, voffB); PG8_STAGE(PG8_SB(0, 1), b2 + hstepB, voffB); PG8_STAGE(PG8_SA(0, 0), a2, voffA);
;             PG8_WAIT_V(8); PG8_WAIT_L(0); PG8_BAR; PG8_MMA(1, 0, At, B0); PG8_MMA(1, 1, At, B1); PG8_BAR; PG8_SCHED;
	s_setprio 1
	s_waitcnt lgkmcnt(0)
	v_mfma_f32_16x16x32_bf16 v[140:143], v[40:43], v[160:163], v[140:143]
	v_mfma_f32_16x16x32_bf16 v[136:139], v[56:59], v[160:163], v[136:139]
	v_mfma_f32_16x16x32_bf16 v[124:127], v[40:43], v[186:189], v[124:127]
	v_mfma_f32_16x16x32_bf16 v[120:123], v[56:59], v[186:189], v[120:123]
	v_mfma_f32_16x16x32_bf16 v[108:111], v[40:43], v[194:197], v[108:111]
	v_mfma_f32_16x16x32_bf16 v[104:107], v[56:59], v[194:197], v[104:107]
	v_mfma_f32_16x16x32_bf16 v[92:95], v[40:43], v[202:205], v[92:95]
	v_mfma_f32_16x16x32_bf16 v[88:91], v[56:59], v[202:205], v[88:91]
	v_mfma_f32_16x16x32_bf16 v[140:143], v[44:47], v[164:167], v[140:143]
	v_mfma_f32_16x16x32_bf16 v[136:139], v[60:63], v[164:167], v[136:139]
	v_mfma_f32_16x16x32_bf16 v[124:127], v[44:47], v[190:193], v[124:127]
	v_mfma_f32_16x16x32_bf16 v[120:123], v[60:63], v[190:193], v[120:123]
	v_mfma_f32_16x16x32_bf16 v[108:111], v[44:47], v[198:201], v[108:111]
	v_mfma_f32_16x16x32_bf16 v[104:107], v[60:63], v[198:201], v[104:107]
	v_mfma_f32_16x16x32_bf16 v[92:95], v[44:47], v[214:217], v[92:95]
	v_mfma_f32_16x16x32_bf16 v[88:91], v[60:63], v[214:217], v[88:91]
	v_mfma_f32_16x16x32_bf16 v[132:135], v[144:147], v[160:163], v[132:135]
	v_mfma_f32_16x16x32_bf16 v[128:131], v[152:155], v[160:163], v[128:131]
	v_mfma_f32_16x16x32_bf16 v[116:119], v[144:147], v[186:189], v[116:119]
	v_mfma_f32_16x16x32_bf16 v[112:115], v[152:155], v[186:189], v[112:115]
	v_mfma_f32_16x16x32_bf16 v[100:103], v[144:147], v[194:197], v[100:103]
	v_mfma_f32_16x16x32_bf16 v[96:99], v[152:155], v[194:197], v[96:99]
	v_mfma_f32_16x16x32_bf16 v[84:87], v[144:147], v[202:205], v[84:87]
	v_mfma_f32_16x16x32_bf16 v[80:83], v[152:155], v[202:205], v[80:83]
	v_mfma_f32_16x16x32_bf16 v[132:135], v[148:151], v[164:167], v[132:135]
	v_mfma_f32_16x16x32_bf16 v[128:131], v[156:159], v[164:167], v[128:131]
	v_mfma_f32_16x16x32_bf16 v[116:119], v[148:151], v[190:193], v[116:119]
	v_mfma_f32_16x16x32_bf16 v[112:115], v[156:159], v[190:193], v[112:115]
	v_mfma_f32_16x16x32_bf16 v[100:103], v[148:151], v[198:201], v[100:103]
	v_mfma_f32_16x16x32_bf16 v[96:99], v[156:159], v[198:201], v[96:99]
	v_mfma_f32_16x16x32_bf16 v[84:87], v[148:151], v[214:217], v[84:87]
	v_mfma_f32_16x16x32_bf16 v[80:83], v[156:159], v[214:217], v[80:83]
	s_setprio 0
	s_barrier
	s_add_i32 s86, s81, s68
	v_lshl_add_u64 v[218:219], s[62:63], 0, v[170:171]
	s_mov_b32 m0, s86
	ds_read_b128 v[160:163], v210 offset:16384
	ds_read_b128 v[164:167], v210 offset:17408
	ds_read_b128 v[186:189], v210 offset:18432
	ds_read_b128 v[190:193], v210 offset:19456
	ds_read_b128 v[194:197], v210 offset:20480
	ds_read_b128 v[198:201], v210 offset:21504
	ds_read_b128 v[202:205], v210 offset:22528
	ds_read_b128 v[214:217], v210 offset:23552
	global_load_lds_dwordx4 v[218:219], off
	s_add_i32 m0, s86, 0x2000
	s_add_u32 s86, s62, 0x40000
	v_lshl_add_u64 v[220:221], s[62:63], 0, v[174:175]
	s_addc_u32 s87, s63, 0
	s_add_i32 s88, s82, s68
	global_load_lds_dwordx4 v[220:221], off
	v_lshl_add_u64 v[222:223], s[86:87], 0, v[170:171]
	s_mov_b32 m0, s88
	v_lshl_add_u64 v[226:227], s[64:65], 0, v[172:173]
	global_load_lds_dwordx4 v[222:223], off
	v_lshl_add_u64 v[222:223], s[86:87], 0, v[174:175]
	s_add_i32 m0, s88, 0x2000
	s_nop 0
	global_load_lds_dwordx4 v[222:223], off
	v_lshl_add_u64 v[222:223], s[64:65], 0, v[168:169]
	s_mov_b32 m0, s69
	s_nop 0
	global_load_lds_dwordx4 v[222:223], off
	s_mov_b32 m0, s70
	s_nop 0
	global_load_lds_dwordx4 v[226:227], off
	s_waitcnt vmcnt(8)
	s_waitcnt lgkmcnt(0)
	s_barrier
	s_setprio 1
	s_waitcnt lgkmcnt(0)
	v_mfma_f32_16x16x32_bf16 v[76:79], v[40:43], v[160:163], v[76:79]
	v_mfma_f32_16x16x32_bf16 v[72:75], v[56:59], v[160:163], v[72:75]
	v_mfma_f32_16x16x32_bf16 v[52:55], v[40:43], v[186:189], v[52:55]
	v_mfma_f32_16x16x32_bf16 v[48:51], v[56:59], v[186:189], v[48:51]
	v_mfma_f32_16x16x32_bf16 v[28:31], v[40:43], v[194:197], v[28:31]
	v_mfma_f32_16x16x32_bf16 v[24:27], v[56:59], v[194:197], v[24:27]
	v_mfma_f32_16x16x32_bf16 v[12:15], v[40:43], v[202:205], v[12:15]
	v_mfma_f32_16x16x32_bf16 v[8:11], v[56:59], v[202:205], v[8:11]
	v_mfma_f32_16x16x32_bf16 v[76:79], v[44:47], v[164:167], v[76:79]
	v_mfma_f32_16x16x32_bf16 v[72:75], v[60:63], v[164:167], v[72:75]
	v_mfma_f32_16x16x32_bf16 v[52:55], v[44:47], v[190:193], v[52:55]
	v_mfma_f32_16x16x32_bf16 v[48:51], v[60:63], v[190:193], v[48:51]
	v_mfma_f32_16x16x32_bf16 v[28:31], v[44:47], v[198:201], v[28:31]
	v_mfma_f32_16x16x32_bf16 v[24:27], v[60:63], v[198:201], v[24:27]
	v_mfma_f32_16x16x32_bf16 v[12:15], v[44:47], v[214:217], v[12:15]
	v_mfma_f32_16x16x32_bf16 v[8:11], v[60:63], v[214:217], v[8:11]
	v_mfma_f32_16x16x32_bf16 v[36:39], v[144:147], v[186:189], v[36:39]
	v_mfma_f32_16x16x32_bf16 v[32:35], v[152:155], v[186:189], v[32:35]
	v_mfma_f32_16x16x32_bf16 v[20:23], v[144:147], v[194:197], v[20:23]
	v_mfma_f32_16x16x32_bf16 v[16:19], v[152:155], v[194:197], v[16:19]
	v_mfma_f32_16x16x32_bf16 v[4:7], v[144:147], v[202:205], v[4:7]
	v_mfma_f32_16x16x32_bf16 v[0:3], v[152:155], v[202:205], v[0:3]
	v_mfma_f32_16x16x32_bf16 v[40:43], v[144:147], v[160:163], v[68:71]
	v_mfma_f32_16x16x32_bf16 v[44:47], v[152:155], v[160:163], v[64:67]
	v_mfma_f32_16x16x32_bf16 v[36:39], v[148:151], v[190:193], v[36:39]
	v_mfma_f32_16x16x32_bf16 v[32:35], v[156:159], v[190:193], v[32:35]
	v_mfma_f32_16x16x32_bf16 v[20:23], v[148:151], v[198:201], v[20:23]
	v_mfma_f32_16x16x32_bf16 v[16:19], v[156:159], v[198:201], v[16:19]
	v_mfma_f32_16x16x32_bf16 v[4:7], v[148:151], v[214:217], v[4:7]
	v_mfma_f32_16x16x32_bf16 v[0:3], v[156:159], v[214:217], v[0:3]
	v_mfma_f32_16x16x32_bf16 v[40:43], v[148:151], v[164:167], v[40:43]
	v_mfma_f32_16x16x32_bf16 v[44:47], v[156:159], v[164:167], v[44:47]
	s_setprio 0
	s_barrier
; #define PG8_STAGE(bufoff, gbase, voff) do { _Pragma("unroll") for (int _i = 0; _i < 2; ++_i) \
;         __builtin_amdgcn_global_load_lds((const unsigned*)((const char*)(gbase) + (voff)[_i]), (LAS unsigned*)(lds + (bufoff) + ldsw + _i * 8192), 16, 0, 0); } while (0)
; #define PG8_LDA(dst, b, h) do { _Pragma("unroll") for (int m = 0; m < 4; ++m) _Pragma("unroll") for (int k = 0; k < 2; ++k) dst[m][k] = *(const LAS bf16x8*)(lds + PG8_SA(b, h) + aoff + m * 2048 + k * 1024); } while (0)
; #define PG8_LDB(dst, b, h) do { _Pragma("unroll") for (int n = 0; n < 2; ++n) _Pragma("unroll") for (int k = 0; k < 2; ++k) dst[n][k] = *(const LAS bf16x8*)(lds + PG8_SB(b, h) + boff + n * 2048 + k * 1024); } while (0)
; #define PG8_MMA(ai, bj, At, Bt) do { __builtin_amdgcn_s_setprio(1); _Pragma("unroll") for (int m = 0; m < 4; ++m) _Pragma("unroll") for (int n = 0; n < 2; ++n) _Pragma("unroll") for (int k = 0; k < 2; ++k) \
;         acc[ai][bj][m][n] = __builtin_amdgcn_mfma_f32_16x16x32_bf16(Bt[n][k], At[m][k], acc[ai][bj][m][n], 0, 0, 0); __builtin_amdgcn_s_setprio(0); } while (0)
; #define PG8_WAIT_V(n) asm volatile("s_waitcnt vmcnt(" #n ")" ::: "memory")
; #define PG8_WAIT_L(n) asm volatile("s_waitcnt lgkmcnt(" #n ")" ::: "memory")
; #define PG8_BAR __builtin_amdgcn_s_barrier()
; #define PG8_SCHED __builtin_amdgcn_sched_barrier(0)
; template <class Epi>
; __device__ __forceinline__ void gemm_phase(LAS unsigned char* lds, const Gemm g, const StaticOrder& S, const Epi& E) {
;     ...
;             PG8_LDB(B0, 1, 0); PG8_LDB(B1, 1, 1); PG8_SCHED; PG8_LDA(At, 1, 0); PG8_STAGE(PG8_SA(0, 1), a2 + hstepA, voffA);
;             PG8_WAIT_V(8); PG8_WAIT_L(0); PG8_BAR; PG8_MMA(0, 0, At, B0); PG8_MMA(0, 1, At, B1); PG8_BAR; PG8_SCHED;
	s_add_i32 s86, 0, 0x18000
	s_add_i32 s87, 0, 0x1c000
	v_add_u32_e32 v68, s86, v207
	v_add_u32_e32 v156, s87, v207
	ds_read_b128 v[56:59], v68
	ds_read_b128 v[60:63], v68 offset:1024
	ds_read_b128 v[64:67], v68 offset:2048
	ds_read_b128 v[68:71], v68 offset:3072
	ds_read_b128 v[144:147], v156
	ds_read_b128 v[148:151], v156 offset:1024
	ds_read_b128 v[152:155], v156 offset:2048
	ds_read_b128 v[156:159], v156 offset:3072
	s_add_u32 s64, s64, 0x40000
	s_addc_u32 s65, s65, 0
	s_mov_b32 m0, s71
	v_lshl_add_u64 v[228:229], s[64:65], 0, v[168:169]
	ds_read_b128 v[160:163], v210 offset:32768
	ds_read_b128 v[164:167], v210 offset:33792
	ds_read_b128 v[186:189], v210 offset:34816
	ds_read_b128 v[190:193], v210 offset:35840
	ds_read_b128 v[194:197], v210 offset:36864
	ds_read_b128 v[198:201], v210 offset:37888
	ds_read_b128 v[202:205], v210 offset:38912
	ds_read_b128 v[214:217], v210 offset:39936
	global_load_lds_dwordx4 v[228:229], off
	v_lshl_add_u64 v[228:229], s[64:65], 0, v[172:173]
	s_mov_b32 m0, s72
	s_nop 0
	global_load_lds_dwordx4 v[228:229], off
	s_waitcnt vmcnt(8)
	s_waitcnt lgkmcnt(0)
	s_barrier
	s_setprio 1
	s_waitcnt lgkmcnt(0)
	v_mfma_f32_16x16x32_bf16 v[140:143], v[56:59], v[160:163], v[140:143]
	v_mfma_f32_16x16x32_bf16 v[136:139], v[64:67], v[160:163], v[136:139]
	v_mfma_f32_16x16x32_bf16 v[124:127], v[56:59], v[186:189], v[124:127]
	v_mfma_f32_16x16x32_bf16 v[120:123], v[64:67], v[186:189], v[120:123]
	v_mfma_f32_16x16x32_bf16 v[108:111], v[56:59], v[194:197], v[108:111]
	v_mfma_f32_16x16x32_bf16 v[104:107], v[64:67], v[194:197], v[104:107]
	v_mfma_f32_16x16x32_bf16 v[92:95], v[56:59], v[202:205], v[92:95]
	v_mfma_f32_16x16x32_bf16 v[88:91], v[64:67], v[202:205], v[88:91]
	v_mfma_f32_16x16x32_bf16 v[140:143], v[60:63], v[164:167], v[140:143]
	v_mfma_f32_16x16x32_bf16 v[136:139], v[68:71], v[164:167], v[136:139]
	v_mfma_f32_16x16x32_bf16 v[124:127], v[60:63], v[190:193], v[124:127]
	v_mfma_f32_16x16x32_bf16 v[120:123], v[68:71], v[190:193], v[120:123]
	v_mfma_f32_16x16x32_bf16 v[108:111], v[60:63], v[198:201], v[108:111]
	v_mfma_f32_16x16x32_bf16 v[104:107], v[68:71], v[198:201], v[104:107]
	v_mfma_f32_16x16x32_bf16 v[92:95], v[60:63], v[214:217], v[92:95]
	v_mfma_f32_16x16x32_bf16 v[88:91], v[68:71], v[214:217], v[88:91]
	v_mfma_f32_16x16x32_bf16 v[132:135], v[144:147], v[160:163], v[132:135]
	v_mfma_f32_16x16x32_bf16 v[128:131], v[152:155], v[160:163], v[128:131]
	v_mfma_f32_16x16x32_bf16 v[116:119], v[144:147], v[186:189], v[116:119]
	v_mfma_f32_16x16x32_bf16 v[112:115], v[152:155], v[186:189], v[112:115]
	v_mfma_f32_16x16x32_bf16 v[100:103], v[144:147], v[194:197], v[100:103]
	v_mfma_f32_16x16x32_bf16 v[96:99], v[152:155], v[194:197], v[96:99]
	v_mfma_f32_16x16x32_bf16 v[84:87], v[144:147], v[202:205], v[84:87]
	v_mfma_f32_16x16x32_bf16 v[80:83], v[152:155], v[202:205], v[80:83]
	v_mfma_f32_16x16x32_bf16 v[132:135], v[148:151], v[164:167], v[132:135]
	v_mfma_f32_16x16x32_bf16 v[128:131], v[156:159], v[164:167], v[128:131]
	v_mfma_f32_16x16x32_bf16 v[116:119], v[148:151], v[190:193], v[116:119]
	v_mfma_f32_16x16x32_bf16 v[112:115], v[156:159], v[190:193], v[112:115]
	v_mfma_f32_16x16x32_bf16 v[100:103], v[148:151], v[198:201], v[100:103]
	v_mfma_f32_16x16x32_bf16 v[96:99], v[156:159], v[198:201], v[96:99]
	v_mfma_f32_16x16x32_bf16 v[84:87], v[148:151], v[214:217], v[84:87]
	v_mfma_f32_16x16x32_bf16 v[80:83], v[156:159], v[214:217], v[80:83]
	s_setprio 0
	s_barrier
; #define PG8_STAGE(bufoff, gbase, voff) do { _Pragma("unroll") for (int _i = 0; _i < 2; ++_i) \
;         __builtin_amdgcn_global_load_lds((const unsigned*)((const char*)(gbase) + (voff)[_i]), (LAS unsigned*)(lds + (bufoff) + ldsw + _i * 8192), 16, 0, 0); } while (0)
; #define PG8_LDA(dst, b, h) do { _Pragma("unroll") for (int m = 0; m < 4; ++m) _Pragma("unroll") for (int k = 0; k < 2; ++k) dst[m][k] = *(const LAS bf16x8*)(lds + PG8_SA(b, h) + aoff + m * 2048 + k * 1024); } while (0)
; #define PG8_MMA(ai, bj, At, Bt) do { __builtin_amdgcn_s_setprio(1); _Pragma("unroll") for (int m = 0; m < 4; ++m) _Pragma("unroll") for (int n = 0; n < 2; ++n) _Pragma("unroll") for (int k = 0; k < 2; ++k) \
;         acc[ai][bj][m][n] = __builtin_amdgcn_mfma_f32_16x16x32_bf16(Bt[n][k], At[m][k], acc[ai][bj][m][n], 0, 0, 0); __builtin_amdgcn_s_setprio(0); } while (0)
; #define PG8_WAIT_V(n) asm volatile("s_waitcnt vmcnt(" #n ")" ::: "memory")
; #define PG8_WAIT_L(n) asm volatile("s_waitcnt lgkmcnt(" #n ")" ::: "memory")
; #define PG8_BAR __builtin_amdgcn_s_barrier()
; #define PG8_SCHED __builtin_amdgcn_sched_barrier(0)
; template <class Epi>
; __device__ __forceinline__ void gemm_phase(LAS unsigned char* lds, const Gemm g, const StaticOrder& S, const Epi& E) {
;     ...
;             PG8_LDA(At, 1, 1); PG8_STAGE(PG8_SB(1, 0), b3, voffB); PG8_STAGE(PG8_SB(1, 1), b3 + hstepB, voffB); PG8_STAGE(PG8_SA(1, 0), a3, voffA);
;             PG8_WAIT_V(8); PG8_WAIT_L(0); PG8_BAR; PG8_MMA(1, 0, At, B0); PG8_MMA(1, 1, At, B1); PG8_BAR; PG8_SCHED;
;         }
;         if (wr == 0) PG8_BAR;
	s_add_i32 s64, s86, s68
	v_lshl_add_u64 v[218:219], v[218:219], 0, s[18:19]
	s_mov_b32 m0, s64
	ds_read_b128 v[160:163], v210 offset:49152
	ds_read_b128 v[164:167], v210 offset:50176
	ds_read_b128 v[186:189], v210 offset:51200
	ds_read_b128 v[190:193], v210 offset:52224
	ds_read_b128 v[194:197], v210 offset:53248
	ds_read_b128 v[198:201], v210 offset:54272
	ds_read_b128 v[202:205], v210 offset:55296
	ds_read_b128 v[214:217], v210 offset:56320
	global_load_lds_dwordx4 v[218:219], off
	s_add_i32 m0, s64, 0x2000
	s_add_u32 s62, s62, 0x40080
	v_lshl_add_u64 v[218:219], v[220:221], 0, s[18:19]
	s_addc_u32 s63, s63, 0
	s_add_i32 s64, s87, s68
	global_load_lds_dwordx4 v[218:219], off
	v_lshl_add_u64 v[218:219], s[62:63], 0, v[170:171]
	s_mov_b32 m0, s64
	s_nop 0
	global_load_lds_dwordx4 v[218:219], off
	v_lshl_add_u64 v[218:219], s[62:63], 0, v[174:175]
	s_add_i32 m0, s64, 0x2000
	s_nop 0
	global_load_lds_dwordx4 v[218:219], off
	v_lshl_add_u64 v[218:219], v[222:223], 0, s[18:19]
	s_mov_b32 m0, s76
	s_nop 0
	global_load_lds_dwordx4 v[218:219], off
	v_lshl_add_u64 v[218:219], v[226:227], 0, s[18:19]
	s_mov_b32 m0, s77
	s_nop 0
	global_load_lds_dwordx4 v[218:219], off
	s_waitcnt vmcnt(8)
	s_waitcnt lgkmcnt(0)
	s_barrier
	s_setprio 1
	s_waitcnt lgkmcnt(0)
	v_mfma_f32_16x16x32_bf16 v[76:79], v[56:59], v[160:163], v[76:79]
	v_mfma_f32_16x16x32_bf16 v[72:75], v[64:67], v[160:163], v[72:75]
	v_mfma_f32_16x16x32_bf16 v[52:55], v[56:59], v[186:189], v[52:55]
	v_mfma_f32_16x16x32_bf16 v[48:51], v[64:67], v[186:189], v[48:51]
	v_mfma_f32_16x16x32_bf16 v[28:31], v[56:59], v[194:197], v[28:31]
	v_mfma_f32_16x16x32_bf16 v[24:27], v[64:67], v[194:197], v[24:27]
	v_mfma_f32_16x16x32_bf16 v[12:15], v[56:59], v[202:205], v[12:15]
	v_mfma_f32_16x16x32_bf16 v[8:11], v[64:67], v[202:205], v[8:11]
	v_mfma_f32_16x16x32_bf16 v[76:79], v[60:63], v[164:167], v[76:79]
	v_mfma_f32_16x16x32_bf16 v[72:75], v[68:71], v[164:167], v[72:75]
	v_mfma_f32_16x16x32_bf16 v[52:55], v[60:63], v[190:193], v[52:55]
	v_mfma_f32_16x16x32_bf16 v[48:51], v[68:71], v[190:193], v[48:51]
	v_mfma_f32_16x16x32_bf16 v[28:31], v[60:63], v[198:201], v[28:31]
	v_mfma_f32_16x16x32_bf16 v[24:27], v[68:71], v[198:201], v[24:27]
	v_mfma_f32_16x16x32_bf16 v[12:15], v[60:63], v[214:217], v[12:15]
	v_mfma_f32_16x16x32_bf16 v[8:11], v[68:71], v[214:217], v[8:11]
	v_mfma_f32_16x16x32_bf16 v[40:43], v[144:147], v[160:163], v[40:43]
	v_mfma_f32_16x16x32_bf16 v[68:71], v[148:151], v[164:167], v[40:43]
	v_mfma_f32_16x16x32_bf16 v[40:43], v[152:155], v[160:163], v[44:47]
	v_mfma_f32_16x16x32_bf16 v[36:39], v[144:147], v[186:189], v[36:39]
	v_mfma_f32_16x16x32_bf16 v[32:35], v[152:155], v[186:189], v[32:35]
	v_mfma_f32_16x16x32_bf16 v[20:23], v[144:147], v[194:197], v[20:23]
	v_mfma_f32_16x16x32_bf16 v[16:19], v[152:155], v[194:197], v[16:19]
	v_mfma_f32_16x16x32_bf16 v[4:7], v[144:147], v[202:205], v[4:7]
	v_mfma_f32_16x16x32_bf16 v[0:3], v[152:155], v[202:205], v[0:3]
	v_mfma_f32_16x16x32_bf16 v[64:67], v[156:159], v[164:167], v[40:43]
	v_mfma_f32_16x16x32_bf16 v[36:39], v[148:151], v[190:193], v[36:39]
	v_mfma_f32_16x16x32_bf16 v[32:35], v[156:159], v[190:193], v[32:35]
	v_mfma_f32_16x16x32_bf16 v[20:23], v[148:151], v[198:201], v[20:23]
	v_mfma_f32_16x16x32_bf16 v[16:19], v[156:159], v[198:201], v[16:19]
	v_mfma_f32_16x16x32_bf16 v[4:7], v[148:151], v[214:217], v[4:7]
	v_mfma_f32_16x16x32_bf16 v[0:3], v[156:159], v[214:217], v[0:3]
	s_setprio 0
	s_barrier
	s_add_i32 s85, s85, 2
	s_add_u32 s56, s56, 0x100
	s_addc_u32 s57, s57, 0
	s_add_u32 s83, s83, 0x100
	s_addc_u32 s84, s84, 0
	s_cmp_gt_u32 s85, 13
	s_cbranch_scc0 .LBB0_889
	s_and_b64 vcc, exec, s[22:23]
	s_cbranch_vccz .LBB0_892
	s_barrier

; #define PG8_STAGE(bufoff, gbase, voff) do { _Pragma("unroll") for (int _i = 0; _i < 2; ++_i) \
;         __builtin_amdgcn_global_load_lds((const unsigned*)((const char*)(gbase) + (voff)[_i]), (LAS unsigned*)(lds + (bufoff) + ldsw + _i * 8192), 16, 0, 0); } while (0)
; #define PG8_LDA(dst, b, h) do { _Pragma("unroll") for (int m = 0; m < 4; ++m) _Pragma("unroll") for (int k = 0; k < 2; ++k) dst[m][k] = *(const LAS bf16x8*)(lds + PG8_SA(b, h) + aoff + m * 2048 + k * 1024); } while (0)
; #define PG8_LDB(dst, b, h) do { _Pragma("unroll") for (int n = 0; n < 2; ++n) _Pragma("unroll") for (int k = 0; k < 2; ++k) dst[n][k] = *(const LAS bf16x8*)(lds + PG8_SB(b, h) + boff + n * 2048 + k * 1024); } while (0)
; #define PG8_MMA(ai, bj, At, Bt) do { __builtin_amdgcn_s_setprio(1); _Pragma("unroll") for (int m = 0; m < 4; ++m) _Pragma("unroll") for (int n = 0; n < 2; ++n) _Pragma("unroll") for (int k = 0; k < 2; ++k) \
;         acc[ai][bj][m][n] = __builtin_amdgcn_mfma_f32_16x16x32_bf16(Bt[n][k], At[m][k], acc[ai][bj][m][n], 0, 0, 0); __builtin_amdgcn_s_setprio(0); } while (0)
; #define PG8_BAR __builtin_amdgcn_s_barrier()
; template <class Epi>
; __device__ __forceinline__ void gemm_phase(LAS unsigned char* lds, const Gemm g, const StaticOrder& S, const Epi& E) {
;     ...
;         const bool has_next = S.next(ui + 1, nxt);
;         const char* nA = has_next ? (const char*)g.A + (size_t)nxt.pm * tstepA : cA; const char* nB = has_next ? (const char*)g.Bt + (size_t)nxt.pn * tstepB : cB;
; #pragma nounroll
;         for (int t = 0; t < nt; t += 2) {
;             const bool last = (t == nt - 2);
;             const char* a1 = cA + (size_t)(t + 1) * kstep;
;             const char* a2 = last ? nA : cA + (size_t)(t + 2) * kstep; const char* b2 = last ? nB : cB + (size_t)(t + 2) * kstep;
;             const char* a3 = a2 + kstep; const char* b3 = b2 + kstep;
;             PG8_LDB(B0, 0, 0); PG8_LDB(B1, 0, 1); PG8_SCHED; PG8_LDA(At, 0, 0); PG8_STAGE(PG8_SA(1, 1), a1 + hstepA, voffA);
;             PG8_WAIT_V(8); PG8_WAIT_L(0); PG8_BAR; PG8_MMA(0, 0, At, B0); PG8_MMA(0, 1, At, B1); PG8_BAR; PG8_SCHED;
;             PG8_LDA(At, 0, 1); PG8_STAGE(PG8_SB(0, 0), b2, voffB); PG8_STAGE(PG8_SB(0, 1), b2 + hstepB, voffB); PG8_STAGE(PG8_SA(0, 0), a2, voffA);
;             PG8_WAIT_V(8); PG8_WAIT_L(0); PG8_BAR; PG8_MMA(1, 0, At, B0); PG8_MMA(1, 1, At, B1); PG8_BAR; PG8_SCHED;
.LBB0_1017:
	s_ashr_i32 s35, s34, 31
	s_lshl_b64 s[38:39], s[34:35], 19
	s_add_u32 s38, s24, s38
	s_addc_u32 s39, s25, s39
	s_and_b64 s[42:43], s[4:5], exec
	s_cselect_b32 s7, s39, s55
	s_cselect_b32 s35, s38, s54
	s_ashr_i32 s23, s22, 31
	s_lshl_b64 s[42:43], s[22:23], 19
	s_add_u32 s42, s33, s42
	s_addc_u32 s43, s64, s43
	s_and_b64 s[62:63], s[4:5], exec
	s_cselect_b32 s23, s43, s57
	s_cselect_b32 s53, s42, s56
	s_add_u32 s54, s54, 0x40080
	s_addc_u32 s55, s55, 0
	s_add_u32 s83, s56, 0x100
	s_nop 0
	s_addc_u32 s84, s57, 0
	s_mov_b32 s85, -2
	v_lshl_add_u32 v248, s6, 8, v227
	v_add_u32_e32 v248, s74, v248
	v_ashrrev_i32_e32 v249, 31, v248
	v_lshl_add_u64 v[248:249], v[248:249], 2, s[10:11]
	global_load_dword v240, v[248:249], off
	global_load_dword v241, v[248:249], off offset:64
	global_load_dword v242, v[248:249], off offset:128
	global_load_dword v243, v[248:249], off offset:192
	global_load_dword v244, v[248:249], off offset:512
	global_load_dword v245, v[248:249], off offset:576
	global_load_dword v246, v[248:249], off offset:640
	global_load_dword v247, v[248:249], off offset:704
	ds_read_b128 v[0:3], v230
	ds_read_b128 v[4:7], v230 offset:1024
	ds_read_b128 v[8:11], v230 offset:2048
	ds_read_b128 v[12:15], v230 offset:3072
	ds_read_b128 v[144:147], v231
	ds_read_b128 v[148:151], v231 offset:1024
	ds_read_b128 v[152:155], v231 offset:2048
	ds_read_b128 v[156:159], v231 offset:3072
	s_add_u32 s56, s54, 0xfffc0080
	s_addc_u32 s57, s55, -1
	s_cmp_eq_u32 s85, 12
	s_cselect_b32 s63, s7, s57
	s_cselect_b32 s62, s35, s56
	s_cselect_b32 s57, s23, s84
	s_cselect_b32 s56, s53, s83
	v_lshl_add_u64 v[212:213], s[54:55], 0, v[188:189]
	s_add_i32 m0, s68, 0xc000
	ds_read_b128 v[160:163], v232
	ds_read_b128 v[164:167], v232 offset:1024
	ds_read_b128 v[168:171], v232 offset:2048
	ds_read_b128 v[172:175], v232 offset:3072
	ds_read_b128 v[196:199], v232 offset:4096
	ds_read_b128 v[200:203], v232 offset:5120
	ds_read_b128 v[204:207], v232 offset:6144
	ds_read_b128 v[208:211], v232 offset:7168
	global_load_lds_dwordx4 v[212:213], off
	v_lshl_add_u64 v[212:213], s[54:55], 0, v[190:191]
	s_add_i32 m0, s68, 0xe000
	s_nop 0
	global_load_lds_dwordx4 v[212:213], off
	s_waitcnt vmcnt(8)
	s_waitcnt lgkmcnt(0)
	s_barrier
	s_setprio 1
	s_waitcnt lgkmcnt(0)
	v_mfma_f32_16x16x32_bf16 v[140:143], v[0:3], v[160:163], 0
	v_mfma_f32_16x16x32_bf16 v[132:135], v[8:11], v[160:163], 0
	v_mfma_f32_16x16x32_bf16 v[124:127], v[0:3], v[168:171], 0
	v_mfma_f32_16x16x32_bf16 v[120:123], v[8:11], v[168:171], 0
	v_mfma_f32_16x16x32_bf16 v[108:111], v[0:3], v[196:199], 0
	v_mfma_f32_16x16x32_bf16 v[104:107], v[8:11], v[196:199], 0
	v_mfma_f32_16x16x32_bf16 v[92:95], v[0:3], v[204:207], 0
	v_mfma_f32_16x16x32_bf16 v[88:91], v[8:11], v[204:207], 0
	v_mfma_f32_16x16x32_bf16 v[140:143], v[4:7], v[164:167], v[140:143]
	v_mfma_f32_16x16x32_bf16 v[132:135], v[12:15], v[164:167], v[132:135]
	v_mfma_f32_16x16x32_bf16 v[124:127], v[4:7], v[172:175], v[124:127]
	v_mfma_f32_16x16x32_bf16 v[120:123], v[12:15], v[172:175], v[120:123]
	v_mfma_f32_16x16x32_bf16 v[108:111], v[4:7], v[200:203], v[108:111]
	v_mfma_f32_16x16x32_bf16 v[104:107], v[12:15], v[200:203], v[104:107]
	v_mfma_f32_16x16x32_bf16 v[92:95], v[4:7], v[208:211], v[92:95]
	v_mfma_f32_16x16x32_bf16 v[88:91], v[12:15], v[208:211], v[88:91]
	v_mfma_f32_16x16x32_bf16 v[136:139], v[144:147], v[160:163], 0
	v_mfma_f32_16x16x32_bf16 v[128:131], v[152:155], v[160:163], 0
	v_mfma_f32_16x16x32_bf16 v[116:119], v[144:147], v[168:171], 0
	v_mfma_f32_16x16x32_bf16 v[112:115], v[152:155], v[168:171], 0
	v_mfma_f32_16x16x32_bf16 v[100:103], v[144:147], v[196:199], 0
	v_mfma_f32_16x16x32_bf16 v[96:99], v[152:155], v[196:199], 0
	v_mfma_f32_16x16x32_bf16 v[84:87], v[144:147], v[204:207], 0
	v_mfma_f32_16x16x32_bf16 v[80:83], v[152:155], v[204:207], 0
	v_mfma_f32_16x16x32_bf16 v[136:139], v[148:151], v[164:167], v[136:139]
	v_mfma_f32_16x16x32_bf16 v[128:131], v[156:159], v[164:167], v[128:131]
	v_mfma_f32_16x16x32_bf16 v[116:119], v[148:151], v[172:175], v[116:119]
	v_mfma_f32_16x16x32_bf16 v[112:115], v[156:159], v[172:175], v[112:115]
	v_mfma_f32_16x16x32_bf16 v[100:103], v[148:151], v[200:203], v[100:103]
	v_mfma_f32_16x16x32_bf16 v[96:99], v[156:159], v[200:203], v[96:99]
	v_mfma_f32_16x16x32_bf16 v[84:87], v[148:151], v[208:211], v[84:87]
	v_mfma_f32_16x16x32_bf16 v[80:83], v[156:159], v[208:211], v[80:83]
	s_setprio 0
	s_barrier
	s_add_i32 s86, s81, s65
	v_lshl_add_u64 v[212:213], s[56:57], 0, v[180:181]
	s_mov_b32 m0, s86
	ds_read_b128 v[160:163], v232 offset:16384
	ds_read_b128 v[164:167], v232 offset:17408
	ds_read_b128 v[168:171], v232 offset:18432
	ds_read_b128 v[172:175], v232 offset:19456
	ds_read_b128 v[196:199], v232 offset:20480
	ds_read_b128 v[200:203], v232 offset:21504
	ds_read_b128 v[204:207], v232 offset:22528
	ds_read_b128 v[208:211], v232 offset:23552
	global_load_lds_dwordx4 v[212:213], off
	s_add_i32 m0, s86, 0x2000
	s_add_u32 s86, s56, 0x40000
	v_lshl_add_u64 v[214:215], s[56:57], 0, v[184:185]
	s_addc_u32 s87, s57, 0
	s_add_i32 s88, s82, s65
	global_load_lds_dwordx4 v[214:215], off
	v_lshl_add_u64 v[216:217], s[86:87], 0, v[180:181]
	s_mov_b32 m0, s88
	v_lshl_add_u64 v[218:219], s[62:63], 0, v[182:183]
	global_load_lds_dwordx4 v[216:217], off
	v_lshl_add_u64 v[216:217], s[86:87], 0, v[184:185]
	s_add_i32 m0, s88, 0x2000
	s_nop 0
	global_load_lds_dwordx4 v[216:217], off
	v_lshl_add_u64 v[216:217], s[62:63], 0, v[178:179]
	s_mov_b32 m0, s68
	s_nop 0
	global_load_lds_dwordx4 v[216:217], off
	s_mov_b32 m0, s69
	s_nop 0
	global_load_lds_dwordx4 v[218:219], off
	s_waitcnt vmcnt(8)
	s_waitcnt lgkmcnt(0)
	s_barrier
; #define PG8_STAGE(bufoff, gbase, voff) do { _Pragma("unroll") for (int _i = 0; _i < 2; ++_i) \
;         __builtin_amdgcn_global_load_lds((const unsigned*)((const char*)(gbase) + (voff)[_i]), (LAS unsigned*)(lds + (bufoff) + ldsw + _i * 8192), 16, 0, 0); } while (0)
; #define PG8_LDA(dst, b, h) do { _Pragma("unroll") for (int m = 0; m < 4; ++m) _Pragma("unroll") for (int k = 0; k < 2; ++k) dst[m][k] = *(const LAS bf16x8*)(lds + PG8_SA(b, h) + aoff + m * 2048 + k * 1024); } while (0)
; #define PG8_LDB(dst, b, h) do { _Pragma("unroll") for (int n = 0; n < 2; ++n) _Pragma("unroll") for (int k = 0; k < 2; ++k) dst[n][k] = *(const LAS bf16x8*)(lds + PG8_SB(b, h) + boff + n * 2048 + k * 1024); } while (0)
; #define PG8_MMA(ai, bj, At, Bt) do { __builtin_amdgcn_s_setprio(1); _Pragma("unroll") for (int m = 0; m < 4; ++m) _Pragma("unroll") for (int n = 0; n < 2; ++n) _Pragma("unroll") for (int k = 0; k < 2; ++k) \
;         acc[ai][bj][m][n] = __builtin_amdgcn_mfma_f32_16x16x32_bf16(Bt[n][k], At[m][k], acc[ai][bj][m][n], 0, 0, 0); __builtin_amdgcn_s_setprio(0); } while (0)
; #define PG8_WAIT_V(n) asm volatile("s_waitcnt vmcnt(" #n ")" ::: "memory")
; #define PG8_WAIT_L(n) asm volatile("s_waitcnt lgkmcnt(" #n ")" ::: "memory")
; #define PG8_BAR __builtin_amdgcn_s_barrier()
; #define PG8_SCHED __builtin_amdgcn_sched_barrier(0)
; template <class Epi>
; __device__ __forceinline__ void gemm_phase(LAS unsigned char* lds, const Gemm g, const StaticOrder& S, const Epi& E) {
;     ...
;             PG8_WAIT_V(8); PG8_WAIT_L(0); PG8_BAR; PG8_MMA(1, 0, At, B0); PG8_MMA(1, 1, At, B1); PG8_BAR; PG8_SCHED;
;             PG8_LDB(B0, 1, 0); PG8_LDB(B1, 1, 1); PG8_SCHED; PG8_LDA(At, 1, 0); PG8_STAGE(PG8_SA(0, 1), a2 + hstepA, voffA);
;             PG8_WAIT_V(8); PG8_WAIT_L(0); PG8_BAR; PG8_MMA(0, 0, At, B0); PG8_MMA(0, 1, At, B1); PG8_BAR; PG8_SCHED;
	s_setprio 1
	s_waitcnt lgkmcnt(0)
	v_mfma_f32_16x16x32_bf16 v[76:79], v[0:3], v[160:163], 0
	v_mfma_f32_16x16x32_bf16 v[72:75], v[8:11], v[160:163], 0
	v_mfma_f32_16x16x32_bf16 v[60:63], v[0:3], v[168:171], 0
	v_mfma_f32_16x16x32_bf16 v[56:59], v[8:11], v[168:171], 0
	v_mfma_f32_16x16x32_bf16 v[44:47], v[0:3], v[196:199], 0
	v_mfma_f32_16x16x32_bf16 v[40:43], v[8:11], v[196:199], 0
	v_mfma_f32_16x16x32_bf16 v[0:3], v[0:3], v[204:207], 0
	v_mfma_f32_16x16x32_bf16 v[76:79], v[4:7], v[164:167], v[76:79]
	v_mfma_f32_16x16x32_bf16 v[72:75], v[12:15], v[164:167], v[72:75]
	v_mfma_f32_16x16x32_bf16 v[60:63], v[4:7], v[172:175], v[60:63]
	v_mfma_f32_16x16x32_bf16 v[56:59], v[12:15], v[172:175], v[56:59]
	v_mfma_f32_16x16x32_bf16 v[44:47], v[4:7], v[200:203], v[44:47]
	v_mfma_f32_16x16x32_bf16 v[40:43], v[12:15], v[200:203], v[40:43]
	v_mfma_f32_16x16x32_bf16 v[0:3], v[4:7], v[208:211], v[0:3]
	v_mfma_f32_16x16x32_bf16 v[4:7], v[8:11], v[204:207], 0
	v_mfma_f32_16x16x32_bf16 v[4:7], v[12:15], v[208:211], v[4:7]
	v_mfma_f32_16x16x32_bf16 v[20:23], v[144:147], v[168:171], 0
	v_mfma_f32_16x16x32_bf16 v[52:55], v[148:151], v[172:175], v[20:23]
	v_mfma_f32_16x16x32_bf16 v[20:23], v[152:155], v[168:171], 0
	v_mfma_f32_16x16x32_bf16 v[48:51], v[156:159], v[172:175], v[20:23]
	v_mfma_f32_16x16x32_bf16 v[20:23], v[144:147], v[196:199], 0
	v_mfma_f32_16x16x32_bf16 v[36:39], v[148:151], v[200:203], v[20:23]
	v_mfma_f32_16x16x32_bf16 v[20:23], v[152:155], v[196:199], 0
	v_mfma_f32_16x16x32_bf16 v[32:35], v[156:159], v[200:203], v[20:23]
	v_mfma_f32_16x16x32_bf16 v[20:23], v[144:147], v[204:207], 0
	v_mfma_f32_16x16x32_bf16 v[16:19], v[152:155], v[204:207], 0
	v_mfma_f32_16x16x32_bf16 v[8:11], v[144:147], v[160:163], 0
	v_mfma_f32_16x16x32_bf16 v[12:15], v[152:155], v[160:163], 0
	v_mfma_f32_16x16x32_bf16 v[24:27], v[148:151], v[208:211], v[20:23]
	v_mfma_f32_16x16x32_bf16 v[16:19], v[156:159], v[208:211], v[16:19]
	v_mfma_f32_16x16x32_bf16 v[8:11], v[148:151], v[164:167], v[8:11]
	v_mfma_f32_16x16x32_bf16 v[12:15], v[156:159], v[164:167], v[12:15]
	s_setprio 0
	s_barrier
	s_add_i32 s86, 0, 0x18000
	s_add_i32 s87, 0, 0x1c000
	v_add_u32_e32 v68, s86, v229
	v_add_u32_e32 v156, s87, v229
	ds_read_b128 v[20:23], v68
	ds_read_b128 v[28:31], v68 offset:1024
	ds_read_b128 v[64:67], v68 offset:2048
	ds_read_b128 v[68:71], v68 offset:3072
	ds_read_b128 v[144:147], v156
	ds_read_b128 v[148:151], v156 offset:1024
	ds_read_b128 v[152:155], v156 offset:2048
	ds_read_b128 v[156:159], v156 offset:3072
	s_add_u32 s62, s62, 0x40000
	s_addc_u32 s63, s63, 0
	s_mov_b32 m0, s70
	v_lshl_add_u64 v[220:221], s[62:63], 0, v[178:179]
	ds_read_b128 v[160:163], v232 offset:32768
	ds_read_b128 v[164:167], v232 offset:33792
	ds_read_b128 v[168:171], v232 offset:34816
	ds_read_b128 v[172:175], v232 offset:35840
	ds_read_b128 v[196:199], v232 offset:36864
	ds_read_b128 v[200:203], v232 offset:37888
	ds_read_b128 v[204:207], v232 offset:38912
	ds_read_b128 v[208:211], v232 offset:39936
	global_load_lds_dwordx4 v[220:221], off
	v_lshl_add_u64 v[220:221], s[62:63], 0, v[182:183]
	s_mov_b32 m0, s71
	s_nop 0
	global_load_lds_dwordx4 v[220:221], off
	s_waitcnt vmcnt(8)
	s_waitcnt lgkmcnt(0)
	s_barrier
	s_setprio 1
	s_waitcnt lgkmcnt(0)
	v_mfma_f32_16x16x32_bf16 v[140:143], v[20:23], v[160:163], v[140:143]
	v_mfma_f32_16x16x32_bf16 v[132:135], v[64:67], v[160:163], v[132:135]
	v_mfma_f32_16x16x32_bf16 v[124:127], v[20:23], v[168:171], v[124:127]
	v_mfma_f32_16x16x32_bf16 v[120:123], v[64:67], v[168:171], v[120:123]
	v_mfma_f32_16x16x32_bf16 v[108:111], v[20:23], v[196:199], v[108:111]
	v_mfma_f32_16x16x32_bf16 v[104:107], v[64:67], v[196:199], v[104:107]
	v_mfma_f32_16x16x32_bf16 v[92:95], v[20:23], v[204:207], v[92:95]
	v_mfma_f32_16x16x32_bf16 v[88:91], v[64:67], v[204:207], v[88:91]
	v_mfma_f32_16x16x32_bf16 v[140:143], v[28:31], v[164:167], v[140:143]
	v_mfma_f32_16x16x32_bf16 v[132:135], v[68:71], v[164:167], v[132:135]
	v_mfma_f32_16x16x32_bf16 v[124:127], v[28:31], v[172:175], v[124:127]
	v_mfma_f32_16x16x32_bf16 v[120:123], v[68:71], v[172:175], v[120:123]
	v_mfma_f32_16x16x32_bf16 v[108:111], v[28:31], v[200:203], v[108:111]
	v_mfma_f32_16x16x32_bf16 v[104:107], v[68:71], v[200:203], v[104:107]
	v_mfma_f32_16x16x32_bf16 v[92:95], v[28:31], v[208:211], v[92:95]
	v_mfma_f32_16x16x32_bf16 v[88:91], v[68:71], v[208:211], v[88:91]
	v_mfma_f32_16x16x32_bf16 v[136:139], v[144:147], v[160:163], v[136:139]
	v_mfma_f32_16x16x32_bf16 v[128:131], v[152:155], v[160:163], v[128:131]
	v_mfma_f32_16x16x32_bf16 v[116:119], v[144:147], v[168:171], v[116:119]
	v_mfma_f32_16x16x32_bf16 v[112:115], v[152:155], v[168:171], v[112:115]
	v_mfma_f32_16x16x32_bf16 v[100:103], v[144:147], v[196:199], v[100:103]
	v_mfma_f32_16x16x32_bf16 v[96:99], v[152:155], v[196:199], v[96:99]
	v_mfma_f32_16x16x32_bf16 v[84:87], v[144:147], v[204:207], v[84:87]
	v_mfma_f32_16x16x32_bf16 v[80:83], v[152:155], v[204:207], v[80:83]
	v_mfma_f32_16x16x32_bf16 v[136:139], v[148:151], v[164:167], v[136:139]
	v_mfma_f32_16x16x32_bf16 v[128:131], v[156:159], v[164:167], v[128:131]
	v_mfma_f32_16x16x32_bf16 v[116:119], v[148:151], v[172:175], v[116:119]
	v_mfma_f32_16x16x32_bf16 v[112:115], v[156:159], v[172:175], v[112:115]
	v_mfma_f32_16x16x32_bf16 v[100:103], v[148:151], v[200:203], v[100:103]
	v_mfma_f32_16x16x32_bf16 v[96:99], v[156:159], v[200:203], v[96:99]
	v_mfma_f32_16x16x32_bf16 v[84:87], v[148:151], v[208:211], v[84:87]
	v_mfma_f32_16x16x32_bf16 v[80:83], v[156:159], v[208:211], v[80:83]
	s_setprio 0
	s_barrier
; #define PG8_STAGE(bufoff, gbase, voff) do { _Pragma("unroll") for (int _i = 0; _i < 2; ++_i) \
;         __builtin_amdgcn_global_load_lds((const unsigned*)((const char*)(gbase) + (voff)[_i]), (LAS unsigned*)(lds + (bufoff) + ldsw + _i * 8192), 16, 0, 0); } while (0)
; #define PG8_LDA(dst, b, h) do { _Pragma("unroll") for (int m = 0; m < 4; ++m) _Pragma("unroll") for (int k = 0; k < 2; ++k) dst[m][k] = *(const LAS bf16x8*)(lds + PG8_SA(b, h) + aoff + m * 2048 + k * 1024); } while (0)
; #define PG8_LDB(dst, b, h) do { _Pragma("unroll") for (int n = 0; n < 2; ++n) _Pragma("unroll") for (int k = 0; k < 2; ++k) dst[n][k] = *(const LAS bf16x8*)(lds + PG8_SB(b, h) + boff + n * 2048 + k * 1024); } while (0)
; #define PG8_MMA(ai, bj, At, Bt) do { __builtin_amdgcn_s_setprio(1); _Pragma("unroll") for (int m = 0; m < 4; ++m) _Pragma("unroll") for (int n = 0; n < 2; ++n) _Pragma("unroll") for (int k = 0; k < 2; ++k) \
;         acc[ai][bj][m][n] = __builtin_amdgcn_mfma_f32_16x16x32_bf16(Bt[n][k], At[m][k], acc[ai][bj][m][n], 0, 0, 0); __builtin_amdgcn_s_setprio(0); } while (0)
; #define PG8_WAIT_V(n) asm volatile("s_waitcnt vmcnt(" #n ")" ::: "memory")
; #define PG8_WAIT_L(n) asm volatile("s_waitcnt lgkmcnt(" #n ")" ::: "memory")
; #define PG8_BAR __builtin_amdgcn_s_barrier()
; #define PG8_SCHED __builtin_amdgcn_sched_barrier(0)
; template <class Epi>
; __device__ __forceinline__ void gemm_phase(LAS unsigned char* lds, const Gemm g, const StaticOrder& S, const Epi& E) {
;     ...
;             PG8_LDB(B0, 0, 0); PG8_LDB(B1, 0, 1); PG8_SCHED; PG8_LDA(At, 0, 0); PG8_STAGE(PG8_SA(1, 1), a1 + hstepA, voffA);
;     ...
;             PG8_LDA(At, 1, 1); PG8_STAGE(PG8_SB(1, 0), b3, voffB); PG8_STAGE(PG8_SB(1, 1), b3 + hstepB, voffB); PG8_STAGE(PG8_SA(1, 0), a3, voffA);
;             PG8_WAIT_V(8); PG8_WAIT_L(0); PG8_BAR; PG8_MMA(1, 0, At, B0); PG8_MMA(1, 1, At, B1); PG8_BAR; PG8_SCHED;
	s_add_i32 s62, s86, s65
	v_lshl_add_u64 v[212:213], v[212:213], 0, s[16:17]
	s_mov_b32 m0, s62
	ds_read_b128 v[160:163], v232 offset:49152
	ds_read_b128 v[164:167], v232 offset:50176
	ds_read_b128 v[168:171], v232 offset:51200
	ds_read_b128 v[172:175], v232 offset:52224
	ds_read_b128 v[196:199], v232 offset:53248
	ds_read_b128 v[200:203], v232 offset:54272
	ds_read_b128 v[204:207], v232 offset:55296
	ds_read_b128 v[208:211], v232 offset:56320
	global_load_lds_dwordx4 v[212:213], off
	s_add_i32 m0, s62, 0x2000
	s_add_u32 s56, s56, 0x40080
	v_lshl_add_u64 v[212:213], v[214:215], 0, s[16:17]
	s_addc_u32 s57, s57, 0
	s_add_i32 s62, s87, s65
	global_load_lds_dwordx4 v[212:213], off
	v_lshl_add_u64 v[212:213], s[56:57], 0, v[180:181]
	s_mov_b32 m0, s62
	s_nop 0
	global_load_lds_dwordx4 v[212:213], off
	v_lshl_add_u64 v[212:213], s[56:57], 0, v[184:185]
	s_add_i32 m0, s62, 0x2000
	s_nop 0
	global_load_lds_dwordx4 v[212:213], off
	v_lshl_add_u64 v[212:213], v[216:217], 0, s[16:17]
	s_mov_b32 m0, s76
	s_nop 0
	global_load_lds_dwordx4 v[212:213], off
	v_lshl_add_u64 v[212:213], v[218:219], 0, s[16:17]
	s_mov_b32 m0, s77
	s_nop 0
	global_load_lds_dwordx4 v[212:213], off
	s_waitcnt vmcnt(8)
	s_waitcnt lgkmcnt(0)
	s_barrier
	s_setprio 1
	s_waitcnt lgkmcnt(0)
	v_mfma_f32_16x16x32_bf16 v[76:79], v[20:23], v[160:163], v[76:79]
	v_mfma_f32_16x16x32_bf16 v[60:63], v[20:23], v[168:171], v[60:63]
	v_mfma_f32_16x16x32_bf16 v[44:47], v[20:23], v[196:199], v[44:47]
	v_mfma_f32_16x16x32_bf16 v[0:3], v[20:23], v[204:207], v[0:3]
	v_mfma_f32_16x16x32_bf16 v[76:79], v[28:31], v[164:167], v[76:79]
	v_mfma_f32_16x16x32_bf16 v[72:75], v[64:67], v[160:163], v[72:75]
	v_mfma_f32_16x16x32_bf16 v[60:63], v[28:31], v[172:175], v[60:63]
	v_mfma_f32_16x16x32_bf16 v[56:59], v[64:67], v[168:171], v[56:59]
	v_mfma_f32_16x16x32_bf16 v[44:47], v[28:31], v[200:203], v[44:47]
	v_mfma_f32_16x16x32_bf16 v[40:43], v[64:67], v[196:199], v[40:43]
	v_mfma_f32_16x16x32_bf16 v[28:31], v[28:31], v[208:211], v[0:3]
	v_mfma_f32_16x16x32_bf16 v[0:3], v[64:67], v[204:207], v[4:7]
	v_mfma_f32_16x16x32_bf16 v[72:75], v[68:71], v[164:167], v[72:75]
	v_mfma_f32_16x16x32_bf16 v[56:59], v[68:71], v[172:175], v[56:59]
	v_mfma_f32_16x16x32_bf16 v[40:43], v[68:71], v[200:203], v[40:43]
	v_mfma_f32_16x16x32_bf16 v[20:23], v[68:71], v[208:211], v[0:3]
	v_mfma_f32_16x16x32_bf16 v[0:3], v[144:147], v[160:163], v[8:11]
	v_mfma_f32_16x16x32_bf16 v[68:71], v[148:151], v[164:167], v[0:3]
	v_mfma_f32_16x16x32_bf16 v[0:3], v[152:155], v[160:163], v[12:15]
	v_mfma_f32_16x16x32_bf16 v[64:67], v[156:159], v[164:167], v[0:3]
	v_mfma_f32_16x16x32_bf16 v[0:3], v[144:147], v[168:171], v[52:55]
	v_mfma_f32_16x16x32_bf16 v[52:55], v[148:151], v[172:175], v[0:3]
	v_mfma_f32_16x16x32_bf16 v[0:3], v[152:155], v[168:171], v[48:51]
	v_mfma_f32_16x16x32_bf16 v[48:51], v[156:159], v[172:175], v[0:3]
	v_mfma_f32_16x16x32_bf16 v[0:3], v[144:147], v[196:199], v[36:39]
	v_mfma_f32_16x16x32_bf16 v[36:39], v[148:151], v[200:203], v[0:3]
	v_mfma_f32_16x16x32_bf16 v[0:3], v[152:155], v[196:199], v[32:35]
	v_mfma_f32_16x16x32_bf16 v[32:35], v[156:159], v[200:203], v[0:3]
	v_mfma_f32_16x16x32_bf16 v[0:3], v[144:147], v[204:207], v[24:27]
	v_mfma_f32_16x16x32_bf16 v[24:27], v[148:151], v[208:211], v[0:3]
	v_mfma_f32_16x16x32_bf16 v[0:3], v[152:155], v[204:207], v[16:19]
	v_mfma_f32_16x16x32_bf16 v[16:19], v[156:159], v[208:211], v[0:3]
	s_setprio 0
	s_barrier
	s_add_i32 s85, s85, 2
	s_add_u32 s54, s54, 0x100
	s_addc_u32 s55, s55, 0
	s_add_u32 s83, s83, 0x100
	s_addc_u32 s84, s84, 0
	s_cmp_gt_u32 s85, 13
.LBB0_1018:
	ds_read_b128 v[0:3], v230
	ds_read_b128 v[4:7], v230 offset:1024
	ds_read_b128 v[8:11], v230 offset:2048
	ds_read_b128 v[12:15], v230 offset:3072
	ds_read_b128 v[144:147], v231
	ds_read_b128 v[148:151], v231 offset:1024
	ds_read_b128 v[152:155], v231 offset:2048
	ds_read_b128 v[156:159], v231 offset:3072
	s_add_u32 s56, s54, 0xfffc0080
	s_addc_u32 s57, s55, -1
	s_cmp_eq_u32 s85, 12
	s_cselect_b32 s63, s7, s57
	s_cselect_b32 s62, s35, s56
	s_cselect_b32 s57, s23, s84
	s_cselect_b32 s56, s53, s83
	v_lshl_add_u64 v[212:213], s[54:55], 0, v[188:189]
	s_add_i32 m0, s68, 0xc000
	ds_read_b128 v[160:163], v232
	ds_read_b128 v[164:167], v232 offset:1024
	ds_read_b128 v[168:171], v232 offset:2048
	ds_read_b128 v[172:175], v232 offset:3072
	ds_read_b128 v[196:199], v232 offset:4096
	ds_read_b128 v[200:203], v232 offset:5120
	ds_read_b128 v[204:207], v232 offset:6144
	ds_read_b128 v[208:211], v232 offset:7168
	global_load_lds_dwordx4 v[212:213], off
	v_lshl_add_u64 v[212:213], s[54:55], 0, v[190:191]
	s_add_i32 m0, s68, 0xe000
	s_nop 0
	global_load_lds_dwordx4 v[212:213], off
	s_waitcnt vmcnt(8)
	s_waitcnt lgkmcnt(0)
	s_barrier
; #define PG8_STAGE(bufoff, gbase, voff) do { _Pragma("unroll") for (int _i = 0; _i < 2; ++_i) \
;         __builtin_amdgcn_global_load_lds((const unsigned*)((const char*)(gbase) + (voff)[_i]), (LAS unsigned*)(lds + (bufoff) + ldsw + _i * 8192), 16, 0, 0); } while (0)
; #define PG8_LDA(dst, b, h) do { _Pragma("unroll") for (int m = 0; m < 4; ++m) _Pragma("unroll") for (int k = 0; k < 2; ++k) dst[m][k] = *(const LAS bf16x8*)(lds + PG8_SA(b, h) + aoff + m * 2048 + k * 1024); } while (0)
; #define PG8_MMA(ai, bj, At, Bt) do { __builtin_amdgcn_s_setprio(1); _Pragma("unroll") for (int m = 0; m < 4; ++m) _Pragma("unroll") for (int n = 0; n < 2; ++n) _Pragma("unroll") for (int k = 0; k < 2; ++k) \
;         acc[ai][bj][m][n] = __builtin_amdgcn_mfma_f32_16x16x32_bf16(Bt[n][k], At[m][k], acc[ai][bj][m][n], 0, 0, 0); __builtin_amdgcn_s_setprio(0); } while (0)
; #define PG8_WAIT_V(n) asm volatile("s_waitcnt vmcnt(" #n ")" ::: "memory")
; #define PG8_WAIT_L(n) asm volatile("s_waitcnt lgkmcnt(" #n ")" ::: "memory")
; #define PG8_BAR __builtin_amdgcn_s_barrier()
; #define PG8_SCHED __builtin_amdgcn_sched_barrier(0)
; template <class Epi>
; __device__ __forceinline__ void gemm_phase(LAS unsigned char* lds, const Gemm g, const StaticOrder& S, const Epi& E) {
;     ...
;             PG8_WAIT_V(8); PG8_WAIT_L(0); PG8_BAR; PG8_MMA(0, 0, At, B0); PG8_MMA(0, 1, At, B1); PG8_BAR; PG8_SCHED;
;             PG8_LDA(At, 0, 1); PG8_STAGE(PG8_SB(0, 0), b2, voffB); PG8_STAGE(PG8_SB(0, 1), b2 + hstepB, voffB); PG8_STAGE(PG8_SA(0, 0), a2, voffA);
;             PG8_WAIT_V(8); PG8_WAIT_L(0); PG8_BAR; PG8_MMA(1, 0, At, B0); PG8_MMA(1, 1, At, B1); PG8_BAR; PG8_SCHED;
	s_setprio 1
	s_waitcnt lgkmcnt(0)
	v_mfma_f32_16x16x32_bf16 v[140:143], v[0:3], v[160:163], v[140:143]
	v_mfma_f32_16x16x32_bf16 v[132:135], v[8:11], v[160:163], v[132:135]
	v_mfma_f32_16x16x32_bf16 v[124:127], v[0:3], v[168:171], v[124:127]
	v_mfma_f32_16x16x32_bf16 v[120:123], v[8:11], v[168:171], v[120:123]
	v_mfma_f32_16x16x32_bf16 v[108:111], v[0:3], v[196:199], v[108:111]
	v_mfma_f32_16x16x32_bf16 v[104:107], v[8:11], v[196:199], v[104:107]
	v_mfma_f32_16x16x32_bf16 v[92:95], v[0:3], v[204:207], v[92:95]
	v_mfma_f32_16x16x32_bf16 v[88:91], v[8:11], v[204:207], v[88:91]
	v_mfma_f32_16x16x32_bf16 v[140:143], v[4:7], v[164:167], v[140:143]
	v_mfma_f32_16x16x32_bf16 v[132:135], v[12:15], v[164:167], v[132:135]
	v_mfma_f32_16x16x32_bf16 v[124:127], v[4:7], v[172:175], v[124:127]
	v_mfma_f32_16x16x32_bf16 v[120:123], v[12:15], v[172:175], v[120:123]
	v_mfma_f32_16x16x32_bf16 v[108:111], v[4:7], v[200:203], v[108:111]
	v_mfma_f32_16x16x32_bf16 v[104:107], v[12:15], v[200:203], v[104:107]
	v_mfma_f32_16x16x32_bf16 v[92:95], v[4:7], v[208:211], v[92:95]
	v_mfma_f32_16x16x32_bf16 v[88:91], v[12:15], v[208:211], v[88:91]
	v_mfma_f32_16x16x32_bf16 v[136:139], v[144:147], v[160:163], v[136:139]
	v_mfma_f32_16x16x32_bf16 v[128:131], v[152:155], v[160:163], v[128:131]
	v_mfma_f32_16x16x32_bf16 v[116:119], v[144:147], v[168:171], v[116:119]
	v_mfma_f32_16x16x32_bf16 v[112:115], v[152:155], v[168:171], v[112:115]
	v_mfma_f32_16x16x32_bf16 v[100:103], v[144:147], v[196:199], v[100:103]
	v_mfma_f32_16x16x32_bf16 v[96:99], v[152:155], v[196:199], v[96:99]
	v_mfma_f32_16x16x32_bf16 v[84:87], v[144:147], v[204:207], v[84:87]
	v_mfma_f32_16x16x32_bf16 v[80:83], v[152:155], v[204:207], v[80:83]
	v_mfma_f32_16x16x32_bf16 v[136:139], v[148:151], v[164:167], v[136:139]
	v_mfma_f32_16x16x32_bf16 v[128:131], v[156:159], v[164:167], v[128:131]
	v_mfma_f32_16x16x32_bf16 v[116:119], v[148:151], v[172:175], v[116:119]
	v_mfma_f32_16x16x32_bf16 v[112:115], v[156:159], v[172:175], v[112:115]
	v_mfma_f32_16x16x32_bf16 v[100:103], v[148:151], v[200:203], v[100:103]
	v_mfma_f32_16x16x32_bf16 v[96:99], v[156:159], v[200:203], v[96:99]
	v_mfma_f32_16x16x32_bf16 v[84:87], v[148:151], v[208:211], v[84:87]
	v_mfma_f32_16x16x32_bf16 v[80:83], v[156:159], v[208:211], v[80:83]
	s_setprio 0
	s_barrier
	s_add_i32 s86, s81, s65
	v_lshl_add_u64 v[212:213], s[56:57], 0, v[180:181]
	s_mov_b32 m0, s86
	ds_read_b128 v[160:163], v232 offset:16384
	ds_read_b128 v[164:167], v232 offset:17408
	ds_read_b128 v[168:171], v232 offset:18432
	ds_read_b128 v[172:175], v232 offset:19456
	ds_read_b128 v[196:199], v232 offset:20480
	ds_read_b128 v[200:203], v232 offset:21504
	ds_read_b128 v[204:207], v232 offset:22528
	ds_read_b128 v[208:211], v232 offset:23552
	global_load_lds_dwordx4 v[212:213], off
	s_add_i32 m0, s86, 0x2000
	s_add_u32 s86, s56, 0x40000
	v_lshl_add_u64 v[214:215], s[56:57], 0, v[184:185]
	s_addc_u32 s87, s57, 0
	s_add_i32 s88, s82, s65
	global_load_lds_dwordx4 v[214:215], off
	v_lshl_add_u64 v[216:217], s[86:87], 0, v[180:181]
	s_mov_b32 m0, s88
	v_lshl_add_u64 v[218:219], s[62:63], 0, v[182:183]
	global_load_lds_dwordx4 v[216:217], off
	v_lshl_add_u64 v[216:217], s[86:87], 0, v[184:185]
	s_add_i32 m0, s88, 0x2000
	s_nop 0
	global_load_lds_dwordx4 v[216:217], off
	v_lshl_add_u64 v[216:217], s[62:63], 0, v[178:179]
	s_mov_b32 m0, s68
	s_nop 0
	global_load_lds_dwordx4 v[216:217], off
	s_mov_b32 m0, s69
	s_nop 0
	global_load_lds_dwordx4 v[218:219], off
	s_waitcnt vmcnt(8)
	s_waitcnt lgkmcnt(0)
	s_barrier
	s_setprio 1
	s_waitcnt lgkmcnt(0)
	v_mfma_f32_16x16x32_bf16 v[76:79], v[0:3], v[160:163], v[76:79]
	v_mfma_f32_16x16x32_bf16 v[72:75], v[8:11], v[160:163], v[72:75]
	v_mfma_f32_16x16x32_bf16 v[60:63], v[0:3], v[168:171], v[60:63]
	v_mfma_f32_16x16x32_bf16 v[56:59], v[8:11], v[168:171], v[56:59]
	v_mfma_f32_16x16x32_bf16 v[44:47], v[0:3], v[196:199], v[44:47]
	v_mfma_f32_16x16x32_bf16 v[40:43], v[8:11], v[196:199], v[40:43]
	v_mfma_f32_16x16x32_bf16 v[0:3], v[0:3], v[204:207], v[28:31]
	v_mfma_f32_16x16x32_bf16 v[76:79], v[4:7], v[164:167], v[76:79]
	v_mfma_f32_16x16x32_bf16 v[72:75], v[12:15], v[164:167], v[72:75]
	v_mfma_f32_16x16x32_bf16 v[60:63], v[4:7], v[172:175], v[60:63]
	v_mfma_f32_16x16x32_bf16 v[56:59], v[12:15], v[172:175], v[56:59]
	v_mfma_f32_16x16x32_bf16 v[44:47], v[4:7], v[200:203], v[44:47]
	v_mfma_f32_16x16x32_bf16 v[40:43], v[12:15], v[200:203], v[40:43]
	v_mfma_f32_16x16x32_bf16 v[0:3], v[4:7], v[208:211], v[0:3]
	v_mfma_f32_16x16x32_bf16 v[4:7], v[8:11], v[204:207], v[20:23]
	v_mfma_f32_16x16x32_bf16 v[4:7], v[12:15], v[208:211], v[4:7]
	v_mfma_f32_16x16x32_bf16 v[20:23], v[144:147], v[168:171], v[52:55]
	v_mfma_f32_16x16x32_bf16 v[52:55], v[148:151], v[172:175], v[20:23]
	v_mfma_f32_16x16x32_bf16 v[20:23], v[152:155], v[168:171], v[48:51]
	v_mfma_f32_16x16x32_bf16 v[48:51], v[156:159], v[172:175], v[20:23]
	v_mfma_f32_16x16x32_bf16 v[20:23], v[144:147], v[196:199], v[36:39]
	v_mfma_f32_16x16x32_bf16 v[36:39], v[148:151], v[200:203], v[20:23]
	v_mfma_f32_16x16x32_bf16 v[20:23], v[152:155], v[196:199], v[32:35]
	v_mfma_f32_16x16x32_bf16 v[32:35], v[156:159], v[200:203], v[20:23]
	v_mfma_f32_16x16x32_bf16 v[20:23], v[144:147], v[204:207], v[24:27]
	v_mfma_f32_16x16x32_bf16 v[16:19], v[152:155], v[204:207], v[16:19]
	v_mfma_f32_16x16x32_bf16 v[8:11], v[144:147], v[160:163], v[68:71]
	v_mfma_f32_16x16x32_bf16 v[12:15], v[152:155], v[160:163], v[64:67]
	v_mfma_f32_16x16x32_bf16 v[24:27], v[148:151], v[208:211], v[20:23]
	v_mfma_f32_16x16x32_bf16 v[16:19], v[156:159], v[208:211], v[16:19]
	v_mfma_f32_16x16x32_bf16 v[8:11], v[148:151], v[164:167], v[8:11]
	v_mfma_f32_16x16x32_bf16 v[12:15], v[156:159], v[164:167], v[12:15]
	s_setprio 0
	s_barrier
; #define PG8_STAGE(bufoff, gbase, voff) do { _Pragma("unroll") for (int _i = 0; _i < 2; ++_i) \
;         __builtin_amdgcn_global_load_lds((const unsigned*)((const char*)(gbase) + (voff)[_i]), (LAS unsigned*)(lds + (bufoff) + ldsw + _i * 8192), 16, 0, 0); } while (0)
; #define PG8_LDA(dst, b, h) do { _Pragma("unroll") for (int m = 0; m < 4; ++m) _Pragma("unroll") for (int k = 0; k < 2; ++k) dst[m][k] = *(const LAS bf16x8*)(lds + PG8_SA(b, h) + aoff + m * 2048 + k * 1024); } while (0)
; #define PG8_LDB(dst, b, h) do { _Pragma("unroll") for (int n = 0; n < 2; ++n) _Pragma("unroll") for (int k = 0; k < 2; ++k) dst[n][k] = *(const LAS bf16x8*)(lds + PG8_SB(b, h) + boff + n * 2048 + k * 1024); } while (0)
; #define PG8_MMA(ai, bj, At, Bt) do { __builtin_amdgcn_s_setprio(1); _Pragma("unroll") for (int m = 0; m < 4; ++m) _Pragma("unroll") for (int n = 0; n < 2; ++n) _Pragma("unroll") for (int k = 0; k < 2; ++k) \
;         acc[ai][bj][m][n] = __builtin_amdgcn_mfma_f32_16x16x32_bf16(Bt[n][k], At[m][k], acc[ai][bj][m][n], 0, 0, 0); __builtin_amdgcn_s_setprio(0); } while (0)
; #define PG8_WAIT_V(n) asm volatile("s_waitcnt vmcnt(" #n ")" ::: "memory")
; #define PG8_WAIT_L(n) asm volatile("s_waitcnt lgkmcnt(" #n ")" ::: "memory")
; #define PG8_BAR __builtin_amdgcn_s_barrier()
; #define PG8_SCHED __builtin_amdgcn_sched_barrier(0)
; template <class Epi>
; __device__ __forceinline__ void gemm_phase(LAS unsigned char* lds, const Gemm g, const StaticOrder& S, const Epi& E) {
;     ...
;             PG8_LDB(B0, 1, 0); PG8_LDB(B1, 1, 1); PG8_SCHED; PG8_LDA(At, 1, 0); PG8_STAGE(PG8_SA(0, 1), a2 + hstepA, voffA);
;             PG8_WAIT_V(8); PG8_WAIT_L(0); PG8_BAR; PG8_MMA(0, 0, At, B0); PG8_MMA(0, 1, At, B1); PG8_BAR; PG8_SCHED;
	s_add_i32 s86, 0, 0x18000
	s_add_i32 s87, 0, 0x1c000
	v_add_u32_e32 v68, s86, v229
	v_add_u32_e32 v156, s87, v229
	ds_read_b128 v[20:23], v68
	ds_read_b128 v[28:31], v68 offset:1024
	ds_read_b128 v[64:67], v68 offset:2048
	ds_read_b128 v[68:71], v68 offset:3072
	ds_read_b128 v[144:147], v156
	ds_read_b128 v[148:151], v156 offset:1024
	ds_read_b128 v[152:155], v156 offset:2048
	ds_read_b128 v[156:159], v156 offset:3072
	s_add_u32 s62, s62, 0x40000
	s_addc_u32 s63, s63, 0
	s_mov_b32 m0, s70
	v_lshl_add_u64 v[220:221], s[62:63], 0, v[178:179]
	ds_read_b128 v[160:163], v232 offset:32768
	ds_read_b128 v[164:167], v232 offset:33792
	ds_read_b128 v[168:171], v232 offset:34816
	ds_read_b128 v[172:175], v232 offset:35840
	ds_read_b128 v[196:199], v232 offset:36864
	ds_read_b128 v[200:203], v232 offset:37888
	ds_read_b128 v[204:207], v232 offset:38912
	ds_read_b128 v[208:211], v232 offset:39936
	global_load_lds_dwordx4 v[220:221], off
	v_lshl_add_u64 v[220:221], s[62:63], 0, v[182:183]
	s_mov_b32 m0, s71
	s_nop 0
	global_load_lds_dwordx4 v[220:221], off
	s_waitcnt vmcnt(8)
	s_waitcnt lgkmcnt(0)
	s_barrier
	s_setprio 1
	s_waitcnt lgkmcnt(0)
	v_mfma_f32_16x16x32_bf16 v[140:143], v[20:23], v[160:163], v[140:143]
	v_mfma_f32_16x16x32_bf16 v[132:135], v[64:67], v[160:163], v[132:135]
	v_mfma_f32_16x16x32_bf16 v[124:127], v[20:23], v[168:171], v[124:127]
	v_mfma_f32_16x16x32_bf16 v[120:123], v[64:67], v[168:171], v[120:123]
	v_mfma_f32_16x16x32_bf16 v[108:111], v[20:23], v[196:199], v[108:111]
	v_mfma_f32_16x16x32_bf16 v[104:107], v[64:67], v[196:199], v[104:107]
	v_mfma_f32_16x16x32_bf16 v[92:95], v[20:23], v[204:207], v[92:95]
	v_mfma_f32_16x16x32_bf16 v[88:91], v[64:67], v[204:207], v[88:91]
	v_mfma_f32_16x16x32_bf16 v[140:143], v[28:31], v[164:167], v[140:143]
	v_mfma_f32_16x16x32_bf16 v[132:135], v[68:71], v[164:167], v[132:135]
	v_mfma_f32_16x16x32_bf16 v[124:127], v[28:31], v[172:175], v[124:127]
	v_mfma_f32_16x16x32_bf16 v[120:123], v[68:71], v[172:175], v[120:123]
	v_mfma_f32_16x16x32_bf16 v[108:111], v[28:31], v[200:203], v[108:111]
	v_mfma_f32_16x16x32_bf16 v[104:107], v[68:71], v[200:203], v[104:107]
	v_mfma_f32_16x16x32_bf16 v[92:95], v[28:31], v[208:211], v[92:95]
	v_mfma_f32_16x16x32_bf16 v[88:91], v[68:71], v[208:211], v[88:91]
	v_mfma_f32_16x16x32_bf16 v[136:139], v[144:147], v[160:163], v[136:139]
	v_mfma_f32_16x16x32_bf16 v[128:131], v[152:155], v[160:163], v[128:131]
	v_mfma_f32_16x16x32_bf16 v[116:119], v[144:147], v[168:171], v[116:119]
	v_mfma_f32_16x16x32_bf16 v[112:115], v[152:155], v[168:171], v[112:115]
	v_mfma_f32_16x16x32_bf16 v[100:103], v[144:147], v[196:199], v[100:103]
	v_mfma_f32_16x16x32_bf16 v[96:99], v[152:155], v[196:199], v[96:99]
	v_mfma_f32_16x16x32_bf16 v[84:87], v[144:147], v[204:207], v[84:87]
	v_mfma_f32_16x16x32_bf16 v[80:83], v[152:155], v[204:207], v[80:83]
	v_mfma_f32_16x16x32_bf16 v[136:139], v[148:151], v[164:167], v[136:139]
	v_mfma_f32_16x16x32_bf16 v[128:131], v[156:159], v[164:167], v[128:131]
	v_mfma_f32_16x16x32_bf16 v[116:119], v[148:151], v[172:175], v[116:119]
	v_mfma_f32_16x16x32_bf16 v[112:115], v[156:159], v[172:175], v[112:115]
	v_mfma_f32_16x16x32_bf16 v[100:103], v[148:151], v[200:203], v[100:103]
	v_mfma_f32_16x16x32_bf16 v[96:99], v[156:159], v[200:203], v[96:99]
	v_mfma_f32_16x16x32_bf16 v[84:87], v[148:151], v[208:211], v[84:87]
	v_mfma_f32_16x16x32_bf16 v[80:83], v[156:159], v[208:211], v[80:83]
	s_setprio 0
	s_barrier
; #define PG8_STAGE(bufoff, gbase, voff) do { _Pragma("unroll") for (int _i = 0; _i < 2; ++_i) \
;         __builtin_amdgcn_global_load_lds((const unsigned*)((const char*)(gbase) + (voff)[_i]), (LAS unsigned*)(lds + (bufoff) + ldsw + _i * 8192), 16, 0, 0); } while (0)
; #define PG8_LDA(dst, b, h) do { _Pragma("unroll") for (int m = 0; m < 4; ++m) _Pragma("unroll") for (int k = 0; k < 2; ++k) dst[m][k] = *(const LAS bf16x8*)(lds + PG8_SA(b, h) + aoff + m * 2048 + k * 1024); } while (0)
; #define PG8_MMA(ai, bj, At, Bt) do { __builtin_amdgcn_s_setprio(1); _Pragma("unroll") for (int m = 0; m < 4; ++m) _Pragma("unroll") for (int n = 0; n < 2; ++n) _Pragma("unroll") for (int k = 0; k < 2; ++k) \
;         acc[ai][bj][m][n] = __builtin_amdgcn_mfma_f32_16x16x32_bf16(Bt[n][k], At[m][k], acc[ai][bj][m][n], 0, 0, 0); __builtin_amdgcn_s_setprio(0); } while (0)
; #define PG8_WAIT_V(n) asm volatile("s_waitcnt vmcnt(" #n ")" ::: "memory")
; #define PG8_WAIT_L(n) asm volatile("s_waitcnt lgkmcnt(" #n ")" ::: "memory")
; #define PG8_BAR __builtin_amdgcn_s_barrier()
; #define PG8_SCHED __builtin_amdgcn_sched_barrier(0)
; template <class Epi>
; __device__ __forceinline__ void gemm_phase(LAS unsigned char* lds, const Gemm g, const StaticOrder& S, const Epi& E) {
;     ...
;             PG8_LDA(At, 1, 1); PG8_STAGE(PG8_SB(1, 0), b3, voffB); PG8_STAGE(PG8_SB(1, 1), b3 + hstepB, voffB); PG8_STAGE(PG8_SA(1, 0), a3, voffA);
;             PG8_WAIT_V(8); PG8_WAIT_L(0); PG8_BAR; PG8_MMA(1, 0, At, B0); PG8_MMA(1, 1, At, B1); PG8_BAR; PG8_SCHED;
;         }
;         if (wr == 0) PG8_BAR;
	s_add_i32 s62, s86, s65
	v_lshl_add_u64 v[212:213], v[212:213], 0, s[16:17]
	s_mov_b32 m0, s62
	ds_read_b128 v[160:163], v232 offset:49152
	ds_read_b128 v[164:167], v232 offset:50176
	ds_read_b128 v[168:171], v232 offset:51200
	ds_read_b128 v[172:175], v232 offset:52224
	ds_read_b128 v[196:199], v232 offset:53248
	ds_read_b128 v[200:203], v232 offset:54272
	ds_read_b128 v[204:207], v232 offset:55296
	ds_read_b128 v[208:211], v232 offset:56320
	global_load_lds_dwordx4 v[212:213], off
	s_add_i32 m0, s62, 0x2000
	s_add_u32 s56, s56, 0x40080
	v_lshl_add_u64 v[212:213], v[214:215], 0, s[16:17]
	s_addc_u32 s57, s57, 0
	s_add_i32 s62, s87, s65
	global_load_lds_dwordx4 v[212:213], off
	v_lshl_add_u64 v[212:213], s[56:57], 0, v[180:181]
	s_mov_b32 m0, s62
	s_nop 0
	global_load_lds_dwordx4 v[212:213], off
	v_lshl_add_u64 v[212:213], s[56:57], 0, v[184:185]
	s_add_i32 m0, s62, 0x2000
	s_nop 0
	global_load_lds_dwordx4 v[212:213], off
	v_lshl_add_u64 v[212:213], v[216:217], 0, s[16:17]
	s_mov_b32 m0, s76
	s_nop 0
	global_load_lds_dwordx4 v[212:213], off
	v_lshl_add_u64 v[212:213], v[218:219], 0, s[16:17]
	s_mov_b32 m0, s77
	s_nop 0
	global_load_lds_dwordx4 v[212:213], off
	s_waitcnt vmcnt(8)
	s_waitcnt lgkmcnt(0)
	s_barrier
	s_setprio 1
	s_waitcnt lgkmcnt(0)
	v_mfma_f32_16x16x32_bf16 v[76:79], v[20:23], v[160:163], v[76:79]
	v_mfma_f32_16x16x32_bf16 v[60:63], v[20:23], v[168:171], v[60:63]
	v_mfma_f32_16x16x32_bf16 v[44:47], v[20:23], v[196:199], v[44:47]
	v_mfma_f32_16x16x32_bf16 v[0:3], v[20:23], v[204:207], v[0:3]
	v_mfma_f32_16x16x32_bf16 v[76:79], v[28:31], v[164:167], v[76:79]
	v_mfma_f32_16x16x32_bf16 v[72:75], v[64:67], v[160:163], v[72:75]
	v_mfma_f32_16x16x32_bf16 v[60:63], v[28:31], v[172:175], v[60:63]
	v_mfma_f32_16x16x32_bf16 v[56:59], v[64:67], v[168:171], v[56:59]
	v_mfma_f32_16x16x32_bf16 v[44:47], v[28:31], v[200:203], v[44:47]
	v_mfma_f32_16x16x32_bf16 v[40:43], v[64:67], v[196:199], v[40:43]
	v_mfma_f32_16x16x32_bf16 v[28:31], v[28:31], v[208:211], v[0:3]
	v_mfma_f32_16x16x32_bf16 v[0:3], v[64:67], v[204:207], v[4:7]
	v_mfma_f32_16x16x32_bf16 v[72:75], v[68:71], v[164:167], v[72:75]
	v_mfma_f32_16x16x32_bf16 v[56:59], v[68:71], v[172:175], v[56:59]
	v_mfma_f32_16x16x32_bf16 v[40:43], v[68:71], v[200:203], v[40:43]
	v_mfma_f32_16x16x32_bf16 v[20:23], v[68:71], v[208:211], v[0:3]
	v_mfma_f32_16x16x32_bf16 v[0:3], v[144:147], v[160:163], v[8:11]
	v_mfma_f32_16x16x32_bf16 v[68:71], v[148:151], v[164:167], v[0:3]
	v_mfma_f32_16x16x32_bf16 v[0:3], v[152:155], v[160:163], v[12:15]
	v_mfma_f32_16x16x32_bf16 v[64:67], v[156:159], v[164:167], v[0:3]
	v_mfma_f32_16x16x32_bf16 v[0:3], v[144:147], v[168:171], v[52:55]
	v_mfma_f32_16x16x32_bf16 v[52:55], v[148:151], v[172:175], v[0:3]
	v_mfma_f32_16x16x32_bf16 v[0:3], v[152:155], v[168:171], v[48:51]
	v_mfma_f32_16x16x32_bf16 v[48:51], v[156:159], v[172:175], v[0:3]
	v_mfma_f32_16x16x32_bf16 v[0:3], v[144:147], v[196:199], v[36:39]
	v_mfma_f32_16x16x32_bf16 v[36:39], v[148:151], v[200:203], v[0:3]
	v_mfma_f32_16x16x32_bf16 v[0:3], v[152:155], v[196:199], v[32:35]
	v_mfma_f32_16x16x32_bf16 v[32:35], v[156:159], v[200:203], v[0:3]
	v_mfma_f32_16x16x32_bf16 v[0:3], v[144:147], v[204:207], v[24:27]
	v_mfma_f32_16x16x32_bf16 v[24:27], v[148:151], v[208:211], v[0:3]
	v_mfma_f32_16x16x32_bf16 v[0:3], v[152:155], v[204:207], v[16:19]
	v_mfma_f32_16x16x32_bf16 v[16:19], v[156:159], v[208:211], v[0:3]
	s_setprio 0
	s_barrier
	s_add_i32 s85, s85, 2
	s_add_u32 s54, s54, 0x100
	s_addc_u32 s55, s55, 0
	s_add_u32 s83, s83, 0x100
	s_addc_u32 s84, s84, 0
	s_cmp_gt_u32 s85, 13
	s_cbranch_scc0 .LBB0_1018
	s_and_b64 vcc, exec, s[18:19]
	s_cbranch_vccz .LBB0_1021
	s_barrier

; #define PG8_STAGE(bufoff, gbase, voff) do { _Pragma("unroll") for (int _i = 0; _i < 2; ++_i) \
;         __builtin_amdgcn_global_load_lds((const unsigned*)((const char*)(gbase) + (voff)[_i]), (LAS unsigned*)(lds + (bufoff) + ldsw + _i * 8192), 16, 0, 0); } while (0)
; #define PG8_LDA(dst, b, h) do { _Pragma("unroll") for (int m = 0; m < 4; ++m) _Pragma("unroll") for (int k = 0; k < 2; ++k) dst[m][k] = *(const LAS bf16x8*)(lds + PG8_SA(b, h) + aoff + m * 2048 + k * 1024); } while (0)
; #define PG8_LDB(dst, b, h) do { _Pragma("unroll") for (int n = 0; n < 2; ++n) _Pragma("unroll") for (int k = 0; k < 2; ++k) dst[n][k] = *(const LAS bf16x8*)(lds + PG8_SB(b, h) + boff + n * 2048 + k * 1024); } while (0)
; #define PG8_MMA(ai, bj, At, Bt) do { __builtin_amdgcn_s_setprio(1); _Pragma("unroll") for (int m = 0; m < 4; ++m) _Pragma("unroll") for (int n = 0; n < 2; ++n) _Pragma("unroll") for (int k = 0; k < 2; ++k) \
;         acc[ai][bj][m][n] = __builtin_amdgcn_mfma_f32_16x16x32_bf16(Bt[n][k], At[m][k], acc[ai][bj][m][n], 0, 0, 0); __builtin_amdgcn_s_setprio(0); } while (0)
; #define PG8_BAR __builtin_amdgcn_s_barrier()
; template <class Epi>
; __device__ __forceinline__ void gemm_phase(LAS unsigned char* lds, const Gemm g, const StaticOrder& S, const Epi& E) {
;     ...
;         const bool has_next = S.next(ui + 1, nxt);
;         const char* nA = has_next ? (const char*)g.A + (size_t)nxt.pm * tstepA : cA; const char* nB = has_next ? (const char*)g.Bt + (size_t)nxt.pn * tstepB : cB;
; #pragma nounroll
;         for (int t = 0; t < nt; t += 2) {
;             const bool last = (t == nt - 2);
;             const char* a1 = cA + (size_t)(t + 1) * kstep;
;             const char* a2 = last ? nA : cA + (size_t)(t + 2) * kstep; const char* b2 = last ? nB : cB + (size_t)(t + 2) * kstep;
;             const char* a3 = a2 + kstep; const char* b3 = b2 + kstep;
;             PG8_LDB(B0, 0, 0); PG8_LDB(B1, 0, 1); PG8_SCHED; PG8_LDA(At, 0, 0); PG8_STAGE(PG8_SA(1, 1), a1 + hstepA, voffA);
;             PG8_WAIT_V(8); PG8_WAIT_L(0); PG8_BAR; PG8_MMA(0, 0, At, B0); PG8_MMA(0, 1, At, B1); PG8_BAR; PG8_SCHED;
;             PG8_LDA(At, 0, 1); PG8_STAGE(PG8_SB(0, 0), b2, voffB); PG8_STAGE(PG8_SB(0, 1), b2 + hstepB, voffB); PG8_STAGE(PG8_SA(0, 0), a2, voffA);
;             PG8_WAIT_V(8); PG8_WAIT_L(0); PG8_BAR; PG8_MMA(1, 0, At, B0); PG8_MMA(1, 1, At, B1); PG8_BAR; PG8_SCHED;
.LBB0_1232:
	s_ashr_i32 s23, s22, 31
	s_lshl_b64 s[34:35], s[22:23], 19
	s_add_u32 s34, s24, s34
	s_addc_u32 s35, s25, s35
	s_and_b64 s[38:39], s[4:5], exec
	s_cselect_b32 s23, s35, s53
	s_cselect_b32 s76, s34, s52
	s_ashr_i32 s21, s20, 31
	s_lshl_b64 s[38:39], s[20:21], 19
	s_add_u32 s38, s19, s38
	s_addc_u32 s39, s33, s39
	s_and_b64 s[56:57], s[4:5], exec
	s_cselect_b32 s21, s39, s55
	s_cselect_b32 s77, s38, s54
	s_add_u32 s52, s52, 0x40080
	s_addc_u32 s53, s53, 0
	s_add_u32 s78, s54, 0x100
	s_addc_u32 s79, s55, 0
	s_mov_b32 s80, -2
	ds_read_b128 v[56:59], v189
	ds_read_b128 v[60:63], v189 offset:1024
	ds_read_b128 v[72:75], v189 offset:2048
	ds_read_b128 v[76:79], v189 offset:3072
	ds_read_b128 v[144:147], v195
	ds_read_b128 v[148:151], v195 offset:1024
	ds_read_b128 v[168:171], v195 offset:2048
	ds_read_b128 v[178:181], v195 offset:3072
	s_add_u32 s54, s52, 0xfffc0080
	s_addc_u32 s55, s53, -1
	s_cmp_eq_u32 s80, 12
	s_cselect_b32 s57, s23, s55
	s_cselect_b32 s56, s76, s54
	s_cselect_b32 s55, s21, s79
	s_cselect_b32 s54, s77, s78
	v_lshl_add_u64 v[174:175], s[52:53], 0, v[160:161]
	s_add_i32 m0, s43, 0xc000
	ds_read_b128 v[184:187], v201
	ds_read_b128 v[190:193], v201 offset:1024
	ds_read_b128 v[196:199], v201 offset:2048
	ds_read_b128 v[202:205], v201 offset:3072
	ds_read_b128 v[208:211], v201 offset:4096
	ds_read_b128 v[212:215], v201 offset:5120
	ds_read_b128 v[216:219], v201 offset:6144
	ds_read_b128 v[220:223], v201 offset:7168
	global_load_lds_dwordx4 v[174:175], off
	v_lshl_add_u64 v[174:175], s[52:53], 0, v[162:163]
	s_add_i32 m0, s43, 0xe000
	s_nop 0
	global_load_lds_dwordx4 v[174:175], off
	s_waitcnt vmcnt(8)
	s_waitcnt lgkmcnt(0)
	s_barrier
	s_setprio 1
	s_waitcnt lgkmcnt(0)
	v_mfma_f32_16x16x32_bf16 v[140:143], v[56:59], v[184:187], 0
	v_mfma_f32_16x16x32_bf16 v[136:139], v[72:75], v[184:187], 0
	v_mfma_f32_16x16x32_bf16 v[124:127], v[56:59], v[196:199], 0
	v_mfma_f32_16x16x32_bf16 v[120:123], v[72:75], v[196:199], 0
	v_mfma_f32_16x16x32_bf16 v[108:111], v[56:59], v[208:211], 0
	v_mfma_f32_16x16x32_bf16 v[104:107], v[72:75], v[208:211], 0
	v_mfma_f32_16x16x32_bf16 v[92:95], v[56:59], v[216:219], 0
	v_mfma_f32_16x16x32_bf16 v[88:91], v[72:75], v[216:219], 0
	v_mfma_f32_16x16x32_bf16 v[140:143], v[60:63], v[190:193], v[140:143]
	v_mfma_f32_16x16x32_bf16 v[136:139], v[76:79], v[190:193], v[136:139]
	v_mfma_f32_16x16x32_bf16 v[124:127], v[60:63], v[202:205], v[124:127]
	v_mfma_f32_16x16x32_bf16 v[120:123], v[76:79], v[202:205], v[120:123]
	v_mfma_f32_16x16x32_bf16 v[108:111], v[60:63], v[212:215], v[108:111]
	v_mfma_f32_16x16x32_bf16 v[104:107], v[76:79], v[212:215], v[104:107]
	v_mfma_f32_16x16x32_bf16 v[92:95], v[60:63], v[220:223], v[92:95]
	v_mfma_f32_16x16x32_bf16 v[88:91], v[76:79], v[220:223], v[88:91]
	v_mfma_f32_16x16x32_bf16 v[132:135], v[144:147], v[184:187], 0
	v_mfma_f32_16x16x32_bf16 v[128:131], v[168:171], v[184:187], 0
	v_mfma_f32_16x16x32_bf16 v[116:119], v[144:147], v[196:199], 0
	v_mfma_f32_16x16x32_bf16 v[112:115], v[168:171], v[196:199], 0
	v_mfma_f32_16x16x32_bf16 v[100:103], v[144:147], v[208:211], 0
	v_mfma_f32_16x16x32_bf16 v[96:99], v[168:171], v[208:211], 0
	v_mfma_f32_16x16x32_bf16 v[84:87], v[144:147], v[216:219], 0
	v_mfma_f32_16x16x32_bf16 v[80:83], v[168:171], v[216:219], 0
	v_mfma_f32_16x16x32_bf16 v[132:135], v[148:151], v[190:193], v[132:135]
	v_mfma_f32_16x16x32_bf16 v[128:131], v[178:181], v[190:193], v[128:131]
	v_mfma_f32_16x16x32_bf16 v[116:119], v[148:151], v[202:205], v[116:119]
	v_mfma_f32_16x16x32_bf16 v[112:115], v[178:181], v[202:205], v[112:115]
	v_mfma_f32_16x16x32_bf16 v[100:103], v[148:151], v[212:215], v[100:103]
	v_mfma_f32_16x16x32_bf16 v[96:99], v[178:181], v[212:215], v[96:99]
	v_mfma_f32_16x16x32_bf16 v[84:87], v[148:151], v[220:223], v[84:87]
	v_mfma_f32_16x16x32_bf16 v[80:83], v[178:181], v[220:223], v[80:83]
	s_setprio 0
	s_barrier
	s_add_i32 s81, s73, s58
	v_lshl_add_u64 v[174:175], s[54:55], 0, v[154:155]
	s_mov_b32 m0, s81
	ds_read_b128 v[184:187], v201 offset:16384
	ds_read_b128 v[190:193], v201 offset:17408
	ds_read_b128 v[196:199], v201 offset:18432
	ds_read_b128 v[202:205], v201 offset:19456
	ds_read_b128 v[208:211], v201 offset:20480
	ds_read_b128 v[212:215], v201 offset:21504
	ds_read_b128 v[216:219], v201 offset:22528
	ds_read_b128 v[220:223], v201 offset:23552
	global_load_lds_dwordx4 v[174:175], off
	s_add_i32 m0, s81, 0x2000
	s_add_u32 s82, s54, 0x40000
	v_lshl_add_u64 v[224:225], s[54:55], 0, v[158:159]
	s_addc_u32 s83, s55, 0
	s_add_i32 s81, s74, s58
	global_load_lds_dwordx4 v[224:225], off
	v_lshl_add_u64 v[226:227], s[82:83], 0, v[154:155]
	s_mov_b32 m0, s81
	v_lshl_add_u64 v[228:229], s[56:57], 0, v[156:157]
	global_load_lds_dwordx4 v[226:227], off
	v_lshl_add_u64 v[226:227], s[82:83], 0, v[158:159]
	s_add_i32 m0, s81, 0x2000
	s_nop 0
	global_load_lds_dwordx4 v[226:227], off
	v_lshl_add_u64 v[226:227], s[56:57], 0, v[152:153]
	s_mov_b32 m0, s43
	s_nop 0
	global_load_lds_dwordx4 v[226:227], off
	s_mov_b32 m0, s59
	s_nop 0
	global_load_lds_dwordx4 v[228:229], off
	s_waitcnt vmcnt(8)
	s_waitcnt lgkmcnt(0)
	s_barrier
; #define PG8_STAGE(bufoff, gbase, voff) do { _Pragma("unroll") for (int _i = 0; _i < 2; ++_i) \
;         __builtin_amdgcn_global_load_lds((const unsigned*)((const char*)(gbase) + (voff)[_i]), (LAS unsigned*)(lds + (bufoff) + ldsw + _i * 8192), 16, 0, 0); } while (0)
; #define PG8_LDA(dst, b, h) do { _Pragma("unroll") for (int m = 0; m < 4; ++m) _Pragma("unroll") for (int k = 0; k < 2; ++k) dst[m][k] = *(const LAS bf16x8*)(lds + PG8_SA(b, h) + aoff + m * 2048 + k * 1024); } while (0)
; #define PG8_LDB(dst, b, h) do { _Pragma("unroll") for (int n = 0; n < 2; ++n) _Pragma("unroll") for (int k = 0; k < 2; ++k) dst[n][k] = *(const LAS bf16x8*)(lds + PG8_SB(b, h) + boff + n * 2048 + k * 1024); } while (0)
; #define PG8_MMA(ai, bj, At, Bt) do { __builtin_amdgcn_s_setprio(1); _Pragma("unroll") for (int m = 0; m < 4; ++m) _Pragma("unroll") for (int n = 0; n < 2; ++n) _Pragma("unroll") for (int k = 0; k < 2; ++k) \
;         acc[ai][bj][m][n] = __builtin_amdgcn_mfma_f32_16x16x32_bf16(Bt[n][k], At[m][k], acc[ai][bj][m][n], 0, 0, 0); __builtin_amdgcn_s_setprio(0); } while (0)
; #define PG8_WAIT_V(n) asm volatile("s_waitcnt vmcnt(" #n ")" ::: "memory")
; #define PG8_WAIT_L(n) asm volatile("s_waitcnt lgkmcnt(" #n ")" ::: "memory")
; #define PG8_BAR __builtin_amdgcn_s_barrier()
; #define PG8_SCHED __builtin_amdgcn_sched_barrier(0)
; template <class Epi>
; __device__ __forceinline__ void gemm_phase(LAS unsigned char* lds, const Gemm g, const StaticOrder& S, const Epi& E) {
;     ...
;             PG8_WAIT_V(8); PG8_WAIT_L(0); PG8_BAR; PG8_MMA(1, 0, At, B0); PG8_MMA(1, 1, At, B1); PG8_BAR; PG8_SCHED;
;             PG8_LDB(B0, 1, 0); PG8_LDB(B1, 1, 1); PG8_SCHED; PG8_LDA(At, 1, 0); PG8_STAGE(PG8_SA(0, 1), a2 + hstepA, voffA);
;             PG8_WAIT_V(8); PG8_WAIT_L(0); PG8_BAR; PG8_MMA(0, 0, At, B0); PG8_MMA(0, 1, At, B1); PG8_BAR; PG8_SCHED;
	s_setprio 1
	s_waitcnt lgkmcnt(0)
	v_mfma_f32_16x16x32_bf16 v[68:71], v[56:59], v[184:187], 0
	v_mfma_f32_16x16x32_bf16 v[64:67], v[72:75], v[184:187], 0
	v_mfma_f32_16x16x32_bf16 v[44:47], v[56:59], v[196:199], 0
	v_mfma_f32_16x16x32_bf16 v[40:43], v[72:75], v[196:199], 0
	v_mfma_f32_16x16x32_bf16 v[28:31], v[56:59], v[208:211], 0
	v_mfma_f32_16x16x32_bf16 v[24:27], v[72:75], v[208:211], 0
	v_mfma_f32_16x16x32_bf16 v[12:15], v[56:59], v[216:219], 0
	v_mfma_f32_16x16x32_bf16 v[8:11], v[72:75], v[216:219], 0
	v_mfma_f32_16x16x32_bf16 v[68:71], v[60:63], v[190:193], v[68:71]
	v_mfma_f32_16x16x32_bf16 v[64:67], v[76:79], v[190:193], v[64:67]
	v_mfma_f32_16x16x32_bf16 v[44:47], v[60:63], v[202:205], v[44:47]
	v_mfma_f32_16x16x32_bf16 v[40:43], v[76:79], v[202:205], v[40:43]
	v_mfma_f32_16x16x32_bf16 v[28:31], v[60:63], v[212:215], v[28:31]
	v_mfma_f32_16x16x32_bf16 v[24:27], v[76:79], v[212:215], v[24:27]
	v_mfma_f32_16x16x32_bf16 v[12:15], v[60:63], v[220:223], v[12:15]
	v_mfma_f32_16x16x32_bf16 v[8:11], v[76:79], v[220:223], v[8:11]
	v_mfma_f32_16x16x32_bf16 v[52:55], v[144:147], v[184:187], 0
	v_mfma_f32_16x16x32_bf16 v[48:51], v[168:171], v[184:187], 0
	v_mfma_f32_16x16x32_bf16 v[36:39], v[144:147], v[196:199], 0
	v_mfma_f32_16x16x32_bf16 v[32:35], v[168:171], v[196:199], 0
	v_mfma_f32_16x16x32_bf16 v[20:23], v[144:147], v[208:211], 0
	v_mfma_f32_16x16x32_bf16 v[16:19], v[168:171], v[208:211], 0
	v_mfma_f32_16x16x32_bf16 v[4:7], v[144:147], v[216:219], 0
	v_mfma_f32_16x16x32_bf16 v[0:3], v[168:171], v[216:219], 0
	v_mfma_f32_16x16x32_bf16 v[52:55], v[148:151], v[190:193], v[52:55]
	v_mfma_f32_16x16x32_bf16 v[48:51], v[178:181], v[190:193], v[48:51]
	v_mfma_f32_16x16x32_bf16 v[36:39], v[148:151], v[202:205], v[36:39]
	v_mfma_f32_16x16x32_bf16 v[32:35], v[178:181], v[202:205], v[32:35]
	v_mfma_f32_16x16x32_bf16 v[20:23], v[148:151], v[212:215], v[20:23]
	v_mfma_f32_16x16x32_bf16 v[16:19], v[178:181], v[212:215], v[16:19]
	v_mfma_f32_16x16x32_bf16 v[4:7], v[148:151], v[220:223], v[4:7]
	v_mfma_f32_16x16x32_bf16 v[0:3], v[178:181], v[220:223], v[0:3]
	s_setprio 0
	s_barrier
	s_add_i32 s81, 0, 0x18000
	s_add_i32 s82, 0, 0x1c000
	v_add_u32_e32 v76, s81, v183
	v_add_u32_e32 v172, s82, v183
	ds_read_b128 v[56:59], v76
	ds_read_b128 v[60:63], v76 offset:1024
	ds_read_b128 v[72:75], v76 offset:2048
	ds_read_b128 v[76:79], v76 offset:3072
	ds_read_b128 v[144:147], v172
	ds_read_b128 v[148:151], v172 offset:1024
	ds_read_b128 v[168:171], v172 offset:2048
	ds_read_b128 v[178:181], v172 offset:3072
	s_add_u32 s56, s56, 0x40000
	s_addc_u32 s57, s57, 0
	s_mov_b32 m0, s62
	v_lshl_add_u64 v[230:231], s[56:57], 0, v[152:153]
	ds_read_b128 v[184:187], v201 offset:32768
	ds_read_b128 v[190:193], v201 offset:33792
	ds_read_b128 v[196:199], v201 offset:34816
	ds_read_b128 v[202:205], v201 offset:35840
	ds_read_b128 v[208:211], v201 offset:36864
	ds_read_b128 v[212:215], v201 offset:37888
	ds_read_b128 v[216:219], v201 offset:38912
	ds_read_b128 v[220:223], v201 offset:39936
	global_load_lds_dwordx4 v[230:231], off
	v_lshl_add_u64 v[230:231], s[56:57], 0, v[156:157]
	s_mov_b32 m0, s63
	s_nop 0
	global_load_lds_dwordx4 v[230:231], off
	s_waitcnt vmcnt(8)
	s_waitcnt lgkmcnt(0)
	s_barrier
	s_setprio 1
	s_waitcnt lgkmcnt(0)
	v_mfma_f32_16x16x32_bf16 v[140:143], v[56:59], v[184:187], v[140:143]
	v_mfma_f32_16x16x32_bf16 v[136:139], v[72:75], v[184:187], v[136:139]
	v_mfma_f32_16x16x32_bf16 v[124:127], v[56:59], v[196:199], v[124:127]
	v_mfma_f32_16x16x32_bf16 v[120:123], v[72:75], v[196:199], v[120:123]
	v_mfma_f32_16x16x32_bf16 v[108:111], v[56:59], v[208:211], v[108:111]
	v_mfma_f32_16x16x32_bf16 v[104:107], v[72:75], v[208:211], v[104:107]
	v_mfma_f32_16x16x32_bf16 v[92:95], v[56:59], v[216:219], v[92:95]
	v_mfma_f32_16x16x32_bf16 v[88:91], v[72:75], v[216:219], v[88:91]
	v_mfma_f32_16x16x32_bf16 v[140:143], v[60:63], v[190:193], v[140:143]
	v_mfma_f32_16x16x32_bf16 v[136:139], v[76:79], v[190:193], v[136:139]
	v_mfma_f32_16x16x32_bf16 v[124:127], v[60:63], v[202:205], v[124:127]
	v_mfma_f32_16x16x32_bf16 v[120:123], v[76:79], v[202:205], v[120:123]
	v_mfma_f32_16x16x32_bf16 v[108:111], v[60:63], v[212:215], v[108:111]
	v_mfma_f32_16x16x32_bf16 v[104:107], v[76:79], v[212:215], v[104:107]
	v_mfma_f32_16x16x32_bf16 v[92:95], v[60:63], v[220:223], v[92:95]
	v_mfma_f32_16x16x32_bf16 v[88:91], v[76:79], v[220:223], v[88:91]
	v_mfma_f32_16x16x32_bf16 v[132:135], v[144:147], v[184:187], v[132:135]
	v_mfma_f32_16x16x32_bf16 v[128:131], v[168:171], v[184:187], v[128:131]
	v_mfma_f32_16x16x32_bf16 v[116:119], v[144:147], v[196:199], v[116:119]
	v_mfma_f32_16x16x32_bf16 v[112:115], v[168:171], v[196:199], v[112:115]
	v_mfma_f32_16x16x32_bf16 v[100:103], v[144:147], v[208:211], v[100:103]
	v_mfma_f32_16x16x32_bf16 v[96:99], v[168:171], v[208:211], v[96:99]
	v_mfma_f32_16x16x32_bf16 v[84:87], v[144:147], v[216:219], v[84:87]
	v_mfma_f32_16x16x32_bf16 v[80:83], v[168:171], v[216:219], v[80:83]
	v_mfma_f32_16x16x32_bf16 v[132:135], v[148:151], v[190:193], v[132:135]
	v_mfma_f32_16x16x32_bf16 v[128:131], v[178:181], v[190:193], v[128:131]
	v_mfma_f32_16x16x32_bf16 v[116:119], v[148:151], v[202:205], v[116:119]
	v_mfma_f32_16x16x32_bf16 v[112:115], v[178:181], v[202:205], v[112:115]
	v_mfma_f32_16x16x32_bf16 v[100:103], v[148:151], v[212:215], v[100:103]
	v_mfma_f32_16x16x32_bf16 v[96:99], v[178:181], v[212:215], v[96:99]
	v_mfma_f32_16x16x32_bf16 v[84:87], v[148:151], v[220:223], v[84:87]
	v_mfma_f32_16x16x32_bf16 v[80:83], v[178:181], v[220:223], v[80:83]
	s_setprio 0
	s_barrier
; #define PG8_STAGE(bufoff, gbase, voff) do { _Pragma("unroll") for (int _i = 0; _i < 2; ++_i) \
;         __builtin_amdgcn_global_load_lds((const unsigned*)((const char*)(gbase) + (voff)[_i]), (LAS unsigned*)(lds + (bufoff) + ldsw + _i * 8192), 16, 0, 0); } while (0)
; #define PG8_LDA(dst, b, h) do { _Pragma("unroll") for (int m = 0; m < 4; ++m) _Pragma("unroll") for (int k = 0; k < 2; ++k) dst[m][k] = *(const LAS bf16x8*)(lds + PG8_SA(b, h) + aoff + m * 2048 + k * 1024); } while (0)
; #define PG8_LDB(dst, b, h) do { _Pragma("unroll") for (int n = 0; n < 2; ++n) _Pragma("unroll") for (int k = 0; k < 2; ++k) dst[n][k] = *(const LAS bf16x8*)(lds + PG8_SB(b, h) + boff + n * 2048 + k * 1024); } while (0)
; #define PG8_MMA(ai, bj, At, Bt) do { __builtin_amdgcn_s_setprio(1); _Pragma("unroll") for (int m = 0; m < 4; ++m) _Pragma("unroll") for (int n = 0; n < 2; ++n) _Pragma("unroll") for (int k = 0; k < 2; ++k) \
;         acc[ai][bj][m][n] = __builtin_amdgcn_mfma_f32_16x16x32_bf16(Bt[n][k], At[m][k], acc[ai][bj][m][n], 0, 0, 0); __builtin_amdgcn_s_setprio(0); } while (0)
; #define PG8_WAIT_V(n) asm volatile("s_waitcnt vmcnt(" #n ")" ::: "memory")
; #define PG8_WAIT_L(n) asm volatile("s_waitcnt lgkmcnt(" #n ")" ::: "memory")
; #define PG8_BAR __builtin_amdgcn_s_barrier()
; #define PG8_SCHED __builtin_amdgcn_sched_barrier(0)
; template <class Epi>
; __device__ __forceinline__ void gemm_phase(LAS unsigned char* lds, const Gemm g, const StaticOrder& S, const Epi& E) {
;     ...
;             PG8_LDB(B0, 0, 0); PG8_LDB(B1, 0, 1); PG8_SCHED; PG8_LDA(At, 0, 0); PG8_STAGE(PG8_SA(1, 1), a1 + hstepA, voffA);
;     ...
;             PG8_LDA(At, 1, 1); PG8_STAGE(PG8_SB(1, 0), b3, voffB); PG8_STAGE(PG8_SB(1, 1), b3 + hstepB, voffB); PG8_STAGE(PG8_SA(1, 0), a3, voffA);
;             PG8_WAIT_V(8); PG8_WAIT_L(0); PG8_BAR; PG8_MMA(1, 0, At, B0); PG8_MMA(1, 1, At, B1); PG8_BAR; PG8_SCHED;
	s_add_i32 s56, s81, s58
	v_lshl_add_u64 v[174:175], v[174:175], 0, s[12:13]
	s_mov_b32 m0, s56
	ds_read_b128 v[184:187], v201 offset:49152
	ds_read_b128 v[190:193], v201 offset:50176
	ds_read_b128 v[196:199], v201 offset:51200
	ds_read_b128 v[202:205], v201 offset:52224
	ds_read_b128 v[208:211], v201 offset:53248
	ds_read_b128 v[212:215], v201 offset:54272
	ds_read_b128 v[216:219], v201 offset:55296
	ds_read_b128 v[220:223], v201 offset:56320
	global_load_lds_dwordx4 v[174:175], off
	s_add_i32 m0, s56, 0x2000
	s_add_u32 s54, s54, 0x40080
	v_lshl_add_u64 v[174:175], v[224:225], 0, s[12:13]
	s_addc_u32 s55, s55, 0
	s_add_i32 s56, s82, s58
	global_load_lds_dwordx4 v[174:175], off
	v_lshl_add_u64 v[174:175], s[54:55], 0, v[154:155]
	s_mov_b32 m0, s56
	s_nop 0
	global_load_lds_dwordx4 v[174:175], off
	v_lshl_add_u64 v[174:175], s[54:55], 0, v[158:159]
	s_add_i32 m0, s56, 0x2000
	s_nop 0
	global_load_lds_dwordx4 v[174:175], off
	v_lshl_add_u64 v[174:175], v[226:227], 0, s[12:13]
	s_mov_b32 m0, s69
	s_nop 0
	global_load_lds_dwordx4 v[174:175], off
	v_lshl_add_u64 v[174:175], v[228:229], 0, s[12:13]
	s_mov_b32 m0, s70
	s_nop 0
	global_load_lds_dwordx4 v[174:175], off
	s_waitcnt vmcnt(8)
	s_waitcnt lgkmcnt(0)
	s_barrier
	s_setprio 1
	s_waitcnt lgkmcnt(0)
	v_mfma_f32_16x16x32_bf16 v[68:71], v[56:59], v[184:187], v[68:71]
	v_mfma_f32_16x16x32_bf16 v[64:67], v[72:75], v[184:187], v[64:67]
	v_mfma_f32_16x16x32_bf16 v[44:47], v[56:59], v[196:199], v[44:47]
	v_mfma_f32_16x16x32_bf16 v[40:43], v[72:75], v[196:199], v[40:43]
	v_mfma_f32_16x16x32_bf16 v[28:31], v[56:59], v[208:211], v[28:31]
	v_mfma_f32_16x16x32_bf16 v[24:27], v[72:75], v[208:211], v[24:27]
	v_mfma_f32_16x16x32_bf16 v[12:15], v[56:59], v[216:219], v[12:15]
	v_mfma_f32_16x16x32_bf16 v[8:11], v[72:75], v[216:219], v[8:11]
	v_mfma_f32_16x16x32_bf16 v[68:71], v[60:63], v[190:193], v[68:71]
	v_mfma_f32_16x16x32_bf16 v[64:67], v[76:79], v[190:193], v[64:67]
	v_mfma_f32_16x16x32_bf16 v[44:47], v[60:63], v[202:205], v[44:47]
	v_mfma_f32_16x16x32_bf16 v[40:43], v[76:79], v[202:205], v[40:43]
	v_mfma_f32_16x16x32_bf16 v[28:31], v[60:63], v[212:215], v[28:31]
	v_mfma_f32_16x16x32_bf16 v[24:27], v[76:79], v[212:215], v[24:27]
	v_mfma_f32_16x16x32_bf16 v[12:15], v[60:63], v[220:223], v[12:15]
	v_mfma_f32_16x16x32_bf16 v[8:11], v[76:79], v[220:223], v[8:11]
	v_mfma_f32_16x16x32_bf16 v[52:55], v[144:147], v[184:187], v[52:55]
	v_mfma_f32_16x16x32_bf16 v[48:51], v[168:171], v[184:187], v[48:51]
	v_mfma_f32_16x16x32_bf16 v[36:39], v[144:147], v[196:199], v[36:39]
	v_mfma_f32_16x16x32_bf16 v[32:35], v[168:171], v[196:199], v[32:35]
	v_mfma_f32_16x16x32_bf16 v[20:23], v[144:147], v[208:211], v[20:23]
	v_mfma_f32_16x16x32_bf16 v[16:19], v[168:171], v[208:211], v[16:19]
	v_mfma_f32_16x16x32_bf16 v[4:7], v[144:147], v[216:219], v[4:7]
	v_mfma_f32_16x16x32_bf16 v[0:3], v[168:171], v[216:219], v[0:3]
	v_mfma_f32_16x16x32_bf16 v[52:55], v[148:151], v[190:193], v[52:55]
	v_mfma_f32_16x16x32_bf16 v[48:51], v[178:181], v[190:193], v[48:51]
	v_mfma_f32_16x16x32_bf16 v[36:39], v[148:151], v[202:205], v[36:39]
	v_mfma_f32_16x16x32_bf16 v[32:35], v[178:181], v[202:205], v[32:35]
	v_mfma_f32_16x16x32_bf16 v[20:23], v[148:151], v[212:215], v[20:23]
	v_mfma_f32_16x16x32_bf16 v[16:19], v[178:181], v[212:215], v[16:19]
	v_mfma_f32_16x16x32_bf16 v[4:7], v[148:151], v[220:223], v[4:7]
	v_mfma_f32_16x16x32_bf16 v[0:3], v[178:181], v[220:223], v[0:3]
	s_setprio 0
	s_barrier
	s_add_i32 s80, s80, 2
	s_add_u32 s52, s52, 0x100
	s_addc_u32 s53, s53, 0
	s_add_u32 s78, s78, 0x100
	s_addc_u32 s79, s79, 0
	s_cmp_gt_u32 s80, 13
.LBB0_1233:
	ds_read_b128 v[56:59], v189
	ds_read_b128 v[60:63], v189 offset:1024
	ds_read_b128 v[72:75], v189 offset:2048
	ds_read_b128 v[76:79], v189 offset:3072
	ds_read_b128 v[144:147], v195
	ds_read_b128 v[148:151], v195 offset:1024
	ds_read_b128 v[168:171], v195 offset:2048
	ds_read_b128 v[178:181], v195 offset:3072
	s_add_u32 s54, s52, 0xfffc0080
	s_addc_u32 s55, s53, -1
	s_cmp_eq_u32 s80, 12
	s_cselect_b32 s57, s23, s55
	s_cselect_b32 s56, s76, s54
	s_cselect_b32 s55, s21, s79
	s_cselect_b32 s54, s77, s78
	v_lshl_add_u64 v[174:175], s[52:53], 0, v[160:161]
	s_add_i32 m0, s43, 0xc000
	ds_read_b128 v[184:187], v201
	ds_read_b128 v[190:193], v201 offset:1024
	ds_read_b128 v[196:199], v201 offset:2048
	ds_read_b128 v[202:205], v201 offset:3072
	ds_read_b128 v[208:211], v201 offset:4096
	ds_read_b128 v[212:215], v201 offset:5120
	ds_read_b128 v[216:219], v201 offset:6144
	ds_read_b128 v[220:223], v201 offset:7168
	global_load_lds_dwordx4 v[174:175], off
	v_lshl_add_u64 v[174:175], s[52:53], 0, v[162:163]
	s_add_i32 m0, s43, 0xe000
	s_nop 0
	global_load_lds_dwordx4 v[174:175], off
	s_waitcnt vmcnt(8)
	s_waitcnt lgkmcnt(0)
	s_barrier
; #define PG8_STAGE(bufoff, gbase, voff) do { _Pragma("unroll") for (int _i = 0; _i < 2; ++_i) \
;         __builtin_amdgcn_global_load_lds((const unsigned*)((const char*)(gbase) + (voff)[_i]), (LAS unsigned*)(lds + (bufoff) + ldsw + _i * 8192), 16, 0, 0); } while (0)
; #define PG8_LDA(dst, b, h) do { _Pragma("unroll") for (int m = 0; m < 4; ++m) _Pragma("unroll") for (int k = 0; k < 2; ++k) dst[m][k] = *(const LAS bf16x8*)(lds + PG8_SA(b, h) + aoff + m * 2048 + k * 1024); } while (0)
; #define PG8_MMA(ai, bj, At, Bt) do { __builtin_amdgcn_s_setprio(1); _Pragma("unroll") for (int m = 0; m < 4; ++m) _Pragma("unroll") for (int n = 0; n < 2; ++n) _Pragma("unroll") for (int k = 0; k < 2; ++k) \
;         acc[ai][bj][m][n] = __builtin_amdgcn_mfma_f32_16x16x32_bf16(Bt[n][k], At[m][k], acc[ai][bj][m][n], 0, 0, 0); __builtin_amdgcn_s_setprio(0); } while (0)
; #define PG8_WAIT_V(n) asm volatile("s_waitcnt vmcnt(" #n ")" ::: "memory")
; #define PG8_WAIT_L(n) asm volatile("s_waitcnt lgkmcnt(" #n ")" ::: "memory")
; #define PG8_BAR __builtin_amdgcn_s_barrier()
; #define PG8_SCHED __builtin_amdgcn_sched_barrier(0)
; template <class Epi>
; __device__ __forceinline__ void gemm_phase(LAS unsigned char* lds, const Gemm g, const StaticOrder& S, const Epi& E) {
;     ...
;             PG8_WAIT_V(8); PG8_WAIT_L(0); PG8_BAR; PG8_MMA(0, 0, At, B0); PG8_MMA(0, 1, At, B1); PG8_BAR; PG8_SCHED;
;             PG8_LDA(At, 0, 1); PG8_STAGE(PG8_SB(0, 0), b2, voffB); PG8_STAGE(PG8_SB(0, 1), b2 + hstepB, voffB); PG8_STAGE(PG8_SA(0, 0), a2, voffA);
;             PG8_WAIT_V(8); PG8_WAIT_L(0); PG8_BAR; PG8_MMA(1, 0, At, B0); PG8_MMA(1, 1, At, B1); PG8_BAR; PG8_SCHED;
	s_setprio 1
	s_waitcnt lgkmcnt(0)
	v_mfma_f32_16x16x32_bf16 v[140:143], v[56:59], v[184:187], v[140:143]
	v_mfma_f32_16x16x32_bf16 v[136:139], v[72:75], v[184:187], v[136:139]
	v_mfma_f32_16x16x32_bf16 v[124:127], v[56:59], v[196:199], v[124:127]
	v_mfma_f32_16x16x32_bf16 v[120:123], v[72:75], v[196:199], v[120:123]
	v_mfma_f32_16x16x32_bf16 v[108:111], v[56:59], v[208:211], v[108:111]
	v_mfma_f32_16x16x32_bf16 v[104:107], v[72:75], v[208:211], v[104:107]
	v_mfma_f32_16x16x32_bf16 v[92:95], v[56:59], v[216:219], v[92:95]
	v_mfma_f32_16x16x32_bf16 v[88:91], v[72:75], v[216:219], v[88:91]
	v_mfma_f32_16x16x32_bf16 v[140:143], v[60:63], v[190:193], v[140:143]
	v_mfma_f32_16x16x32_bf16 v[136:139], v[76:79], v[190:193], v[136:139]
	v_mfma_f32_16x16x32_bf16 v[124:127], v[60:63], v[202:205], v[124:127]
	v_mfma_f32_16x16x32_bf16 v[120:123], v[76:79], v[202:205], v[120:123]
	v_mfma_f32_16x16x32_bf16 v[108:111], v[60:63], v[212:215], v[108:111]
	v_mfma_f32_16x16x32_bf16 v[104:107], v[76:79], v[212:215], v[104:107]
	v_mfma_f32_16x16x32_bf16 v[92:95], v[60:63], v[220:223], v[92:95]
	v_mfma_f32_16x16x32_bf16 v[88:91], v[76:79], v[220:223], v[88:91]
	v_mfma_f32_16x16x32_bf16 v[132:135], v[144:147], v[184:187], v[132:135]
	v_mfma_f32_16x16x32_bf16 v[128:131], v[168:171], v[184:187], v[128:131]
	v_mfma_f32_16x16x32_bf16 v[116:119], v[144:147], v[196:199], v[116:119]
	v_mfma_f32_16x16x32_bf16 v[112:115], v[168:171], v[196:199], v[112:115]
	v_mfma_f32_16x16x32_bf16 v[100:103], v[144:147], v[208:211], v[100:103]
	v_mfma_f32_16x16x32_bf16 v[96:99], v[168:171], v[208:211], v[96:99]
	v_mfma_f32_16x16x32_bf16 v[84:87], v[144:147], v[216:219], v[84:87]
	v_mfma_f32_16x16x32_bf16 v[80:83], v[168:171], v[216:219], v[80:83]
	v_mfma_f32_16x16x32_bf16 v[132:135], v[148:151], v[190:193], v[132:135]
	v_mfma_f32_16x16x32_bf16 v[128:131], v[178:181], v[190:193], v[128:131]
	v_mfma_f32_16x16x32_bf16 v[116:119], v[148:151], v[202:205], v[116:119]
	v_mfma_f32_16x16x32_bf16 v[112:115], v[178:181], v[202:205], v[112:115]
	v_mfma_f32_16x16x32_bf16 v[100:103], v[148:151], v[212:215], v[100:103]
	v_mfma_f32_16x16x32_bf16 v[96:99], v[178:181], v[212:215], v[96:99]
	v_mfma_f32_16x16x32_bf16 v[84:87], v[148:151], v[220:223], v[84:87]
	v_mfma_f32_16x16x32_bf16 v[80:83], v[178:181], v[220:223], v[80:83]
	s_setprio 0
	s_barrier
	s_add_i32 s81, s73, s58
	v_lshl_add_u64 v[174:175], s[54:55], 0, v[154:155]
	s_mov_b32 m0, s81
	ds_read_b128 v[184:187], v201 offset:16384
	ds_read_b128 v[190:193], v201 offset:17408
	ds_read_b128 v[196:199], v201 offset:18432
	ds_read_b128 v[202:205], v201 offset:19456
	ds_read_b128 v[208:211], v201 offset:20480
	ds_read_b128 v[212:215], v201 offset:21504
	ds_read_b128 v[216:219], v201 offset:22528
	ds_read_b128 v[220:223], v201 offset:23552
	global_load_lds_dwordx4 v[174:175], off
	s_add_i32 m0, s81, 0x2000
	s_add_u32 s82, s54, 0x40000
	v_lshl_add_u64 v[224:225], s[54:55], 0, v[158:159]
	s_addc_u32 s83, s55, 0
	s_add_i32 s81, s74, s58
	global_load_lds_dwordx4 v[224:225], off
	v_lshl_add_u64 v[226:227], s[82:83], 0, v[154:155]
	s_mov_b32 m0, s81
	v_lshl_add_u64 v[228:229], s[56:57], 0, v[156:157]
	global_load_lds_dwordx4 v[226:227], off
	v_lshl_add_u64 v[226:227], s[82:83], 0, v[158:159]
	s_add_i32 m0, s81, 0x2000
	s_nop 0
	global_load_lds_dwordx4 v[226:227], off
	v_lshl_add_u64 v[226:227], s[56:57], 0, v[152:153]
	s_mov_b32 m0, s43
	s_nop 0
	global_load_lds_dwordx4 v[226:227], off
	s_mov_b32 m0, s59
	s_nop 0
	global_load_lds_dwordx4 v[228:229], off
	s_waitcnt vmcnt(8)
	s_waitcnt lgkmcnt(0)
	s_barrier
	s_setprio 1
	s_waitcnt lgkmcnt(0)
	v_mfma_f32_16x16x32_bf16 v[68:71], v[56:59], v[184:187], v[68:71]
	v_mfma_f32_16x16x32_bf16 v[64:67], v[72:75], v[184:187], v[64:67]
	v_mfma_f32_16x16x32_bf16 v[44:47], v[56:59], v[196:199], v[44:47]
	v_mfma_f32_16x16x32_bf16 v[40:43], v[72:75], v[196:199], v[40:43]
	v_mfma_f32_16x16x32_bf16 v[28:31], v[56:59], v[208:211], v[28:31]
	v_mfma_f32_16x16x32_bf16 v[24:27], v[72:75], v[208:211], v[24:27]
	v_mfma_f32_16x16x32_bf16 v[12:15], v[56:59], v[216:219], v[12:15]
	v_mfma_f32_16x16x32_bf16 v[8:11], v[72:75], v[216:219], v[8:11]
	v_mfma_f32_16x16x32_bf16 v[68:71], v[60:63], v[190:193], v[68:71]
	v_mfma_f32_16x16x32_bf16 v[64:67], v[76:79], v[190:193], v[64:67]
	v_mfma_f32_16x16x32_bf16 v[44:47], v[60:63], v[202:205], v[44:47]
	v_mfma_f32_16x16x32_bf16 v[40:43], v[76:79], v[202:205], v[40:43]
	v_mfma_f32_16x16x32_bf16 v[28:31], v[60:63], v[212:215], v[28:31]
	v_mfma_f32_16x16x32_bf16 v[24:27], v[76:79], v[212:215], v[24:27]
	v_mfma_f32_16x16x32_bf16 v[12:15], v[60:63], v[220:223], v[12:15]
	v_mfma_f32_16x16x32_bf16 v[8:11], v[76:79], v[220:223], v[8:11]
	v_mfma_f32_16x16x32_bf16 v[52:55], v[144:147], v[184:187], v[52:55]
	v_mfma_f32_16x16x32_bf16 v[48:51], v[168:171], v[184:187], v[48:51]
	v_mfma_f32_16x16x32_bf16 v[36:39], v[144:147], v[196:199], v[36:39]
	v_mfma_f32_16x16x32_bf16 v[32:35], v[168:171], v[196:199], v[32:35]
	v_mfma_f32_16x16x32_bf16 v[20:23], v[144:147], v[208:211], v[20:23]
	v_mfma_f32_16x16x32_bf16 v[16:19], v[168:171], v[208:211], v[16:19]
	v_mfma_f32_16x16x32_bf16 v[4:7], v[144:147], v[216:219], v[4:7]
	v_mfma_f32_16x16x32_bf16 v[0:3], v[168:171], v[216:219], v[0:3]
	v_mfma_f32_16x16x32_bf16 v[52:55], v[148:151], v[190:193], v[52:55]
	v_mfma_f32_16x16x32_bf16 v[48:51], v[178:181], v[190:193], v[48:51]
	v_mfma_f32_16x16x32_bf16 v[36:39], v[148:151], v[202:205], v[36:39]
	v_mfma_f32_16x16x32_bf16 v[32:35], v[178:181], v[202:205], v[32:35]
	v_mfma_f32_16x16x32_bf16 v[20:23], v[148:151], v[212:215], v[20:23]
	v_mfma_f32_16x16x32_bf16 v[16:19], v[178:181], v[212:215], v[16:19]
	v_mfma_f32_16x16x32_bf16 v[4:7], v[148:151], v[220:223], v[4:7]
	v_mfma_f32_16x16x32_bf16 v[0:3], v[178:181], v[220:223], v[0:3]
	s_setprio 0
	s_barrier
; #define PG8_STAGE(bufoff, gbase, voff) do { _Pragma("unroll") for (int _i = 0; _i < 2; ++_i) \
;         __builtin_amdgcn_global_load_lds((const unsigned*)((const char*)(gbase) + (voff)[_i]), (LAS unsigned*)(lds + (bufoff) + ldsw + _i * 8192), 16, 0, 0); } while (0)
; #define PG8_LDA(dst, b, h) do { _Pragma("unroll") for (int m = 0; m < 4; ++m) _Pragma("unroll") for (int k = 0; k < 2; ++k) dst[m][k] = *(const LAS bf16x8*)(lds + PG8_SA(b, h) + aoff + m * 2048 + k * 1024); } while (0)
; #define PG8_LDB(dst, b, h) do { _Pragma("unroll") for (int n = 0; n < 2; ++n) _Pragma("unroll") for (int k = 0; k < 2; ++k) dst[n][k] = *(const LAS bf16x8*)(lds + PG8_SB(b, h) + boff + n * 2048 + k * 1024); } while (0)
; #define PG8_MMA(ai, bj, At, Bt) do { __builtin_amdgcn_s_setprio(1); _Pragma("unroll") for (int m = 0; m < 4; ++m) _Pragma("unroll") for (int n = 0; n < 2; ++n) _Pragma("unroll") for (int k = 0; k < 2; ++k) \
;         acc[ai][bj][m][n] = __builtin_amdgcn_mfma_f32_16x16x32_bf16(Bt[n][k], At[m][k], acc[ai][bj][m][n], 0, 0, 0); __builtin_amdgcn_s_setprio(0); } while (0)
; #define PG8_WAIT_V(n) asm volatile("s_waitcnt vmcnt(" #n ")" ::: "memory")
; #define PG8_WAIT_L(n) asm volatile("s_waitcnt lgkmcnt(" #n ")" ::: "memory")
; #define PG8_BAR __builtin_amdgcn_s_barrier()
; #define PG8_SCHED __builtin_amdgcn_sched_barrier(0)
; template <class Epi>
; __device__ __forceinline__ void gemm_phase(LAS unsigned char* lds, const Gemm g, const StaticOrder& S, const Epi& E) {
;     ...
;             PG8_LDB(B0, 1, 0); PG8_LDB(B1, 1, 1); PG8_SCHED; PG8_LDA(At, 1, 0); PG8_STAGE(PG8_SA(0, 1), a2 + hstepA, voffA);
;             PG8_WAIT_V(8); PG8_WAIT_L(0); PG8_BAR; PG8_MMA(0, 0, At, B0); PG8_MMA(0, 1, At, B1); PG8_BAR; PG8_SCHED;
	s_add_i32 s81, 0, 0x18000
	s_add_i32 s82, 0, 0x1c000
	v_add_u32_e32 v76, s81, v183
	v_add_u32_e32 v172, s82, v183
	ds_read_b128 v[56:59], v76
	ds_read_b128 v[60:63], v76 offset:1024
	ds_read_b128 v[72:75], v76 offset:2048
	ds_read_b128 v[76:79], v76 offset:3072
	ds_read_b128 v[144:147], v172
	ds_read_b128 v[148:151], v172 offset:1024
	ds_read_b128 v[168:171], v172 offset:2048
	ds_read_b128 v[178:181], v172 offset:3072
	s_add_u32 s56, s56, 0x40000
	s_addc_u32 s57, s57, 0
	s_mov_b32 m0, s62
	v_lshl_add_u64 v[230:231], s[56:57], 0, v[152:153]
	ds_read_b128 v[184:187], v201 offset:32768
	ds_read_b128 v[190:193], v201 offset:33792
	ds_read_b128 v[196:199], v201 offset:34816
	ds_read_b128 v[202:205], v201 offset:35840
	ds_read_b128 v[208:211], v201 offset:36864
	ds_read_b128 v[212:215], v201 offset:37888
	ds_read_b128 v[216:219], v201 offset:38912
	ds_read_b128 v[220:223], v201 offset:39936
	global_load_lds_dwordx4 v[230:231], off
	v_lshl_add_u64 v[230:231], s[56:57], 0, v[156:157]
	s_mov_b32 m0, s63
	s_nop 0
	global_load_lds_dwordx4 v[230:231], off
	s_waitcnt vmcnt(8)
	s_waitcnt lgkmcnt(0)
	s_barrier
	s_setprio 1
	s_waitcnt lgkmcnt(0)
	v_mfma_f32_16x16x32_bf16 v[140:143], v[56:59], v[184:187], v[140:143]
	v_mfma_f32_16x16x32_bf16 v[136:139], v[72:75], v[184:187], v[136:139]
	v_mfma_f32_16x16x32_bf16 v[124:127], v[56:59], v[196:199], v[124:127]
	v_mfma_f32_16x16x32_bf16 v[120:123], v[72:75], v[196:199], v[120:123]
	v_mfma_f32_16x16x32_bf16 v[108:111], v[56:59], v[208:211], v[108:111]
	v_mfma_f32_16x16x32_bf16 v[104:107], v[72:75], v[208:211], v[104:107]
	v_mfma_f32_16x16x32_bf16 v[92:95], v[56:59], v[216:219], v[92:95]
	v_mfma_f32_16x16x32_bf16 v[88:91], v[72:75], v[216:219], v[88:91]
	v_mfma_f32_16x16x32_bf16 v[140:143], v[60:63], v[190:193], v[140:143]
	v_mfma_f32_16x16x32_bf16 v[136:139], v[76:79], v[190:193], v[136:139]
	v_mfma_f32_16x16x32_bf16 v[124:127], v[60:63], v[202:205], v[124:127]
	v_mfma_f32_16x16x32_bf16 v[120:123], v[76:79], v[202:205], v[120:123]
	v_mfma_f32_16x16x32_bf16 v[108:111], v[60:63], v[212:215], v[108:111]
	v_mfma_f32_16x16x32_bf16 v[104:107], v[76:79], v[212:215], v[104:107]
	v_mfma_f32_16x16x32_bf16 v[92:95], v[60:63], v[220:223], v[92:95]
	v_mfma_f32_16x16x32_bf16 v[88:91], v[76:79], v[220:223], v[88:91]
	v_mfma_f32_16x16x32_bf16 v[132:135], v[144:147], v[184:187], v[132:135]
	v_mfma_f32_16x16x32_bf16 v[128:131], v[168:171], v[184:187], v[128:131]
	v_mfma_f32_16x16x32_bf16 v[116:119], v[144:147], v[196:199], v[116:119]
	v_mfma_f32_16x16x32_bf16 v[112:115], v[168:171], v[196:199], v[112:115]
	v_mfma_f32_16x16x32_bf16 v[100:103], v[144:147], v[208:211], v[100:103]
	v_mfma_f32_16x16x32_bf16 v[96:99], v[168:171], v[208:211], v[96:99]
	v_mfma_f32_16x16x32_bf16 v[84:87], v[144:147], v[216:219], v[84:87]
	v_mfma_f32_16x16x32_bf16 v[80:83], v[168:171], v[216:219], v[80:83]
	v_mfma_f32_16x16x32_bf16 v[132:135], v[148:151], v[190:193], v[132:135]
	v_mfma_f32_16x16x32_bf16 v[128:131], v[178:181], v[190:193], v[128:131]
	v_mfma_f32_16x16x32_bf16 v[116:119], v[148:151], v[202:205], v[116:119]
	v_mfma_f32_16x16x32_bf16 v[112:115], v[178:181], v[202:205], v[112:115]
	v_mfma_f32_16x16x32_bf16 v[100:103], v[148:151], v[212:215], v[100:103]
	v_mfma_f32_16x16x32_bf16 v[96:99], v[178:181], v[212:215], v[96:99]
	v_mfma_f32_16x16x32_bf16 v[84:87], v[148:151], v[220:223], v[84:87]
	v_mfma_f32_16x16x32_bf16 v[80:83], v[178:181], v[220:223], v[80:83]
	s_setprio 0
	s_barrier
; #define PG8_STAGE(bufoff, gbase, voff) do { _Pragma("unroll") for (int _i = 0; _i < 2; ++_i) \
;         __builtin_amdgcn_global_load_lds((const unsigned*)((const char*)(gbase) + (voff)[_i]), (LAS unsigned*)(lds + (bufoff) + ldsw + _i * 8192), 16, 0, 0); } while (0)
; #define PG8_LDA(dst, b, h) do { _Pragma("unroll") for (int m = 0; m < 4; ++m) _Pragma("unroll") for (int k = 0; k < 2; ++k) dst[m][k] = *(const LAS bf16x8*)(lds + PG8_SA(b, h) + aoff + m * 2048 + k * 1024); } while (0)
; #define PG8_MMA(ai, bj, At, Bt) do { __builtin_amdgcn_s_setprio(1); _Pragma("unroll") for (int m = 0; m < 4; ++m) _Pragma("unroll") for (int n = 0; n < 2; ++n) _Pragma("unroll") for (int k = 0; k < 2; ++k) \
;         acc[ai][bj][m][n] = __builtin_amdgcn_mfma_f32_16x16x32_bf16(Bt[n][k], At[m][k], acc[ai][bj][m][n], 0, 0, 0); __builtin_amdgcn_s_setprio(0); } while (0)
; #define PG8_WAIT_V(n) asm volatile("s_waitcnt vmcnt(" #n ")" ::: "memory")
; #define PG8_WAIT_L(n) asm volatile("s_waitcnt lgkmcnt(" #n ")" ::: "memory")
; #define PG8_BAR __builtin_amdgcn_s_barrier()
; #define PG8_SCHED __builtin_amdgcn_sched_barrier(0)
; template <class Epi>
; __device__ __forceinline__ void gemm_phase(LAS unsigned char* lds, const Gemm g, const StaticOrder& S, const Epi& E) {
;     ...
;             PG8_LDA(At, 1, 1); PG8_STAGE(PG8_SB(1, 0), b3, voffB); PG8_STAGE(PG8_SB(1, 1), b3 + hstepB, voffB); PG8_STAGE(PG8_SA(1, 0), a3, voffA);
;             PG8_WAIT_V(8); PG8_WAIT_L(0); PG8_BAR; PG8_MMA(1, 0, At, B0); PG8_MMA(1, 1, At, B1); PG8_BAR; PG8_SCHED;
;         }
;         if (wr == 0) PG8_BAR;
	s_add_i32 s56, s81, s58
	v_lshl_add_u64 v[174:175], v[174:175], 0, s[12:13]
	s_mov_b32 m0, s56
	ds_read_b128 v[184:187], v201 offset:49152
	ds_read_b128 v[190:193], v201 offset:50176
	ds_read_b128 v[196:199], v201 offset:51200
	ds_read_b128 v[202:205], v201 offset:52224
	ds_read_b128 v[208:211], v201 offset:53248
	ds_read_b128 v[212:215], v201 offset:54272
	ds_read_b128 v[216:219], v201 offset:55296
	ds_read_b128 v[220:223], v201 offset:56320
	global_load_lds_dwordx4 v[174:175], off
	s_add_i32 m0, s56, 0x2000
	s_add_u32 s54, s54, 0x40080
	v_lshl_add_u64 v[174:175], v[224:225], 0, s[12:13]
	s_addc_u32 s55, s55, 0
	s_add_i32 s56, s82, s58
	global_load_lds_dwordx4 v[174:175], off
	v_lshl_add_u64 v[174:175], s[54:55], 0, v[154:155]
	s_mov_b32 m0, s56
	s_nop 0
	global_load_lds_dwordx4 v[174:175], off
	v_lshl_add_u64 v[174:175], s[54:55], 0, v[158:159]
	s_add_i32 m0, s56, 0x2000
	s_nop 0
	global_load_lds_dwordx4 v[174:175], off
	v_lshl_add_u64 v[174:175], v[226:227], 0, s[12:13]
	s_mov_b32 m0, s69
	s_nop 0
	global_load_lds_dwordx4 v[174:175], off
	v_lshl_add_u64 v[174:175], v[228:229], 0, s[12:13]
	s_mov_b32 m0, s70
	s_nop 0
	global_load_lds_dwordx4 v[174:175], off
	s_waitcnt vmcnt(8)
	s_waitcnt lgkmcnt(0)
	s_barrier
	s_setprio 1
	s_waitcnt lgkmcnt(0)
	v_mfma_f32_16x16x32_bf16 v[68:71], v[56:59], v[184:187], v[68:71]
	v_mfma_f32_16x16x32_bf16 v[64:67], v[72:75], v[184:187], v[64:67]
	v_mfma_f32_16x16x32_bf16 v[44:47], v[56:59], v[196:199], v[44:47]
	v_mfma_f32_16x16x32_bf16 v[40:43], v[72:75], v[196:199], v[40:43]
	v_mfma_f32_16x16x32_bf16 v[28:31], v[56:59], v[208:211], v[28:31]
	v_mfma_f32_16x16x32_bf16 v[24:27], v[72:75], v[208:211], v[24:27]
	v_mfma_f32_16x16x32_bf16 v[12:15], v[56:59], v[216:219], v[12:15]
	v_mfma_f32_16x16x32_bf16 v[8:11], v[72:75], v[216:219], v[8:11]
	v_mfma_f32_16x16x32_bf16 v[68:71], v[60:63], v[190:193], v[68:71]
	v_mfma_f32_16x16x32_bf16 v[64:67], v[76:79], v[190:193], v[64:67]
	v_mfma_f32_16x16x32_bf16 v[44:47], v[60:63], v[202:205], v[44:47]
	v_mfma_f32_16x16x32_bf16 v[40:43], v[76:79], v[202:205], v[40:43]
	v_mfma_f32_16x16x32_bf16 v[28:31], v[60:63], v[212:215], v[28:31]
	v_mfma_f32_16x16x32_bf16 v[24:27], v[76:79], v[212:215], v[24:27]
	v_mfma_f32_16x16x32_bf16 v[12:15], v[60:63], v[220:223], v[12:15]
	v_mfma_f32_16x16x32_bf16 v[8:11], v[76:79], v[220:223], v[8:11]
	v_mfma_f32_16x16x32_bf16 v[52:55], v[144:147], v[184:187], v[52:55]
	v_mfma_f32_16x16x32_bf16 v[48:51], v[168:171], v[184:187], v[48:51]
	v_mfma_f32_16x16x32_bf16 v[36:39], v[144:147], v[196:199], v[36:39]
	v_mfma_f32_16x16x32_bf16 v[32:35], v[168:171], v[196:199], v[32:35]
	v_mfma_f32_16x16x32_bf16 v[20:23], v[144:147], v[208:211], v[20:23]
	v_mfma_f32_16x16x32_bf16 v[16:19], v[168:171], v[208:211], v[16:19]
	v_mfma_f32_16x16x32_bf16 v[4:7], v[144:147], v[216:219], v[4:7]
	v_mfma_f32_16x16x32_bf16 v[0:3], v[168:171], v[216:219], v[0:3]
	v_mfma_f32_16x16x32_bf16 v[52:55], v[148:151], v[190:193], v[52:55]
	v_mfma_f32_16x16x32_bf16 v[48:51], v[178:181], v[190:193], v[48:51]
	v_mfma_f32_16x16x32_bf16 v[36:39], v[148:151], v[202:205], v[36:39]
	v_mfma_f32_16x16x32_bf16 v[32:35], v[178:181], v[202:205], v[32:35]
	v_mfma_f32_16x16x32_bf16 v[20:23], v[148:151], v[212:215], v[20:23]
	v_mfma_f32_16x16x32_bf16 v[16:19], v[178:181], v[212:215], v[16:19]
	v_mfma_f32_16x16x32_bf16 v[4:7], v[148:151], v[220:223], v[4:7]
	v_mfma_f32_16x16x32_bf16 v[0:3], v[178:181], v[220:223], v[0:3]
	s_setprio 0
	s_barrier
	s_add_i32 s80, s80, 2
	s_add_u32 s52, s52, 0x100
	s_addc_u32 s53, s53, 0
	s_add_u32 s78, s78, 0x100
	s_addc_u32 s79, s79, 0
	s_cmp_gt_u32 s80, 13
	s_cbranch_scc0 .LBB0_1233
	s_and_b64 vcc, exec, s[14:15]
	s_cbranch_vccz .LBB0_1236
	s_barrier

; #define PG8_STAGE(bufoff, gbase, voff) do { _Pragma("unroll") for (int _i = 0; _i < 2; ++_i) \
;         __builtin_amdgcn_global_load_lds((const unsigned*)((const char*)(gbase) + (voff)[_i]), (LAS unsigned*)(lds + (bufoff) + ldsw + _i * 8192), 16, 0, 0); } while (0)
; #define PG8_LDA(dst, b, h) do { _Pragma("unroll") for (int m = 0; m < 4; ++m) _Pragma("unroll") for (int k = 0; k < 2; ++k) dst[m][k] = *(const LAS bf16x8*)(lds + PG8_SA(b, h) + aoff + m * 2048 + k * 1024); } while (0)
; #define PG8_LDB(dst, b, h) do { _Pragma("unroll") for (int n = 0; n < 2; ++n) _Pragma("unroll") for (int k = 0; k < 2; ++k) dst[n][k] = *(const LAS bf16x8*)(lds + PG8_SB(b, h) + boff + n * 2048 + k * 1024); } while (0)
; #define PG8_MMA(ai, bj, At, Bt) do { __builtin_amdgcn_s_setprio(1); _Pragma("unroll") for (int m = 0; m < 4; ++m) _Pragma("unroll") for (int n = 0; n < 2; ++n) _Pragma("unroll") for (int k = 0; k < 2; ++k) \
;         acc[ai][bj][m][n] = __builtin_amdgcn_mfma_f32_16x16x32_bf16(Bt[n][k], At[m][k], acc[ai][bj][m][n], 0, 0, 0); __builtin_amdgcn_s_setprio(0); } while (0)
; #define PG8_BAR __builtin_amdgcn_s_barrier()
; template <class Epi>
; __device__ __forceinline__ void gemm_phase(LAS unsigned char* lds, const Gemm g, const StaticOrder& S, const Epi& E) {
;     ...
;         const bool has_next = S.next(ui + 1, nxt);
;         const char* nA = has_next ? (const char*)g.A + (size_t)nxt.pm * tstepA : cA; const char* nB = has_next ? (const char*)g.Bt + (size_t)nxt.pn * tstepB : cB;
; #pragma nounroll
;         for (int t = 0; t < nt; t += 2) {
;             const bool last = (t == nt - 2);
;             const char* a1 = cA + (size_t)(t + 1) * kstep;
;             const char* a2 = last ? nA : cA + (size_t)(t + 2) * kstep; const char* b2 = last ? nB : cB + (size_t)(t + 2) * kstep;
;             const char* a3 = a2 + kstep; const char* b3 = b2 + kstep;
;             PG8_LDB(B0, 0, 0); PG8_LDB(B1, 0, 1); PG8_SCHED; PG8_LDA(At, 0, 0); PG8_STAGE(PG8_SA(1, 1), a1 + hstepA, voffA);
;             PG8_WAIT_V(8); PG8_WAIT_L(0); PG8_BAR; PG8_MMA(0, 0, At, B0); PG8_MMA(0, 1, At, B1); PG8_BAR; PG8_SCHED;
;             PG8_LDA(At, 0, 1); PG8_STAGE(PG8_SB(0, 0), b2, voffB); PG8_STAGE(PG8_SB(0, 1), b2 + hstepB, voffB); PG8_STAGE(PG8_SA(0, 0), a2, voffA);
;             PG8_WAIT_V(8); PG8_WAIT_L(0); PG8_BAR; PG8_MMA(1, 0, At, B0); PG8_MMA(1, 1, At, B1); PG8_BAR; PG8_SCHED;
.LBB0_1313:
	s_ashr_i32 s19, s18, 31
	s_lshl_b64 s[20:21], s[18:19], 21
	s_add_u32 s20, s26, s20
	s_addc_u32 s21, s27, s21
	s_and_b64 s[22:23], s[4:5], exec
	s_cselect_b32 s1, s21, s39
	s_cselect_b32 s19, s20, s38
	s_ashr_i32 s17, s16, 31
	s_lshl_b64 s[22:23], s[16:17], 20
	s_add_u32 s22, s3, s22
	s_addc_u32 s23, s33, s23
	s_and_b64 s[52:53], s[4:5], exec
	s_cselect_b32 s17, s23, s43
	s_cselect_b32 s70, s22, s42
	s_add_u32 s38, s38, 0x100080
	s_addc_u32 s39, s39, 0
	s_add_u32 s71, s42, 0x100
	s_addc_u32 s72, s43, 0
	s_mov_b32 s73, -2
	s_waitcnt lgkmcnt(0)
	ds_read_b128 v[128:131], v182
	ds_read_b128 v[132:135], v182 offset:1024
	ds_read_b128 v[136:139], v182 offset:2048
	ds_read_b128 v[140:143], v182 offset:3072
	ds_read_b128 v[160:163], v183
	ds_read_b128 v[164:167], v183 offset:1024
	ds_read_b128 v[168:171], v183 offset:2048
	ds_read_b128 v[172:175], v183 offset:3072
	s_add_u32 s42, s38, 0xfff00080
	s_addc_u32 s43, s39, -1
	s_cmp_eq_u32 s73, 28
	s_cselect_b32 s53, s1, s43
	s_cselect_b32 s52, s19, s42
	s_cselect_b32 s43, s17, s72
	s_cselect_b32 s42, s70, s71
	v_lshl_add_u64 v[178:179], s[38:39], 0, v[152:153]
	s_add_i32 m0, s35, 0xc000
	ds_read_b128 v[186:189], v184
	ds_read_b128 v[190:193], v184 offset:1024
	ds_read_b128 v[194:197], v184 offset:2048
	ds_read_b128 v[198:201], v184 offset:3072
	ds_read_b128 v[202:205], v184 offset:4096
	ds_read_b128 v[206:209], v184 offset:5120
	ds_read_b128 v[210:213], v184 offset:6144
	ds_read_b128 v[214:217], v184 offset:7168
	global_load_lds_dwordx4 v[178:179], off
	v_lshl_add_u64 v[178:179], s[38:39], 0, v[154:155]
	s_add_i32 m0, s35, 0xe000
	s_nop 0
	global_load_lds_dwordx4 v[178:179], off
	s_waitcnt vmcnt(8)
	s_waitcnt lgkmcnt(0)
	s_barrier
	s_setprio 1
	s_waitcnt lgkmcnt(0)
	v_mfma_f32_16x16x32_bf16 v[124:127], v[128:131], v[186:189], 0
	v_mfma_f32_16x16x32_bf16 v[120:123], v[136:139], v[186:189], 0
	v_mfma_f32_16x16x32_bf16 v[108:111], v[128:131], v[194:197], 0
	v_mfma_f32_16x16x32_bf16 v[104:107], v[136:139], v[194:197], 0
	v_mfma_f32_16x16x32_bf16 v[92:95], v[128:131], v[202:205], 0
	v_mfma_f32_16x16x32_bf16 v[88:91], v[136:139], v[202:205], 0
	v_mfma_f32_16x16x32_bf16 v[76:79], v[128:131], v[210:213], 0
	v_mfma_f32_16x16x32_bf16 v[72:75], v[136:139], v[210:213], 0
	v_mfma_f32_16x16x32_bf16 v[124:127], v[132:135], v[190:193], v[124:127]
	v_mfma_f32_16x16x32_bf16 v[120:123], v[140:143], v[190:193], v[120:123]
	v_mfma_f32_16x16x32_bf16 v[108:111], v[132:135], v[198:201], v[108:111]
	v_mfma_f32_16x16x32_bf16 v[104:107], v[140:143], v[198:201], v[104:107]
	v_mfma_f32_16x16x32_bf16 v[92:95], v[132:135], v[206:209], v[92:95]
	v_mfma_f32_16x16x32_bf16 v[88:91], v[140:143], v[206:209], v[88:91]
	v_mfma_f32_16x16x32_bf16 v[76:79], v[132:135], v[214:217], v[76:79]
	v_mfma_f32_16x16x32_bf16 v[72:75], v[140:143], v[214:217], v[72:75]
	v_mfma_f32_16x16x32_bf16 v[116:119], v[160:163], v[186:189], 0
	v_mfma_f32_16x16x32_bf16 v[112:115], v[168:171], v[186:189], 0
	v_mfma_f32_16x16x32_bf16 v[100:103], v[160:163], v[194:197], 0
	v_mfma_f32_16x16x32_bf16 v[96:99], v[168:171], v[194:197], 0
	v_mfma_f32_16x16x32_bf16 v[84:87], v[160:163], v[202:205], 0
	v_mfma_f32_16x16x32_bf16 v[80:83], v[168:171], v[202:205], 0
	v_mfma_f32_16x16x32_bf16 v[68:71], v[160:163], v[210:213], 0
	v_mfma_f32_16x16x32_bf16 v[64:67], v[168:171], v[210:213], 0
	v_mfma_f32_16x16x32_bf16 v[116:119], v[164:167], v[190:193], v[116:119]
	v_mfma_f32_16x16x32_bf16 v[112:115], v[172:175], v[190:193], v[112:115]
	v_mfma_f32_16x16x32_bf16 v[100:103], v[164:167], v[198:201], v[100:103]
	v_mfma_f32_16x16x32_bf16 v[96:99], v[172:175], v[198:201], v[96:99]
	v_mfma_f32_16x16x32_bf16 v[84:87], v[164:167], v[206:209], v[84:87]
	v_mfma_f32_16x16x32_bf16 v[80:83], v[172:175], v[206:209], v[80:83]
	v_mfma_f32_16x16x32_bf16 v[68:71], v[164:167], v[214:217], v[68:71]
	v_mfma_f32_16x16x32_bf16 v[64:67], v[172:175], v[214:217], v[64:67]
	s_setprio 0
	s_barrier
	s_add_i32 s74, s68, s54
	v_lshl_add_u64 v[178:179], s[42:43], 0, v[146:147]
	s_mov_b32 m0, s74
	ds_read_b128 v[186:189], v184 offset:16384
	ds_read_b128 v[190:193], v184 offset:17408
	ds_read_b128 v[194:197], v184 offset:18432
	ds_read_b128 v[198:201], v184 offset:19456
	ds_read_b128 v[202:205], v184 offset:20480
	ds_read_b128 v[206:209], v184 offset:21504
	ds_read_b128 v[210:213], v184 offset:22528
	ds_read_b128 v[214:217], v184 offset:23552
	global_load_lds_dwordx4 v[178:179], off
	s_add_i32 m0, s74, 0x2000
	s_add_u32 s74, s42, 0x80000
	v_lshl_add_u64 v[218:219], s[42:43], 0, v[150:151]
	s_addc_u32 s75, s43, 0
	s_add_i32 s76, s69, s54
	global_load_lds_dwordx4 v[218:219], off
	v_lshl_add_u64 v[220:221], s[74:75], 0, v[146:147]
	s_mov_b32 m0, s76
	v_lshl_add_u64 v[222:223], s[52:53], 0, v[148:149]
	global_load_lds_dwordx4 v[220:221], off
	v_lshl_add_u64 v[220:221], s[74:75], 0, v[150:151]
	s_add_i32 m0, s76, 0x2000
	s_nop 0
	global_load_lds_dwordx4 v[220:221], off
	v_lshl_add_u64 v[220:221], s[52:53], 0, v[144:145]
	s_mov_b32 m0, s35
	s_nop 0
	global_load_lds_dwordx4 v[220:221], off
	s_mov_b32 m0, s55
	s_nop 0
	global_load_lds_dwordx4 v[222:223], off
	s_waitcnt vmcnt(8)
	s_waitcnt lgkmcnt(0)
	s_barrier
; #define PG8_STAGE(bufoff, gbase, voff) do { _Pragma("unroll") for (int _i = 0; _i < 2; ++_i) \
;         __builtin_amdgcn_global_load_lds((const unsigned*)((const char*)(gbase) + (voff)[_i]), (LAS unsigned*)(lds + (bufoff) + ldsw + _i * 8192), 16, 0, 0); } while (0)
; #define PG8_LDA(dst, b, h) do { _Pragma("unroll") for (int m = 0; m < 4; ++m) _Pragma("unroll") for (int k = 0; k < 2; ++k) dst[m][k] = *(const LAS bf16x8*)(lds + PG8_SA(b, h) + aoff + m * 2048 + k * 1024); } while (0)
; #define PG8_LDB(dst, b, h) do { _Pragma("unroll") for (int n = 0; n < 2; ++n) _Pragma("unroll") for (int k = 0; k < 2; ++k) dst[n][k] = *(const LAS bf16x8*)(lds + PG8_SB(b, h) + boff + n * 2048 + k * 1024); } while (0)
; #define PG8_MMA(ai, bj, At, Bt) do { __builtin_amdgcn_s_setprio(1); _Pragma("unroll") for (int m = 0; m < 4; ++m) _Pragma("unroll") for (int n = 0; n < 2; ++n) _Pragma("unroll") for (int k = 0; k < 2; ++k) \
;         acc[ai][bj][m][n] = __builtin_amdgcn_mfma_f32_16x16x32_bf16(Bt[n][k], At[m][k], acc[ai][bj][m][n], 0, 0, 0); __builtin_amdgcn_s_setprio(0); } while (0)
; #define PG8_WAIT_V(n) asm volatile("s_waitcnt vmcnt(" #n ")" ::: "memory")
; #define PG8_WAIT_L(n) asm volatile("s_waitcnt lgkmcnt(" #n ")" ::: "memory")
; #define PG8_BAR __builtin_amdgcn_s_barrier()
; #define PG8_SCHED __builtin_amdgcn_sched_barrier(0)
; template <class Epi>
; __device__ __forceinline__ void gemm_phase(LAS unsigned char* lds, const Gemm g, const StaticOrder& S, const Epi& E) {
;     ...
;             PG8_WAIT_V(8); PG8_WAIT_L(0); PG8_BAR; PG8_MMA(1, 0, At, B0); PG8_MMA(1, 1, At, B1); PG8_BAR; PG8_SCHED;
;             PG8_LDB(B0, 1, 0); PG8_LDB(B1, 1, 1); PG8_SCHED; PG8_LDA(At, 1, 0); PG8_STAGE(PG8_SA(0, 1), a2 + hstepA, voffA);
;             PG8_WAIT_V(8); PG8_WAIT_L(0); PG8_BAR; PG8_MMA(0, 0, At, B0); PG8_MMA(0, 1, At, B1); PG8_BAR; PG8_SCHED;
	s_setprio 1
	s_waitcnt lgkmcnt(0)
	v_mfma_f32_16x16x32_bf16 v[60:63], v[128:131], v[186:189], 0
	v_mfma_f32_16x16x32_bf16 v[56:59], v[136:139], v[186:189], 0
	v_mfma_f32_16x16x32_bf16 v[44:47], v[128:131], v[194:197], 0
	v_mfma_f32_16x16x32_bf16 v[40:43], v[136:139], v[194:197], 0
	v_mfma_f32_16x16x32_bf16 v[28:31], v[128:131], v[202:205], 0
	v_mfma_f32_16x16x32_bf16 v[24:27], v[136:139], v[202:205], 0
	v_mfma_f32_16x16x32_bf16 v[12:15], v[128:131], v[210:213], 0
	v_mfma_f32_16x16x32_bf16 v[8:11], v[136:139], v[210:213], 0
	v_mfma_f32_16x16x32_bf16 v[60:63], v[132:135], v[190:193], v[60:63]
	v_mfma_f32_16x16x32_bf16 v[56:59], v[140:143], v[190:193], v[56:59]
	v_mfma_f32_16x16x32_bf16 v[44:47], v[132:135], v[198:201], v[44:47]
	v_mfma_f32_16x16x32_bf16 v[40:43], v[140:143], v[198:201], v[40:43]
	v_mfma_f32_16x16x32_bf16 v[28:31], v[132:135], v[206:209], v[28:31]
	v_mfma_f32_16x16x32_bf16 v[24:27], v[140:143], v[206:209], v[24:27]
	v_mfma_f32_16x16x32_bf16 v[12:15], v[132:135], v[214:217], v[12:15]
	v_mfma_f32_16x16x32_bf16 v[8:11], v[140:143], v[214:217], v[8:11]
	v_mfma_f32_16x16x32_bf16 v[52:55], v[160:163], v[186:189], 0
	v_mfma_f32_16x16x32_bf16 v[48:51], v[168:171], v[186:189], 0
	v_mfma_f32_16x16x32_bf16 v[36:39], v[160:163], v[194:197], 0
	v_mfma_f32_16x16x32_bf16 v[32:35], v[168:171], v[194:197], 0
	v_mfma_f32_16x16x32_bf16 v[20:23], v[160:163], v[202:205], 0
	v_mfma_f32_16x16x32_bf16 v[16:19], v[168:171], v[202:205], 0
	v_mfma_f32_16x16x32_bf16 v[4:7], v[160:163], v[210:213], 0
	v_mfma_f32_16x16x32_bf16 v[0:3], v[168:171], v[210:213], 0
	v_mfma_f32_16x16x32_bf16 v[52:55], v[164:167], v[190:193], v[52:55]
	v_mfma_f32_16x16x32_bf16 v[48:51], v[172:175], v[190:193], v[48:51]
	v_mfma_f32_16x16x32_bf16 v[36:39], v[164:167], v[198:201], v[36:39]
	v_mfma_f32_16x16x32_bf16 v[32:35], v[172:175], v[198:201], v[32:35]
	v_mfma_f32_16x16x32_bf16 v[20:23], v[164:167], v[206:209], v[20:23]
	v_mfma_f32_16x16x32_bf16 v[16:19], v[172:175], v[206:209], v[16:19]
	v_mfma_f32_16x16x32_bf16 v[4:7], v[164:167], v[214:217], v[4:7]
	v_mfma_f32_16x16x32_bf16 v[0:3], v[172:175], v[214:217], v[0:3]
	s_setprio 0
	s_barrier
	s_add_i32 s74, 0, 0x18000
	s_add_i32 s75, 0, 0x1c000
	v_add_u32_e32 v140, s74, v181
	v_add_u32_e32 v172, s75, v181
	ds_read_b128 v[128:131], v140
	ds_read_b128 v[132:135], v140 offset:1024
	ds_read_b128 v[136:139], v140 offset:2048
	ds_read_b128 v[140:143], v140 offset:3072
	ds_read_b128 v[160:163], v172
	ds_read_b128 v[164:167], v172 offset:1024
	ds_read_b128 v[168:171], v172 offset:2048
	ds_read_b128 v[172:175], v172 offset:3072
	s_add_u32 s52, s52, 0x100000
	s_addc_u32 s53, s53, 0
	s_mov_b32 m0, s56
	v_lshl_add_u64 v[224:225], s[52:53], 0, v[144:145]
	ds_read_b128 v[186:189], v184 offset:32768
	ds_read_b128 v[190:193], v184 offset:33792
	ds_read_b128 v[194:197], v184 offset:34816
	ds_read_b128 v[198:201], v184 offset:35840
	ds_read_b128 v[202:205], v184 offset:36864
	ds_read_b128 v[206:209], v184 offset:37888
	ds_read_b128 v[210:213], v184 offset:38912
	ds_read_b128 v[214:217], v184 offset:39936
	global_load_lds_dwordx4 v[224:225], off
	v_lshl_add_u64 v[224:225], s[52:53], 0, v[148:149]
	s_mov_b32 m0, s57
	s_nop 0
	global_load_lds_dwordx4 v[224:225], off
	s_waitcnt vmcnt(8)
	s_waitcnt lgkmcnt(0)
	s_barrier
	s_setprio 1
	s_waitcnt lgkmcnt(0)
	v_mfma_f32_16x16x32_bf16 v[124:127], v[128:131], v[186:189], v[124:127]
	v_mfma_f32_16x16x32_bf16 v[120:123], v[136:139], v[186:189], v[120:123]
	v_mfma_f32_16x16x32_bf16 v[108:111], v[128:131], v[194:197], v[108:111]
	v_mfma_f32_16x16x32_bf16 v[104:107], v[136:139], v[194:197], v[104:107]
	v_mfma_f32_16x16x32_bf16 v[92:95], v[128:131], v[202:205], v[92:95]
	v_mfma_f32_16x16x32_bf16 v[88:91], v[136:139], v[202:205], v[88:91]
	v_mfma_f32_16x16x32_bf16 v[76:79], v[128:131], v[210:213], v[76:79]
	v_mfma_f32_16x16x32_bf16 v[72:75], v[136:139], v[210:213], v[72:75]
	v_mfma_f32_16x16x32_bf16 v[124:127], v[132:135], v[190:193], v[124:127]
	v_mfma_f32_16x16x32_bf16 v[120:123], v[140:143], v[190:193], v[120:123]
	v_mfma_f32_16x16x32_bf16 v[108:111], v[132:135], v[198:201], v[108:111]
	v_mfma_f32_16x16x32_bf16 v[104:107], v[140:143], v[198:201], v[104:107]
	v_mfma_f32_16x16x32_bf16 v[92:95], v[132:135], v[206:209], v[92:95]
	v_mfma_f32_16x16x32_bf16 v[88:91], v[140:143], v[206:209], v[88:91]
	v_mfma_f32_16x16x32_bf16 v[76:79], v[132:135], v[214:217], v[76:79]
	v_mfma_f32_16x16x32_bf16 v[72:75], v[140:143], v[214:217], v[72:75]
	v_mfma_f32_16x16x32_bf16 v[116:119], v[160:163], v[186:189], v[116:119]
	v_mfma_f32_16x16x32_bf16 v[112:115], v[168:171], v[186:189], v[112:115]
	v_mfma_f32_16x16x32_bf16 v[100:103], v[160:163], v[194:197], v[100:103]
	v_mfma_f32_16x16x32_bf16 v[96:99], v[168:171], v[194:197], v[96:99]
	v_mfma_f32_16x16x32_bf16 v[84:87], v[160:163], v[202:205], v[84:87]
	v_mfma_f32_16x16x32_bf16 v[80:83], v[168:171], v[202:205], v[80:83]
	v_mfma_f32_16x16x32_bf16 v[68:71], v[160:163], v[210:213], v[68:71]
	v_mfma_f32_16x16x32_bf16 v[64:67], v[168:171], v[210:213], v[64:67]
	v_mfma_f32_16x16x32_bf16 v[116:119], v[164:167], v[190:193], v[116:119]
	v_mfma_f32_16x16x32_bf16 v[112:115], v[172:175], v[190:193], v[112:115]
	v_mfma_f32_16x16x32_bf16 v[100:103], v[164:167], v[198:201], v[100:103]
	v_mfma_f32_16x16x32_bf16 v[96:99], v[172:175], v[198:201], v[96:99]
	v_mfma_f32_16x16x32_bf16 v[84:87], v[164:167], v[206:209], v[84:87]
	v_mfma_f32_16x16x32_bf16 v[80:83], v[172:175], v[206:209], v[80:83]
	v_mfma_f32_16x16x32_bf16 v[68:71], v[164:167], v[214:217], v[68:71]
	v_mfma_f32_16x16x32_bf16 v[64:67], v[172:175], v[214:217], v[64:67]
	s_setprio 0
	s_barrier
; #define PG8_STAGE(bufoff, gbase, voff) do { _Pragma("unroll") for (int _i = 0; _i < 2; ++_i) \
;         __builtin_amdgcn_global_load_lds((const unsigned*)((const char*)(gbase) + (voff)[_i]), (LAS unsigned*)(lds + (bufoff) + ldsw + _i * 8192), 16, 0, 0); } while (0)
; #define PG8_LDA(dst, b, h) do { _Pragma("unroll") for (int m = 0; m < 4; ++m) _Pragma("unroll") for (int k = 0; k < 2; ++k) dst[m][k] = *(const LAS bf16x8*)(lds + PG8_SA(b, h) + aoff + m * 2048 + k * 1024); } while (0)
; #define PG8_LDB(dst, b, h) do { _Pragma("unroll") for (int n = 0; n < 2; ++n) _Pragma("unroll") for (int k = 0; k < 2; ++k) dst[n][k] = *(const LAS bf16x8*)(lds + PG8_SB(b, h) + boff + n * 2048 + k * 1024); } while (0)
; #define PG8_MMA(ai, bj, At, Bt) do { __builtin_amdgcn_s_setprio(1); _Pragma("unroll") for (int m = 0; m < 4; ++m) _Pragma("unroll") for (int n = 0; n < 2; ++n) _Pragma("unroll") for (int k = 0; k < 2; ++k) \
;         acc[ai][bj][m][n] = __builtin_amdgcn_mfma_f32_16x16x32_bf16(Bt[n][k], At[m][k], acc[ai][bj][m][n], 0, 0, 0); __builtin_amdgcn_s_setprio(0); } while (0)
; #define PG8_WAIT_V(n) asm volatile("s_waitcnt vmcnt(" #n ")" ::: "memory")
; #define PG8_WAIT_L(n) asm volatile("s_waitcnt lgkmcnt(" #n ")" ::: "memory")
; #define PG8_BAR __builtin_amdgcn_s_barrier()
; #define PG8_SCHED __builtin_amdgcn_sched_barrier(0)
; template <class Epi>
; __device__ __forceinline__ void gemm_phase(LAS unsigned char* lds, const Gemm g, const StaticOrder& S, const Epi& E) {
;     ...
;             PG8_LDB(B0, 0, 0); PG8_LDB(B1, 0, 1); PG8_SCHED; PG8_LDA(At, 0, 0); PG8_STAGE(PG8_SA(1, 1), a1 + hstepA, voffA);
;     ...
;             PG8_LDA(At, 1, 1); PG8_STAGE(PG8_SB(1, 0), b3, voffB); PG8_STAGE(PG8_SB(1, 1), b3 + hstepB, voffB); PG8_STAGE(PG8_SA(1, 0), a3, voffA);
;             PG8_WAIT_V(8); PG8_WAIT_L(0); PG8_BAR; PG8_MMA(1, 0, At, B0); PG8_MMA(1, 1, At, B1); PG8_BAR; PG8_SCHED;
	s_add_i32 s52, s74, s54
	v_lshl_add_u64 v[178:179], v[178:179], 0, s[12:13]
	s_mov_b32 m0, s52
	ds_read_b128 v[186:189], v184 offset:49152
	ds_read_b128 v[190:193], v184 offset:50176
	ds_read_b128 v[194:197], v184 offset:51200
	ds_read_b128 v[198:201], v184 offset:52224
	ds_read_b128 v[202:205], v184 offset:53248
	ds_read_b128 v[206:209], v184 offset:54272
	ds_read_b128 v[210:213], v184 offset:55296
	ds_read_b128 v[214:217], v184 offset:56320
	global_load_lds_dwordx4 v[178:179], off
	s_add_i32 m0, s52, 0x2000
	s_add_u32 s42, s42, 0x80080
	v_lshl_add_u64 v[178:179], v[218:219], 0, s[12:13]
	s_addc_u32 s43, s43, 0
	s_add_i32 s52, s75, s54
	global_load_lds_dwordx4 v[178:179], off
	v_lshl_add_u64 v[178:179], s[42:43], 0, v[146:147]
	s_mov_b32 m0, s52
	s_nop 0
	global_load_lds_dwordx4 v[178:179], off
	v_lshl_add_u64 v[178:179], s[42:43], 0, v[150:151]
	s_add_i32 m0, s52, 0x2000
	s_nop 0
	global_load_lds_dwordx4 v[178:179], off
	v_lshl_add_u64 v[178:179], v[220:221], 0, s[12:13]
	s_mov_b32 m0, s61
	s_nop 0
	global_load_lds_dwordx4 v[178:179], off
	v_lshl_add_u64 v[178:179], v[222:223], 0, s[12:13]
	s_mov_b32 m0, s62
	s_nop 0
	global_load_lds_dwordx4 v[178:179], off
	s_waitcnt vmcnt(8)
	s_waitcnt lgkmcnt(0)
	s_barrier
	s_setprio 1
	s_waitcnt lgkmcnt(0)
	v_mfma_f32_16x16x32_bf16 v[60:63], v[128:131], v[186:189], v[60:63]
	v_mfma_f32_16x16x32_bf16 v[56:59], v[136:139], v[186:189], v[56:59]
	v_mfma_f32_16x16x32_bf16 v[44:47], v[128:131], v[194:197], v[44:47]
	v_mfma_f32_16x16x32_bf16 v[40:43], v[136:139], v[194:197], v[40:43]
	v_mfma_f32_16x16x32_bf16 v[28:31], v[128:131], v[202:205], v[28:31]
	v_mfma_f32_16x16x32_bf16 v[24:27], v[136:139], v[202:205], v[24:27]
	v_mfma_f32_16x16x32_bf16 v[12:15], v[128:131], v[210:213], v[12:15]
	v_mfma_f32_16x16x32_bf16 v[8:11], v[136:139], v[210:213], v[8:11]
	v_mfma_f32_16x16x32_bf16 v[60:63], v[132:135], v[190:193], v[60:63]
	v_mfma_f32_16x16x32_bf16 v[56:59], v[140:143], v[190:193], v[56:59]
	v_mfma_f32_16x16x32_bf16 v[44:47], v[132:135], v[198:201], v[44:47]
	v_mfma_f32_16x16x32_bf16 v[40:43], v[140:143], v[198:201], v[40:43]
	v_mfma_f32_16x16x32_bf16 v[28:31], v[132:135], v[206:209], v[28:31]
	v_mfma_f32_16x16x32_bf16 v[24:27], v[140:143], v[206:209], v[24:27]
	v_mfma_f32_16x16x32_bf16 v[12:15], v[132:135], v[214:217], v[12:15]
	v_mfma_f32_16x16x32_bf16 v[8:11], v[140:143], v[214:217], v[8:11]
	v_mfma_f32_16x16x32_bf16 v[52:55], v[160:163], v[186:189], v[52:55]
	v_mfma_f32_16x16x32_bf16 v[48:51], v[168:171], v[186:189], v[48:51]
	v_mfma_f32_16x16x32_bf16 v[36:39], v[160:163], v[194:197], v[36:39]
	v_mfma_f32_16x16x32_bf16 v[32:35], v[168:171], v[194:197], v[32:35]
	v_mfma_f32_16x16x32_bf16 v[20:23], v[160:163], v[202:205], v[20:23]
	v_mfma_f32_16x16x32_bf16 v[16:19], v[168:171], v[202:205], v[16:19]
	v_mfma_f32_16x16x32_bf16 v[4:7], v[160:163], v[210:213], v[4:7]
	v_mfma_f32_16x16x32_bf16 v[0:3], v[168:171], v[210:213], v[0:3]
	v_mfma_f32_16x16x32_bf16 v[52:55], v[164:167], v[190:193], v[52:55]
	v_mfma_f32_16x16x32_bf16 v[48:51], v[172:175], v[190:193], v[48:51]
	v_mfma_f32_16x16x32_bf16 v[36:39], v[164:167], v[198:201], v[36:39]
	v_mfma_f32_16x16x32_bf16 v[32:35], v[172:175], v[198:201], v[32:35]
	v_mfma_f32_16x16x32_bf16 v[20:23], v[164:167], v[206:209], v[20:23]
	v_mfma_f32_16x16x32_bf16 v[16:19], v[172:175], v[206:209], v[16:19]
	v_mfma_f32_16x16x32_bf16 v[4:7], v[164:167], v[214:217], v[4:7]
	v_mfma_f32_16x16x32_bf16 v[0:3], v[172:175], v[214:217], v[0:3]
	s_setprio 0
	s_barrier
	s_add_i32 s73, s73, 2
	s_add_u32 s38, s38, 0x100
	s_addc_u32 s39, s39, 0
	s_add_u32 s71, s71, 0x100
	s_addc_u32 s72, s72, 0
	s_cmp_gt_u32 s73, 29
.LBB0_1314:
	ds_read_b128 v[128:131], v182
	ds_read_b128 v[132:135], v182 offset:1024
	ds_read_b128 v[136:139], v182 offset:2048
	ds_read_b128 v[140:143], v182 offset:3072
	ds_read_b128 v[160:163], v183
	ds_read_b128 v[164:167], v183 offset:1024
	ds_read_b128 v[168:171], v183 offset:2048
	ds_read_b128 v[172:175], v183 offset:3072
	s_add_u32 s42, s38, 0xfff00080
	s_addc_u32 s43, s39, -1
	s_cmp_eq_u32 s73, 28
	s_cselect_b32 s53, s1, s43
	s_cselect_b32 s52, s19, s42
	s_cselect_b32 s43, s17, s72
	s_cselect_b32 s42, s70, s71
	v_lshl_add_u64 v[178:179], s[38:39], 0, v[152:153]
	s_add_i32 m0, s35, 0xc000
	ds_read_b128 v[186:189], v184
	ds_read_b128 v[190:193], v184 offset:1024
	ds_read_b128 v[194:197], v184 offset:2048
	ds_read_b128 v[198:201], v184 offset:3072
	ds_read_b128 v[202:205], v184 offset:4096
	ds_read_b128 v[206:209], v184 offset:5120
	ds_read_b128 v[210:213], v184 offset:6144
	ds_read_b128 v[214:217], v184 offset:7168
	global_load_lds_dwordx4 v[178:179], off
	v_lshl_add_u64 v[178:179], s[38:39], 0, v[154:155]
	s_add_i32 m0, s35, 0xe000
	s_nop 0
	global_load_lds_dwordx4 v[178:179], off
	s_waitcnt vmcnt(8)
	s_waitcnt lgkmcnt(0)
	s_barrier
; #define PG8_STAGE(bufoff, gbase, voff) do { _Pragma("unroll") for (int _i = 0; _i < 2; ++_i) \
;         __builtin_amdgcn_global_load_lds((const unsigned*)((const char*)(gbase) + (voff)[_i]), (LAS unsigned*)(lds + (bufoff) + ldsw + _i * 8192), 16, 0, 0); } while (0)
; #define PG8_LDA(dst, b, h) do { _Pragma("unroll") for (int m = 0; m < 4; ++m) _Pragma("unroll") for (int k = 0; k < 2; ++k) dst[m][k] = *(const LAS bf16x8*)(lds + PG8_SA(b, h) + aoff + m * 2048 + k * 1024); } while (0)
; #define PG8_LDB(dst, b, h) do { _Pragma("unroll") for (int n = 0; n < 2; ++n) _Pragma("unroll") for (int k = 0; k < 2; ++k) dst[n][k] = *(const LAS bf16x8*)(lds + PG8_SB(b, h) + boff + n * 2048 + k * 1024); } while (0)
; #define PG8_MMA(ai, bj, At, Bt) do { __builtin_amdgcn_s_setprio(1); _Pragma("unroll") for (int m = 0; m < 4; ++m) _Pragma("unroll") for (int n = 0; n < 2; ++n) _Pragma("unroll") for (int k = 0; k < 2; ++k) \
;         acc[ai][bj][m][n] = __builtin_amdgcn_mfma_f32_16x16x32_bf16(Bt[n][k], At[m][k], acc[ai][bj][m][n], 0, 0, 0); __builtin_amdgcn_s_setprio(0); } while (0)
; #define PG8_WAIT_V(n) asm volatile("s_waitcnt vmcnt(" #n ")" ::: "memory")
; #define PG8_WAIT_L(n) asm volatile("s_waitcnt lgkmcnt(" #n ")" ::: "memory")
; #define PG8_BAR __builtin_amdgcn_s_barrier()
; #define PG8_SCHED __builtin_amdgcn_sched_barrier(0)
; template <class Epi>
; __device__ __forceinline__ void gemm_phase(LAS unsigned char* lds, const Gemm g, const StaticOrder& S, const Epi& E) {
;     ...
;             PG8_LDB(B0, 0, 0); PG8_LDB(B1, 0, 1); PG8_SCHED; PG8_LDA(At, 0, 0); PG8_STAGE(PG8_SA(1, 1), a1 + hstepA, voffA);
;             PG8_WAIT_V(8); PG8_WAIT_L(0); PG8_BAR; PG8_MMA(0, 0, At, B0); PG8_MMA(0, 1, At, B1); PG8_BAR; PG8_SCHED;
;             PG8_LDA(At, 0, 1); PG8_STAGE(PG8_SB(0, 0), b2, voffB); PG8_STAGE(PG8_SB(0, 1), b2 + hstepB, voffB); PG8_STAGE(PG8_SA(0, 0), a2, voffA);
;             PG8_WAIT_V(8); PG8_WAIT_L(0); PG8_BAR; PG8_MMA(1, 0, At, B0); PG8_MMA(1, 1, At, B1); PG8_BAR; PG8_SCHED;
;             PG8_LDB(B0, 1, 0); PG8_LDB(B1, 1, 1); PG8_SCHED; PG8_LDA(At, 1, 0); PG8_STAGE(PG8_SA(0, 1), a2 + hstepA, voffA);
;             PG8_WAIT_V(8); PG8_WAIT_L(0); PG8_BAR; PG8_MMA(0, 0, At, B0); PG8_MMA(0, 1, At, B1); PG8_BAR; PG8_SCHED;
	s_setprio 1
	s_waitcnt lgkmcnt(0)
	v_mfma_f32_16x16x32_bf16 v[124:127], v[128:131], v[186:189], v[124:127]
	v_mfma_f32_16x16x32_bf16 v[120:123], v[136:139], v[186:189], v[120:123]
	v_mfma_f32_16x16x32_bf16 v[108:111], v[128:131], v[194:197], v[108:111]
	v_mfma_f32_16x16x32_bf16 v[104:107], v[136:139], v[194:197], v[104:107]
	v_mfma_f32_16x16x32_bf16 v[92:95], v[128:131], v[202:205], v[92:95]
	v_mfma_f32_16x16x32_bf16 v[88:91], v[136:139], v[202:205], v[88:91]
	v_mfma_f32_16x16x32_bf16 v[76:79], v[128:131], v[210:213], v[76:79]
	v_mfma_f32_16x16x32_bf16 v[72:75], v[136:139], v[210:213], v[72:75]
	v_mfma_f32_16x16x32_bf16 v[124:127], v[132:135], v[190:193], v[124:127]
	v_mfma_f32_16x16x32_bf16 v[120:123], v[140:143], v[190:193], v[120:123]
	v_mfma_f32_16x16x32_bf16 v[108:111], v[132:135], v[198:201], v[108:111]
	v_mfma_f32_16x16x32_bf16 v[104:107], v[140:143], v[198:201], v[104:107]
	v_mfma_f32_16x16x32_bf16 v[92:95], v[132:135], v[206:209], v[92:95]
	v_mfma_f32_16x16x32_bf16 v[88:91], v[140:143], v[206:209], v[88:91]
	v_mfma_f32_16x16x32_bf16 v[76:79], v[132:135], v[214:217], v[76:79]
	v_mfma_f32_16x16x32_bf16 v[72:75], v[140:143], v[214:217], v[72:75]
	v_mfma_f32_16x16x32_bf16 v[116:119], v[160:163], v[186:189], v[116:119]
	v_mfma_f32_16x16x32_bf16 v[112:115], v[168:171], v[186:189], v[112:115]
	v_mfma_f32_16x16x32_bf16 v[100:103], v[160:163], v[194:197], v[100:103]
	v_mfma_f32_16x16x32_bf16 v[96:99], v[168:171], v[194:197], v[96:99]
	v_mfma_f32_16x16x32_bf16 v[84:87], v[160:163], v[202:205], v[84:87]
	v_mfma_f32_16x16x32_bf16 v[80:83], v[168:171], v[202:205], v[80:83]
	v_mfma_f32_16x16x32_bf16 v[68:71], v[160:163], v[210:213], v[68:71]
	v_mfma_f32_16x16x32_bf16 v[64:67], v[168:171], v[210:213], v[64:67]
	v_mfma_f32_16x16x32_bf16 v[116:119], v[164:167], v[190:193], v[116:119]
	v_mfma_f32_16x16x32_bf16 v[112:115], v[172:175], v[190:193], v[112:115]
	v_mfma_f32_16x16x32_bf16 v[100:103], v[164:167], v[198:201], v[100:103]
	v_mfma_f32_16x16x32_bf16 v[96:99], v[172:175], v[198:201], v[96:99]
	v_mfma_f32_16x16x32_bf16 v[84:87], v[164:167], v[206:209], v[84:87]
	v_mfma_f32_16x16x32_bf16 v[80:83], v[172:175], v[206:209], v[80:83]
	v_mfma_f32_16x16x32_bf16 v[68:71], v[164:167], v[214:217], v[68:71]
	v_mfma_f32_16x16x32_bf16 v[64:67], v[172:175], v[214:217], v[64:67]
	s_setprio 0
	s_barrier
	s_add_i32 s74, s68, s54
	v_lshl_add_u64 v[178:179], s[42:43], 0, v[146:147]
	s_mov_b32 m0, s74
	ds_read_b128 v[186:189], v184 offset:16384
	ds_read_b128 v[190:193], v184 offset:17408
	ds_read_b128 v[194:197], v184 offset:18432
	ds_read_b128 v[198:201], v184 offset:19456
	ds_read_b128 v[202:205], v184 offset:20480
	ds_read_b128 v[206:209], v184 offset:21504
	ds_read_b128 v[210:213], v184 offset:22528
	ds_read_b128 v[214:217], v184 offset:23552
	global_load_lds_dwordx4 v[178:179], off
	s_add_i32 m0, s74, 0x2000
	s_add_u32 s74, s42, 0x80000
	v_lshl_add_u64 v[218:219], s[42:43], 0, v[150:151]
	s_addc_u32 s75, s43, 0
	s_add_i32 s76, s69, s54
	global_load_lds_dwordx4 v[218:219], off
	v_lshl_add_u64 v[220:221], s[74:75], 0, v[146:147]
	s_mov_b32 m0, s76
	v_lshl_add_u64 v[222:223], s[52:53], 0, v[148:149]
	global_load_lds_dwordx4 v[220:221], off
	v_lshl_add_u64 v[220:221], s[74:75], 0, v[150:151]
	s_add_i32 m0, s76, 0x2000
	s_nop 0
	global_load_lds_dwordx4 v[220:221], off
	v_lshl_add_u64 v[220:221], s[52:53], 0, v[144:145]
	s_mov_b32 m0, s35
	s_nop 0
	global_load_lds_dwordx4 v[220:221], off
	s_mov_b32 m0, s55
	s_nop 0
	global_load_lds_dwordx4 v[222:223], off
	s_waitcnt vmcnt(8)
	s_waitcnt lgkmcnt(0)
	s_barrier
	s_setprio 1
	s_waitcnt lgkmcnt(0)
	v_mfma_f32_16x16x32_bf16 v[60:63], v[128:131], v[186:189], v[60:63]
	v_mfma_f32_16x16x32_bf16 v[56:59], v[136:139], v[186:189], v[56:59]
	v_mfma_f32_16x16x32_bf16 v[44:47], v[128:131], v[194:197], v[44:47]
	v_mfma_f32_16x16x32_bf16 v[40:43], v[136:139], v[194:197], v[40:43]
	v_mfma_f32_16x16x32_bf16 v[28:31], v[128:131], v[202:205], v[28:31]
	v_mfma_f32_16x16x32_bf16 v[24:27], v[136:139], v[202:205], v[24:27]
	v_mfma_f32_16x16x32_bf16 v[12:15], v[128:131], v[210:213], v[12:15]
	v_mfma_f32_16x16x32_bf16 v[8:11], v[136:139], v[210:213], v[8:11]
	v_mfma_f32_16x16x32_bf16 v[60:63], v[132:135], v[190:193], v[60:63]
	v_mfma_f32_16x16x32_bf16 v[56:59], v[140:143], v[190:193], v[56:59]
	v_mfma_f32_16x16x32_bf16 v[44:47], v[132:135], v[198:201], v[44:47]
	v_mfma_f32_16x16x32_bf16 v[40:43], v[140:143], v[198:201], v[40:43]
	v_mfma_f32_16x16x32_bf16 v[28:31], v[132:135], v[206:209], v[28:31]
	v_mfma_f32_16x16x32_bf16 v[24:27], v[140:143], v[206:209], v[24:27]
	v_mfma_f32_16x16x32_bf16 v[12:15], v[132:135], v[214:217], v[12:15]
	v_mfma_f32_16x16x32_bf16 v[8:11], v[140:143], v[214:217], v[8:11]
	v_mfma_f32_16x16x32_bf16 v[52:55], v[160:163], v[186:189], v[52:55]
	v_mfma_f32_16x16x32_bf16 v[48:51], v[168:171], v[186:189], v[48:51]
	v_mfma_f32_16x16x32_bf16 v[36:39], v[160:163], v[194:197], v[36:39]
	v_mfma_f32_16x16x32_bf16 v[32:35], v[168:171], v[194:197], v[32:35]
	v_mfma_f32_16x16x32_bf16 v[20:23], v[160:163], v[202:205], v[20:23]
	v_mfma_f32_16x16x32_bf16 v[16:19], v[168:171], v[202:205], v[16:19]
	v_mfma_f32_16x16x32_bf16 v[4:7], v[160:163], v[210:213], v[4:7]
	v_mfma_f32_16x16x32_bf16 v[0:3], v[168:171], v[210:213], v[0:3]
	v_mfma_f32_16x16x32_bf16 v[52:55], v[164:167], v[190:193], v[52:55]
	v_mfma_f32_16x16x32_bf16 v[48:51], v[172:175], v[190:193], v[48:51]
	v_mfma_f32_16x16x32_bf16 v[36:39], v[164:167], v[198:201], v[36:39]
	v_mfma_f32_16x16x32_bf16 v[32:35], v[172:175], v[198:201], v[32:35]
	v_mfma_f32_16x16x32_bf16 v[20:23], v[164:167], v[206:209], v[20:23]
	v_mfma_f32_16x16x32_bf16 v[16:19], v[172:175], v[206:209], v[16:19]
	v_mfma_f32_16x16x32_bf16 v[4:7], v[164:167], v[214:217], v[4:7]
	v_mfma_f32_16x16x32_bf16 v[0:3], v[172:175], v[214:217], v[0:3]
	s_setprio 0
	s_barrier
; #define PG8_STAGE(bufoff, gbase, voff) do { _Pragma("unroll") for (int _i = 0; _i < 2; ++_i) \
;         __builtin_amdgcn_global_load_lds((const unsigned*)((const char*)(gbase) + (voff)[_i]), (LAS unsigned*)(lds + (bufoff) + ldsw + _i * 8192), 16, 0, 0); } while (0)
; #define PG8_LDA(dst, b, h) do { _Pragma("unroll") for (int m = 0; m < 4; ++m) _Pragma("unroll") for (int k = 0; k < 2; ++k) dst[m][k] = *(const LAS bf16x8*)(lds + PG8_SA(b, h) + aoff + m * 2048 + k * 1024); } while (0)
; #define PG8_MMA(ai, bj, At, Bt) do { __builtin_amdgcn_s_setprio(1); _Pragma("unroll") for (int m = 0; m < 4; ++m) _Pragma("unroll") for (int n = 0; n < 2; ++n) _Pragma("unroll") for (int k = 0; k < 2; ++k) \
;         acc[ai][bj][m][n] = __builtin_amdgcn_mfma_f32_16x16x32_bf16(Bt[n][k], At[m][k], acc[ai][bj][m][n], 0, 0, 0); __builtin_amdgcn_s_setprio(0); } while (0)
; #define PG8_WAIT_V(n) asm volatile("s_waitcnt vmcnt(" #n ")" ::: "memory")
; #define PG8_WAIT_L(n) asm volatile("s_waitcnt lgkmcnt(" #n ")" ::: "memory")
; #define PG8_BAR __builtin_amdgcn_s_barrier()
; #define PG8_SCHED __builtin_amdgcn_sched_barrier(0)
; template <class Epi>
; __device__ __forceinline__ void gemm_phase(LAS unsigned char* lds, const Gemm g, const StaticOrder& S, const Epi& E) {
;     ...
;             PG8_LDA(At, 1, 1); PG8_STAGE(PG8_SB(1, 0), b3, voffB); PG8_STAGE(PG8_SB(1, 1), b3 + hstepB, voffB); PG8_STAGE(PG8_SA(1, 0), a3, voffA);
;             PG8_WAIT_V(8); PG8_WAIT_L(0); PG8_BAR; PG8_MMA(1, 0, At, B0); PG8_MMA(1, 1, At, B1); PG8_BAR; PG8_SCHED;
	s_add_i32 s74, 0, 0x18000
	s_add_i32 s75, 0, 0x1c000
	v_add_u32_e32 v140, s74, v181
	v_add_u32_e32 v172, s75, v181
	ds_read_b128 v[128:131], v140
	ds_read_b128 v[132:135], v140 offset:1024
	ds_read_b128 v[136:139], v140 offset:2048
	ds_read_b128 v[140:143], v140 offset:3072
	ds_read_b128 v[160:163], v172
	ds_read_b128 v[164:167], v172 offset:1024
	ds_read_b128 v[168:171], v172 offset:2048
	ds_read_b128 v[172:175], v172 offset:3072
	s_add_u32 s52, s52, 0x100000
	s_addc_u32 s53, s53, 0
	s_mov_b32 m0, s56
	v_lshl_add_u64 v[224:225], s[52:53], 0, v[144:145]
	ds_read_b128 v[186:189], v184 offset:32768
	ds_read_b128 v[190:193], v184 offset:33792
	ds_read_b128 v[194:197], v184 offset:34816
	ds_read_b128 v[198:201], v184 offset:35840
	ds_read_b128 v[202:205], v184 offset:36864
	ds_read_b128 v[206:209], v184 offset:37888
	ds_read_b128 v[210:213], v184 offset:38912
	ds_read_b128 v[214:217], v184 offset:39936
	global_load_lds_dwordx4 v[224:225], off
	v_lshl_add_u64 v[224:225], s[52:53], 0, v[148:149]
	s_mov_b32 m0, s57
	s_nop 0
	global_load_lds_dwordx4 v[224:225], off
	s_waitcnt vmcnt(8)
	s_waitcnt lgkmcnt(0)
	s_barrier
	s_setprio 1
	s_waitcnt lgkmcnt(0)
	v_mfma_f32_16x16x32_bf16 v[124:127], v[128:131], v[186:189], v[124:127]
	v_mfma_f32_16x16x32_bf16 v[120:123], v[136:139], v[186:189], v[120:123]
	v_mfma_f32_16x16x32_bf16 v[108:111], v[128:131], v[194:197], v[108:111]
	v_mfma_f32_16x16x32_bf16 v[104:107], v[136:139], v[194:197], v[104:107]
	v_mfma_f32_16x16x32_bf16 v[92:95], v[128:131], v[202:205], v[92:95]
	v_mfma_f32_16x16x32_bf16 v[88:91], v[136:139], v[202:205], v[88:91]
	v_mfma_f32_16x16x32_bf16 v[76:79], v[128:131], v[210:213], v[76:79]
	v_mfma_f32_16x16x32_bf16 v[72:75], v[136:139], v[210:213], v[72:75]
	v_mfma_f32_16x16x32_bf16 v[124:127], v[132:135], v[190:193], v[124:127]
	v_mfma_f32_16x16x32_bf16 v[120:123], v[140:143], v[190:193], v[120:123]
	v_mfma_f32_16x16x32_bf16 v[108:111], v[132:135], v[198:201], v[108:111]
	v_mfma_f32_16x16x32_bf16 v[104:107], v[140:143], v[198:201], v[104:107]
	v_mfma_f32_16x16x32_bf16 v[92:95], v[132:135], v[206:209], v[92:95]
	v_mfma_f32_16x16x32_bf16 v[88:91], v[140:143], v[206:209], v[88:91]
	v_mfma_f32_16x16x32_bf16 v[76:79], v[132:135], v[214:217], v[76:79]
	v_mfma_f32_16x16x32_bf16 v[72:75], v[140:143], v[214:217], v[72:75]
	v_mfma_f32_16x16x32_bf16 v[116:119], v[160:163], v[186:189], v[116:119]
	v_mfma_f32_16x16x32_bf16 v[112:115], v[168:171], v[186:189], v[112:115]
	v_mfma_f32_16x16x32_bf16 v[100:103], v[160:163], v[194:197], v[100:103]
	v_mfma_f32_16x16x32_bf16 v[96:99], v[168:171], v[194:197], v[96:99]
	v_mfma_f32_16x16x32_bf16 v[84:87], v[160:163], v[202:205], v[84:87]
	v_mfma_f32_16x16x32_bf16 v[80:83], v[168:171], v[202:205], v[80:83]
	v_mfma_f32_16x16x32_bf16 v[68:71], v[160:163], v[210:213], v[68:71]
	v_mfma_f32_16x16x32_bf16 v[64:67], v[168:171], v[210:213], v[64:67]
	v_mfma_f32_16x16x32_bf16 v[116:119], v[164:167], v[190:193], v[116:119]
	v_mfma_f32_16x16x32_bf16 v[112:115], v[172:175], v[190:193], v[112:115]
	v_mfma_f32_16x16x32_bf16 v[100:103], v[164:167], v[198:201], v[100:103]
	v_mfma_f32_16x16x32_bf16 v[96:99], v[172:175], v[198:201], v[96:99]
	v_mfma_f32_16x16x32_bf16 v[84:87], v[164:167], v[206:209], v[84:87]
	v_mfma_f32_16x16x32_bf16 v[80:83], v[172:175], v[206:209], v[80:83]
	v_mfma_f32_16x16x32_bf16 v[68:71], v[164:167], v[214:217], v[68:71]
	v_mfma_f32_16x16x32_bf16 v[64:67], v[172:175], v[214:217], v[64:67]
	s_setprio 0
	s_barrier
; #define PG8_STAGE(bufoff, gbase, voff) do { _Pragma("unroll") for (int _i = 0; _i < 2; ++_i) \
;         __builtin_amdgcn_global_load_lds((const unsigned*)((const char*)(gbase) + (voff)[_i]), (LAS unsigned*)(lds + (bufoff) + ldsw + _i * 8192), 16, 0, 0); } while (0)
; #define PG8_LDA(dst, b, h) do { _Pragma("unroll") for (int m = 0; m < 4; ++m) _Pragma("unroll") for (int k = 0; k < 2; ++k) dst[m][k] = *(const LAS bf16x8*)(lds + PG8_SA(b, h) + aoff + m * 2048 + k * 1024); } while (0)
; #define PG8_MMA(ai, bj, At, Bt) do { __builtin_amdgcn_s_setprio(1); _Pragma("unroll") for (int m = 0; m < 4; ++m) _Pragma("unroll") for (int n = 0; n < 2; ++n) _Pragma("unroll") for (int k = 0; k < 2; ++k) \
;         acc[ai][bj][m][n] = __builtin_amdgcn_mfma_f32_16x16x32_bf16(Bt[n][k], At[m][k], acc[ai][bj][m][n], 0, 0, 0); __builtin_amdgcn_s_setprio(0); } while (0)
; #define PG8_WAIT_V(n) asm volatile("s_waitcnt vmcnt(" #n ")" ::: "memory")
; #define PG8_WAIT_L(n) asm volatile("s_waitcnt lgkmcnt(" #n ")" ::: "memory")
; #define PG8_BAR __builtin_amdgcn_s_barrier()
; #define PG8_SCHED __builtin_amdgcn_sched_barrier(0)
; template <class Epi>
; __device__ __forceinline__ void gemm_phase(LAS unsigned char* lds, const Gemm g, const StaticOrder& S, const Epi& E) {
;     ...
;             PG8_LDA(At, 1, 1); PG8_STAGE(PG8_SB(1, 0), b3, voffB); PG8_STAGE(PG8_SB(1, 1), b3 + hstepB, voffB); PG8_STAGE(PG8_SA(1, 0), a3, voffA);
;             PG8_WAIT_V(8); PG8_WAIT_L(0); PG8_BAR; PG8_MMA(1, 0, At, B0); PG8_MMA(1, 1, At, B1); PG8_BAR; PG8_SCHED;
;         }
	s_add_i32 s52, s74, s54
	v_lshl_add_u64 v[178:179], v[178:179], 0, s[12:13]
	s_mov_b32 m0, s52
	ds_read_b128 v[186:189], v184 offset:49152
	ds_read_b128 v[190:193], v184 offset:50176
	ds_read_b128 v[194:197], v184 offset:51200
	ds_read_b128 v[198:201], v184 offset:52224
	ds_read_b128 v[202:205], v184 offset:53248
	ds_read_b128 v[206:209], v184 offset:54272
	ds_read_b128 v[210:213], v184 offset:55296
	ds_read_b128 v[214:217], v184 offset:56320
	global_load_lds_dwordx4 v[178:179], off
	s_add_i32 m0, s52, 0x2000
	s_add_u32 s42, s42, 0x80080
	v_lshl_add_u64 v[178:179], v[218:219], 0, s[12:13]
	s_addc_u32 s43, s43, 0
	s_add_i32 s52, s75, s54
	global_load_lds_dwordx4 v[178:179], off
	v_lshl_add_u64 v[178:179], s[42:43], 0, v[146:147]
	s_mov_b32 m0, s52
	s_nop 0
	global_load_lds_dwordx4 v[178:179], off
	v_lshl_add_u64 v[178:179], s[42:43], 0, v[150:151]
	s_add_i32 m0, s52, 0x2000
	s_nop 0
	global_load_lds_dwordx4 v[178:179], off
	v_lshl_add_u64 v[178:179], v[220:221], 0, s[12:13]
	s_mov_b32 m0, s61
	s_nop 0
	global_load_lds_dwordx4 v[178:179], off
	v_lshl_add_u64 v[178:179], v[222:223], 0, s[12:13]
	s_mov_b32 m0, s62
	s_nop 0
	global_load_lds_dwordx4 v[178:179], off
	s_waitcnt vmcnt(8)
	s_waitcnt lgkmcnt(0)
	s_barrier
	s_setprio 1
	s_waitcnt lgkmcnt(0)
	v_mfma_f32_16x16x32_bf16 v[60:63], v[128:131], v[186:189], v[60:63]
	v_mfma_f32_16x16x32_bf16 v[56:59], v[136:139], v[186:189], v[56:59]
	v_mfma_f32_16x16x32_bf16 v[44:47], v[128:131], v[194:197], v[44:47]
	v_mfma_f32_16x16x32_bf16 v[40:43], v[136:139], v[194:197], v[40:43]
	v_mfma_f32_16x16x32_bf16 v[28:31], v[128:131], v[202:205], v[28:31]
	v_mfma_f32_16x16x32_bf16 v[24:27], v[136:139], v[202:205], v[24:27]
	v_mfma_f32_16x16x32_bf16 v[12:15], v[128:131], v[210:213], v[12:15]
	v_mfma_f32_16x16x32_bf16 v[8:11], v[136:139], v[210:213], v[8:11]
	v_mfma_f32_16x16x32_bf16 v[60:63], v[132:135], v[190:193], v[60:63]
	v_mfma_f32_16x16x32_bf16 v[56:59], v[140:143], v[190:193], v[56:59]
	v_mfma_f32_16x16x32_bf16 v[44:47], v[132:135], v[198:201], v[44:47]
	v_mfma_f32_16x16x32_bf16 v[40:43], v[140:143], v[198:201], v[40:43]
	v_mfma_f32_16x16x32_bf16 v[28:31], v[132:135], v[206:209], v[28:31]
	v_mfma_f32_16x16x32_bf16 v[24:27], v[140:143], v[206:209], v[24:27]
	v_mfma_f32_16x16x32_bf16 v[12:15], v[132:135], v[214:217], v[12:15]
	v_mfma_f32_16x16x32_bf16 v[8:11], v[140:143], v[214:217], v[8:11]
	v_mfma_f32_16x16x32_bf16 v[52:55], v[160:163], v[186:189], v[52:55]
	v_mfma_f32_16x16x32_bf16 v[48:51], v[168:171], v[186:189], v[48:51]
	v_mfma_f32_16x16x32_bf16 v[36:39], v[160:163], v[194:197], v[36:39]
	v_mfma_f32_16x16x32_bf16 v[32:35], v[168:171], v[194:197], v[32:35]
	v_mfma_f32_16x16x32_bf16 v[20:23], v[160:163], v[202:205], v[20:23]
	v_mfma_f32_16x16x32_bf16 v[16:19], v[168:171], v[202:205], v[16:19]
	v_mfma_f32_16x16x32_bf16 v[4:7], v[160:163], v[210:213], v[4:7]
	v_mfma_f32_16x16x32_bf16 v[0:3], v[168:171], v[210:213], v[0:3]
	v_mfma_f32_16x16x32_bf16 v[52:55], v[164:167], v[190:193], v[52:55]
	v_mfma_f32_16x16x32_bf16 v[48:51], v[172:175], v[190:193], v[48:51]
	v_mfma_f32_16x16x32_bf16 v[36:39], v[164:167], v[198:201], v[36:39]
	v_mfma_f32_16x16x32_bf16 v[32:35], v[172:175], v[198:201], v[32:35]
	v_mfma_f32_16x16x32_bf16 v[20:23], v[164:167], v[206:209], v[20:23]
	v_mfma_f32_16x16x32_bf16 v[16:19], v[172:175], v[206:209], v[16:19]
	v_mfma_f32_16x16x32_bf16 v[4:7], v[164:167], v[214:217], v[4:7]
	v_mfma_f32_16x16x32_bf16 v[0:3], v[172:175], v[214:217], v[0:3]
	s_setprio 0
	s_barrier
	s_add_i32 s73, s73, 2
	s_add_u32 s38, s38, 0x100
	s_addc_u32 s39, s39, 0
	s_add_u32 s71, s71, 0x100
	s_addc_u32 s72, s72, 0
	s_cmp_gt_u32 s73, 29
	s_cbranch_scc0 .LBB0_1314
	s_and_b64 vcc, exec, s[14:15]
	s_cbranch_vccz .LBB0_1317
	s_barrier

; #define PG8_STAGE(bufoff, gbase, voff) do { _Pragma("unroll") for (int _i = 0; _i < 2; ++_i) \
;         __builtin_amdgcn_global_load_lds((const unsigned*)((const char*)(gbase) + (voff)[_i]), (LAS unsigned*)(lds + (bufoff) + ldsw + _i * 8192), 16, 0, 0); } while (0)
; #define PG8_LDA(dst, b, h) do { _Pragma("unroll") for (int m = 0; m < 4; ++m) _Pragma("unroll") for (int k = 0; k < 2; ++k) dst[m][k] = *(const LAS bf16x8*)(lds + PG8_SA(b, h) + aoff + m * 2048 + k * 1024); } while (0)
; #define PG8_LDB(dst, b, h) do { _Pragma("unroll") for (int n = 0; n < 2; ++n) _Pragma("unroll") for (int k = 0; k < 2; ++k) dst[n][k] = *(const LAS bf16x8*)(lds + PG8_SB(b, h) + boff + n * 2048 + k * 1024); } while (0)
; #define PG8_MMA(ai, bj, At, Bt) do { __builtin_amdgcn_s_setprio(1); _Pragma("unroll") for (int m = 0; m < 4; ++m) _Pragma("unroll") for (int n = 0; n < 2; ++n) _Pragma("unroll") for (int k = 0; k < 2; ++k) \
;         acc[ai][bj][m][n] = __builtin_amdgcn_mfma_f32_16x16x32_bf16(Bt[n][k], At[m][k], acc[ai][bj][m][n], 0, 0, 0); __builtin_amdgcn_s_setprio(0); } while (0)
; #define PG8_BAR __builtin_amdgcn_s_barrier()
; template <class Epi>
; __device__ __forceinline__ void gemm_phase(LAS unsigned char* lds, const Gemm g, const StaticOrder& S, const Epi& E) {
;     ...
;         const bool has_next = S.next(ui + 1, nxt);
;         const char* nA = has_next ? (const char*)g.A + (size_t)nxt.pm * tstepA : cA; const char* nB = has_next ? (const char*)g.Bt + (size_t)nxt.pn * tstepB : cB;
; #pragma nounroll
;         for (int t = 0; t < nt; t += 2) {
;             const bool last = (t == nt - 2);
;             const char* a1 = cA + (size_t)(t + 1) * kstep;
;             const char* a2 = last ? nA : cA + (size_t)(t + 2) * kstep; const char* b2 = last ? nB : cB + (size_t)(t + 2) * kstep;
;             const char* a3 = a2 + kstep; const char* b3 = b2 + kstep;
;             PG8_LDB(B0, 0, 0); PG8_LDB(B1, 0, 1); PG8_SCHED; PG8_LDA(At, 0, 0); PG8_STAGE(PG8_SA(1, 1), a1 + hstepA, voffA);
;             PG8_WAIT_V(8); PG8_WAIT_L(0); PG8_BAR; PG8_MMA(0, 0, At, B0); PG8_MMA(0, 1, At, B1); PG8_BAR; PG8_SCHED;
;             PG8_LDA(At, 0, 1); PG8_STAGE(PG8_SB(0, 0), b2, voffB); PG8_STAGE(PG8_SB(0, 1), b2 + hstepB, voffB); PG8_STAGE(PG8_SA(0, 0), a2, voffA);
;             PG8_WAIT_V(8); PG8_WAIT_L(0); PG8_BAR; PG8_MMA(1, 0, At, B0); PG8_MMA(1, 1, At, B1); PG8_BAR; PG8_SCHED;
.LBB0_1402:
	s_ashr_i32 s69, s68, 31
	s_lshl_b64 s[12:13], s[68:69], 19
	s_add_u32 s70, s24, s12
	s_addc_u32 s71, s25, s13
	s_and_b64 s[12:13], s[4:5], exec
	s_cselect_b32 s1, s71, s9
	s_cselect_b32 s7, s70, s8
	s_ashr_i32 s65, s64, 31
	s_lshl_b64 s[12:13], s[64:65], 19
	s_add_u32 s72, s3, s12
	s_addc_u32 s73, s33, s13
	s_and_b64 s[12:13], s[4:5], exec
	s_cselect_b32 s65, s73, s11
	s_cselect_b32 s69, s72, s10
	s_add_u32 s8, s8, 0x40080
	s_addc_u32 s9, s9, 0
	s_add_u32 s74, s10, 0x100
	s_addc_u32 s75, s11, 0
	s_mov_b32 s87, -2
	v_lshl_add_u32 v248, s6, 8, v151
	v_add_u32_e32 v248, s63, v248
	v_ashrrev_i32_e32 v249, 31, v248
	v_lshl_add_u64 v[248:249], v[248:249], 2, s[18:19]
	global_load_dword v240, v[248:249], off
	global_load_dword v241, v[248:249], off offset:64
	global_load_dword v242, v[248:249], off offset:128
	global_load_dword v243, v[248:249], off offset:192
	global_load_dword v244, v[248:249], off offset:512
	global_load_dword v245, v[248:249], off offset:576
	global_load_dword v246, v[248:249], off offset:640
	global_load_dword v247, v[248:249], off offset:704
	ds_read_b128 v[146:149], v162
	ds_read_b128 v[166:169], v162 offset:1024
	ds_read_b128 v[170:173], v162 offset:2048
	ds_read_b128 v[178:181], v162 offset:3072
	ds_read_b128 v[182:185], v163
	ds_read_b128 v[186:189], v163 offset:1024
	ds_read_b128 v[190:193], v163 offset:2048
	ds_read_b128 v[194:197], v163 offset:3072
	s_add_u32 s10, s8, 0xfffc0080
	s_addc_u32 s11, s9, -1
	s_cmp_eq_u32 s87, 12
	s_cselect_b32 s13, s1, s11
	s_cselect_b32 s12, s7, s10
	s_cselect_b32 s11, s65, s75
	s_cselect_b32 s10, s69, s74
	v_lshl_add_u64 v[174:175], s[8:9], 0, v[138:139]
	s_add_i32 m0, s53, 0xc000
	ds_read_b128 v[198:201], v164
	ds_read_b128 v[202:205], v164 offset:1024
	ds_read_b128 v[206:209], v164 offset:2048
	ds_read_b128 v[210:213], v164 offset:3072
	ds_read_b128 v[214:217], v164 offset:4096
	ds_read_b128 v[218:221], v164 offset:5120
	ds_read_b128 v[222:225], v164 offset:6144
	ds_read_b128 v[226:229], v164 offset:7168
	global_load_lds_dwordx4 v[174:175], off
	v_lshl_add_u64 v[174:175], s[8:9], 0, v[140:141]
	s_add_i32 m0, s53, 0xe000
	s_nop 0
	global_load_lds_dwordx4 v[174:175], off
	s_waitcnt vmcnt(8)
	s_waitcnt lgkmcnt(0)
	s_barrier
	s_setprio 1
	s_waitcnt lgkmcnt(0)
	v_mfma_f32_16x16x32_bf16 v[124:127], v[146:149], v[198:201], 0
	v_mfma_f32_16x16x32_bf16 v[120:123], v[170:173], v[198:201], 0
	v_mfma_f32_16x16x32_bf16 v[112:115], v[146:149], v[206:209], 0
	v_mfma_f32_16x16x32_bf16 v[104:107], v[170:173], v[206:209], 0
	v_mfma_f32_16x16x32_bf16 v[100:103], v[146:149], v[214:217], 0
	v_mfma_f32_16x16x32_bf16 v[92:95], v[170:173], v[214:217], 0
	v_mfma_f32_16x16x32_bf16 v[84:87], v[146:149], v[222:225], 0
	v_mfma_f32_16x16x32_bf16 v[76:79], v[170:173], v[222:225], 0
	v_mfma_f32_16x16x32_bf16 v[124:127], v[166:169], v[202:205], v[124:127]
	v_mfma_f32_16x16x32_bf16 v[120:123], v[178:181], v[202:205], v[120:123]
	v_mfma_f32_16x16x32_bf16 v[112:115], v[166:169], v[210:213], v[112:115]
	v_mfma_f32_16x16x32_bf16 v[104:107], v[178:181], v[210:213], v[104:107]
	v_mfma_f32_16x16x32_bf16 v[100:103], v[166:169], v[218:221], v[100:103]
	v_mfma_f32_16x16x32_bf16 v[92:95], v[178:181], v[218:221], v[92:95]
	v_mfma_f32_16x16x32_bf16 v[84:87], v[166:169], v[226:229], v[84:87]
	v_mfma_f32_16x16x32_bf16 v[76:79], v[178:181], v[226:229], v[76:79]
	v_mfma_f32_16x16x32_bf16 v[116:119], v[182:185], v[198:201], 0
	v_mfma_f32_16x16x32_bf16 v[108:111], v[190:193], v[198:201], 0
	v_mfma_f32_16x16x32_bf16 v[96:99], v[182:185], v[206:209], 0
	v_mfma_f32_16x16x32_bf16 v[88:91], v[190:193], v[206:209], 0
	v_mfma_f32_16x16x32_bf16 v[80:83], v[182:185], v[214:217], 0
	v_mfma_f32_16x16x32_bf16 v[72:75], v[190:193], v[214:217], 0
	v_mfma_f32_16x16x32_bf16 v[68:71], v[182:185], v[222:225], 0
	v_mfma_f32_16x16x32_bf16 v[64:67], v[190:193], v[222:225], 0
	v_mfma_f32_16x16x32_bf16 v[116:119], v[186:189], v[202:205], v[116:119]
	v_mfma_f32_16x16x32_bf16 v[108:111], v[194:197], v[202:205], v[108:111]
	v_mfma_f32_16x16x32_bf16 v[96:99], v[186:189], v[210:213], v[96:99]
	v_mfma_f32_16x16x32_bf16 v[88:91], v[194:197], v[210:213], v[88:91]
	v_mfma_f32_16x16x32_bf16 v[80:83], v[186:189], v[218:221], v[80:83]
	v_mfma_f32_16x16x32_bf16 v[72:75], v[194:197], v[218:221], v[72:75]
	v_mfma_f32_16x16x32_bf16 v[68:71], v[186:189], v[226:229], v[68:71]
	v_mfma_f32_16x16x32_bf16 v[64:67], v[194:197], v[226:229], v[64:67]
	s_setprio 0
	s_barrier
	s_add_i32 s88, s83, s43
	v_lshl_add_u64 v[174:175], s[10:11], 0, v[130:131]
	s_mov_b32 m0, s88
	ds_read_b128 v[198:201], v164 offset:16384
	ds_read_b128 v[202:205], v164 offset:17408
	ds_read_b128 v[206:209], v164 offset:18432
	ds_read_b128 v[210:213], v164 offset:19456
	ds_read_b128 v[214:217], v164 offset:20480
	ds_read_b128 v[218:221], v164 offset:21504
	ds_read_b128 v[222:225], v164 offset:22528
	ds_read_b128 v[226:229], v164 offset:23552
	global_load_lds_dwordx4 v[174:175], off
	s_add_i32 m0, s88, 0x2000
	s_add_u32 s88, s10, 0x40000
	v_lshl_add_u64 v[230:231], s[10:11], 0, v[134:135]
	s_addc_u32 s89, s11, 0
	s_add_i32 s90, s84, s43
	global_load_lds_dwordx4 v[230:231], off
	v_lshl_add_u64 v[232:233], s[88:89], 0, v[130:131]
	s_mov_b32 m0, s90
	v_lshl_add_u64 v[234:235], s[12:13], 0, v[132:133]
	global_load_lds_dwordx4 v[232:233], off
	v_lshl_add_u64 v[232:233], s[88:89], 0, v[134:135]
	s_add_i32 m0, s90, 0x2000
	s_nop 0
	global_load_lds_dwordx4 v[232:233], off
	v_lshl_add_u64 v[232:233], s[12:13], 0, v[128:129]
	s_mov_b32 m0, s53
	s_nop 0
	global_load_lds_dwordx4 v[232:233], off
	s_mov_b32 m0, s55
	s_nop 0
	global_load_lds_dwordx4 v[234:235], off
	s_waitcnt vmcnt(8)
	s_waitcnt lgkmcnt(0)
	s_barrier
; #define PG8_STAGE(bufoff, gbase, voff) do { _Pragma("unroll") for (int _i = 0; _i < 2; ++_i) \
;         __builtin_amdgcn_global_load_lds((const unsigned*)((const char*)(gbase) + (voff)[_i]), (LAS unsigned*)(lds + (bufoff) + ldsw + _i * 8192), 16, 0, 0); } while (0)
; #define PG8_LDA(dst, b, h) do { _Pragma("unroll") for (int m = 0; m < 4; ++m) _Pragma("unroll") for (int k = 0; k < 2; ++k) dst[m][k] = *(const LAS bf16x8*)(lds + PG8_SA(b, h) + aoff + m * 2048 + k * 1024); } while (0)
; #define PG8_LDB(dst, b, h) do { _Pragma("unroll") for (int n = 0; n < 2; ++n) _Pragma("unroll") for (int k = 0; k < 2; ++k) dst[n][k] = *(const LAS bf16x8*)(lds + PG8_SB(b, h) + boff + n * 2048 + k * 1024); } while (0)
; #define PG8_MMA(ai, bj, At, Bt) do { __builtin_amdgcn_s_setprio(1); _Pragma("unroll") for (int m = 0; m < 4; ++m) _Pragma("unroll") for (int n = 0; n < 2; ++n) _Pragma("unroll") for (int k = 0; k < 2; ++k) \
;         acc[ai][bj][m][n] = __builtin_amdgcn_mfma_f32_16x16x32_bf16(Bt[n][k], At[m][k], acc[ai][bj][m][n], 0, 0, 0); __builtin_amdgcn_s_setprio(0); } while (0)
; #define PG8_WAIT_V(n) asm volatile("s_waitcnt vmcnt(" #n ")" ::: "memory")
; #define PG8_WAIT_L(n) asm volatile("s_waitcnt lgkmcnt(" #n ")" ::: "memory")
; #define PG8_BAR __builtin_amdgcn_s_barrier()
; #define PG8_SCHED __builtin_amdgcn_sched_barrier(0)
; template <class Epi>
; __device__ __forceinline__ void gemm_phase(LAS unsigned char* lds, const Gemm g, const StaticOrder& S, const Epi& E) {
;     ...
;             PG8_WAIT_V(8); PG8_WAIT_L(0); PG8_BAR; PG8_MMA(1, 0, At, B0); PG8_MMA(1, 1, At, B1); PG8_BAR; PG8_SCHED;
;             PG8_LDB(B0, 1, 0); PG8_LDB(B1, 1, 1); PG8_SCHED; PG8_LDA(At, 1, 0); PG8_STAGE(PG8_SA(0, 1), a2 + hstepA, voffA);
;             PG8_WAIT_V(8); PG8_WAIT_L(0); PG8_BAR; PG8_MMA(0, 0, At, B0); PG8_MMA(0, 1, At, B1); PG8_BAR; PG8_SCHED;
;             PG8_LDA(At, 1, 1); PG8_STAGE(PG8_SB(1, 0), b3, voffB); PG8_STAGE(PG8_SB(1, 1), b3 + hstepB, voffB); PG8_STAGE(PG8_SA(1, 0), a3, voffA);
;             PG8_WAIT_V(8); PG8_WAIT_L(0); PG8_BAR; PG8_MMA(1, 0, At, B0); PG8_MMA(1, 1, At, B1); PG8_BAR; PG8_SCHED;
	s_setprio 1
	s_waitcnt lgkmcnt(0)
	v_mfma_f32_16x16x32_bf16 v[60:63], v[146:149], v[198:201], 0
	v_mfma_f32_16x16x32_bf16 v[56:59], v[170:173], v[198:201], 0
	v_mfma_f32_16x16x32_bf16 v[52:55], v[146:149], v[206:209], 0
	v_mfma_f32_16x16x32_bf16 v[44:47], v[170:173], v[206:209], 0
	v_mfma_f32_16x16x32_bf16 v[36:39], v[146:149], v[214:217], 0
	v_mfma_f32_16x16x32_bf16 v[28:31], v[170:173], v[214:217], 0
	v_mfma_f32_16x16x32_bf16 v[20:23], v[146:149], v[222:225], 0
	v_mfma_f32_16x16x32_bf16 v[12:15], v[170:173], v[222:225], 0
	v_mfma_f32_16x16x32_bf16 v[60:63], v[166:169], v[202:205], v[60:63]
	v_mfma_f32_16x16x32_bf16 v[56:59], v[178:181], v[202:205], v[56:59]
	v_mfma_f32_16x16x32_bf16 v[52:55], v[166:169], v[210:213], v[52:55]
	v_mfma_f32_16x16x32_bf16 v[44:47], v[178:181], v[210:213], v[44:47]
	v_mfma_f32_16x16x32_bf16 v[36:39], v[166:169], v[218:221], v[36:39]
	v_mfma_f32_16x16x32_bf16 v[28:31], v[178:181], v[218:221], v[28:31]
	v_mfma_f32_16x16x32_bf16 v[20:23], v[166:169], v[226:229], v[20:23]
	v_mfma_f32_16x16x32_bf16 v[12:15], v[178:181], v[226:229], v[12:15]
	v_mfma_f32_16x16x32_bf16 v[48:51], v[182:185], v[198:201], 0
	v_mfma_f32_16x16x32_bf16 v[40:43], v[190:193], v[198:201], 0
	v_mfma_f32_16x16x32_bf16 v[32:35], v[182:185], v[206:209], 0
	v_mfma_f32_16x16x32_bf16 v[24:27], v[190:193], v[206:209], 0
	v_mfma_f32_16x16x32_bf16 v[16:19], v[182:185], v[214:217], 0
	v_mfma_f32_16x16x32_bf16 v[8:11], v[190:193], v[214:217], 0
	v_mfma_f32_16x16x32_bf16 v[4:7], v[182:185], v[222:225], 0
	v_mfma_f32_16x16x32_bf16 v[0:3], v[190:193], v[222:225], 0
	v_mfma_f32_16x16x32_bf16 v[48:51], v[186:189], v[202:205], v[48:51]
	v_mfma_f32_16x16x32_bf16 v[40:43], v[194:197], v[202:205], v[40:43]
	v_mfma_f32_16x16x32_bf16 v[32:35], v[186:189], v[210:213], v[32:35]
	v_mfma_f32_16x16x32_bf16 v[24:27], v[194:197], v[210:213], v[24:27]
	v_mfma_f32_16x16x32_bf16 v[16:19], v[186:189], v[218:221], v[16:19]
	v_mfma_f32_16x16x32_bf16 v[8:11], v[194:197], v[218:221], v[8:11]
	v_mfma_f32_16x16x32_bf16 v[4:7], v[186:189], v[226:229], v[4:7]
	v_mfma_f32_16x16x32_bf16 v[0:3], v[194:197], v[226:229], v[0:3]
	s_setprio 0
	s_barrier
	s_add_i32 s88, 0, 0x18000
	v_add_u32_e32 v136, s88, v161
	s_add_i32 s89, 0, 0x1c000
	ds_read_b128 v[146:149], v136
	ds_read_b128 v[166:169], v136 offset:1024
	ds_read_b128 v[170:173], v136 offset:2048
	ds_read_b128 v[178:181], v136 offset:3072
	v_add_u32_e32 v136, s89, v161
	ds_read_b128 v[182:185], v136
	ds_read_b128 v[186:189], v136 offset:1024
	ds_read_b128 v[190:193], v136 offset:2048
	ds_read_b128 v[194:197], v136 offset:3072
	s_add_u32 s12, s12, 0x40000
	s_addc_u32 s13, s13, 0
	s_mov_b32 m0, s57
	v_lshl_add_u64 v[236:237], s[12:13], 0, v[128:129]
	ds_read_b128 v[198:201], v164 offset:32768
	ds_read_b128 v[202:205], v164 offset:33792
	ds_read_b128 v[206:209], v164 offset:34816
	ds_read_b128 v[210:213], v164 offset:35840
	ds_read_b128 v[214:217], v164 offset:36864
	ds_read_b128 v[218:221], v164 offset:37888
	ds_read_b128 v[222:225], v164 offset:38912
	ds_read_b128 v[226:229], v164 offset:39936
	global_load_lds_dwordx4 v[236:237], off
	v_lshl_add_u64 v[236:237], s[12:13], 0, v[132:133]
	s_mov_b32 m0, s59
	s_nop 0
	global_load_lds_dwordx4 v[236:237], off
	s_waitcnt vmcnt(8)
	s_waitcnt lgkmcnt(0)
	s_barrier
	s_setprio 1
	s_waitcnt lgkmcnt(0)
	v_mfma_f32_16x16x32_bf16 v[124:127], v[146:149], v[198:201], v[124:127]
	v_mfma_f32_16x16x32_bf16 v[120:123], v[170:173], v[198:201], v[120:123]
	v_mfma_f32_16x16x32_bf16 v[112:115], v[146:149], v[206:209], v[112:115]
	v_mfma_f32_16x16x32_bf16 v[104:107], v[170:173], v[206:209], v[104:107]
	v_mfma_f32_16x16x32_bf16 v[100:103], v[146:149], v[214:217], v[100:103]
	v_mfma_f32_16x16x32_bf16 v[92:95], v[170:173], v[214:217], v[92:95]
	v_mfma_f32_16x16x32_bf16 v[84:87], v[146:149], v[222:225], v[84:87]
	v_mfma_f32_16x16x32_bf16 v[76:79], v[170:173], v[222:225], v[76:79]
	v_mfma_f32_16x16x32_bf16 v[124:127], v[166:169], v[202:205], v[124:127]
	v_mfma_f32_16x16x32_bf16 v[120:123], v[178:181], v[202:205], v[120:123]
	v_mfma_f32_16x16x32_bf16 v[112:115], v[166:169], v[210:213], v[112:115]
	v_mfma_f32_16x16x32_bf16 v[104:107], v[178:181], v[210:213], v[104:107]
	v_mfma_f32_16x16x32_bf16 v[100:103], v[166:169], v[218:221], v[100:103]
	v_mfma_f32_16x16x32_bf16 v[92:95], v[178:181], v[218:221], v[92:95]
	v_mfma_f32_16x16x32_bf16 v[84:87], v[166:169], v[226:229], v[84:87]
	v_mfma_f32_16x16x32_bf16 v[76:79], v[178:181], v[226:229], v[76:79]
	v_mfma_f32_16x16x32_bf16 v[116:119], v[182:185], v[198:201], v[116:119]
	v_mfma_f32_16x16x32_bf16 v[108:111], v[190:193], v[198:201], v[108:111]
	v_mfma_f32_16x16x32_bf16 v[96:99], v[182:185], v[206:209], v[96:99]
	v_mfma_f32_16x16x32_bf16 v[88:91], v[190:193], v[206:209], v[88:91]
	v_mfma_f32_16x16x32_bf16 v[80:83], v[182:185], v[214:217], v[80:83]
	v_mfma_f32_16x16x32_bf16 v[72:75], v[190:193], v[214:217], v[72:75]
	v_mfma_f32_16x16x32_bf16 v[68:71], v[182:185], v[222:225], v[68:71]
	v_mfma_f32_16x16x32_bf16 v[64:67], v[190:193], v[222:225], v[64:67]
	v_mfma_f32_16x16x32_bf16 v[116:119], v[186:189], v[202:205], v[116:119]
	v_mfma_f32_16x16x32_bf16 v[108:111], v[194:197], v[202:205], v[108:111]
	v_mfma_f32_16x16x32_bf16 v[96:99], v[186:189], v[210:213], v[96:99]
	v_mfma_f32_16x16x32_bf16 v[88:91], v[194:197], v[210:213], v[88:91]
	v_mfma_f32_16x16x32_bf16 v[80:83], v[186:189], v[218:221], v[80:83]
	v_mfma_f32_16x16x32_bf16 v[72:75], v[194:197], v[218:221], v[72:75]
	v_mfma_f32_16x16x32_bf16 v[68:71], v[186:189], v[226:229], v[68:71]
	v_mfma_f32_16x16x32_bf16 v[64:67], v[194:197], v[226:229], v[64:67]
	s_setprio 0
	s_barrier
; #define PG8_STAGE(bufoff, gbase, voff) do { _Pragma("unroll") for (int _i = 0; _i < 2; ++_i) \
;         __builtin_amdgcn_global_load_lds((const unsigned*)((const char*)(gbase) + (voff)[_i]), (LAS unsigned*)(lds + (bufoff) + ldsw + _i * 8192), 16, 0, 0); } while (0)
; #define PG8_LDA(dst, b, h) do { _Pragma("unroll") for (int m = 0; m < 4; ++m) _Pragma("unroll") for (int k = 0; k < 2; ++k) dst[m][k] = *(const LAS bf16x8*)(lds + PG8_SA(b, h) + aoff + m * 2048 + k * 1024); } while (0)
; #define PG8_LDB(dst, b, h) do { _Pragma("unroll") for (int n = 0; n < 2; ++n) _Pragma("unroll") for (int k = 0; k < 2; ++k) dst[n][k] = *(const LAS bf16x8*)(lds + PG8_SB(b, h) + boff + n * 2048 + k * 1024); } while (0)
; #define PG8_WAIT_V(n) asm volatile("s_waitcnt vmcnt(" #n ")" ::: "memory")
; #define PG8_WAIT_L(n) asm volatile("s_waitcnt lgkmcnt(" #n ")" ::: "memory")
; template <class Epi>
; __device__ __forceinline__ void gemm_phase(LAS unsigned char* lds, const Gemm g, const StaticOrder& S, const Epi& E) {
;     ...
;         for (int t = 0; t < nt; t += 2) {
;             const bool last = (t == nt - 2);
;             const char* a1 = cA + (size_t)(t + 1) * kstep;
;             const char* a2 = last ? nA : cA + (size_t)(t + 2) * kstep; const char* b2 = last ? nB : cB + (size_t)(t + 2) * kstep;
;             const char* a3 = a2 + kstep; const char* b3 = b2 + kstep;
;             PG8_LDB(B0, 0, 0); PG8_LDB(B1, 0, 1); PG8_SCHED; PG8_LDA(At, 0, 0); PG8_STAGE(PG8_SA(1, 1), a1 + hstepA, voffA);
;             PG8_WAIT_V(8); PG8_WAIT_L(0); PG8_BAR; PG8_MMA(0, 0, At, B0); PG8_MMA(0, 1, At, B1); PG8_BAR; PG8_SCHED;
;             PG8_LDA(At, 0, 1); PG8_STAGE(PG8_SB(0, 0), b2, voffB); PG8_STAGE(PG8_SB(0, 1), b2 + hstepB, voffB); PG8_STAGE(PG8_SA(0, 0), a2, voffA);
;             PG8_WAIT_V(8); PG8_WAIT_L(0); PG8_BAR; PG8_MMA(1, 0, At, B0); PG8_MMA(1, 1, At, B1); PG8_BAR; PG8_SCHED;
;             PG8_LDB(B0, 1, 0); PG8_LDB(B1, 1, 1); PG8_SCHED; PG8_LDA(At, 1, 0); PG8_STAGE(PG8_SA(0, 1), a2 + hstepA, voffA);
;             PG8_WAIT_V(8); PG8_WAIT_L(0); PG8_BAR; PG8_MMA(0, 0, At, B0); PG8_MMA(0, 1, At, B1); PG8_BAR; PG8_SCHED;
;             PG8_LDA(At, 1, 1); PG8_STAGE(PG8_SB(1, 0), b3, voffB); PG8_STAGE(PG8_SB(1, 1), b3 + hstepB, voffB); PG8_STAGE(PG8_SA(1, 0), a3, voffA);
;             PG8_WAIT_V(8); PG8_WAIT_L(0); PG8_BAR; PG8_MMA(1, 0, At, B0); PG8_MMA(1, 1, At, B1); PG8_BAR; PG8_SCHED;
	s_add_i32 s12, s88, s43
	v_lshl_add_u64 v[174:175], v[174:175], 0, s[34:35]
	s_mov_b32 m0, s12
	ds_read_b128 v[198:201], v164 offset:49152
	ds_read_b128 v[202:205], v164 offset:50176
	ds_read_b128 v[206:209], v164 offset:51200
	ds_read_b128 v[210:213], v164 offset:52224
	ds_read_b128 v[214:217], v164 offset:53248
	ds_read_b128 v[218:221], v164 offset:54272
	ds_read_b128 v[222:225], v164 offset:55296
	ds_read_b128 v[226:229], v164 offset:56320
	global_load_lds_dwordx4 v[174:175], off
	s_add_i32 m0, s12, 0x2000
	s_add_u32 s10, s10, 0x40080
	v_lshl_add_u64 v[174:175], v[230:231], 0, s[34:35]
	s_addc_u32 s11, s11, 0
	s_add_i32 s12, s89, s43
	global_load_lds_dwordx4 v[174:175], off
	v_lshl_add_u64 v[174:175], s[10:11], 0, v[130:131]
	s_mov_b32 m0, s12
	s_nop 0
	global_load_lds_dwordx4 v[174:175], off
	v_lshl_add_u64 v[174:175], s[10:11], 0, v[134:135]
	s_add_i32 m0, s12, 0x2000
	s_nop 0
	global_load_lds_dwordx4 v[174:175], off
	v_lshl_add_u64 v[174:175], v[232:233], 0, s[34:35]
	s_mov_b32 m0, s77
	s_nop 0
	global_load_lds_dwordx4 v[174:175], off
	v_lshl_add_u64 v[174:175], v[234:235], 0, s[34:35]
	s_mov_b32 m0, s78
	s_nop 0
	global_load_lds_dwordx4 v[174:175], off
	s_waitcnt vmcnt(8)
	s_waitcnt lgkmcnt(0)
	s_barrier
	s_setprio 1
	s_waitcnt lgkmcnt(0)
	v_mfma_f32_16x16x32_bf16 v[60:63], v[146:149], v[198:201], v[60:63]
	v_mfma_f32_16x16x32_bf16 v[56:59], v[170:173], v[198:201], v[56:59]
	v_mfma_f32_16x16x32_bf16 v[52:55], v[146:149], v[206:209], v[52:55]
	v_mfma_f32_16x16x32_bf16 v[44:47], v[170:173], v[206:209], v[44:47]
	v_mfma_f32_16x16x32_bf16 v[36:39], v[146:149], v[214:217], v[36:39]
	v_mfma_f32_16x16x32_bf16 v[28:31], v[170:173], v[214:217], v[28:31]
	v_mfma_f32_16x16x32_bf16 v[20:23], v[146:149], v[222:225], v[20:23]
	v_mfma_f32_16x16x32_bf16 v[12:15], v[170:173], v[222:225], v[12:15]
	v_mfma_f32_16x16x32_bf16 v[60:63], v[166:169], v[202:205], v[60:63]
	v_mfma_f32_16x16x32_bf16 v[56:59], v[178:181], v[202:205], v[56:59]
	v_mfma_f32_16x16x32_bf16 v[52:55], v[166:169], v[210:213], v[52:55]
	v_mfma_f32_16x16x32_bf16 v[44:47], v[178:181], v[210:213], v[44:47]
	v_mfma_f32_16x16x32_bf16 v[36:39], v[166:169], v[218:221], v[36:39]
	v_mfma_f32_16x16x32_bf16 v[28:31], v[178:181], v[218:221], v[28:31]
	v_mfma_f32_16x16x32_bf16 v[20:23], v[166:169], v[226:229], v[20:23]
	v_mfma_f32_16x16x32_bf16 v[12:15], v[178:181], v[226:229], v[12:15]
	v_mfma_f32_16x16x32_bf16 v[48:51], v[182:185], v[198:201], v[48:51]
	v_mfma_f32_16x16x32_bf16 v[40:43], v[190:193], v[198:201], v[40:43]
	v_mfma_f32_16x16x32_bf16 v[32:35], v[182:185], v[206:209], v[32:35]
	v_mfma_f32_16x16x32_bf16 v[24:27], v[190:193], v[206:209], v[24:27]
	v_mfma_f32_16x16x32_bf16 v[16:19], v[182:185], v[214:217], v[16:19]
	v_mfma_f32_16x16x32_bf16 v[8:11], v[190:193], v[214:217], v[8:11]
	v_mfma_f32_16x16x32_bf16 v[4:7], v[182:185], v[222:225], v[4:7]
	v_mfma_f32_16x16x32_bf16 v[0:3], v[190:193], v[222:225], v[0:3]
	v_mfma_f32_16x16x32_bf16 v[48:51], v[186:189], v[202:205], v[48:51]
	v_mfma_f32_16x16x32_bf16 v[40:43], v[194:197], v[202:205], v[40:43]
	v_mfma_f32_16x16x32_bf16 v[32:35], v[186:189], v[210:213], v[32:35]
	v_mfma_f32_16x16x32_bf16 v[24:27], v[194:197], v[210:213], v[24:27]
	v_mfma_f32_16x16x32_bf16 v[16:19], v[186:189], v[218:221], v[16:19]
	v_mfma_f32_16x16x32_bf16 v[8:11], v[194:197], v[218:221], v[8:11]
	v_mfma_f32_16x16x32_bf16 v[4:7], v[186:189], v[226:229], v[4:7]
	v_mfma_f32_16x16x32_bf16 v[0:3], v[194:197], v[226:229], v[0:3]
	s_setprio 0
	s_barrier
	s_add_i32 s87, s87, 2
	s_add_u32 s8, s8, 0x100
	s_addc_u32 s9, s9, 0
	s_add_u32 s74, s74, 0x100
	s_addc_u32 s75, s75, 0
	s_cmp_gt_u32 s87, 13
.LBB0_1403:
	ds_read_b128 v[146:149], v162
	ds_read_b128 v[166:169], v162 offset:1024
	ds_read_b128 v[170:173], v162 offset:2048
	ds_read_b128 v[178:181], v162 offset:3072
	ds_read_b128 v[182:185], v163
	ds_read_b128 v[186:189], v163 offset:1024
	ds_read_b128 v[190:193], v163 offset:2048
	ds_read_b128 v[194:197], v163 offset:3072
	s_add_u32 s10, s8, 0xfffc0080
	s_addc_u32 s11, s9, -1
	s_cmp_eq_u32 s87, 12
	s_cselect_b32 s13, s1, s11
	s_cselect_b32 s12, s7, s10
	s_cselect_b32 s11, s65, s75
	s_cselect_b32 s10, s69, s74
	v_lshl_add_u64 v[174:175], s[8:9], 0, v[138:139]
	s_add_i32 m0, s53, 0xc000
	ds_read_b128 v[198:201], v164
	ds_read_b128 v[202:205], v164 offset:1024
	ds_read_b128 v[206:209], v164 offset:2048
	ds_read_b128 v[210:213], v164 offset:3072
	ds_read_b128 v[214:217], v164 offset:4096
	ds_read_b128 v[218:221], v164 offset:5120
	ds_read_b128 v[222:225], v164 offset:6144
	ds_read_b128 v[226:229], v164 offset:7168
	global_load_lds_dwordx4 v[174:175], off
	v_lshl_add_u64 v[174:175], s[8:9], 0, v[140:141]
	s_add_i32 m0, s53, 0xe000
	s_nop 0
	global_load_lds_dwordx4 v[174:175], off
	s_waitcnt vmcnt(8)
	s_waitcnt lgkmcnt(0)
	s_barrier
; #define PG8_STAGE(bufoff, gbase, voff) do { _Pragma("unroll") for (int _i = 0; _i < 2; ++_i) \
;         __builtin_amdgcn_global_load_lds((const unsigned*)((const char*)(gbase) + (voff)[_i]), (LAS unsigned*)(lds + (bufoff) + ldsw + _i * 8192), 16, 0, 0); } while (0)
; #define PG8_LDA(dst, b, h) do { _Pragma("unroll") for (int m = 0; m < 4; ++m) _Pragma("unroll") for (int k = 0; k < 2; ++k) dst[m][k] = *(const LAS bf16x8*)(lds + PG8_SA(b, h) + aoff + m * 2048 + k * 1024); } while (0)
; #define PG8_LDB(dst, b, h) do { _Pragma("unroll") for (int n = 0; n < 2; ++n) _Pragma("unroll") for (int k = 0; k < 2; ++k) dst[n][k] = *(const LAS bf16x8*)(lds + PG8_SB(b, h) + boff + n * 2048 + k * 1024); } while (0)
; #define PG8_MMA(ai, bj, At, Bt) do { __builtin_amdgcn_s_setprio(1); _Pragma("unroll") for (int m = 0; m < 4; ++m) _Pragma("unroll") for (int n = 0; n < 2; ++n) _Pragma("unroll") for (int k = 0; k < 2; ++k) \
;         acc[ai][bj][m][n] = __builtin_amdgcn_mfma_f32_16x16x32_bf16(Bt[n][k], At[m][k], acc[ai][bj][m][n], 0, 0, 0); __builtin_amdgcn_s_setprio(0); } while (0)
; #define PG8_WAIT_V(n) asm volatile("s_waitcnt vmcnt(" #n ")" ::: "memory")
; #define PG8_WAIT_L(n) asm volatile("s_waitcnt lgkmcnt(" #n ")" ::: "memory")
; #define PG8_BAR __builtin_amdgcn_s_barrier()
; #define PG8_SCHED __builtin_amdgcn_sched_barrier(0)
; template <class Epi>
; __device__ __forceinline__ void gemm_phase(LAS unsigned char* lds, const Gemm g, const StaticOrder& S, const Epi& E) {
;     ...
;             PG8_WAIT_V(8); PG8_WAIT_L(0); PG8_BAR; PG8_MMA(0, 0, At, B0); PG8_MMA(0, 1, At, B1); PG8_BAR; PG8_SCHED;
;             PG8_LDA(At, 0, 1); PG8_STAGE(PG8_SB(0, 0), b2, voffB); PG8_STAGE(PG8_SB(0, 1), b2 + hstepB, voffB); PG8_STAGE(PG8_SA(0, 0), a2, voffA);
;             PG8_WAIT_V(8); PG8_WAIT_L(0); PG8_BAR; PG8_MMA(1, 0, At, B0); PG8_MMA(1, 1, At, B1); PG8_BAR; PG8_SCHED;
;             PG8_LDB(B0, 1, 0); PG8_LDB(B1, 1, 1); PG8_SCHED; PG8_LDA(At, 1, 0); PG8_STAGE(PG8_SA(0, 1), a2 + hstepA, voffA);
;             PG8_WAIT_V(8); PG8_WAIT_L(0); PG8_BAR; PG8_MMA(0, 0, At, B0); PG8_MMA(0, 1, At, B1); PG8_BAR; PG8_SCHED;
	s_setprio 1
	s_waitcnt lgkmcnt(0)
	v_mfma_f32_16x16x32_bf16 v[124:127], v[146:149], v[198:201], v[124:127]
	v_mfma_f32_16x16x32_bf16 v[120:123], v[170:173], v[198:201], v[120:123]
	v_mfma_f32_16x16x32_bf16 v[112:115], v[146:149], v[206:209], v[112:115]
	v_mfma_f32_16x16x32_bf16 v[104:107], v[170:173], v[206:209], v[104:107]
	v_mfma_f32_16x16x32_bf16 v[100:103], v[146:149], v[214:217], v[100:103]
	v_mfma_f32_16x16x32_bf16 v[92:95], v[170:173], v[214:217], v[92:95]
	v_mfma_f32_16x16x32_bf16 v[84:87], v[146:149], v[222:225], v[84:87]
	v_mfma_f32_16x16x32_bf16 v[76:79], v[170:173], v[222:225], v[76:79]
	v_mfma_f32_16x16x32_bf16 v[124:127], v[166:169], v[202:205], v[124:127]
	v_mfma_f32_16x16x32_bf16 v[120:123], v[178:181], v[202:205], v[120:123]
	v_mfma_f32_16x16x32_bf16 v[112:115], v[166:169], v[210:213], v[112:115]
	v_mfma_f32_16x16x32_bf16 v[104:107], v[178:181], v[210:213], v[104:107]
	v_mfma_f32_16x16x32_bf16 v[100:103], v[166:169], v[218:221], v[100:103]
	v_mfma_f32_16x16x32_bf16 v[92:95], v[178:181], v[218:221], v[92:95]
	v_mfma_f32_16x16x32_bf16 v[84:87], v[166:169], v[226:229], v[84:87]
	v_mfma_f32_16x16x32_bf16 v[76:79], v[178:181], v[226:229], v[76:79]
	v_mfma_f32_16x16x32_bf16 v[116:119], v[182:185], v[198:201], v[116:119]
	v_mfma_f32_16x16x32_bf16 v[108:111], v[190:193], v[198:201], v[108:111]
	v_mfma_f32_16x16x32_bf16 v[96:99], v[182:185], v[206:209], v[96:99]
	v_mfma_f32_16x16x32_bf16 v[88:91], v[190:193], v[206:209], v[88:91]
	v_mfma_f32_16x16x32_bf16 v[80:83], v[182:185], v[214:217], v[80:83]
	v_mfma_f32_16x16x32_bf16 v[72:75], v[190:193], v[214:217], v[72:75]
	v_mfma_f32_16x16x32_bf16 v[68:71], v[182:185], v[222:225], v[68:71]
	v_mfma_f32_16x16x32_bf16 v[64:67], v[190:193], v[222:225], v[64:67]
	v_mfma_f32_16x16x32_bf16 v[116:119], v[186:189], v[202:205], v[116:119]
	v_mfma_f32_16x16x32_bf16 v[108:111], v[194:197], v[202:205], v[108:111]
	v_mfma_f32_16x16x32_bf16 v[96:99], v[186:189], v[210:213], v[96:99]
	v_mfma_f32_16x16x32_bf16 v[88:91], v[194:197], v[210:213], v[88:91]
	v_mfma_f32_16x16x32_bf16 v[80:83], v[186:189], v[218:221], v[80:83]
	v_mfma_f32_16x16x32_bf16 v[72:75], v[194:197], v[218:221], v[72:75]
	v_mfma_f32_16x16x32_bf16 v[68:71], v[186:189], v[226:229], v[68:71]
	v_mfma_f32_16x16x32_bf16 v[64:67], v[194:197], v[226:229], v[64:67]
	s_setprio 0
	s_barrier
	s_add_i32 s88, s83, s43
	v_lshl_add_u64 v[174:175], s[10:11], 0, v[130:131]
	s_mov_b32 m0, s88
	ds_read_b128 v[198:201], v164 offset:16384
	ds_read_b128 v[202:205], v164 offset:17408
	ds_read_b128 v[206:209], v164 offset:18432
	ds_read_b128 v[210:213], v164 offset:19456
	ds_read_b128 v[214:217], v164 offset:20480
	ds_read_b128 v[218:221], v164 offset:21504
	ds_read_b128 v[222:225], v164 offset:22528
	ds_read_b128 v[226:229], v164 offset:23552
	global_load_lds_dwordx4 v[174:175], off
	s_add_i32 m0, s88, 0x2000
	s_add_u32 s88, s10, 0x40000
	v_lshl_add_u64 v[230:231], s[10:11], 0, v[134:135]
	s_addc_u32 s89, s11, 0
	s_add_i32 s90, s84, s43
	global_load_lds_dwordx4 v[230:231], off
	v_lshl_add_u64 v[232:233], s[88:89], 0, v[130:131]
	s_mov_b32 m0, s90
	v_lshl_add_u64 v[234:235], s[12:13], 0, v[132:133]
	global_load_lds_dwordx4 v[232:233], off
	v_lshl_add_u64 v[232:233], s[88:89], 0, v[134:135]
	s_add_i32 m0, s90, 0x2000
	s_nop 0
	global_load_lds_dwordx4 v[232:233], off
	v_lshl_add_u64 v[232:233], s[12:13], 0, v[128:129]
	s_mov_b32 m0, s53
	s_nop 0
	global_load_lds_dwordx4 v[232:233], off
	s_mov_b32 m0, s55
	s_nop 0
	global_load_lds_dwordx4 v[234:235], off
	s_waitcnt vmcnt(8)
	s_waitcnt lgkmcnt(0)
	s_barrier
	s_setprio 1
	s_waitcnt lgkmcnt(0)
	v_mfma_f32_16x16x32_bf16 v[60:63], v[146:149], v[198:201], v[60:63]
	v_mfma_f32_16x16x32_bf16 v[56:59], v[170:173], v[198:201], v[56:59]
	v_mfma_f32_16x16x32_bf16 v[52:55], v[146:149], v[206:209], v[52:55]
	v_mfma_f32_16x16x32_bf16 v[44:47], v[170:173], v[206:209], v[44:47]
	v_mfma_f32_16x16x32_bf16 v[36:39], v[146:149], v[214:217], v[36:39]
	v_mfma_f32_16x16x32_bf16 v[28:31], v[170:173], v[214:217], v[28:31]
	v_mfma_f32_16x16x32_bf16 v[20:23], v[146:149], v[222:225], v[20:23]
	v_mfma_f32_16x16x32_bf16 v[12:15], v[170:173], v[222:225], v[12:15]
	v_mfma_f32_16x16x32_bf16 v[60:63], v[166:169], v[202:205], v[60:63]
	v_mfma_f32_16x16x32_bf16 v[56:59], v[178:181], v[202:205], v[56:59]
	v_mfma_f32_16x16x32_bf16 v[52:55], v[166:169], v[210:213], v[52:55]
	v_mfma_f32_16x16x32_bf16 v[44:47], v[178:181], v[210:213], v[44:47]
	v_mfma_f32_16x16x32_bf16 v[36:39], v[166:169], v[218:221], v[36:39]
	v_mfma_f32_16x16x32_bf16 v[28:31], v[178:181], v[218:221], v[28:31]
	v_mfma_f32_16x16x32_bf16 v[20:23], v[166:169], v[226:229], v[20:23]
	v_mfma_f32_16x16x32_bf16 v[12:15], v[178:181], v[226:229], v[12:15]
	v_mfma_f32_16x16x32_bf16 v[48:51], v[182:185], v[198:201], v[48:51]
	v_mfma_f32_16x16x32_bf16 v[40:43], v[190:193], v[198:201], v[40:43]
	v_mfma_f32_16x16x32_bf16 v[32:35], v[182:185], v[206:209], v[32:35]
	v_mfma_f32_16x16x32_bf16 v[24:27], v[190:193], v[206:209], v[24:27]
	v_mfma_f32_16x16x32_bf16 v[16:19], v[182:185], v[214:217], v[16:19]
	v_mfma_f32_16x16x32_bf16 v[8:11], v[190:193], v[214:217], v[8:11]
	v_mfma_f32_16x16x32_bf16 v[4:7], v[182:185], v[222:225], v[4:7]
	v_mfma_f32_16x16x32_bf16 v[0:3], v[190:193], v[222:225], v[0:3]
	v_mfma_f32_16x16x32_bf16 v[48:51], v[186:189], v[202:205], v[48:51]
	v_mfma_f32_16x16x32_bf16 v[40:43], v[194:197], v[202:205], v[40:43]
	v_mfma_f32_16x16x32_bf16 v[32:35], v[186:189], v[210:213], v[32:35]
	v_mfma_f32_16x16x32_bf16 v[24:27], v[194:197], v[210:213], v[24:27]
	v_mfma_f32_16x16x32_bf16 v[16:19], v[186:189], v[218:221], v[16:19]
	v_mfma_f32_16x16x32_bf16 v[8:11], v[194:197], v[218:221], v[8:11]
	v_mfma_f32_16x16x32_bf16 v[4:7], v[186:189], v[226:229], v[4:7]
	v_mfma_f32_16x16x32_bf16 v[0:3], v[194:197], v[226:229], v[0:3]
	s_setprio 0
	s_barrier
; #define PG8_STAGE(bufoff, gbase, voff) do { _Pragma("unroll") for (int _i = 0; _i < 2; ++_i) \
;         __builtin_amdgcn_global_load_lds((const unsigned*)((const char*)(gbase) + (voff)[_i]), (LAS unsigned*)(lds + (bufoff) + ldsw + _i * 8192), 16, 0, 0); } while (0)
; #define PG8_LDA(dst, b, h) do { _Pragma("unroll") for (int m = 0; m < 4; ++m) _Pragma("unroll") for (int k = 0; k < 2; ++k) dst[m][k] = *(const LAS bf16x8*)(lds + PG8_SA(b, h) + aoff + m * 2048 + k * 1024); } while (0)
; #define PG8_MMA(ai, bj, At, Bt) do { __builtin_amdgcn_s_setprio(1); _Pragma("unroll") for (int m = 0; m < 4; ++m) _Pragma("unroll") for (int n = 0; n < 2; ++n) _Pragma("unroll") for (int k = 0; k < 2; ++k) \
;         acc[ai][bj][m][n] = __builtin_amdgcn_mfma_f32_16x16x32_bf16(Bt[n][k], At[m][k], acc[ai][bj][m][n], 0, 0, 0); __builtin_amdgcn_s_setprio(0); } while (0)
; #define PG8_WAIT_V(n) asm volatile("s_waitcnt vmcnt(" #n ")" ::: "memory")
; #define PG8_WAIT_L(n) asm volatile("s_waitcnt lgkmcnt(" #n ")" ::: "memory")
; #define PG8_BAR __builtin_amdgcn_s_barrier()
; #define PG8_SCHED __builtin_amdgcn_sched_barrier(0)
; template <class Epi>
; __device__ __forceinline__ void gemm_phase(LAS unsigned char* lds, const Gemm g, const StaticOrder& S, const Epi& E) {
;     ...
;             PG8_LDA(At, 1, 1); PG8_STAGE(PG8_SB(1, 0), b3, voffB); PG8_STAGE(PG8_SB(1, 1), b3 + hstepB, voffB); PG8_STAGE(PG8_SA(1, 0), a3, voffA);
;             PG8_WAIT_V(8); PG8_WAIT_L(0); PG8_BAR; PG8_MMA(1, 0, At, B0); PG8_MMA(1, 1, At, B1); PG8_BAR; PG8_SCHED;
	s_add_i32 s88, 0, 0x18000
	v_add_u32_e32 v136, s88, v161
	s_add_i32 s89, 0, 0x1c000
	ds_read_b128 v[146:149], v136
	ds_read_b128 v[166:169], v136 offset:1024
	ds_read_b128 v[170:173], v136 offset:2048
	ds_read_b128 v[178:181], v136 offset:3072
	v_add_u32_e32 v136, s89, v161
	ds_read_b128 v[182:185], v136
	ds_read_b128 v[186:189], v136 offset:1024
	ds_read_b128 v[190:193], v136 offset:2048
	ds_read_b128 v[194:197], v136 offset:3072
	s_add_u32 s12, s12, 0x40000
	s_addc_u32 s13, s13, 0
	s_mov_b32 m0, s57
	v_lshl_add_u64 v[236:237], s[12:13], 0, v[128:129]
	ds_read_b128 v[198:201], v164 offset:32768
	ds_read_b128 v[202:205], v164 offset:33792
	ds_read_b128 v[206:209], v164 offset:34816
	ds_read_b128 v[210:213], v164 offset:35840
	ds_read_b128 v[214:217], v164 offset:36864
	ds_read_b128 v[218:221], v164 offset:37888
	ds_read_b128 v[222:225], v164 offset:38912
	ds_read_b128 v[226:229], v164 offset:39936
	global_load_lds_dwordx4 v[236:237], off
	v_lshl_add_u64 v[236:237], s[12:13], 0, v[132:133]
	s_mov_b32 m0, s59
	s_nop 0
	global_load_lds_dwordx4 v[236:237], off
	s_waitcnt vmcnt(8)
	s_waitcnt lgkmcnt(0)
	s_barrier
	s_setprio 1
	s_waitcnt lgkmcnt(0)
	v_mfma_f32_16x16x32_bf16 v[124:127], v[146:149], v[198:201], v[124:127]
	v_mfma_f32_16x16x32_bf16 v[120:123], v[170:173], v[198:201], v[120:123]
	v_mfma_f32_16x16x32_bf16 v[112:115], v[146:149], v[206:209], v[112:115]
	v_mfma_f32_16x16x32_bf16 v[104:107], v[170:173], v[206:209], v[104:107]
	v_mfma_f32_16x16x32_bf16 v[100:103], v[146:149], v[214:217], v[100:103]
	v_mfma_f32_16x16x32_bf16 v[92:95], v[170:173], v[214:217], v[92:95]
	v_mfma_f32_16x16x32_bf16 v[84:87], v[146:149], v[222:225], v[84:87]
	v_mfma_f32_16x16x32_bf16 v[76:79], v[170:173], v[222:225], v[76:79]
	v_mfma_f32_16x16x32_bf16 v[124:127], v[166:169], v[202:205], v[124:127]
	v_mfma_f32_16x16x32_bf16 v[120:123], v[178:181], v[202:205], v[120:123]
	v_mfma_f32_16x16x32_bf16 v[112:115], v[166:169], v[210:213], v[112:115]
	v_mfma_f32_16x16x32_bf16 v[104:107], v[178:181], v[210:213], v[104:107]
	v_mfma_f32_16x16x32_bf16 v[100:103], v[166:169], v[218:221], v[100:103]
	v_mfma_f32_16x16x32_bf16 v[92:95], v[178:181], v[218:221], v[92:95]
	v_mfma_f32_16x16x32_bf16 v[84:87], v[166:169], v[226:229], v[84:87]
	v_mfma_f32_16x16x32_bf16 v[76:79], v[178:181], v[226:229], v[76:79]
	v_mfma_f32_16x16x32_bf16 v[116:119], v[182:185], v[198:201], v[116:119]
	v_mfma_f32_16x16x32_bf16 v[108:111], v[190:193], v[198:201], v[108:111]
	v_mfma_f32_16x16x32_bf16 v[96:99], v[182:185], v[206:209], v[96:99]
	v_mfma_f32_16x16x32_bf16 v[88:91], v[190:193], v[206:209], v[88:91]
	v_mfma_f32_16x16x32_bf16 v[80:83], v[182:185], v[214:217], v[80:83]
	v_mfma_f32_16x16x32_bf16 v[72:75], v[190:193], v[214:217], v[72:75]
	v_mfma_f32_16x16x32_bf16 v[68:71], v[182:185], v[222:225], v[68:71]
	v_mfma_f32_16x16x32_bf16 v[64:67], v[190:193], v[222:225], v[64:67]
	v_mfma_f32_16x16x32_bf16 v[116:119], v[186:189], v[202:205], v[116:119]
	v_mfma_f32_16x16x32_bf16 v[108:111], v[194:197], v[202:205], v[108:111]
	v_mfma_f32_16x16x32_bf16 v[96:99], v[186:189], v[210:213], v[96:99]
	v_mfma_f32_16x16x32_bf16 v[88:91], v[194:197], v[210:213], v[88:91]
	v_mfma_f32_16x16x32_bf16 v[80:83], v[186:189], v[218:221], v[80:83]
	v_mfma_f32_16x16x32_bf16 v[72:75], v[194:197], v[218:221], v[72:75]
	v_mfma_f32_16x16x32_bf16 v[68:71], v[186:189], v[226:229], v[68:71]
	v_mfma_f32_16x16x32_bf16 v[64:67], v[194:197], v[226:229], v[64:67]
	s_setprio 0
	s_barrier
; #define PG8_STAGE(bufoff, gbase, voff) do { _Pragma("unroll") for (int _i = 0; _i < 2; ++_i) \
;         __builtin_amdgcn_global_load_lds((const unsigned*)((const char*)(gbase) + (voff)[_i]), (LAS unsigned*)(lds + (bufoff) + ldsw + _i * 8192), 16, 0, 0); } while (0)
; #define PG8_LDA(dst, b, h) do { _Pragma("unroll") for (int m = 0; m < 4; ++m) _Pragma("unroll") for (int k = 0; k < 2; ++k) dst[m][k] = *(const LAS bf16x8*)(lds + PG8_SA(b, h) + aoff + m * 2048 + k * 1024); } while (0)
; #define PG8_MMA(ai, bj, At, Bt) do { __builtin_amdgcn_s_setprio(1); _Pragma("unroll") for (int m = 0; m < 4; ++m) _Pragma("unroll") for (int n = 0; n < 2; ++n) _Pragma("unroll") for (int k = 0; k < 2; ++k) \
;         acc[ai][bj][m][n] = __builtin_amdgcn_mfma_f32_16x16x32_bf16(Bt[n][k], At[m][k], acc[ai][bj][m][n], 0, 0, 0); __builtin_amdgcn_s_setprio(0); } while (0)
; #define PG8_WAIT_V(n) asm volatile("s_waitcnt vmcnt(" #n ")" ::: "memory")
; #define PG8_WAIT_L(n) asm volatile("s_waitcnt lgkmcnt(" #n ")" ::: "memory")
; #define PG8_BAR __builtin_amdgcn_s_barrier()
; #define PG8_SCHED __builtin_amdgcn_sched_barrier(0)
; template <class Epi>
; __device__ __forceinline__ void gemm_phase(LAS unsigned char* lds, const Gemm g, const StaticOrder& S, const Epi& E) {
;     ...
;             PG8_LDA(At, 1, 1); PG8_STAGE(PG8_SB(1, 0), b3, voffB); PG8_STAGE(PG8_SB(1, 1), b3 + hstepB, voffB); PG8_STAGE(PG8_SA(1, 0), a3, voffA);
;             PG8_WAIT_V(8); PG8_WAIT_L(0); PG8_BAR; PG8_MMA(1, 0, At, B0); PG8_MMA(1, 1, At, B1); PG8_BAR; PG8_SCHED;
;         }
	s_add_i32 s12, s88, s43
	v_lshl_add_u64 v[174:175], v[174:175], 0, s[34:35]
	s_mov_b32 m0, s12
	ds_read_b128 v[198:201], v164 offset:49152
	ds_read_b128 v[202:205], v164 offset:50176
	ds_read_b128 v[206:209], v164 offset:51200
	ds_read_b128 v[210:213], v164 offset:52224
	ds_read_b128 v[214:217], v164 offset:53248
	ds_read_b128 v[218:221], v164 offset:54272
	ds_read_b128 v[222:225], v164 offset:55296
	ds_read_b128 v[226:229], v164 offset:56320
	global_load_lds_dwordx4 v[174:175], off
	s_add_i32 m0, s12, 0x2000
	s_add_u32 s10, s10, 0x40080
	v_lshl_add_u64 v[174:175], v[230:231], 0, s[34:35]
	s_addc_u32 s11, s11, 0
	s_add_i32 s12, s89, s43
	global_load_lds_dwordx4 v[174:175], off
	v_lshl_add_u64 v[174:175], s[10:11], 0, v[130:131]
	s_mov_b32 m0, s12
	s_nop 0
	global_load_lds_dwordx4 v[174:175], off
	v_lshl_add_u64 v[174:175], s[10:11], 0, v[134:135]
	s_add_i32 m0, s12, 0x2000
	s_nop 0
	global_load_lds_dwordx4 v[174:175], off
	v_lshl_add_u64 v[174:175], v[232:233], 0, s[34:35]
	s_mov_b32 m0, s77
	s_nop 0
	global_load_lds_dwordx4 v[174:175], off
	v_lshl_add_u64 v[174:175], v[234:235], 0, s[34:35]
	s_mov_b32 m0, s78
	s_nop 0
	global_load_lds_dwordx4 v[174:175], off
	s_waitcnt vmcnt(8)
	s_waitcnt lgkmcnt(0)
	s_barrier
	s_setprio 1
	s_waitcnt lgkmcnt(0)
	v_mfma_f32_16x16x32_bf16 v[60:63], v[146:149], v[198:201], v[60:63]
	v_mfma_f32_16x16x32_bf16 v[56:59], v[170:173], v[198:201], v[56:59]
	v_mfma_f32_16x16x32_bf16 v[52:55], v[146:149], v[206:209], v[52:55]
	v_mfma_f32_16x16x32_bf16 v[44:47], v[170:173], v[206:209], v[44:47]
	v_mfma_f32_16x16x32_bf16 v[36:39], v[146:149], v[214:217], v[36:39]
	v_mfma_f32_16x16x32_bf16 v[28:31], v[170:173], v[214:217], v[28:31]
	v_mfma_f32_16x16x32_bf16 v[20:23], v[146:149], v[222:225], v[20:23]
	v_mfma_f32_16x16x32_bf16 v[12:15], v[170:173], v[222:225], v[12:15]
	v_mfma_f32_16x16x32_bf16 v[60:63], v[166:169], v[202:205], v[60:63]
	v_mfma_f32_16x16x32_bf16 v[56:59], v[178:181], v[202:205], v[56:59]
	v_mfma_f32_16x16x32_bf16 v[52:55], v[166:169], v[210:213], v[52:55]
	v_mfma_f32_16x16x32_bf16 v[44:47], v[178:181], v[210:213], v[44:47]
	v_mfma_f32_16x16x32_bf16 v[36:39], v[166:169], v[218:221], v[36:39]
	v_mfma_f32_16x16x32_bf16 v[28:31], v[178:181], v[218:221], v[28:31]
	v_mfma_f32_16x16x32_bf16 v[20:23], v[166:169], v[226:229], v[20:23]
	v_mfma_f32_16x16x32_bf16 v[12:15], v[178:181], v[226:229], v[12:15]
	v_mfma_f32_16x16x32_bf16 v[48:51], v[182:185], v[198:201], v[48:51]
	v_mfma_f32_16x16x32_bf16 v[40:43], v[190:193], v[198:201], v[40:43]
	v_mfma_f32_16x16x32_bf16 v[32:35], v[182:185], v[206:209], v[32:35]
	v_mfma_f32_16x16x32_bf16 v[24:27], v[190:193], v[206:209], v[24:27]
	v_mfma_f32_16x16x32_bf16 v[16:19], v[182:185], v[214:217], v[16:19]
	v_mfma_f32_16x16x32_bf16 v[8:11], v[190:193], v[214:217], v[8:11]
	v_mfma_f32_16x16x32_bf16 v[4:7], v[182:185], v[222:225], v[4:7]
	v_mfma_f32_16x16x32_bf16 v[0:3], v[190:193], v[222:225], v[0:3]
	v_mfma_f32_16x16x32_bf16 v[48:51], v[186:189], v[202:205], v[48:51]
	v_mfma_f32_16x16x32_bf16 v[40:43], v[194:197], v[202:205], v[40:43]
	v_mfma_f32_16x16x32_bf16 v[32:35], v[186:189], v[210:213], v[32:35]
	v_mfma_f32_16x16x32_bf16 v[24:27], v[194:197], v[210:213], v[24:27]
	v_mfma_f32_16x16x32_bf16 v[16:19], v[186:189], v[218:221], v[16:19]
	v_mfma_f32_16x16x32_bf16 v[8:11], v[194:197], v[218:221], v[8:11]
	v_mfma_f32_16x16x32_bf16 v[4:7], v[186:189], v[226:229], v[4:7]
	v_mfma_f32_16x16x32_bf16 v[0:3], v[194:197], v[226:229], v[0:3]
	s_setprio 0
	s_barrier
	s_add_i32 s87, s87, 2
	s_add_u32 s8, s8, 0x100
	s_addc_u32 s9, s9, 0
	s_add_u32 s74, s74, 0x100
	s_addc_u32 s75, s75, 0
	s_cmp_gt_u32 s87, 13
	s_cbranch_scc0 .LBB0_1403
	s_and_b64 vcc, exec, s[38:39]
	s_cbranch_vccz .LBB0_1406
	s_barrier

; #define PG8_STAGE(bufoff, gbase, voff) do { _Pragma("unroll") for (int _i = 0; _i < 2; ++_i) \
;         __builtin_amdgcn_global_load_lds((const unsigned*)((const char*)(gbase) + (voff)[_i]), (LAS unsigned*)(lds + (bufoff) + ldsw + _i * 8192), 16, 0, 0); } while (0)
; #define PG8_LDA(dst, b, h) do { _Pragma("unroll") for (int m = 0; m < 4; ++m) _Pragma("unroll") for (int k = 0; k < 2; ++k) dst[m][k] = *(const LAS bf16x8*)(lds + PG8_SA(b, h) + aoff + m * 2048 + k * 1024); } while (0)
; #define PG8_LDB(dst, b, h) do { _Pragma("unroll") for (int n = 0; n < 2; ++n) _Pragma("unroll") for (int k = 0; k < 2; ++k) dst[n][k] = *(const LAS bf16x8*)(lds + PG8_SB(b, h) + boff + n * 2048 + k * 1024); } while (0)
; #define PG8_MMA(ai, bj, At, Bt) do { __builtin_amdgcn_s_setprio(1); _Pragma("unroll") for (int m = 0; m < 4; ++m) _Pragma("unroll") for (int n = 0; n < 2; ++n) _Pragma("unroll") for (int k = 0; k < 2; ++k) \
;         acc[ai][bj][m][n] = __builtin_amdgcn_mfma_f32_16x16x32_bf16(Bt[n][k], At[m][k], acc[ai][bj][m][n], 0, 0, 0); __builtin_amdgcn_s_setprio(0); } while (0)
; #define PG8_WAIT_V(n) asm volatile("s_waitcnt vmcnt(" #n ")" ::: "memory")
; template <class Epi>
; __device__ __forceinline__ void gemm_phase(LAS unsigned char* lds, const Gemm g, const StaticOrder& S, const Epi& E) {
;     ...
;         const char* nA = has_next ? (const char*)g.A + (size_t)nxt.pm * tstepA : cA; const char* nB = has_next ? (const char*)g.Bt + (size_t)nxt.pn * tstepB : cB;
; #pragma nounroll
;         for (int t = 0; t < nt; t += 2) {
;             const bool last = (t == nt - 2);
;             const char* a1 = cA + (size_t)(t + 1) * kstep;
;             const char* a2 = last ? nA : cA + (size_t)(t + 2) * kstep; const char* b2 = last ? nB : cB + (size_t)(t + 2) * kstep;
;             const char* a3 = a2 + kstep; const char* b3 = b2 + kstep;
;             PG8_LDB(B0, 0, 0); PG8_LDB(B1, 0, 1); PG8_SCHED; PG8_LDA(At, 0, 0); PG8_STAGE(PG8_SA(1, 1), a1 + hstepA, voffA);
;             PG8_WAIT_V(8); PG8_WAIT_L(0); PG8_BAR; PG8_MMA(0, 0, At, B0); PG8_MMA(0, 1, At, B1); PG8_BAR; PG8_SCHED;
;             PG8_LDA(At, 0, 1); PG8_STAGE(PG8_SB(0, 0), b2, voffB); PG8_STAGE(PG8_SB(0, 1), b2 + hstepB, voffB); PG8_STAGE(PG8_SA(0, 0), a2, voffA);
;             PG8_WAIT_V(8); PG8_WAIT_L(0); PG8_BAR; PG8_MMA(1, 0, At, B0); PG8_MMA(1, 1, At, B1); PG8_BAR; PG8_SCHED;
.LBB0_1469:
	s_add_u32 s62, s42, s56
	s_addc_u32 s63, s43, s57
	s_add_u32 s60, s62, 0x100
	s_addc_u32 s61, s63, 0
	s_and_b64 s[58:59], s[54:55], exec
	s_cselect_b32 s59, s1, s61
	s_cselect_b32 s58, s19, s60
	s_add_u32 s56, s38, s56
	s_addc_u32 s57, s39, s57
	s_add_u32 s56, s56, 0x100
	s_addc_u32 s57, s57, 0
	s_and_b64 s[54:55], s[54:55], exec
	s_cselect_b32 s61, s17, s57
	s_cselect_b32 s60, s84, s56
	s_add_u32 s64, s62, 0x10080
	ds_read_b128 v[140:143], v145
	ds_read_b128 v[154:157], v145 offset:1024
	ds_read_b128 v[158:161], v145 offset:2048
	ds_read_b128 v[162:165], v145 offset:3072
	ds_read_b128 v[166:169], v146
	ds_read_b128 v[170:173], v146 offset:1024
	ds_read_b128 v[178:181], v146 offset:2048
	ds_read_b128 v[182:185], v146 offset:3072
	s_addc_u32 s65, s63, 0
	s_add_i32 s94, s82, s70
	s_add_i32 m0, s35, 0xc000
	s_add_i32 s95, s35, 0xe000
	s_add_i32 s91, s94, 0x2000
	s_add_u32 s62, s60, 0x10000
	s_addc_u32 s63, s61, 0
	s_add_i32 s93, s83, s70
	s_add_i32 s92, s93, 0x2000
	s_add_i32 s90, 0, 0x18000
	s_add_i32 s89, 0, 0x1c000
	s_add_u32 s56, s58, 0x10000
	s_addc_u32 s57, s59, 0
	s_add_i32 s88, s90, s70
	s_add_i32 s86, s88, 0x2000
	s_add_u32 s54, s60, 0x10080
	s_addc_u32 s55, s61, 0
	s_add_i32 s87, s89, s70
	s_add_i32 s85, s87, 0x2000
	v_lshl_add_u64 v[174:175], s[64:65], 0, v[128:129]
	ds_read_b128 v[186:189], v147
	ds_read_b128 v[190:193], v147 offset:1024
	ds_read_b128 v[194:197], v147 offset:2048
	ds_read_b128 v[198:201], v147 offset:3072
	ds_read_b128 v[202:205], v147 offset:4096
	ds_read_b128 v[206:209], v147 offset:5120
	ds_read_b128 v[210:213], v147 offset:6144
	ds_read_b128 v[214:217], v147 offset:7168
	global_load_lds_dwordx4 v[174:175], off
	v_lshl_add_u64 v[174:175], s[64:65], 0, v[132:133]
	s_mov_b32 m0, s95
	s_nop 0
	global_load_lds_dwordx4 v[174:175], off
	s_waitcnt vmcnt(8)
	s_waitcnt lgkmcnt(0)
	s_barrier
	s_setprio 1
	s_waitcnt lgkmcnt(0)
	v_mfma_f32_16x16x32_bf16 v[124:127], v[140:143], v[186:189], v[124:127]
	v_mfma_f32_16x16x32_bf16 v[120:123], v[158:161], v[186:189], v[120:123]
	v_mfma_f32_16x16x32_bf16 v[108:111], v[140:143], v[194:197], v[108:111]
	v_mfma_f32_16x16x32_bf16 v[104:107], v[158:161], v[194:197], v[104:107]
	v_mfma_f32_16x16x32_bf16 v[92:95], v[140:143], v[202:205], v[92:95]
	v_mfma_f32_16x16x32_bf16 v[88:91], v[158:161], v[202:205], v[88:91]
	v_mfma_f32_16x16x32_bf16 v[76:79], v[140:143], v[210:213], v[76:79]
	v_mfma_f32_16x16x32_bf16 v[72:75], v[158:161], v[210:213], v[72:75]
	v_mfma_f32_16x16x32_bf16 v[124:127], v[154:157], v[190:193], v[124:127]
	v_mfma_f32_16x16x32_bf16 v[120:123], v[162:165], v[190:193], v[120:123]
	v_mfma_f32_16x16x32_bf16 v[108:111], v[154:157], v[198:201], v[108:111]
	v_mfma_f32_16x16x32_bf16 v[104:107], v[162:165], v[198:201], v[104:107]
	v_mfma_f32_16x16x32_bf16 v[92:95], v[154:157], v[206:209], v[92:95]
	v_mfma_f32_16x16x32_bf16 v[88:91], v[162:165], v[206:209], v[88:91]
	v_mfma_f32_16x16x32_bf16 v[76:79], v[154:157], v[214:217], v[76:79]
	v_mfma_f32_16x16x32_bf16 v[72:75], v[162:165], v[214:217], v[72:75]
	v_mfma_f32_16x16x32_bf16 v[116:119], v[166:169], v[186:189], v[116:119]
	v_mfma_f32_16x16x32_bf16 v[112:115], v[178:181], v[186:189], v[112:115]
	v_mfma_f32_16x16x32_bf16 v[100:103], v[166:169], v[194:197], v[100:103]
	v_mfma_f32_16x16x32_bf16 v[96:99], v[178:181], v[194:197], v[96:99]
	v_mfma_f32_16x16x32_bf16 v[84:87], v[166:169], v[202:205], v[84:87]
	v_mfma_f32_16x16x32_bf16 v[80:83], v[178:181], v[202:205], v[80:83]
	v_mfma_f32_16x16x32_bf16 v[68:71], v[166:169], v[210:213], v[68:71]
	v_mfma_f32_16x16x32_bf16 v[64:67], v[178:181], v[210:213], v[64:67]
	v_mfma_f32_16x16x32_bf16 v[116:119], v[170:173], v[190:193], v[116:119]
	v_mfma_f32_16x16x32_bf16 v[112:115], v[182:185], v[190:193], v[112:115]
	v_mfma_f32_16x16x32_bf16 v[100:103], v[170:173], v[198:201], v[100:103]
	v_mfma_f32_16x16x32_bf16 v[96:99], v[182:185], v[198:201], v[96:99]
	v_mfma_f32_16x16x32_bf16 v[84:87], v[170:173], v[206:209], v[84:87]
	v_mfma_f32_16x16x32_bf16 v[80:83], v[182:185], v[206:209], v[80:83]
	v_mfma_f32_16x16x32_bf16 v[68:71], v[170:173], v[214:217], v[68:71]
	v_mfma_f32_16x16x32_bf16 v[64:67], v[182:185], v[214:217], v[64:67]
	s_setprio 0
	s_barrier
	s_mov_b32 m0, s94
	v_lshl_add_u64 v[174:175], s[60:61], 0, v[130:131]
	ds_read_b128 v[186:189], v147 offset:16384
	ds_read_b128 v[190:193], v147 offset:17408
	ds_read_b128 v[194:197], v147 offset:18432
	ds_read_b128 v[198:201], v147 offset:19456
	ds_read_b128 v[202:205], v147 offset:20480
	ds_read_b128 v[206:209], v147 offset:21504
	ds_read_b128 v[210:213], v147 offset:22528
	ds_read_b128 v[214:217], v147 offset:23552
	global_load_lds_dwordx4 v[174:175], off
	v_lshl_add_u64 v[218:219], s[60:61], 0, v[134:135]
	s_mov_b32 m0, s91
	v_lshl_add_u64 v[220:221], s[62:63], 0, v[130:131]
	global_load_lds_dwordx4 v[218:219], off
	s_mov_b32 m0, s93
	v_lshl_add_u64 v[222:223], s[58:59], 0, v[132:133]
	global_load_lds_dwordx4 v[220:221], off
	v_lshl_add_u64 v[220:221], s[62:63], 0, v[134:135]
	s_mov_b32 m0, s92
	s_nop 0
	global_load_lds_dwordx4 v[220:221], off
	v_lshl_add_u64 v[220:221], s[58:59], 0, v[128:129]
	s_mov_b32 m0, s35
	s_nop 0
	global_load_lds_dwordx4 v[220:221], off
	s_mov_b32 m0, s71
	s_nop 0
	global_load_lds_dwordx4 v[222:223], off
	s_waitcnt vmcnt(8)
	s_waitcnt lgkmcnt(0)
	s_barrier
; #define PG8_STAGE(bufoff, gbase, voff) do { _Pragma("unroll") for (int _i = 0; _i < 2; ++_i) \
;         __builtin_amdgcn_global_load_lds((const unsigned*)((const char*)(gbase) + (voff)[_i]), (LAS unsigned*)(lds + (bufoff) + ldsw + _i * 8192), 16, 0, 0); } while (0)
; #define PG8_LDA(dst, b, h) do { _Pragma("unroll") for (int m = 0; m < 4; ++m) _Pragma("unroll") for (int k = 0; k < 2; ++k) dst[m][k] = *(const LAS bf16x8*)(lds + PG8_SA(b, h) + aoff + m * 2048 + k * 1024); } while (0)
; #define PG8_LDB(dst, b, h) do { _Pragma("unroll") for (int n = 0; n < 2; ++n) _Pragma("unroll") for (int k = 0; k < 2; ++k) dst[n][k] = *(const LAS bf16x8*)(lds + PG8_SB(b, h) + boff + n * 2048 + k * 1024); } while (0)
; #define PG8_MMA(ai, bj, At, Bt) do { __builtin_amdgcn_s_setprio(1); _Pragma("unroll") for (int m = 0; m < 4; ++m) _Pragma("unroll") for (int n = 0; n < 2; ++n) _Pragma("unroll") for (int k = 0; k < 2; ++k) \
;         acc[ai][bj][m][n] = __builtin_amdgcn_mfma_f32_16x16x32_bf16(Bt[n][k], At[m][k], acc[ai][bj][m][n], 0, 0, 0); __builtin_amdgcn_s_setprio(0); } while (0)
; #define PG8_WAIT_V(n) asm volatile("s_waitcnt vmcnt(" #n ")" ::: "memory")
; #define PG8_WAIT_L(n) asm volatile("s_waitcnt lgkmcnt(" #n ")" ::: "memory")
; #define PG8_BAR __builtin_amdgcn_s_barrier()
; #define PG8_SCHED __builtin_amdgcn_sched_barrier(0)
; template <class Epi>
; __device__ __forceinline__ void gemm_phase(LAS unsigned char* lds, const Gemm g, const StaticOrder& S, const Epi& E) {
;     ...
;             PG8_WAIT_V(8); PG8_WAIT_L(0); PG8_BAR; PG8_MMA(1, 0, At, B0); PG8_MMA(1, 1, At, B1); PG8_BAR; PG8_SCHED;
;             PG8_LDB(B0, 1, 0); PG8_LDB(B1, 1, 1); PG8_SCHED; PG8_LDA(At, 1, 0); PG8_STAGE(PG8_SA(0, 1), a2 + hstepA, voffA);
;             PG8_WAIT_V(8); PG8_WAIT_L(0); PG8_BAR; PG8_MMA(0, 0, At, B0); PG8_MMA(0, 1, At, B1); PG8_BAR; PG8_SCHED;
;             PG8_LDA(At, 1, 1); PG8_STAGE(PG8_SB(1, 0), b3, voffB); PG8_STAGE(PG8_SB(1, 1), b3 + hstepB, voffB); PG8_STAGE(PG8_SA(1, 0), a3, voffA);
;             PG8_WAIT_V(8); PG8_WAIT_L(0); PG8_BAR; PG8_MMA(1, 0, At, B0); PG8_MMA(1, 1, At, B1); PG8_BAR; PG8_SCHED;
	s_setprio 1
	s_waitcnt lgkmcnt(0)
	v_mfma_f32_16x16x32_bf16 v[60:63], v[140:143], v[186:189], v[60:63]
	v_mfma_f32_16x16x32_bf16 v[56:59], v[158:161], v[186:189], v[56:59]
	v_mfma_f32_16x16x32_bf16 v[44:47], v[140:143], v[194:197], v[44:47]
	v_mfma_f32_16x16x32_bf16 v[40:43], v[158:161], v[194:197], v[40:43]
	v_mfma_f32_16x16x32_bf16 v[28:31], v[140:143], v[202:205], v[28:31]
	v_mfma_f32_16x16x32_bf16 v[24:27], v[158:161], v[202:205], v[24:27]
	v_mfma_f32_16x16x32_bf16 v[12:15], v[140:143], v[210:213], v[12:15]
	v_mfma_f32_16x16x32_bf16 v[8:11], v[158:161], v[210:213], v[8:11]
	v_mfma_f32_16x16x32_bf16 v[60:63], v[154:157], v[190:193], v[60:63]
	v_mfma_f32_16x16x32_bf16 v[56:59], v[162:165], v[190:193], v[56:59]
	v_mfma_f32_16x16x32_bf16 v[44:47], v[154:157], v[198:201], v[44:47]
	v_mfma_f32_16x16x32_bf16 v[40:43], v[162:165], v[198:201], v[40:43]
	v_mfma_f32_16x16x32_bf16 v[28:31], v[154:157], v[206:209], v[28:31]
	v_mfma_f32_16x16x32_bf16 v[24:27], v[162:165], v[206:209], v[24:27]
	v_mfma_f32_16x16x32_bf16 v[12:15], v[154:157], v[214:217], v[12:15]
	v_mfma_f32_16x16x32_bf16 v[8:11], v[162:165], v[214:217], v[8:11]
	v_mfma_f32_16x16x32_bf16 v[52:55], v[166:169], v[186:189], v[52:55]
	v_mfma_f32_16x16x32_bf16 v[48:51], v[178:181], v[186:189], v[48:51]
	v_mfma_f32_16x16x32_bf16 v[36:39], v[166:169], v[194:197], v[36:39]
	v_mfma_f32_16x16x32_bf16 v[32:35], v[178:181], v[194:197], v[32:35]
	v_mfma_f32_16x16x32_bf16 v[20:23], v[166:169], v[202:205], v[20:23]
	v_mfma_f32_16x16x32_bf16 v[16:19], v[178:181], v[202:205], v[16:19]
	v_mfma_f32_16x16x32_bf16 v[4:7], v[166:169], v[210:213], v[4:7]
	v_mfma_f32_16x16x32_bf16 v[0:3], v[178:181], v[210:213], v[0:3]
	v_mfma_f32_16x16x32_bf16 v[52:55], v[170:173], v[190:193], v[52:55]
	v_mfma_f32_16x16x32_bf16 v[48:51], v[182:185], v[190:193], v[48:51]
	v_mfma_f32_16x16x32_bf16 v[36:39], v[170:173], v[198:201], v[36:39]
	v_mfma_f32_16x16x32_bf16 v[32:35], v[182:185], v[198:201], v[32:35]
	v_mfma_f32_16x16x32_bf16 v[20:23], v[170:173], v[206:209], v[20:23]
	v_mfma_f32_16x16x32_bf16 v[16:19], v[182:185], v[206:209], v[16:19]
	v_mfma_f32_16x16x32_bf16 v[4:7], v[170:173], v[214:217], v[4:7]
	v_mfma_f32_16x16x32_bf16 v[0:3], v[182:185], v[214:217], v[0:3]
	s_setprio 0
	s_barrier
	v_add_u32_e32 v149, s90, v144
	ds_read_b128 v[140:143], v149
	ds_read_b128 v[154:157], v149 offset:1024
	ds_read_b128 v[158:161], v149 offset:2048
	ds_read_b128 v[162:165], v149 offset:3072
	v_add_u32_e32 v149, s89, v144
	ds_read_b128 v[166:169], v149
	ds_read_b128 v[170:173], v149 offset:1024
	ds_read_b128 v[178:181], v149 offset:2048
	ds_read_b128 v[182:185], v149 offset:3072
	s_mov_b32 m0, s72
	v_lshl_add_u64 v[224:225], s[56:57], 0, v[128:129]
	ds_read_b128 v[186:189], v147 offset:32768
	ds_read_b128 v[190:193], v147 offset:33792
	ds_read_b128 v[194:197], v147 offset:34816
	ds_read_b128 v[198:201], v147 offset:35840
	ds_read_b128 v[202:205], v147 offset:36864
	ds_read_b128 v[206:209], v147 offset:37888
	ds_read_b128 v[210:213], v147 offset:38912
	ds_read_b128 v[214:217], v147 offset:39936
	global_load_lds_dwordx4 v[224:225], off
	v_lshl_add_u64 v[224:225], s[56:57], 0, v[132:133]
	s_mov_b32 m0, s73
	s_nop 0
	global_load_lds_dwordx4 v[224:225], off
	s_waitcnt vmcnt(8)
	s_waitcnt lgkmcnt(0)
	s_barrier
	s_setprio 1
	s_waitcnt lgkmcnt(0)
	v_mfma_f32_16x16x32_bf16 v[124:127], v[140:143], v[186:189], v[124:127]
	v_mfma_f32_16x16x32_bf16 v[120:123], v[158:161], v[186:189], v[120:123]
	v_mfma_f32_16x16x32_bf16 v[108:111], v[140:143], v[194:197], v[108:111]
	v_mfma_f32_16x16x32_bf16 v[104:107], v[158:161], v[194:197], v[104:107]
	v_mfma_f32_16x16x32_bf16 v[92:95], v[140:143], v[202:205], v[92:95]
	v_mfma_f32_16x16x32_bf16 v[88:91], v[158:161], v[202:205], v[88:91]
	v_mfma_f32_16x16x32_bf16 v[76:79], v[140:143], v[210:213], v[76:79]
	v_mfma_f32_16x16x32_bf16 v[72:75], v[158:161], v[210:213], v[72:75]
	v_mfma_f32_16x16x32_bf16 v[124:127], v[154:157], v[190:193], v[124:127]
	v_mfma_f32_16x16x32_bf16 v[120:123], v[162:165], v[190:193], v[120:123]
	v_mfma_f32_16x16x32_bf16 v[108:111], v[154:157], v[198:201], v[108:111]
	v_mfma_f32_16x16x32_bf16 v[104:107], v[162:165], v[198:201], v[104:107]
	v_mfma_f32_16x16x32_bf16 v[92:95], v[154:157], v[206:209], v[92:95]
	v_mfma_f32_16x16x32_bf16 v[88:91], v[162:165], v[206:209], v[88:91]
	v_mfma_f32_16x16x32_bf16 v[76:79], v[154:157], v[214:217], v[76:79]
	v_mfma_f32_16x16x32_bf16 v[72:75], v[162:165], v[214:217], v[72:75]
	v_mfma_f32_16x16x32_bf16 v[116:119], v[166:169], v[186:189], v[116:119]
	v_mfma_f32_16x16x32_bf16 v[112:115], v[178:181], v[186:189], v[112:115]
	v_mfma_f32_16x16x32_bf16 v[100:103], v[166:169], v[194:197], v[100:103]
	v_mfma_f32_16x16x32_bf16 v[96:99], v[178:181], v[194:197], v[96:99]
	v_mfma_f32_16x16x32_bf16 v[84:87], v[166:169], v[202:205], v[84:87]
	v_mfma_f32_16x16x32_bf16 v[80:83], v[178:181], v[202:205], v[80:83]
	v_mfma_f32_16x16x32_bf16 v[68:71], v[166:169], v[210:213], v[68:71]
	v_mfma_f32_16x16x32_bf16 v[64:67], v[178:181], v[210:213], v[64:67]
	v_mfma_f32_16x16x32_bf16 v[116:119], v[170:173], v[190:193], v[116:119]
	v_mfma_f32_16x16x32_bf16 v[112:115], v[182:185], v[190:193], v[112:115]
	v_mfma_f32_16x16x32_bf16 v[100:103], v[170:173], v[198:201], v[100:103]
	v_mfma_f32_16x16x32_bf16 v[96:99], v[182:185], v[198:201], v[96:99]
	v_mfma_f32_16x16x32_bf16 v[84:87], v[170:173], v[206:209], v[84:87]
	v_mfma_f32_16x16x32_bf16 v[80:83], v[182:185], v[206:209], v[80:83]
	v_mfma_f32_16x16x32_bf16 v[68:71], v[170:173], v[214:217], v[68:71]
	v_mfma_f32_16x16x32_bf16 v[64:67], v[182:185], v[214:217], v[64:67]
	s_setprio 0
	s_barrier
; #define PG8_STAGE(bufoff, gbase, voff) do { _Pragma("unroll") for (int _i = 0; _i < 2; ++_i) \
;         __builtin_amdgcn_global_load_lds((const unsigned*)((const char*)(gbase) + (voff)[_i]), (LAS unsigned*)(lds + (bufoff) + ldsw + _i * 8192), 16, 0, 0); } while (0)
; #define PG8_LDA(dst, b, h) do { _Pragma("unroll") for (int m = 0; m < 4; ++m) _Pragma("unroll") for (int k = 0; k < 2; ++k) dst[m][k] = *(const LAS bf16x8*)(lds + PG8_SA(b, h) + aoff + m * 2048 + k * 1024); } while (0)
; #define PG8_MMA(ai, bj, At, Bt) do { __builtin_amdgcn_s_setprio(1); _Pragma("unroll") for (int m = 0; m < 4; ++m) _Pragma("unroll") for (int n = 0; n < 2; ++n) _Pragma("unroll") for (int k = 0; k < 2; ++k) \
;         acc[ai][bj][m][n] = __builtin_amdgcn_mfma_f32_16x16x32_bf16(Bt[n][k], At[m][k], acc[ai][bj][m][n], 0, 0, 0); __builtin_amdgcn_s_setprio(0); } while (0)
; #define PG8_WAIT_V(n) asm volatile("s_waitcnt vmcnt(" #n ")" ::: "memory")
; #define PG8_WAIT_L(n) asm volatile("s_waitcnt lgkmcnt(" #n ")" ::: "memory")
; #define PG8_BAR __builtin_amdgcn_s_barrier()
; #define PG8_SCHED __builtin_amdgcn_sched_barrier(0)
; template <class Epi>
; __device__ __forceinline__ void gemm_phase(LAS unsigned char* lds, const Gemm g, const StaticOrder& S, const Epi& E) {
;     ...
;             PG8_LDA(At, 1, 1); PG8_STAGE(PG8_SB(1, 0), b3, voffB); PG8_STAGE(PG8_SB(1, 1), b3 + hstepB, voffB); PG8_STAGE(PG8_SA(1, 0), a3, voffA);
;             PG8_WAIT_V(8); PG8_WAIT_L(0); PG8_BAR; PG8_MMA(1, 0, At, B0); PG8_MMA(1, 1, At, B1); PG8_BAR; PG8_SCHED;
;         }
	s_mov_b32 m0, s88
	v_lshl_add_u64 v[174:175], v[174:175], 0, s[10:11]
	ds_read_b128 v[186:189], v147 offset:49152
	ds_read_b128 v[190:193], v147 offset:50176
	ds_read_b128 v[194:197], v147 offset:51200
	ds_read_b128 v[198:201], v147 offset:52224
	ds_read_b128 v[202:205], v147 offset:53248
	ds_read_b128 v[206:209], v147 offset:54272
	ds_read_b128 v[210:213], v147 offset:55296
	ds_read_b128 v[214:217], v147 offset:56320
	global_load_lds_dwordx4 v[174:175], off
	v_lshl_add_u64 v[174:175], v[218:219], 0, s[10:11]
	s_mov_b32 m0, s86
	s_nop 0
	global_load_lds_dwordx4 v[174:175], off
	v_lshl_add_u64 v[174:175], s[54:55], 0, v[130:131]
	s_mov_b32 m0, s87
	s_nop 0
	global_load_lds_dwordx4 v[174:175], off
	v_lshl_add_u64 v[174:175], s[54:55], 0, v[134:135]
	s_mov_b32 m0, s85
	s_nop 0
	global_load_lds_dwordx4 v[174:175], off
	v_lshl_add_u64 v[174:175], v[220:221], 0, s[10:11]
	s_mov_b32 m0, s77
	s_nop 0
	global_load_lds_dwordx4 v[174:175], off
	v_lshl_add_u64 v[174:175], v[222:223], 0, s[10:11]
	s_mov_b32 m0, s78
	s_nop 0
	global_load_lds_dwordx4 v[174:175], off
	s_waitcnt vmcnt(8)
	s_waitcnt lgkmcnt(0)
	s_barrier
	s_setprio 1
	s_waitcnt lgkmcnt(0)
	v_mfma_f32_16x16x32_bf16 v[60:63], v[140:143], v[186:189], v[60:63]
	v_mfma_f32_16x16x32_bf16 v[56:59], v[158:161], v[186:189], v[56:59]
	v_mfma_f32_16x16x32_bf16 v[44:47], v[140:143], v[194:197], v[44:47]
	v_mfma_f32_16x16x32_bf16 v[40:43], v[158:161], v[194:197], v[40:43]
	v_mfma_f32_16x16x32_bf16 v[28:31], v[140:143], v[202:205], v[28:31]
	v_mfma_f32_16x16x32_bf16 v[24:27], v[158:161], v[202:205], v[24:27]
	v_mfma_f32_16x16x32_bf16 v[12:15], v[140:143], v[210:213], v[12:15]
	v_mfma_f32_16x16x32_bf16 v[8:11], v[158:161], v[210:213], v[8:11]
	v_mfma_f32_16x16x32_bf16 v[60:63], v[154:157], v[190:193], v[60:63]
	v_mfma_f32_16x16x32_bf16 v[56:59], v[162:165], v[190:193], v[56:59]
	v_mfma_f32_16x16x32_bf16 v[44:47], v[154:157], v[198:201], v[44:47]
	v_mfma_f32_16x16x32_bf16 v[40:43], v[162:165], v[198:201], v[40:43]
	v_mfma_f32_16x16x32_bf16 v[28:31], v[154:157], v[206:209], v[28:31]
	v_mfma_f32_16x16x32_bf16 v[24:27], v[162:165], v[206:209], v[24:27]
	v_mfma_f32_16x16x32_bf16 v[12:15], v[154:157], v[214:217], v[12:15]
	v_mfma_f32_16x16x32_bf16 v[8:11], v[162:165], v[214:217], v[8:11]
	v_mfma_f32_16x16x32_bf16 v[52:55], v[166:169], v[186:189], v[52:55]
	v_mfma_f32_16x16x32_bf16 v[48:51], v[178:181], v[186:189], v[48:51]
	v_mfma_f32_16x16x32_bf16 v[36:39], v[166:169], v[194:197], v[36:39]
	v_mfma_f32_16x16x32_bf16 v[32:35], v[178:181], v[194:197], v[32:35]
	v_mfma_f32_16x16x32_bf16 v[20:23], v[166:169], v[202:205], v[20:23]
	v_mfma_f32_16x16x32_bf16 v[16:19], v[178:181], v[202:205], v[16:19]
	v_mfma_f32_16x16x32_bf16 v[4:7], v[166:169], v[210:213], v[4:7]
	v_mfma_f32_16x16x32_bf16 v[0:3], v[178:181], v[210:213], v[0:3]
	v_mfma_f32_16x16x32_bf16 v[52:55], v[170:173], v[190:193], v[52:55]
	v_mfma_f32_16x16x32_bf16 v[48:51], v[182:185], v[190:193], v[48:51]
	v_mfma_f32_16x16x32_bf16 v[36:39], v[170:173], v[198:201], v[36:39]
	v_mfma_f32_16x16x32_bf16 v[32:35], v[182:185], v[198:201], v[32:35]
	v_mfma_f32_16x16x32_bf16 v[20:23], v[170:173], v[206:209], v[20:23]
	v_mfma_f32_16x16x32_bf16 v[16:19], v[182:185], v[206:209], v[16:19]
	v_mfma_f32_16x16x32_bf16 v[4:7], v[170:173], v[214:217], v[4:7]
	v_mfma_f32_16x16x32_bf16 v[0:3], v[182:185], v[214:217], v[0:3]
	s_setprio 0
	s_barrier
	s_andn2_b64 vcc, exec, s[52:53]
	s_mov_b64 s[54:55], -1
	s_mov_b64 s[52:53], 0
	s_mov_b64 s[56:57], 0x100
	s_cbranch_vccz .LBB0_1469
	s_and_b64 vcc, exec, s[12:13]
	s_cbranch_vccz .LBB0_1472
	s_barrier

; #define PG8_STAGE(bufoff, gbase, voff) do { _Pragma("unroll") for (int _i = 0; _i < 2; ++_i) \
;         __builtin_amdgcn_global_load_lds((const unsigned*)((const char*)(gbase) + (voff)[_i]), (LAS unsigned*)(lds + (bufoff) + ldsw + _i * 8192), 16, 0, 0); } while (0)
; #define PG8_LDA(dst, b, h) do { _Pragma("unroll") for (int m = 0; m < 4; ++m) _Pragma("unroll") for (int k = 0; k < 2; ++k) dst[m][k] = *(const LAS bf16x8*)(lds + PG8_SA(b, h) + aoff + m * 2048 + k * 1024); } while (0)
; #define PG8_LDB(dst, b, h) do { _Pragma("unroll") for (int n = 0; n < 2; ++n) _Pragma("unroll") for (int k = 0; k < 2; ++k) dst[n][k] = *(const LAS bf16x8*)(lds + PG8_SB(b, h) + boff + n * 2048 + k * 1024); } while (0)
; #define PG8_MMA(ai, bj, At, Bt) do { __builtin_amdgcn_s_setprio(1); _Pragma("unroll") for (int m = 0; m < 4; ++m) _Pragma("unroll") for (int n = 0; n < 2; ++n) _Pragma("unroll") for (int k = 0; k < 2; ++k) \
;         acc[ai][bj][m][n] = __builtin_amdgcn_mfma_f32_16x16x32_bf16(Bt[n][k], At[m][k], acc[ai][bj][m][n], 0, 0, 0); __builtin_amdgcn_s_setprio(0); } while (0)
; #define PG8_WAIT_V(n) asm volatile("s_waitcnt vmcnt(" #n ")" ::: "memory")
; #define PG8_WAIT_L(n) asm volatile("s_waitcnt lgkmcnt(" #n ")" ::: "memory")
; #define PG8_BAR __builtin_amdgcn_s_barrier()
; #define PG8_SCHED __builtin_amdgcn_sched_barrier(0)
; template <class Epi>
; __device__ __forceinline__ void gemm_phase(LAS unsigned char* lds, const Gemm g, const StaticOrder& S, const Epi& E) {
;     ...
;         for (int t = 0; t < nt; t += 2) {
;             const bool last = (t == nt - 2);
;             const char* a1 = cA + (size_t)(t + 1) * kstep;
;             const char* a2 = last ? nA : cA + (size_t)(t + 2) * kstep; const char* b2 = last ? nB : cB + (size_t)(t + 2) * kstep;
;             const char* a3 = a2 + kstep; const char* b3 = b2 + kstep;
;             PG8_LDB(B0, 0, 0); PG8_LDB(B1, 0, 1); PG8_SCHED; PG8_LDA(At, 0, 0); PG8_STAGE(PG8_SA(1, 1), a1 + hstepA, voffA);
;             PG8_WAIT_V(8); PG8_WAIT_L(0); PG8_BAR; PG8_MMA(0, 0, At, B0); PG8_MMA(0, 1, At, B1); PG8_BAR; PG8_SCHED;
;             PG8_LDA(At, 0, 1); PG8_STAGE(PG8_SB(0, 0), b2, voffB); PG8_STAGE(PG8_SB(0, 1), b2 + hstepB, voffB); PG8_STAGE(PG8_SA(0, 0), a2, voffA);
;             PG8_WAIT_V(8); PG8_WAIT_L(0); PG8_BAR; PG8_MMA(1, 0, At, B0); PG8_MMA(1, 1, At, B1); PG8_BAR; PG8_SCHED;
.LBB0_1648:
	s_add_u32 s0, s0, 0xb0080
	s_addc_u32 s1, s1, 0
	s_add_u32 s61, s20, 0x100
	s_addc_u32 s62, s21, 0
	s_mov_b32 s63, -2
	s_waitcnt lgkmcnt(0)
	ds_read_b128 v[128:131], v182
	ds_read_b128 v[132:135], v182 offset:1024
	ds_read_b128 v[136:139], v182 offset:2048
	ds_read_b128 v[140:143], v182 offset:3072
	ds_read_b128 v[160:163], v183
	ds_read_b128 v[164:167], v183 offset:1024
	ds_read_b128 v[168:171], v183 offset:2048
	ds_read_b128 v[172:175], v183 offset:3072
	s_add_u32 s20, s0, 0xfff50080
	s_addc_u32 s21, s1, -1
	s_cmp_eq_u32 s63, 40
	s_cselect_b32 s23, s7, s21
	s_cselect_b32 s22, s6, s20
	s_cselect_b32 s21, s19, s62
	s_cselect_b32 s20, s18, s61
	v_lshl_add_u64 v[178:179], s[0:1], 0, v[152:153]
	s_add_i32 m0, s33, 0xc000
	ds_read_b128 v[186:189], v184
	ds_read_b128 v[190:193], v184 offset:1024
	ds_read_b128 v[194:197], v184 offset:2048
	ds_read_b128 v[198:201], v184 offset:3072
	ds_read_b128 v[202:205], v184 offset:4096
	ds_read_b128 v[206:209], v184 offset:5120
	ds_read_b128 v[210:213], v184 offset:6144
	ds_read_b128 v[214:217], v184 offset:7168
	global_load_lds_dwordx4 v[178:179], off
	v_lshl_add_u64 v[178:179], s[0:1], 0, v[154:155]
	s_add_i32 m0, s33, 0xe000
	s_nop 0
	global_load_lds_dwordx4 v[178:179], off
	s_waitcnt vmcnt(8)
	s_waitcnt lgkmcnt(0)
	s_barrier
	s_setprio 1
	s_waitcnt lgkmcnt(0)
	v_mfma_f32_16x16x32_bf16 v[124:127], v[128:131], v[186:189], 0
	v_mfma_f32_16x16x32_bf16 v[120:123], v[136:139], v[186:189], 0
	v_mfma_f32_16x16x32_bf16 v[108:111], v[128:131], v[194:197], 0
	v_mfma_f32_16x16x32_bf16 v[104:107], v[136:139], v[194:197], 0
	v_mfma_f32_16x16x32_bf16 v[92:95], v[128:131], v[202:205], 0
	v_mfma_f32_16x16x32_bf16 v[88:91], v[136:139], v[202:205], 0
	v_mfma_f32_16x16x32_bf16 v[76:79], v[128:131], v[210:213], 0
	v_mfma_f32_16x16x32_bf16 v[72:75], v[136:139], v[210:213], 0
	v_mfma_f32_16x16x32_bf16 v[124:127], v[132:135], v[190:193], v[124:127]
	v_mfma_f32_16x16x32_bf16 v[120:123], v[140:143], v[190:193], v[120:123]
	v_mfma_f32_16x16x32_bf16 v[108:111], v[132:135], v[198:201], v[108:111]
	v_mfma_f32_16x16x32_bf16 v[104:107], v[140:143], v[198:201], v[104:107]
	v_mfma_f32_16x16x32_bf16 v[92:95], v[132:135], v[206:209], v[92:95]
	v_mfma_f32_16x16x32_bf16 v[88:91], v[140:143], v[206:209], v[88:91]
	v_mfma_f32_16x16x32_bf16 v[76:79], v[132:135], v[214:217], v[76:79]
	v_mfma_f32_16x16x32_bf16 v[72:75], v[140:143], v[214:217], v[72:75]
	v_mfma_f32_16x16x32_bf16 v[116:119], v[160:163], v[186:189], 0
	v_mfma_f32_16x16x32_bf16 v[112:115], v[168:171], v[186:189], 0
	v_mfma_f32_16x16x32_bf16 v[100:103], v[160:163], v[194:197], 0
	v_mfma_f32_16x16x32_bf16 v[96:99], v[168:171], v[194:197], 0
	v_mfma_f32_16x16x32_bf16 v[84:87], v[160:163], v[202:205], 0
	v_mfma_f32_16x16x32_bf16 v[80:83], v[168:171], v[202:205], 0
	v_mfma_f32_16x16x32_bf16 v[68:71], v[160:163], v[210:213], 0
	v_mfma_f32_16x16x32_bf16 v[64:67], v[168:171], v[210:213], 0
	v_mfma_f32_16x16x32_bf16 v[116:119], v[164:167], v[190:193], v[116:119]
	v_mfma_f32_16x16x32_bf16 v[112:115], v[172:175], v[190:193], v[112:115]
	v_mfma_f32_16x16x32_bf16 v[100:103], v[164:167], v[198:201], v[100:103]
	v_mfma_f32_16x16x32_bf16 v[96:99], v[172:175], v[198:201], v[96:99]
	v_mfma_f32_16x16x32_bf16 v[84:87], v[164:167], v[206:209], v[84:87]
	v_mfma_f32_16x16x32_bf16 v[80:83], v[172:175], v[206:209], v[80:83]
	v_mfma_f32_16x16x32_bf16 v[68:71], v[164:167], v[214:217], v[68:71]
	v_mfma_f32_16x16x32_bf16 v[64:67], v[172:175], v[214:217], v[64:67]
	s_setprio 0
	s_barrier
	s_add_i32 s64, s55, s29
	v_lshl_add_u64 v[178:179], s[20:21], 0, v[146:147]
	s_mov_b32 m0, s64
	ds_read_b128 v[186:189], v184 offset:16384
	ds_read_b128 v[190:193], v184 offset:17408
	ds_read_b128 v[194:197], v184 offset:18432
	ds_read_b128 v[198:201], v184 offset:19456
	ds_read_b128 v[202:205], v184 offset:20480
	ds_read_b128 v[206:209], v184 offset:21504
	ds_read_b128 v[210:213], v184 offset:22528
	ds_read_b128 v[214:217], v184 offset:23552
	global_load_lds_dwordx4 v[178:179], off
	s_add_i32 m0, s64, 0x2000
	s_add_u32 s64, s20, 0xb0000
	v_lshl_add_u64 v[218:219], s[20:21], 0, v[150:151]
	s_addc_u32 s65, s21, 0
	s_add_i32 s66, s56, s29
	global_load_lds_dwordx4 v[218:219], off
	v_lshl_add_u64 v[220:221], s[64:65], 0, v[146:147]
	s_mov_b32 m0, s66
	v_lshl_add_u64 v[222:223], s[22:23], 0, v[148:149]
	global_load_lds_dwordx4 v[220:221], off
	v_lshl_add_u64 v[220:221], s[64:65], 0, v[150:151]
	s_add_i32 m0, s66, 0x2000
	s_nop 0
	global_load_lds_dwordx4 v[220:221], off
	v_lshl_add_u64 v[220:221], s[22:23], 0, v[144:145]
	s_mov_b32 m0, s33
	s_nop 0
	global_load_lds_dwordx4 v[220:221], off
	s_mov_b32 m0, s34
	s_nop 0
	global_load_lds_dwordx4 v[222:223], off
	s_waitcnt vmcnt(8)
	s_waitcnt lgkmcnt(0)
	s_barrier
; #define PG8_STAGE(bufoff, gbase, voff) do { _Pragma("unroll") for (int _i = 0; _i < 2; ++_i) \
;         __builtin_amdgcn_global_load_lds((const unsigned*)((const char*)(gbase) + (voff)[_i]), (LAS unsigned*)(lds + (bufoff) + ldsw + _i * 8192), 16, 0, 0); } while (0)
; #define PG8_LDA(dst, b, h) do { _Pragma("unroll") for (int m = 0; m < 4; ++m) _Pragma("unroll") for (int k = 0; k < 2; ++k) dst[m][k] = *(const LAS bf16x8*)(lds + PG8_SA(b, h) + aoff + m * 2048 + k * 1024); } while (0)
; #define PG8_LDB(dst, b, h) do { _Pragma("unroll") for (int n = 0; n < 2; ++n) _Pragma("unroll") for (int k = 0; k < 2; ++k) dst[n][k] = *(const LAS bf16x8*)(lds + PG8_SB(b, h) + boff + n * 2048 + k * 1024); } while (0)
; #define PG8_MMA(ai, bj, At, Bt) do { __builtin_amdgcn_s_setprio(1); _Pragma("unroll") for (int m = 0; m < 4; ++m) _Pragma("unroll") for (int n = 0; n < 2; ++n) _Pragma("unroll") for (int k = 0; k < 2; ++k) \
;         acc[ai][bj][m][n] = __builtin_amdgcn_mfma_f32_16x16x32_bf16(Bt[n][k], At[m][k], acc[ai][bj][m][n], 0, 0, 0); __builtin_amdgcn_s_setprio(0); } while (0)
; #define PG8_WAIT_V(n) asm volatile("s_waitcnt vmcnt(" #n ")" ::: "memory")
; #define PG8_WAIT_L(n) asm volatile("s_waitcnt lgkmcnt(" #n ")" ::: "memory")
; #define PG8_BAR __builtin_amdgcn_s_barrier()
; #define PG8_SCHED __builtin_amdgcn_sched_barrier(0)
; template <class Epi>
; __device__ __forceinline__ void gemm_phase(LAS unsigned char* lds, const Gemm g, const StaticOrder& S, const Epi& E) {
;     ...
;             PG8_WAIT_V(8); PG8_WAIT_L(0); PG8_BAR; PG8_MMA(1, 0, At, B0); PG8_MMA(1, 1, At, B1); PG8_BAR; PG8_SCHED;
;             PG8_LDB(B0, 1, 0); PG8_LDB(B1, 1, 1); PG8_SCHED; PG8_LDA(At, 1, 0); PG8_STAGE(PG8_SA(0, 1), a2 + hstepA, voffA);
;             PG8_WAIT_V(8); PG8_WAIT_L(0); PG8_BAR; PG8_MMA(0, 0, At, B0); PG8_MMA(0, 1, At, B1); PG8_BAR; PG8_SCHED;
;             PG8_LDA(At, 1, 1); PG8_STAGE(PG8_SB(1, 0), b3, voffB); PG8_STAGE(PG8_SB(1, 1), b3 + hstepB, voffB); PG8_STAGE(PG8_SA(1, 0), a3, voffA);
;             PG8_WAIT_V(8); PG8_WAIT_L(0); PG8_BAR; PG8_MMA(1, 0, At, B0); PG8_MMA(1, 1, At, B1); PG8_BAR; PG8_SCHED;
	s_setprio 1
	s_waitcnt lgkmcnt(0)
	v_mfma_f32_16x16x32_bf16 v[60:63], v[128:131], v[186:189], 0
	v_mfma_f32_16x16x32_bf16 v[56:59], v[136:139], v[186:189], 0
	v_mfma_f32_16x16x32_bf16 v[44:47], v[128:131], v[194:197], 0
	v_mfma_f32_16x16x32_bf16 v[40:43], v[136:139], v[194:197], 0
	v_mfma_f32_16x16x32_bf16 v[28:31], v[128:131], v[202:205], 0
	v_mfma_f32_16x16x32_bf16 v[24:27], v[136:139], v[202:205], 0
	v_mfma_f32_16x16x32_bf16 v[12:15], v[128:131], v[210:213], 0
	v_mfma_f32_16x16x32_bf16 v[8:11], v[136:139], v[210:213], 0
	v_mfma_f32_16x16x32_bf16 v[60:63], v[132:135], v[190:193], v[60:63]
	v_mfma_f32_16x16x32_bf16 v[56:59], v[140:143], v[190:193], v[56:59]
	v_mfma_f32_16x16x32_bf16 v[44:47], v[132:135], v[198:201], v[44:47]
	v_mfma_f32_16x16x32_bf16 v[40:43], v[140:143], v[198:201], v[40:43]
	v_mfma_f32_16x16x32_bf16 v[28:31], v[132:135], v[206:209], v[28:31]
	v_mfma_f32_16x16x32_bf16 v[24:27], v[140:143], v[206:209], v[24:27]
	v_mfma_f32_16x16x32_bf16 v[12:15], v[132:135], v[214:217], v[12:15]
	v_mfma_f32_16x16x32_bf16 v[8:11], v[140:143], v[214:217], v[8:11]
	v_mfma_f32_16x16x32_bf16 v[52:55], v[160:163], v[186:189], 0
	v_mfma_f32_16x16x32_bf16 v[48:51], v[168:171], v[186:189], 0
	v_mfma_f32_16x16x32_bf16 v[36:39], v[160:163], v[194:197], 0
	v_mfma_f32_16x16x32_bf16 v[32:35], v[168:171], v[194:197], 0
	v_mfma_f32_16x16x32_bf16 v[20:23], v[160:163], v[202:205], 0
	v_mfma_f32_16x16x32_bf16 v[16:19], v[168:171], v[202:205], 0
	v_mfma_f32_16x16x32_bf16 v[4:7], v[160:163], v[210:213], 0
	v_mfma_f32_16x16x32_bf16 v[0:3], v[168:171], v[210:213], 0
	v_mfma_f32_16x16x32_bf16 v[52:55], v[164:167], v[190:193], v[52:55]
	v_mfma_f32_16x16x32_bf16 v[48:51], v[172:175], v[190:193], v[48:51]
	v_mfma_f32_16x16x32_bf16 v[36:39], v[164:167], v[198:201], v[36:39]
	v_mfma_f32_16x16x32_bf16 v[32:35], v[172:175], v[198:201], v[32:35]
	v_mfma_f32_16x16x32_bf16 v[20:23], v[164:167], v[206:209], v[20:23]
	v_mfma_f32_16x16x32_bf16 v[16:19], v[172:175], v[206:209], v[16:19]
	v_mfma_f32_16x16x32_bf16 v[4:7], v[164:167], v[214:217], v[4:7]
	v_mfma_f32_16x16x32_bf16 v[0:3], v[172:175], v[214:217], v[0:3]
	s_setprio 0
	s_barrier
	s_add_i32 s64, 0, 0x18000
	s_add_i32 s65, 0, 0x1c000
	v_add_u32_e32 v140, s64, v181
	v_add_u32_e32 v172, s65, v181
	ds_read_b128 v[128:131], v140
	ds_read_b128 v[132:135], v140 offset:1024
	ds_read_b128 v[136:139], v140 offset:2048
	ds_read_b128 v[140:143], v140 offset:3072
	ds_read_b128 v[160:163], v172
	ds_read_b128 v[164:167], v172 offset:1024
	ds_read_b128 v[168:171], v172 offset:2048
	ds_read_b128 v[172:175], v172 offset:3072
	s_add_u32 s22, s22, 0xb0000
	s_addc_u32 s23, s23, 0
	s_mov_b32 m0, s35
	v_lshl_add_u64 v[224:225], s[22:23], 0, v[144:145]
	ds_read_b128 v[186:189], v184 offset:32768
	ds_read_b128 v[190:193], v184 offset:33792
	ds_read_b128 v[194:197], v184 offset:34816
	ds_read_b128 v[198:201], v184 offset:35840
	ds_read_b128 v[202:205], v184 offset:36864
	ds_read_b128 v[206:209], v184 offset:37888
	ds_read_b128 v[210:213], v184 offset:38912
	ds_read_b128 v[214:217], v184 offset:39936
	global_load_lds_dwordx4 v[224:225], off
	v_lshl_add_u64 v[224:225], s[22:23], 0, v[148:149]
	s_mov_b32 m0, s36
	s_nop 0
	global_load_lds_dwordx4 v[224:225], off
	s_waitcnt vmcnt(8)
	s_waitcnt lgkmcnt(0)
	s_barrier
	s_setprio 1
	s_waitcnt lgkmcnt(0)
	v_mfma_f32_16x16x32_bf16 v[124:127], v[128:131], v[186:189], v[124:127]
	v_mfma_f32_16x16x32_bf16 v[120:123], v[136:139], v[186:189], v[120:123]
	v_mfma_f32_16x16x32_bf16 v[108:111], v[128:131], v[194:197], v[108:111]
	v_mfma_f32_16x16x32_bf16 v[104:107], v[136:139], v[194:197], v[104:107]
	v_mfma_f32_16x16x32_bf16 v[92:95], v[128:131], v[202:205], v[92:95]
	v_mfma_f32_16x16x32_bf16 v[88:91], v[136:139], v[202:205], v[88:91]
	v_mfma_f32_16x16x32_bf16 v[76:79], v[128:131], v[210:213], v[76:79]
	v_mfma_f32_16x16x32_bf16 v[72:75], v[136:139], v[210:213], v[72:75]
	v_mfma_f32_16x16x32_bf16 v[124:127], v[132:135], v[190:193], v[124:127]
	v_mfma_f32_16x16x32_bf16 v[120:123], v[140:143], v[190:193], v[120:123]
	v_mfma_f32_16x16x32_bf16 v[108:111], v[132:135], v[198:201], v[108:111]
	v_mfma_f32_16x16x32_bf16 v[104:107], v[140:143], v[198:201], v[104:107]
	v_mfma_f32_16x16x32_bf16 v[92:95], v[132:135], v[206:209], v[92:95]
	v_mfma_f32_16x16x32_bf16 v[88:91], v[140:143], v[206:209], v[88:91]
	v_mfma_f32_16x16x32_bf16 v[76:79], v[132:135], v[214:217], v[76:79]
	v_mfma_f32_16x16x32_bf16 v[72:75], v[140:143], v[214:217], v[72:75]
	v_mfma_f32_16x16x32_bf16 v[116:119], v[160:163], v[186:189], v[116:119]
	v_mfma_f32_16x16x32_bf16 v[112:115], v[168:171], v[186:189], v[112:115]
	v_mfma_f32_16x16x32_bf16 v[100:103], v[160:163], v[194:197], v[100:103]
	v_mfma_f32_16x16x32_bf16 v[96:99], v[168:171], v[194:197], v[96:99]
	v_mfma_f32_16x16x32_bf16 v[84:87], v[160:163], v[202:205], v[84:87]
	v_mfma_f32_16x16x32_bf16 v[80:83], v[168:171], v[202:205], v[80:83]
	v_mfma_f32_16x16x32_bf16 v[68:71], v[160:163], v[210:213], v[68:71]
	v_mfma_f32_16x16x32_bf16 v[64:67], v[168:171], v[210:213], v[64:67]
	v_mfma_f32_16x16x32_bf16 v[116:119], v[164:167], v[190:193], v[116:119]
	v_mfma_f32_16x16x32_bf16 v[112:115], v[172:175], v[190:193], v[112:115]
	v_mfma_f32_16x16x32_bf16 v[100:103], v[164:167], v[198:201], v[100:103]
	v_mfma_f32_16x16x32_bf16 v[96:99], v[172:175], v[198:201], v[96:99]
	v_mfma_f32_16x16x32_bf16 v[84:87], v[164:167], v[206:209], v[84:87]
	v_mfma_f32_16x16x32_bf16 v[80:83], v[172:175], v[206:209], v[80:83]
	v_mfma_f32_16x16x32_bf16 v[68:71], v[164:167], v[214:217], v[68:71]
	v_mfma_f32_16x16x32_bf16 v[64:67], v[172:175], v[214:217], v[64:67]
	s_setprio 0
	s_barrier
; #define PG8_STAGE(bufoff, gbase, voff) do { _Pragma("unroll") for (int _i = 0; _i < 2; ++_i) \
;         __builtin_amdgcn_global_load_lds((const unsigned*)((const char*)(gbase) + (voff)[_i]), (LAS unsigned*)(lds + (bufoff) + ldsw + _i * 8192), 16, 0, 0); } while (0)
; #define PG8_LDA(dst, b, h) do { _Pragma("unroll") for (int m = 0; m < 4; ++m) _Pragma("unroll") for (int k = 0; k < 2; ++k) dst[m][k] = *(const LAS bf16x8*)(lds + PG8_SA(b, h) + aoff + m * 2048 + k * 1024); } while (0)
; #define PG8_LDB(dst, b, h) do { _Pragma("unroll") for (int n = 0; n < 2; ++n) _Pragma("unroll") for (int k = 0; k < 2; ++k) dst[n][k] = *(const LAS bf16x8*)(lds + PG8_SB(b, h) + boff + n * 2048 + k * 1024); } while (0)
; #define PG8_WAIT_V(n) asm volatile("s_waitcnt vmcnt(" #n ")" ::: "memory")
; #define PG8_WAIT_L(n) asm volatile("s_waitcnt lgkmcnt(" #n ")" ::: "memory")
; template <class Epi>
; __device__ __forceinline__ void gemm_phase(LAS unsigned char* lds, const Gemm g, const StaticOrder& S, const Epi& E) {
;     ...
;         for (int t = 0; t < nt; t += 2) {
;             const bool last = (t == nt - 2);
;             const char* a1 = cA + (size_t)(t + 1) * kstep;
;             const char* a2 = last ? nA : cA + (size_t)(t + 2) * kstep; const char* b2 = last ? nB : cB + (size_t)(t + 2) * kstep;
;             const char* a3 = a2 + kstep; const char* b3 = b2 + kstep;
;             PG8_LDB(B0, 0, 0); PG8_LDB(B1, 0, 1); PG8_SCHED; PG8_LDA(At, 0, 0); PG8_STAGE(PG8_SA(1, 1), a1 + hstepA, voffA);
;             PG8_WAIT_V(8); PG8_WAIT_L(0); PG8_BAR; PG8_MMA(0, 0, At, B0); PG8_MMA(0, 1, At, B1); PG8_BAR; PG8_SCHED;
;             PG8_LDA(At, 0, 1); PG8_STAGE(PG8_SB(0, 0), b2, voffB); PG8_STAGE(PG8_SB(0, 1), b2 + hstepB, voffB); PG8_STAGE(PG8_SA(0, 0), a2, voffA);
;             PG8_WAIT_V(8); PG8_WAIT_L(0); PG8_BAR; PG8_MMA(1, 0, At, B0); PG8_MMA(1, 1, At, B1); PG8_BAR; PG8_SCHED;
;             PG8_LDB(B0, 1, 0); PG8_LDB(B1, 1, 1); PG8_SCHED; PG8_LDA(At, 1, 0); PG8_STAGE(PG8_SA(0, 1), a2 + hstepA, voffA);
;             PG8_WAIT_V(8); PG8_WAIT_L(0); PG8_BAR; PG8_MMA(0, 0, At, B0); PG8_MMA(0, 1, At, B1); PG8_BAR; PG8_SCHED;
;             PG8_LDA(At, 1, 1); PG8_STAGE(PG8_SB(1, 0), b3, voffB); PG8_STAGE(PG8_SB(1, 1), b3 + hstepB, voffB); PG8_STAGE(PG8_SA(1, 0), a3, voffA);
;             PG8_WAIT_V(8); PG8_WAIT_L(0); PG8_BAR; PG8_MMA(1, 0, At, B0); PG8_MMA(1, 1, At, B1); PG8_BAR; PG8_SCHED;
	s_add_i32 s22, s64, s29
	v_lshl_add_u64 v[178:179], v[178:179], 0, s[14:15]
	s_mov_b32 m0, s22
	ds_read_b128 v[186:189], v184 offset:49152
	ds_read_b128 v[190:193], v184 offset:50176
	ds_read_b128 v[194:197], v184 offset:51200
	ds_read_b128 v[198:201], v184 offset:52224
	ds_read_b128 v[202:205], v184 offset:53248
	ds_read_b128 v[206:209], v184 offset:54272
	ds_read_b128 v[210:213], v184 offset:55296
	ds_read_b128 v[214:217], v184 offset:56320
	global_load_lds_dwordx4 v[178:179], off
	s_add_i32 m0, s22, 0x2000
	s_add_u32 s20, s20, 0xb0080
	v_lshl_add_u64 v[178:179], v[218:219], 0, s[14:15]
	s_addc_u32 s21, s21, 0
	s_add_i32 s22, s65, s29
	global_load_lds_dwordx4 v[178:179], off
	v_lshl_add_u64 v[178:179], s[20:21], 0, v[146:147]
	s_mov_b32 m0, s22
	s_nop 0
	global_load_lds_dwordx4 v[178:179], off
	v_lshl_add_u64 v[178:179], s[20:21], 0, v[150:151]
	s_add_i32 m0, s22, 0x2000
	s_nop 0
	global_load_lds_dwordx4 v[178:179], off
	v_lshl_add_u64 v[178:179], v[220:221], 0, s[14:15]
	s_mov_b32 m0, s42
	s_nop 0
	global_load_lds_dwordx4 v[178:179], off
	v_lshl_add_u64 v[178:179], v[222:223], 0, s[14:15]
	s_mov_b32 m0, s43
	s_nop 0
	global_load_lds_dwordx4 v[178:179], off
	s_waitcnt vmcnt(8)
	s_waitcnt lgkmcnt(0)
	s_barrier
	s_setprio 1
	s_waitcnt lgkmcnt(0)
	v_mfma_f32_16x16x32_bf16 v[60:63], v[128:131], v[186:189], v[60:63]
	v_mfma_f32_16x16x32_bf16 v[56:59], v[136:139], v[186:189], v[56:59]
	v_mfma_f32_16x16x32_bf16 v[44:47], v[128:131], v[194:197], v[44:47]
	v_mfma_f32_16x16x32_bf16 v[40:43], v[136:139], v[194:197], v[40:43]
	v_mfma_f32_16x16x32_bf16 v[28:31], v[128:131], v[202:205], v[28:31]
	v_mfma_f32_16x16x32_bf16 v[24:27], v[136:139], v[202:205], v[24:27]
	v_mfma_f32_16x16x32_bf16 v[12:15], v[128:131], v[210:213], v[12:15]
	v_mfma_f32_16x16x32_bf16 v[8:11], v[136:139], v[210:213], v[8:11]
	v_mfma_f32_16x16x32_bf16 v[60:63], v[132:135], v[190:193], v[60:63]
	v_mfma_f32_16x16x32_bf16 v[56:59], v[140:143], v[190:193], v[56:59]
	v_mfma_f32_16x16x32_bf16 v[44:47], v[132:135], v[198:201], v[44:47]
	v_mfma_f32_16x16x32_bf16 v[40:43], v[140:143], v[198:201], v[40:43]
	v_mfma_f32_16x16x32_bf16 v[28:31], v[132:135], v[206:209], v[28:31]
	v_mfma_f32_16x16x32_bf16 v[24:27], v[140:143], v[206:209], v[24:27]
	v_mfma_f32_16x16x32_bf16 v[12:15], v[132:135], v[214:217], v[12:15]
	v_mfma_f32_16x16x32_bf16 v[8:11], v[140:143], v[214:217], v[8:11]
	v_mfma_f32_16x16x32_bf16 v[52:55], v[160:163], v[186:189], v[52:55]
	v_mfma_f32_16x16x32_bf16 v[48:51], v[168:171], v[186:189], v[48:51]
	v_mfma_f32_16x16x32_bf16 v[36:39], v[160:163], v[194:197], v[36:39]
	v_mfma_f32_16x16x32_bf16 v[32:35], v[168:171], v[194:197], v[32:35]
	v_mfma_f32_16x16x32_bf16 v[20:23], v[160:163], v[202:205], v[20:23]
	v_mfma_f32_16x16x32_bf16 v[16:19], v[168:171], v[202:205], v[16:19]
	v_mfma_f32_16x16x32_bf16 v[4:7], v[160:163], v[210:213], v[4:7]
	v_mfma_f32_16x16x32_bf16 v[0:3], v[168:171], v[210:213], v[0:3]
	v_mfma_f32_16x16x32_bf16 v[52:55], v[164:167], v[190:193], v[52:55]
	v_mfma_f32_16x16x32_bf16 v[48:51], v[172:175], v[190:193], v[48:51]
	v_mfma_f32_16x16x32_bf16 v[36:39], v[164:167], v[198:201], v[36:39]
	v_mfma_f32_16x16x32_bf16 v[32:35], v[172:175], v[198:201], v[32:35]
	v_mfma_f32_16x16x32_bf16 v[20:23], v[164:167], v[206:209], v[20:23]
	v_mfma_f32_16x16x32_bf16 v[16:19], v[172:175], v[206:209], v[16:19]
	v_mfma_f32_16x16x32_bf16 v[4:7], v[164:167], v[214:217], v[4:7]
	v_mfma_f32_16x16x32_bf16 v[0:3], v[172:175], v[214:217], v[0:3]
	s_setprio 0
	s_barrier
	s_add_i32 s63, s63, 2
	s_add_u32 s0, s0, 0x100
	s_addc_u32 s1, s1, 0
	s_add_u32 s61, s61, 0x100
	s_addc_u32 s62, s62, 0
	s_cmp_gt_u32 s63, 41
.LBB0_1649:
	ds_read_b128 v[128:131], v182
	ds_read_b128 v[132:135], v182 offset:1024
	ds_read_b128 v[136:139], v182 offset:2048
	ds_read_b128 v[140:143], v182 offset:3072
	ds_read_b128 v[160:163], v183
	ds_read_b128 v[164:167], v183 offset:1024
	ds_read_b128 v[168:171], v183 offset:2048
	ds_read_b128 v[172:175], v183 offset:3072
	s_add_u32 s20, s0, 0xfff50080
	s_addc_u32 s21, s1, -1
	s_cmp_eq_u32 s63, 40
	s_cselect_b32 s23, s7, s21
	s_cselect_b32 s22, s6, s20
	s_cselect_b32 s21, s19, s62
	s_cselect_b32 s20, s18, s61
	v_lshl_add_u64 v[178:179], s[0:1], 0, v[152:153]
	s_add_i32 m0, s33, 0xc000
	ds_read_b128 v[186:189], v184
	ds_read_b128 v[190:193], v184 offset:1024
	ds_read_b128 v[194:197], v184 offset:2048
	ds_read_b128 v[198:201], v184 offset:3072
	ds_read_b128 v[202:205], v184 offset:4096
	ds_read_b128 v[206:209], v184 offset:5120
	ds_read_b128 v[210:213], v184 offset:6144
	ds_read_b128 v[214:217], v184 offset:7168
	global_load_lds_dwordx4 v[178:179], off
	v_lshl_add_u64 v[178:179], s[0:1], 0, v[154:155]
	s_add_i32 m0, s33, 0xe000
	s_nop 0
	global_load_lds_dwordx4 v[178:179], off
	s_waitcnt vmcnt(8)
	s_waitcnt lgkmcnt(0)
	s_barrier
; #define PG8_STAGE(bufoff, gbase, voff) do { _Pragma("unroll") for (int _i = 0; _i < 2; ++_i) \
;         __builtin_amdgcn_global_load_lds((const unsigned*)((const char*)(gbase) + (voff)[_i]), (LAS unsigned*)(lds + (bufoff) + ldsw + _i * 8192), 16, 0, 0); } while (0)
; #define PG8_LDA(dst, b, h) do { _Pragma("unroll") for (int m = 0; m < 4; ++m) _Pragma("unroll") for (int k = 0; k < 2; ++k) dst[m][k] = *(const LAS bf16x8*)(lds + PG8_SA(b, h) + aoff + m * 2048 + k * 1024); } while (0)
; #define PG8_LDB(dst, b, h) do { _Pragma("unroll") for (int n = 0; n < 2; ++n) _Pragma("unroll") for (int k = 0; k < 2; ++k) dst[n][k] = *(const LAS bf16x8*)(lds + PG8_SB(b, h) + boff + n * 2048 + k * 1024); } while (0)
; #define PG8_MMA(ai, bj, At, Bt) do { __builtin_amdgcn_s_setprio(1); _Pragma("unroll") for (int m = 0; m < 4; ++m) _Pragma("unroll") for (int n = 0; n < 2; ++n) _Pragma("unroll") for (int k = 0; k < 2; ++k) \
;         acc[ai][bj][m][n] = __builtin_amdgcn_mfma_f32_16x16x32_bf16(Bt[n][k], At[m][k], acc[ai][bj][m][n], 0, 0, 0); __builtin_amdgcn_s_setprio(0); } while (0)
; #define PG8_WAIT_V(n) asm volatile("s_waitcnt vmcnt(" #n ")" ::: "memory")
; #define PG8_WAIT_L(n) asm volatile("s_waitcnt lgkmcnt(" #n ")" ::: "memory")
; #define PG8_BAR __builtin_amdgcn_s_barrier()
; #define PG8_SCHED __builtin_amdgcn_sched_barrier(0)
; template <class Epi>
; __device__ __forceinline__ void gemm_phase(LAS unsigned char* lds, const Gemm g, const StaticOrder& S, const Epi& E) {
;     ...
;             PG8_WAIT_V(8); PG8_WAIT_L(0); PG8_BAR; PG8_MMA(0, 0, At, B0); PG8_MMA(0, 1, At, B1); PG8_BAR; PG8_SCHED;
;             PG8_LDA(At, 0, 1); PG8_STAGE(PG8_SB(0, 0), b2, voffB); PG8_STAGE(PG8_SB(0, 1), b2 + hstepB, voffB); PG8_STAGE(PG8_SA(0, 0), a2, voffA);
;             PG8_WAIT_V(8); PG8_WAIT_L(0); PG8_BAR; PG8_MMA(1, 0, At, B0); PG8_MMA(1, 1, At, B1); PG8_BAR; PG8_SCHED;
;             PG8_LDB(B0, 1, 0); PG8_LDB(B1, 1, 1); PG8_SCHED; PG8_LDA(At, 1, 0); PG8_STAGE(PG8_SA(0, 1), a2 + hstepA, voffA);
;             PG8_WAIT_V(8); PG8_WAIT_L(0); PG8_BAR; PG8_MMA(0, 0, At, B0); PG8_MMA(0, 1, At, B1); PG8_BAR; PG8_SCHED;
	s_setprio 1
	s_waitcnt lgkmcnt(0)
	v_mfma_f32_16x16x32_bf16 v[124:127], v[128:131], v[186:189], v[124:127]
	v_mfma_f32_16x16x32_bf16 v[120:123], v[136:139], v[186:189], v[120:123]
	v_mfma_f32_16x16x32_bf16 v[108:111], v[128:131], v[194:197], v[108:111]
	v_mfma_f32_16x16x32_bf16 v[104:107], v[136:139], v[194:197], v[104:107]
	v_mfma_f32_16x16x32_bf16 v[92:95], v[128:131], v[202:205], v[92:95]
	v_mfma_f32_16x16x32_bf16 v[88:91], v[136:139], v[202:205], v[88:91]
	v_mfma_f32_16x16x32_bf16 v[76:79], v[128:131], v[210:213], v[76:79]
	v_mfma_f32_16x16x32_bf16 v[72:75], v[136:139], v[210:213], v[72:75]
	v_mfma_f32_16x16x32_bf16 v[124:127], v[132:135], v[190:193], v[124:127]
	v_mfma_f32_16x16x32_bf16 v[120:123], v[140:143], v[190:193], v[120:123]
	v_mfma_f32_16x16x32_bf16 v[108:111], v[132:135], v[198:201], v[108:111]
	v_mfma_f32_16x16x32_bf16 v[104:107], v[140:143], v[198:201], v[104:107]
	v_mfma_f32_16x16x32_bf16 v[92:95], v[132:135], v[206:209], v[92:95]
	v_mfma_f32_16x16x32_bf16 v[88:91], v[140:143], v[206:209], v[88:91]
	v_mfma_f32_16x16x32_bf16 v[76:79], v[132:135], v[214:217], v[76:79]
	v_mfma_f32_16x16x32_bf16 v[72:75], v[140:143], v[214:217], v[72:75]
	v_mfma_f32_16x16x32_bf16 v[116:119], v[160:163], v[186:189], v[116:119]
	v_mfma_f32_16x16x32_bf16 v[112:115], v[168:171], v[186:189], v[112:115]
	v_mfma_f32_16x16x32_bf16 v[100:103], v[160:163], v[194:197], v[100:103]
	v_mfma_f32_16x16x32_bf16 v[96:99], v[168:171], v[194:197], v[96:99]
	v_mfma_f32_16x16x32_bf16 v[84:87], v[160:163], v[202:205], v[84:87]
	v_mfma_f32_16x16x32_bf16 v[80:83], v[168:171], v[202:205], v[80:83]
	v_mfma_f32_16x16x32_bf16 v[68:71], v[160:163], v[210:213], v[68:71]
	v_mfma_f32_16x16x32_bf16 v[64:67], v[168:171], v[210:213], v[64:67]
	v_mfma_f32_16x16x32_bf16 v[116:119], v[164:167], v[190:193], v[116:119]
	v_mfma_f32_16x16x32_bf16 v[112:115], v[172:175], v[190:193], v[112:115]
	v_mfma_f32_16x16x32_bf16 v[100:103], v[164:167], v[198:201], v[100:103]
	v_mfma_f32_16x16x32_bf16 v[96:99], v[172:175], v[198:201], v[96:99]
	v_mfma_f32_16x16x32_bf16 v[84:87], v[164:167], v[206:209], v[84:87]
	v_mfma_f32_16x16x32_bf16 v[80:83], v[172:175], v[206:209], v[80:83]
	v_mfma_f32_16x16x32_bf16 v[68:71], v[164:167], v[214:217], v[68:71]
	v_mfma_f32_16x16x32_bf16 v[64:67], v[172:175], v[214:217], v[64:67]
	s_setprio 0
	s_barrier
	s_add_i32 s64, s55, s29
	v_lshl_add_u64 v[178:179], s[20:21], 0, v[146:147]
	s_mov_b32 m0, s64
	ds_read_b128 v[186:189], v184 offset:16384
	ds_read_b128 v[190:193], v184 offset:17408
	ds_read_b128 v[194:197], v184 offset:18432
	ds_read_b128 v[198:201], v184 offset:19456
	ds_read_b128 v[202:205], v184 offset:20480
	ds_read_b128 v[206:209], v184 offset:21504
	ds_read_b128 v[210:213], v184 offset:22528
	ds_read_b128 v[214:217], v184 offset:23552
	global_load_lds_dwordx4 v[178:179], off
	s_add_i32 m0, s64, 0x2000
	s_add_u32 s64, s20, 0xb0000
	v_lshl_add_u64 v[218:219], s[20:21], 0, v[150:151]
	s_addc_u32 s65, s21, 0
	s_add_i32 s66, s56, s29
	global_load_lds_dwordx4 v[218:219], off
	v_lshl_add_u64 v[220:221], s[64:65], 0, v[146:147]
	s_mov_b32 m0, s66
	v_lshl_add_u64 v[222:223], s[22:23], 0, v[148:149]
	global_load_lds_dwordx4 v[220:221], off
	v_lshl_add_u64 v[220:221], s[64:65], 0, v[150:151]
	s_add_i32 m0, s66, 0x2000
	s_nop 0
	global_load_lds_dwordx4 v[220:221], off
	v_lshl_add_u64 v[220:221], s[22:23], 0, v[144:145]
	s_mov_b32 m0, s33
	s_nop 0
	global_load_lds_dwordx4 v[220:221], off
	s_mov_b32 m0, s34
	s_nop 0
	global_load_lds_dwordx4 v[222:223], off
	s_waitcnt vmcnt(8)
	s_waitcnt lgkmcnt(0)
	s_barrier
	s_setprio 1
	s_waitcnt lgkmcnt(0)
	v_mfma_f32_16x16x32_bf16 v[60:63], v[128:131], v[186:189], v[60:63]
	v_mfma_f32_16x16x32_bf16 v[56:59], v[136:139], v[186:189], v[56:59]
	v_mfma_f32_16x16x32_bf16 v[44:47], v[128:131], v[194:197], v[44:47]
	v_mfma_f32_16x16x32_bf16 v[40:43], v[136:139], v[194:197], v[40:43]
	v_mfma_f32_16x16x32_bf16 v[28:31], v[128:131], v[202:205], v[28:31]
	v_mfma_f32_16x16x32_bf16 v[24:27], v[136:139], v[202:205], v[24:27]
	v_mfma_f32_16x16x32_bf16 v[12:15], v[128:131], v[210:213], v[12:15]
	v_mfma_f32_16x16x32_bf16 v[8:11], v[136:139], v[210:213], v[8:11]
	v_mfma_f32_16x16x32_bf16 v[60:63], v[132:135], v[190:193], v[60:63]
	v_mfma_f32_16x16x32_bf16 v[56:59], v[140:143], v[190:193], v[56:59]
	v_mfma_f32_16x16x32_bf16 v[44:47], v[132:135], v[198:201], v[44:47]
	v_mfma_f32_16x16x32_bf16 v[40:43], v[140:143], v[198:201], v[40:43]
	v_mfma_f32_16x16x32_bf16 v[28:31], v[132:135], v[206:209], v[28:31]
	v_mfma_f32_16x16x32_bf16 v[24:27], v[140:143], v[206:209], v[24:27]
	v_mfma_f32_16x16x32_bf16 v[12:15], v[132:135], v[214:217], v[12:15]
	v_mfma_f32_16x16x32_bf16 v[8:11], v[140:143], v[214:217], v[8:11]
	v_mfma_f32_16x16x32_bf16 v[52:55], v[160:163], v[186:189], v[52:55]
	v_mfma_f32_16x16x32_bf16 v[48:51], v[168:171], v[186:189], v[48:51]
	v_mfma_f32_16x16x32_bf16 v[36:39], v[160:163], v[194:197], v[36:39]
	v_mfma_f32_16x16x32_bf16 v[32:35], v[168:171], v[194:197], v[32:35]
	v_mfma_f32_16x16x32_bf16 v[20:23], v[160:163], v[202:205], v[20:23]
	v_mfma_f32_16x16x32_bf16 v[16:19], v[168:171], v[202:205], v[16:19]
	v_mfma_f32_16x16x32_bf16 v[4:7], v[160:163], v[210:213], v[4:7]
	v_mfma_f32_16x16x32_bf16 v[0:3], v[168:171], v[210:213], v[0:3]
	v_mfma_f32_16x16x32_bf16 v[52:55], v[164:167], v[190:193], v[52:55]
	v_mfma_f32_16x16x32_bf16 v[48:51], v[172:175], v[190:193], v[48:51]
	v_mfma_f32_16x16x32_bf16 v[36:39], v[164:167], v[198:201], v[36:39]
	v_mfma_f32_16x16x32_bf16 v[32:35], v[172:175], v[198:201], v[32:35]
	v_mfma_f32_16x16x32_bf16 v[20:23], v[164:167], v[206:209], v[20:23]
	v_mfma_f32_16x16x32_bf16 v[16:19], v[172:175], v[206:209], v[16:19]
	v_mfma_f32_16x16x32_bf16 v[4:7], v[164:167], v[214:217], v[4:7]
	v_mfma_f32_16x16x32_bf16 v[0:3], v[172:175], v[214:217], v[0:3]
	s_setprio 0
	s_barrier
; #define PG8_STAGE(bufoff, gbase, voff) do { _Pragma("unroll") for (int _i = 0; _i < 2; ++_i) \
;         __builtin_amdgcn_global_load_lds((const unsigned*)((const char*)(gbase) + (voff)[_i]), (LAS unsigned*)(lds + (bufoff) + ldsw + _i * 8192), 16, 0, 0); } while (0)
; #define PG8_LDA(dst, b, h) do { _Pragma("unroll") for (int m = 0; m < 4; ++m) _Pragma("unroll") for (int k = 0; k < 2; ++k) dst[m][k] = *(const LAS bf16x8*)(lds + PG8_SA(b, h) + aoff + m * 2048 + k * 1024); } while (0)
; #define PG8_MMA(ai, bj, At, Bt) do { __builtin_amdgcn_s_setprio(1); _Pragma("unroll") for (int m = 0; m < 4; ++m) _Pragma("unroll") for (int n = 0; n < 2; ++n) _Pragma("unroll") for (int k = 0; k < 2; ++k) \
;         acc[ai][bj][m][n] = __builtin_amdgcn_mfma_f32_16x16x32_bf16(Bt[n][k], At[m][k], acc[ai][bj][m][n], 0, 0, 0); __builtin_amdgcn_s_setprio(0); } while (0)
; #define PG8_WAIT_V(n) asm volatile("s_waitcnt vmcnt(" #n ")" ::: "memory")
; #define PG8_WAIT_L(n) asm volatile("s_waitcnt lgkmcnt(" #n ")" ::: "memory")
; #define PG8_BAR __builtin_amdgcn_s_barrier()
; #define PG8_SCHED __builtin_amdgcn_sched_barrier(0)
; template <class Epi>
; __device__ __forceinline__ void gemm_phase(LAS unsigned char* lds, const Gemm g, const StaticOrder& S, const Epi& E) {
;     ...
;             PG8_LDA(At, 1, 1); PG8_STAGE(PG8_SB(1, 0), b3, voffB); PG8_STAGE(PG8_SB(1, 1), b3 + hstepB, voffB); PG8_STAGE(PG8_SA(1, 0), a3, voffA);
;             PG8_WAIT_V(8); PG8_WAIT_L(0); PG8_BAR; PG8_MMA(1, 0, At, B0); PG8_MMA(1, 1, At, B1); PG8_BAR; PG8_SCHED;
	s_add_i32 s64, 0, 0x18000
	s_add_i32 s65, 0, 0x1c000
	v_add_u32_e32 v140, s64, v181
	v_add_u32_e32 v172, s65, v181
	ds_read_b128 v[128:131], v140
	ds_read_b128 v[132:135], v140 offset:1024
	ds_read_b128 v[136:139], v140 offset:2048
	ds_read_b128 v[140:143], v140 offset:3072
	ds_read_b128 v[160:163], v172
	ds_read_b128 v[164:167], v172 offset:1024
	ds_read_b128 v[168:171], v172 offset:2048
	ds_read_b128 v[172:175], v172 offset:3072
	s_add_u32 s22, s22, 0xb0000
	s_addc_u32 s23, s23, 0
	s_mov_b32 m0, s35
	v_lshl_add_u64 v[224:225], s[22:23], 0, v[144:145]
	ds_read_b128 v[186:189], v184 offset:32768
	ds_read_b128 v[190:193], v184 offset:33792
	ds_read_b128 v[194:197], v184 offset:34816
	ds_read_b128 v[198:201], v184 offset:35840
	ds_read_b128 v[202:205], v184 offset:36864
	ds_read_b128 v[206:209], v184 offset:37888
	ds_read_b128 v[210:213], v184 offset:38912
	ds_read_b128 v[214:217], v184 offset:39936
	global_load_lds_dwordx4 v[224:225], off
	v_lshl_add_u64 v[224:225], s[22:23], 0, v[148:149]
	s_mov_b32 m0, s36
	s_nop 0
	global_load_lds_dwordx4 v[224:225], off
	s_waitcnt vmcnt(8)
	s_waitcnt lgkmcnt(0)
	s_barrier
	s_setprio 1
	s_waitcnt lgkmcnt(0)
	v_mfma_f32_16x16x32_bf16 v[124:127], v[128:131], v[186:189], v[124:127]
	v_mfma_f32_16x16x32_bf16 v[120:123], v[136:139], v[186:189], v[120:123]
	v_mfma_f32_16x16x32_bf16 v[108:111], v[128:131], v[194:197], v[108:111]
	v_mfma_f32_16x16x32_bf16 v[104:107], v[136:139], v[194:197], v[104:107]
	v_mfma_f32_16x16x32_bf16 v[92:95], v[128:131], v[202:205], v[92:95]
	v_mfma_f32_16x16x32_bf16 v[88:91], v[136:139], v[202:205], v[88:91]
	v_mfma_f32_16x16x32_bf16 v[76:79], v[128:131], v[210:213], v[76:79]
	v_mfma_f32_16x16x32_bf16 v[72:75], v[136:139], v[210:213], v[72:75]
	v_mfma_f32_16x16x32_bf16 v[124:127], v[132:135], v[190:193], v[124:127]
	v_mfma_f32_16x16x32_bf16 v[120:123], v[140:143], v[190:193], v[120:123]
	v_mfma_f32_16x16x32_bf16 v[108:111], v[132:135], v[198:201], v[108:111]
	v_mfma_f32_16x16x32_bf16 v[104:107], v[140:143], v[198:201], v[104:107]
	v_mfma_f32_16x16x32_bf16 v[92:95], v[132:135], v[206:209], v[92:95]
	v_mfma_f32_16x16x32_bf16 v[88:91], v[140:143], v[206:209], v[88:91]
	v_mfma_f32_16x16x32_bf16 v[76:79], v[132:135], v[214:217], v[76:79]
	v_mfma_f32_16x16x32_bf16 v[72:75], v[140:143], v[214:217], v[72:75]
	v_mfma_f32_16x16x32_bf16 v[116:119], v[160:163], v[186:189], v[116:119]
	v_mfma_f32_16x16x32_bf16 v[112:115], v[168:171], v[186:189], v[112:115]
	v_mfma_f32_16x16x32_bf16 v[100:103], v[160:163], v[194:197], v[100:103]
	v_mfma_f32_16x16x32_bf16 v[96:99], v[168:171], v[194:197], v[96:99]
	v_mfma_f32_16x16x32_bf16 v[84:87], v[160:163], v[202:205], v[84:87]
	v_mfma_f32_16x16x32_bf16 v[80:83], v[168:171], v[202:205], v[80:83]
	v_mfma_f32_16x16x32_bf16 v[68:71], v[160:163], v[210:213], v[68:71]
	v_mfma_f32_16x16x32_bf16 v[64:67], v[168:171], v[210:213], v[64:67]
	v_mfma_f32_16x16x32_bf16 v[116:119], v[164:167], v[190:193], v[116:119]
	v_mfma_f32_16x16x32_bf16 v[112:115], v[172:175], v[190:193], v[112:115]
	v_mfma_f32_16x16x32_bf16 v[100:103], v[164:167], v[198:201], v[100:103]
	v_mfma_f32_16x16x32_bf16 v[96:99], v[172:175], v[198:201], v[96:99]
	v_mfma_f32_16x16x32_bf16 v[84:87], v[164:167], v[206:209], v[84:87]
	v_mfma_f32_16x16x32_bf16 v[80:83], v[172:175], v[206:209], v[80:83]
	v_mfma_f32_16x16x32_bf16 v[68:71], v[164:167], v[214:217], v[68:71]
	v_mfma_f32_16x16x32_bf16 v[64:67], v[172:175], v[214:217], v[64:67]
	s_setprio 0
	s_barrier
; #define PG8_STAGE(bufoff, gbase, voff) do { _Pragma("unroll") for (int _i = 0; _i < 2; ++_i) \
;         __builtin_amdgcn_global_load_lds((const unsigned*)((const char*)(gbase) + (voff)[_i]), (LAS unsigned*)(lds + (bufoff) + ldsw + _i * 8192), 16, 0, 0); } while (0)
; #define PG8_LDA(dst, b, h) do { _Pragma("unroll") for (int m = 0; m < 4; ++m) _Pragma("unroll") for (int k = 0; k < 2; ++k) dst[m][k] = *(const LAS bf16x8*)(lds + PG8_SA(b, h) + aoff + m * 2048 + k * 1024); } while (0)
; #define PG8_MMA(ai, bj, At, Bt) do { __builtin_amdgcn_s_setprio(1); _Pragma("unroll") for (int m = 0; m < 4; ++m) _Pragma("unroll") for (int n = 0; n < 2; ++n) _Pragma("unroll") for (int k = 0; k < 2; ++k) \
;         acc[ai][bj][m][n] = __builtin_amdgcn_mfma_f32_16x16x32_bf16(Bt[n][k], At[m][k], acc[ai][bj][m][n], 0, 0, 0); __builtin_amdgcn_s_setprio(0); } while (0)
; #define PG8_WAIT_V(n) asm volatile("s_waitcnt vmcnt(" #n ")" ::: "memory")
; #define PG8_WAIT_L(n) asm volatile("s_waitcnt lgkmcnt(" #n ")" ::: "memory")
; #define PG8_BAR __builtin_amdgcn_s_barrier()
; #define PG8_SCHED __builtin_amdgcn_sched_barrier(0)
; template <class Epi>
; __device__ __forceinline__ void gemm_phase(LAS unsigned char* lds, const Gemm g, const StaticOrder& S, const Epi& E) {
;     ...
;             PG8_LDA(At, 1, 1); PG8_STAGE(PG8_SB(1, 0), b3, voffB); PG8_STAGE(PG8_SB(1, 1), b3 + hstepB, voffB); PG8_STAGE(PG8_SA(1, 0), a3, voffA);
;             PG8_WAIT_V(8); PG8_WAIT_L(0); PG8_BAR; PG8_MMA(1, 0, At, B0); PG8_MMA(1, 1, At, B1); PG8_BAR; PG8_SCHED;
;         }
	s_add_i32 s22, s64, s29
	v_lshl_add_u64 v[178:179], v[178:179], 0, s[14:15]
	s_mov_b32 m0, s22
	ds_read_b128 v[186:189], v184 offset:49152
	ds_read_b128 v[190:193], v184 offset:50176
	ds_read_b128 v[194:197], v184 offset:51200
	ds_read_b128 v[198:201], v184 offset:52224
	ds_read_b128 v[202:205], v184 offset:53248
	ds_read_b128 v[206:209], v184 offset:54272
	ds_read_b128 v[210:213], v184 offset:55296
	ds_read_b128 v[214:217], v184 offset:56320
	global_load_lds_dwordx4 v[178:179], off
	s_add_i32 m0, s22, 0x2000
	s_add_u32 s20, s20, 0xb0080
	v_lshl_add_u64 v[178:179], v[218:219], 0, s[14:15]
	s_addc_u32 s21, s21, 0
	s_add_i32 s22, s65, s29
	global_load_lds_dwordx4 v[178:179], off
	v_lshl_add_u64 v[178:179], s[20:21], 0, v[146:147]
	s_mov_b32 m0, s22
	s_nop 0
	global_load_lds_dwordx4 v[178:179], off
	v_lshl_add_u64 v[178:179], s[20:21], 0, v[150:151]
	s_add_i32 m0, s22, 0x2000
	s_nop 0
	global_load_lds_dwordx4 v[178:179], off
	v_lshl_add_u64 v[178:179], v[220:221], 0, s[14:15]
	s_mov_b32 m0, s42
	s_nop 0
	global_load_lds_dwordx4 v[178:179], off
	v_lshl_add_u64 v[178:179], v[222:223], 0, s[14:15]
	s_mov_b32 m0, s43
	s_nop 0
	global_load_lds_dwordx4 v[178:179], off
	s_waitcnt vmcnt(8)
	s_waitcnt lgkmcnt(0)
	s_barrier
	s_setprio 1
	s_waitcnt lgkmcnt(0)
	v_mfma_f32_16x16x32_bf16 v[60:63], v[128:131], v[186:189], v[60:63]
	v_mfma_f32_16x16x32_bf16 v[56:59], v[136:139], v[186:189], v[56:59]
	v_mfma_f32_16x16x32_bf16 v[44:47], v[128:131], v[194:197], v[44:47]
	v_mfma_f32_16x16x32_bf16 v[40:43], v[136:139], v[194:197], v[40:43]
	v_mfma_f32_16x16x32_bf16 v[28:31], v[128:131], v[202:205], v[28:31]
	v_mfma_f32_16x16x32_bf16 v[24:27], v[136:139], v[202:205], v[24:27]
	v_mfma_f32_16x16x32_bf16 v[12:15], v[128:131], v[210:213], v[12:15]
	v_mfma_f32_16x16x32_bf16 v[8:11], v[136:139], v[210:213], v[8:11]
	v_mfma_f32_16x16x32_bf16 v[60:63], v[132:135], v[190:193], v[60:63]
	v_mfma_f32_16x16x32_bf16 v[56:59], v[140:143], v[190:193], v[56:59]
	v_mfma_f32_16x16x32_bf16 v[44:47], v[132:135], v[198:201], v[44:47]
	v_mfma_f32_16x16x32_bf16 v[40:43], v[140:143], v[198:201], v[40:43]
	v_mfma_f32_16x16x32_bf16 v[28:31], v[132:135], v[206:209], v[28:31]
	v_mfma_f32_16x16x32_bf16 v[24:27], v[140:143], v[206:209], v[24:27]
	v_mfma_f32_16x16x32_bf16 v[12:15], v[132:135], v[214:217], v[12:15]
	v_mfma_f32_16x16x32_bf16 v[8:11], v[140:143], v[214:217], v[8:11]
	v_mfma_f32_16x16x32_bf16 v[52:55], v[160:163], v[186:189], v[52:55]
	v_mfma_f32_16x16x32_bf16 v[48:51], v[168:171], v[186:189], v[48:51]
	v_mfma_f32_16x16x32_bf16 v[36:39], v[160:163], v[194:197], v[36:39]
	v_mfma_f32_16x16x32_bf16 v[32:35], v[168:171], v[194:197], v[32:35]
	v_mfma_f32_16x16x32_bf16 v[20:23], v[160:163], v[202:205], v[20:23]
	v_mfma_f32_16x16x32_bf16 v[16:19], v[168:171], v[202:205], v[16:19]
	v_mfma_f32_16x16x32_bf16 v[4:7], v[160:163], v[210:213], v[4:7]
	v_mfma_f32_16x16x32_bf16 v[0:3], v[168:171], v[210:213], v[0:3]
	v_mfma_f32_16x16x32_bf16 v[52:55], v[164:167], v[190:193], v[52:55]
	v_mfma_f32_16x16x32_bf16 v[48:51], v[172:175], v[190:193], v[48:51]
	v_mfma_f32_16x16x32_bf16 v[36:39], v[164:167], v[198:201], v[36:39]
	v_mfma_f32_16x16x32_bf16 v[32:35], v[172:175], v[198:201], v[32:35]
	v_mfma_f32_16x16x32_bf16 v[20:23], v[164:167], v[206:209], v[20:23]
	v_mfma_f32_16x16x32_bf16 v[16:19], v[172:175], v[206:209], v[16:19]
	v_mfma_f32_16x16x32_bf16 v[4:7], v[164:167], v[214:217], v[4:7]
	v_mfma_f32_16x16x32_bf16 v[0:3], v[172:175], v[214:217], v[0:3]
	s_setprio 0
	s_barrier
	s_add_i32 s63, s63, 2
	s_add_u32 s0, s0, 0x100
	s_addc_u32 s1, s1, 0
	s_add_u32 s61, s61, 0x100
	s_addc_u32 s62, s62, 0
	s_cmp_gt_u32 s63, 41
	s_cbranch_scc0 .LBB0_1649
	s_and_b64 vcc, exec, s[16:17]
	s_cbranch_vccz .LBB0_1652
	s_barrier

; #define PG8_STAGE(bufoff, gbase, voff) do { _Pragma("unroll") for (int _i = 0; _i < 2; ++_i) \
;         __builtin_amdgcn_global_load_lds((const unsigned*)((const char*)(gbase) + (voff)[_i]), (LAS unsigned*)(lds + (bufoff) + ldsw + _i * 8192), 16, 0, 0); } while (0)
; #define PG8_LDA(dst, b, h) do { _Pragma("unroll") for (int m = 0; m < 4; ++m) _Pragma("unroll") for (int k = 0; k < 2; ++k) dst[m][k] = *(const LAS bf16x8*)(lds + PG8_SA(b, h) + aoff + m * 2048 + k * 1024); } while (0)
; #define PG8_LDB(dst, b, h) do { _Pragma("unroll") for (int n = 0; n < 2; ++n) _Pragma("unroll") for (int k = 0; k < 2; ++k) dst[n][k] = *(const LAS bf16x8*)(lds + PG8_SB(b, h) + boff + n * 2048 + k * 1024); } while (0)
; #define PG8_MMA(ai, bj, At, Bt) do { __builtin_amdgcn_s_setprio(1); _Pragma("unroll") for (int m = 0; m < 4; ++m) _Pragma("unroll") for (int n = 0; n < 2; ++n) _Pragma("unroll") for (int k = 0; k < 2; ++k) \
;         acc[ai][bj][m][n] = __builtin_amdgcn_mfma_f32_16x16x32_bf16(Bt[n][k], At[m][k], acc[ai][bj][m][n], 0, 0, 0); __builtin_amdgcn_s_setprio(0); } while (0)
; #define PG8_BAR __builtin_amdgcn_s_barrier()
; template <class Epi>
; __device__ __forceinline__ void gemm_phase(LAS unsigned char* lds, const Gemm g, const StaticOrder& S, const Epi& E) {
;     ...
;         const bool has_next = S.next(ui + 1, nxt);
;         const char* nA = has_next ? (const char*)g.A + (size_t)nxt.pm * tstepA : cA; const char* nB = has_next ? (const char*)g.Bt + (size_t)nxt.pn * tstepB : cB;
; #pragma nounroll
;         for (int t = 0; t < nt; t += 2) {
;             const bool last = (t == nt - 2);
;             const char* a1 = cA + (size_t)(t + 1) * kstep;
;             const char* a2 = last ? nA : cA + (size_t)(t + 2) * kstep; const char* b2 = last ? nB : cB + (size_t)(t + 2) * kstep;
;             const char* a3 = a2 + kstep; const char* b3 = b2 + kstep;
;             PG8_LDB(B0, 0, 0); PG8_LDB(B1, 0, 1); PG8_SCHED; PG8_LDA(At, 0, 0); PG8_STAGE(PG8_SA(1, 1), a1 + hstepA, voffA);
;             PG8_WAIT_V(8); PG8_WAIT_L(0); PG8_BAR; PG8_MMA(0, 0, At, B0); PG8_MMA(0, 1, At, B1); PG8_BAR; PG8_SCHED;
;             PG8_LDA(At, 0, 1); PG8_STAGE(PG8_SB(0, 0), b2, voffB); PG8_STAGE(PG8_SB(0, 1), b2 + hstepB, voffB); PG8_STAGE(PG8_SA(0, 0), a2, voffA);
;             PG8_WAIT_V(8); PG8_WAIT_L(0); PG8_BAR; PG8_MMA(1, 0, At, B0); PG8_MMA(1, 1, At, B1); PG8_BAR; PG8_SCHED;
.LBB0_1745:
	s_ashr_i32 s35, s34, 31
	s_lshl_b64 s[36:37], s[34:35], 19
	s_add_u32 s36, s30, s36
	s_addc_u32 s37, s31, s37
	s_and_b64 s[38:39], s[4:5], exec
	s_cselect_b32 s7, s37, s43
	s_cselect_b32 s9, s36, s42
	s_ashr_i32 s29, s28, 31
	s_lshl_b64 s[38:39], s[28:29], 19
	s_add_u32 s38, s3, s38
	s_addc_u32 s39, s33, s39
	s_and_b64 s[44:45], s[4:5], exec
	s_cselect_b32 s29, s39, s53
	s_cselect_b32 s35, s38, s52
	s_add_u32 s42, s42, 0x40080
	s_addc_u32 s43, s43, 0
	s_add_u32 s69, s52, 0x100
	s_addc_u32 s70, s53, 0
	s_mov_b32 s71, -2
	s_waitcnt lgkmcnt(0)
	ds_read_b128 v[40:43], v208
	ds_read_b128 v[44:47], v208 offset:1024
	ds_read_b128 v[56:59], v208 offset:2048
	ds_read_b128 v[60:63], v208 offset:3072
	ds_read_b128 v[144:147], v209
	ds_read_b128 v[148:151], v209 offset:1024
	ds_read_b128 v[152:155], v209 offset:2048
	ds_read_b128 v[156:159], v209 offset:3072
	s_add_u32 s44, s42, 0xfffc0080
	s_addc_u32 s45, s43, -1
	s_cmp_eq_u32 s71, 12
	s_cselect_b32 s53, s7, s45
	s_cselect_b32 s52, s9, s44
	s_cselect_b32 s45, s29, s70
	s_cselect_b32 s44, s35, s69
	v_lshl_add_u64 v[218:219], s[42:43], 0, v[178:179]
	s_add_i32 m0, s55, 0xc000
	ds_read_b128 v[160:163], v210
	ds_read_b128 v[164:167], v210 offset:1024
	ds_read_b128 v[186:189], v210 offset:2048
	ds_read_b128 v[190:193], v210 offset:3072
	ds_read_b128 v[194:197], v210 offset:4096
	ds_read_b128 v[198:201], v210 offset:5120
	ds_read_b128 v[202:205], v210 offset:6144
	ds_read_b128 v[214:217], v210 offset:7168
	global_load_lds_dwordx4 v[218:219], off
	v_lshl_add_u64 v[218:219], s[42:43], 0, v[180:181]
	s_add_i32 m0, s55, 0xe000
	s_nop 0
	global_load_lds_dwordx4 v[218:219], off
	s_waitcnt vmcnt(8)
	s_waitcnt lgkmcnt(0)
	s_barrier
	s_setprio 1
	s_waitcnt lgkmcnt(0)
	v_mfma_f32_16x16x32_bf16 v[140:143], v[40:43], v[160:163], 0
	v_mfma_f32_16x16x32_bf16 v[136:139], v[56:59], v[160:163], 0
	v_mfma_f32_16x16x32_bf16 v[124:127], v[40:43], v[186:189], 0
	v_mfma_f32_16x16x32_bf16 v[120:123], v[56:59], v[186:189], 0
	v_mfma_f32_16x16x32_bf16 v[108:111], v[40:43], v[194:197], 0
	v_mfma_f32_16x16x32_bf16 v[104:107], v[56:59], v[194:197], 0
	v_mfma_f32_16x16x32_bf16 v[92:95], v[40:43], v[202:205], 0
	v_mfma_f32_16x16x32_bf16 v[88:91], v[56:59], v[202:205], 0
	v_mfma_f32_16x16x32_bf16 v[140:143], v[44:47], v[164:167], v[140:143]
	v_mfma_f32_16x16x32_bf16 v[136:139], v[60:63], v[164:167], v[136:139]
	v_mfma_f32_16x16x32_bf16 v[124:127], v[44:47], v[190:193], v[124:127]
	v_mfma_f32_16x16x32_bf16 v[120:123], v[60:63], v[190:193], v[120:123]
	v_mfma_f32_16x16x32_bf16 v[108:111], v[44:47], v[198:201], v[108:111]
	v_mfma_f32_16x16x32_bf16 v[104:107], v[60:63], v[198:201], v[104:107]
	v_mfma_f32_16x16x32_bf16 v[92:95], v[44:47], v[214:217], v[92:95]
	v_mfma_f32_16x16x32_bf16 v[88:91], v[60:63], v[214:217], v[88:91]
	v_mfma_f32_16x16x32_bf16 v[132:135], v[144:147], v[160:163], 0
	v_mfma_f32_16x16x32_bf16 v[128:131], v[152:155], v[160:163], 0
	v_mfma_f32_16x16x32_bf16 v[116:119], v[144:147], v[186:189], 0
	v_mfma_f32_16x16x32_bf16 v[112:115], v[152:155], v[186:189], 0
	v_mfma_f32_16x16x32_bf16 v[100:103], v[144:147], v[194:197], 0
	v_mfma_f32_16x16x32_bf16 v[96:99], v[152:155], v[194:197], 0
	v_mfma_f32_16x16x32_bf16 v[84:87], v[144:147], v[202:205], 0
	v_mfma_f32_16x16x32_bf16 v[80:83], v[152:155], v[202:205], 0
	v_mfma_f32_16x16x32_bf16 v[132:135], v[148:151], v[164:167], v[132:135]
	v_mfma_f32_16x16x32_bf16 v[128:131], v[156:159], v[164:167], v[128:131]
	v_mfma_f32_16x16x32_bf16 v[116:119], v[148:151], v[190:193], v[116:119]
	v_mfma_f32_16x16x32_bf16 v[112:115], v[156:159], v[190:193], v[112:115]
	v_mfma_f32_16x16x32_bf16 v[100:103], v[148:151], v[198:201], v[100:103]
	v_mfma_f32_16x16x32_bf16 v[96:99], v[156:159], v[198:201], v[96:99]
	v_mfma_f32_16x16x32_bf16 v[84:87], v[148:151], v[214:217], v[84:87]
	v_mfma_f32_16x16x32_bf16 v[80:83], v[156:159], v[214:217], v[80:83]
	s_setprio 0
	s_barrier
	s_add_i32 s72, s67, s54
	v_lshl_add_u64 v[218:219], s[44:45], 0, v[170:171]
	s_mov_b32 m0, s72
	ds_read_b128 v[160:163], v210 offset:16384
	ds_read_b128 v[164:167], v210 offset:17408
	ds_read_b128 v[186:189], v210 offset:18432
	ds_read_b128 v[190:193], v210 offset:19456
	ds_read_b128 v[194:197], v210 offset:20480
	ds_read_b128 v[198:201], v210 offset:21504
	ds_read_b128 v[202:205], v210 offset:22528
	ds_read_b128 v[214:217], v210 offset:23552
	global_load_lds_dwordx4 v[218:219], off
	s_add_i32 m0, s72, 0x2000
	s_add_u32 s72, s44, 0x40000
	v_lshl_add_u64 v[220:221], s[44:45], 0, v[174:175]
	s_addc_u32 s73, s45, 0
	s_add_i32 s74, s68, s54
	global_load_lds_dwordx4 v[220:221], off
	v_lshl_add_u64 v[222:223], s[72:73], 0, v[170:171]
	s_mov_b32 m0, s74
	v_lshl_add_u64 v[224:225], s[52:53], 0, v[172:173]
	global_load_lds_dwordx4 v[222:223], off
	v_lshl_add_u64 v[222:223], s[72:73], 0, v[174:175]
	s_add_i32 m0, s74, 0x2000
	s_nop 0
	global_load_lds_dwordx4 v[222:223], off
	v_lshl_add_u64 v[222:223], s[52:53], 0, v[168:169]
	s_mov_b32 m0, s55
	s_nop 0
	global_load_lds_dwordx4 v[222:223], off
	s_mov_b32 m0, s56
	s_nop 0
	global_load_lds_dwordx4 v[224:225], off
	s_waitcnt vmcnt(8)
	s_waitcnt lgkmcnt(0)
	s_barrier
; #define PG8_STAGE(bufoff, gbase, voff) do { _Pragma("unroll") for (int _i = 0; _i < 2; ++_i) \
;         __builtin_amdgcn_global_load_lds((const unsigned*)((const char*)(gbase) + (voff)[_i]), (LAS unsigned*)(lds + (bufoff) + ldsw + _i * 8192), 16, 0, 0); } while (0)
; #define PG8_LDA(dst, b, h) do { _Pragma("unroll") for (int m = 0; m < 4; ++m) _Pragma("unroll") for (int k = 0; k < 2; ++k) dst[m][k] = *(const LAS bf16x8*)(lds + PG8_SA(b, h) + aoff + m * 2048 + k * 1024); } while (0)
; #define PG8_LDB(dst, b, h) do { _Pragma("unroll") for (int n = 0; n < 2; ++n) _Pragma("unroll") for (int k = 0; k < 2; ++k) dst[n][k] = *(const LAS bf16x8*)(lds + PG8_SB(b, h) + boff + n * 2048 + k * 1024); } while (0)
; #define PG8_MMA(ai, bj, At, Bt) do { __builtin_amdgcn_s_setprio(1); _Pragma("unroll") for (int m = 0; m < 4; ++m) _Pragma("unroll") for (int n = 0; n < 2; ++n) _Pragma("unroll") for (int k = 0; k < 2; ++k) \
;         acc[ai][bj][m][n] = __builtin_amdgcn_mfma_f32_16x16x32_bf16(Bt[n][k], At[m][k], acc[ai][bj][m][n], 0, 0, 0); __builtin_amdgcn_s_setprio(0); } while (0)
; #define PG8_WAIT_V(n) asm volatile("s_waitcnt vmcnt(" #n ")" ::: "memory")
; #define PG8_WAIT_L(n) asm volatile("s_waitcnt lgkmcnt(" #n ")" ::: "memory")
; #define PG8_BAR __builtin_amdgcn_s_barrier()
; #define PG8_SCHED __builtin_amdgcn_sched_barrier(0)
; template <class Epi>
; __device__ __forceinline__ void gemm_phase(LAS unsigned char* lds, const Gemm g, const StaticOrder& S, const Epi& E) {
;     ...
;             PG8_WAIT_V(8); PG8_WAIT_L(0); PG8_BAR; PG8_MMA(1, 0, At, B0); PG8_MMA(1, 1, At, B1); PG8_BAR; PG8_SCHED;
;             PG8_LDB(B0, 1, 0); PG8_LDB(B1, 1, 1); PG8_SCHED; PG8_LDA(At, 1, 0); PG8_STAGE(PG8_SA(0, 1), a2 + hstepA, voffA);
;             PG8_WAIT_V(8); PG8_WAIT_L(0); PG8_BAR; PG8_MMA(0, 0, At, B0); PG8_MMA(0, 1, At, B1); PG8_BAR; PG8_SCHED;
;             PG8_LDA(At, 1, 1); PG8_STAGE(PG8_SB(1, 0), b3, voffB); PG8_STAGE(PG8_SB(1, 1), b3 + hstepB, voffB); PG8_STAGE(PG8_SA(1, 0), a3, voffA);
;             PG8_WAIT_V(8); PG8_WAIT_L(0); PG8_BAR; PG8_MMA(1, 0, At, B0); PG8_MMA(1, 1, At, B1); PG8_BAR; PG8_SCHED;
	s_setprio 1
	s_waitcnt lgkmcnt(0)
	v_mfma_f32_16x16x32_bf16 v[76:79], v[40:43], v[160:163], 0
	v_mfma_f32_16x16x32_bf16 v[72:75], v[56:59], v[160:163], 0
	v_mfma_f32_16x16x32_bf16 v[52:55], v[40:43], v[186:189], 0
	v_mfma_f32_16x16x32_bf16 v[48:51], v[56:59], v[186:189], 0
	v_mfma_f32_16x16x32_bf16 v[28:31], v[40:43], v[194:197], 0
	v_mfma_f32_16x16x32_bf16 v[24:27], v[56:59], v[194:197], 0
	v_mfma_f32_16x16x32_bf16 v[12:15], v[40:43], v[202:205], 0
	v_mfma_f32_16x16x32_bf16 v[8:11], v[56:59], v[202:205], 0
	v_mfma_f32_16x16x32_bf16 v[76:79], v[44:47], v[164:167], v[76:79]
	v_mfma_f32_16x16x32_bf16 v[72:75], v[60:63], v[164:167], v[72:75]
	v_mfma_f32_16x16x32_bf16 v[52:55], v[44:47], v[190:193], v[52:55]
	v_mfma_f32_16x16x32_bf16 v[48:51], v[60:63], v[190:193], v[48:51]
	v_mfma_f32_16x16x32_bf16 v[28:31], v[44:47], v[198:201], v[28:31]
	v_mfma_f32_16x16x32_bf16 v[24:27], v[60:63], v[198:201], v[24:27]
	v_mfma_f32_16x16x32_bf16 v[12:15], v[44:47], v[214:217], v[12:15]
	v_mfma_f32_16x16x32_bf16 v[8:11], v[60:63], v[214:217], v[8:11]
	v_mfma_f32_16x16x32_bf16 v[36:39], v[144:147], v[186:189], 0
	v_mfma_f32_16x16x32_bf16 v[32:35], v[152:155], v[186:189], 0
	v_mfma_f32_16x16x32_bf16 v[20:23], v[144:147], v[194:197], 0
	v_mfma_f32_16x16x32_bf16 v[16:19], v[152:155], v[194:197], 0
	v_mfma_f32_16x16x32_bf16 v[4:7], v[144:147], v[202:205], 0
	v_mfma_f32_16x16x32_bf16 v[0:3], v[152:155], v[202:205], 0
	v_mfma_f32_16x16x32_bf16 v[40:43], v[144:147], v[160:163], 0
	v_mfma_f32_16x16x32_bf16 v[44:47], v[152:155], v[160:163], 0
	v_mfma_f32_16x16x32_bf16 v[36:39], v[148:151], v[190:193], v[36:39]
	v_mfma_f32_16x16x32_bf16 v[32:35], v[156:159], v[190:193], v[32:35]
	v_mfma_f32_16x16x32_bf16 v[20:23], v[148:151], v[198:201], v[20:23]
	v_mfma_f32_16x16x32_bf16 v[16:19], v[156:159], v[198:201], v[16:19]
	v_mfma_f32_16x16x32_bf16 v[4:7], v[148:151], v[214:217], v[4:7]
	v_mfma_f32_16x16x32_bf16 v[0:3], v[156:159], v[214:217], v[0:3]
	v_mfma_f32_16x16x32_bf16 v[40:43], v[148:151], v[164:167], v[40:43]
	v_mfma_f32_16x16x32_bf16 v[44:47], v[156:159], v[164:167], v[44:47]
	s_setprio 0
	s_barrier
	s_add_i32 s72, 0, 0x18000
	s_add_i32 s73, 0, 0x1c000
	v_add_u32_e32 v68, s72, v207
	v_add_u32_e32 v156, s73, v207
	ds_read_b128 v[56:59], v68
	ds_read_b128 v[60:63], v68 offset:1024
	ds_read_b128 v[64:67], v68 offset:2048
	ds_read_b128 v[68:71], v68 offset:3072
	ds_read_b128 v[144:147], v156
	ds_read_b128 v[148:151], v156 offset:1024
	ds_read_b128 v[152:155], v156 offset:2048
	ds_read_b128 v[156:159], v156 offset:3072
	s_add_u32 s52, s52, 0x40000
	s_addc_u32 s53, s53, 0
	s_mov_b32 m0, s57
	v_lshl_add_u64 v[226:227], s[52:53], 0, v[168:169]
	ds_read_b128 v[160:163], v210 offset:32768
	ds_read_b128 v[164:167], v210 offset:33792
	ds_read_b128 v[186:189], v210 offset:34816
	ds_read_b128 v[190:193], v210 offset:35840
	ds_read_b128 v[194:197], v210 offset:36864
	ds_read_b128 v[198:201], v210 offset:37888
	ds_read_b128 v[202:205], v210 offset:38912
	ds_read_b128 v[214:217], v210 offset:39936
	global_load_lds_dwordx4 v[226:227], off
	v_lshl_add_u64 v[226:227], s[52:53], 0, v[172:173]
	s_mov_b32 m0, s58
	s_nop 0
	global_load_lds_dwordx4 v[226:227], off
	s_waitcnt vmcnt(8)
	s_waitcnt lgkmcnt(0)
	s_barrier
	s_setprio 1
	s_waitcnt lgkmcnt(0)
	v_mfma_f32_16x16x32_bf16 v[140:143], v[56:59], v[160:163], v[140:143]
	v_mfma_f32_16x16x32_bf16 v[136:139], v[64:67], v[160:163], v[136:139]
	v_mfma_f32_16x16x32_bf16 v[124:127], v[56:59], v[186:189], v[124:127]
	v_mfma_f32_16x16x32_bf16 v[120:123], v[64:67], v[186:189], v[120:123]
	v_mfma_f32_16x16x32_bf16 v[108:111], v[56:59], v[194:197], v[108:111]
	v_mfma_f32_16x16x32_bf16 v[104:107], v[64:67], v[194:197], v[104:107]
	v_mfma_f32_16x16x32_bf16 v[92:95], v[56:59], v[202:205], v[92:95]
	v_mfma_f32_16x16x32_bf16 v[88:91], v[64:67], v[202:205], v[88:91]
	v_mfma_f32_16x16x32_bf16 v[140:143], v[60:63], v[164:167], v[140:143]
	v_mfma_f32_16x16x32_bf16 v[136:139], v[68:71], v[164:167], v[136:139]
	v_mfma_f32_16x16x32_bf16 v[124:127], v[60:63], v[190:193], v[124:127]
	v_mfma_f32_16x16x32_bf16 v[120:123], v[68:71], v[190:193], v[120:123]
	v_mfma_f32_16x16x32_bf16 v[108:111], v[60:63], v[198:201], v[108:111]
	v_mfma_f32_16x16x32_bf16 v[104:107], v[68:71], v[198:201], v[104:107]
	v_mfma_f32_16x16x32_bf16 v[92:95], v[60:63], v[214:217], v[92:95]
	v_mfma_f32_16x16x32_bf16 v[88:91], v[68:71], v[214:217], v[88:91]
	v_mfma_f32_16x16x32_bf16 v[132:135], v[144:147], v[160:163], v[132:135]
	v_mfma_f32_16x16x32_bf16 v[128:131], v[152:155], v[160:163], v[128:131]
	v_mfma_f32_16x16x32_bf16 v[116:119], v[144:147], v[186:189], v[116:119]
	v_mfma_f32_16x16x32_bf16 v[112:115], v[152:155], v[186:189], v[112:115]
	v_mfma_f32_16x16x32_bf16 v[100:103], v[144:147], v[194:197], v[100:103]
	v_mfma_f32_16x16x32_bf16 v[96:99], v[152:155], v[194:197], v[96:99]
	v_mfma_f32_16x16x32_bf16 v[84:87], v[144:147], v[202:205], v[84:87]
	v_mfma_f32_16x16x32_bf16 v[80:83], v[152:155], v[202:205], v[80:83]
	v_mfma_f32_16x16x32_bf16 v[132:135], v[148:151], v[164:167], v[132:135]
	v_mfma_f32_16x16x32_bf16 v[128:131], v[156:159], v[164:167], v[128:131]
	v_mfma_f32_16x16x32_bf16 v[116:119], v[148:151], v[190:193], v[116:119]
	v_mfma_f32_16x16x32_bf16 v[112:115], v[156:159], v[190:193], v[112:115]
	v_mfma_f32_16x16x32_bf16 v[100:103], v[148:151], v[198:201], v[100:103]
	v_mfma_f32_16x16x32_bf16 v[96:99], v[156:159], v[198:201], v[96:99]
	v_mfma_f32_16x16x32_bf16 v[84:87], v[148:151], v[214:217], v[84:87]
	v_mfma_f32_16x16x32_bf16 v[80:83], v[156:159], v[214:217], v[80:83]
	s_setprio 0
	s_barrier
; #define PG8_STAGE(bufoff, gbase, voff) do { _Pragma("unroll") for (int _i = 0; _i < 2; ++_i) \
;         __builtin_amdgcn_global_load_lds((const unsigned*)((const char*)(gbase) + (voff)[_i]), (LAS unsigned*)(lds + (bufoff) + ldsw + _i * 8192), 16, 0, 0); } while (0)
; #define PG8_LDA(dst, b, h) do { _Pragma("unroll") for (int m = 0; m < 4; ++m) _Pragma("unroll") for (int k = 0; k < 2; ++k) dst[m][k] = *(const LAS bf16x8*)(lds + PG8_SA(b, h) + aoff + m * 2048 + k * 1024); } while (0)
; #define PG8_LDB(dst, b, h) do { _Pragma("unroll") for (int n = 0; n < 2; ++n) _Pragma("unroll") for (int k = 0; k < 2; ++k) dst[n][k] = *(const LAS bf16x8*)(lds + PG8_SB(b, h) + boff + n * 2048 + k * 1024); } while (0)
; #define PG8_WAIT_V(n) asm volatile("s_waitcnt vmcnt(" #n ")" ::: "memory")
; #define PG8_WAIT_L(n) asm volatile("s_waitcnt lgkmcnt(" #n ")" ::: "memory")
; template <class Epi>
; __device__ __forceinline__ void gemm_phase(LAS unsigned char* lds, const Gemm g, const StaticOrder& S, const Epi& E) {
;     ...
;         for (int t = 0; t < nt; t += 2) {
;             const bool last = (t == nt - 2);
;             const char* a1 = cA + (size_t)(t + 1) * kstep;
;             const char* a2 = last ? nA : cA + (size_t)(t + 2) * kstep; const char* b2 = last ? nB : cB + (size_t)(t + 2) * kstep;
;             const char* a3 = a2 + kstep; const char* b3 = b2 + kstep;
;             PG8_LDB(B0, 0, 0); PG8_LDB(B1, 0, 1); PG8_SCHED; PG8_LDA(At, 0, 0); PG8_STAGE(PG8_SA(1, 1), a1 + hstepA, voffA);
;             PG8_WAIT_V(8); PG8_WAIT_L(0); PG8_BAR; PG8_MMA(0, 0, At, B0); PG8_MMA(0, 1, At, B1); PG8_BAR; PG8_SCHED;
;             PG8_LDA(At, 0, 1); PG8_STAGE(PG8_SB(0, 0), b2, voffB); PG8_STAGE(PG8_SB(0, 1), b2 + hstepB, voffB); PG8_STAGE(PG8_SA(0, 0), a2, voffA);
;             PG8_WAIT_V(8); PG8_WAIT_L(0); PG8_BAR; PG8_MMA(1, 0, At, B0); PG8_MMA(1, 1, At, B1); PG8_BAR; PG8_SCHED;
;             PG8_LDB(B0, 1, 0); PG8_LDB(B1, 1, 1); PG8_SCHED; PG8_LDA(At, 1, 0); PG8_STAGE(PG8_SA(0, 1), a2 + hstepA, voffA);
;             PG8_WAIT_V(8); PG8_WAIT_L(0); PG8_BAR; PG8_MMA(0, 0, At, B0); PG8_MMA(0, 1, At, B1); PG8_BAR; PG8_SCHED;
;             PG8_LDA(At, 1, 1); PG8_STAGE(PG8_SB(1, 0), b3, voffB); PG8_STAGE(PG8_SB(1, 1), b3 + hstepB, voffB); PG8_STAGE(PG8_SA(1, 0), a3, voffA);
;             PG8_WAIT_V(8); PG8_WAIT_L(0); PG8_BAR; PG8_MMA(1, 0, At, B0); PG8_MMA(1, 1, At, B1); PG8_BAR; PG8_SCHED;
	s_add_i32 s52, s72, s54
	v_lshl_add_u64 v[218:219], v[218:219], 0, s[20:21]
	s_mov_b32 m0, s52
	ds_read_b128 v[160:163], v210 offset:49152
	ds_read_b128 v[164:167], v210 offset:50176
	ds_read_b128 v[186:189], v210 offset:51200
	ds_read_b128 v[190:193], v210 offset:52224
	ds_read_b128 v[194:197], v210 offset:53248
	ds_read_b128 v[198:201], v210 offset:54272
	ds_read_b128 v[202:205], v210 offset:55296
	ds_read_b128 v[214:217], v210 offset:56320
	global_load_lds_dwordx4 v[218:219], off
	s_add_i32 m0, s52, 0x2000
	s_add_u32 s44, s44, 0x40080
	v_lshl_add_u64 v[218:219], v[220:221], 0, s[20:21]
	s_addc_u32 s45, s45, 0
	s_add_i32 s52, s73, s54
	global_load_lds_dwordx4 v[218:219], off
	v_lshl_add_u64 v[218:219], s[44:45], 0, v[170:171]
	s_mov_b32 m0, s52
	s_nop 0
	global_load_lds_dwordx4 v[218:219], off
	v_lshl_add_u64 v[218:219], s[44:45], 0, v[174:175]
	s_add_i32 m0, s52, 0x2000
	s_nop 0
	global_load_lds_dwordx4 v[218:219], off
	v_lshl_add_u64 v[218:219], v[222:223], 0, s[20:21]
	s_mov_b32 m0, s62
	s_nop 0
	global_load_lds_dwordx4 v[218:219], off
	v_lshl_add_u64 v[218:219], v[224:225], 0, s[20:21]
	s_mov_b32 m0, s63
	s_nop 0
	global_load_lds_dwordx4 v[218:219], off
	s_waitcnt vmcnt(8)
	s_waitcnt lgkmcnt(0)
	s_barrier
	s_setprio 1
	s_waitcnt lgkmcnt(0)
	v_mfma_f32_16x16x32_bf16 v[76:79], v[56:59], v[160:163], v[76:79]
	v_mfma_f32_16x16x32_bf16 v[72:75], v[64:67], v[160:163], v[72:75]
	v_mfma_f32_16x16x32_bf16 v[52:55], v[56:59], v[186:189], v[52:55]
	v_mfma_f32_16x16x32_bf16 v[48:51], v[64:67], v[186:189], v[48:51]
	v_mfma_f32_16x16x32_bf16 v[28:31], v[56:59], v[194:197], v[28:31]
	v_mfma_f32_16x16x32_bf16 v[24:27], v[64:67], v[194:197], v[24:27]
	v_mfma_f32_16x16x32_bf16 v[12:15], v[56:59], v[202:205], v[12:15]
	v_mfma_f32_16x16x32_bf16 v[8:11], v[64:67], v[202:205], v[8:11]
	v_mfma_f32_16x16x32_bf16 v[76:79], v[60:63], v[164:167], v[76:79]
	v_mfma_f32_16x16x32_bf16 v[72:75], v[68:71], v[164:167], v[72:75]
	v_mfma_f32_16x16x32_bf16 v[52:55], v[60:63], v[190:193], v[52:55]
	v_mfma_f32_16x16x32_bf16 v[48:51], v[68:71], v[190:193], v[48:51]
	v_mfma_f32_16x16x32_bf16 v[28:31], v[60:63], v[198:201], v[28:31]
	v_mfma_f32_16x16x32_bf16 v[24:27], v[68:71], v[198:201], v[24:27]
	v_mfma_f32_16x16x32_bf16 v[12:15], v[60:63], v[214:217], v[12:15]
	v_mfma_f32_16x16x32_bf16 v[8:11], v[68:71], v[214:217], v[8:11]
	v_mfma_f32_16x16x32_bf16 v[40:43], v[144:147], v[160:163], v[40:43]
	v_mfma_f32_16x16x32_bf16 v[68:71], v[148:151], v[164:167], v[40:43]
	v_mfma_f32_16x16x32_bf16 v[40:43], v[152:155], v[160:163], v[44:47]
	v_mfma_f32_16x16x32_bf16 v[36:39], v[144:147], v[186:189], v[36:39]
	v_mfma_f32_16x16x32_bf16 v[32:35], v[152:155], v[186:189], v[32:35]
	v_mfma_f32_16x16x32_bf16 v[20:23], v[144:147], v[194:197], v[20:23]
	v_mfma_f32_16x16x32_bf16 v[16:19], v[152:155], v[194:197], v[16:19]
	v_mfma_f32_16x16x32_bf16 v[4:7], v[144:147], v[202:205], v[4:7]
	v_mfma_f32_16x16x32_bf16 v[0:3], v[152:155], v[202:205], v[0:3]
	v_mfma_f32_16x16x32_bf16 v[64:67], v[156:159], v[164:167], v[40:43]
	v_mfma_f32_16x16x32_bf16 v[36:39], v[148:151], v[190:193], v[36:39]
	v_mfma_f32_16x16x32_bf16 v[32:35], v[156:159], v[190:193], v[32:35]
	v_mfma_f32_16x16x32_bf16 v[20:23], v[148:151], v[198:201], v[20:23]
	v_mfma_f32_16x16x32_bf16 v[16:19], v[156:159], v[198:201], v[16:19]
	v_mfma_f32_16x16x32_bf16 v[4:7], v[148:151], v[214:217], v[4:7]
	v_mfma_f32_16x16x32_bf16 v[0:3], v[156:159], v[214:217], v[0:3]
	s_setprio 0
	s_barrier
	s_add_i32 s71, s71, 2
	s_add_u32 s42, s42, 0x100
	s_addc_u32 s43, s43, 0
	s_add_u32 s69, s69, 0x100
	s_addc_u32 s70, s70, 0
	s_cmp_gt_u32 s71, 13
.LBB0_1746:
	ds_read_b128 v[40:43], v208
	ds_read_b128 v[44:47], v208 offset:1024
	ds_read_b128 v[56:59], v208 offset:2048
	ds_read_b128 v[60:63], v208 offset:3072
	ds_read_b128 v[144:147], v209
	ds_read_b128 v[148:151], v209 offset:1024
	ds_read_b128 v[152:155], v209 offset:2048
	ds_read_b128 v[156:159], v209 offset:3072
	s_add_u32 s44, s42, 0xfffc0080
	s_addc_u32 s45, s43, -1
	s_cmp_eq_u32 s71, 12
	s_cselect_b32 s53, s7, s45
	s_cselect_b32 s52, s9, s44
	s_cselect_b32 s45, s29, s70
	s_cselect_b32 s44, s35, s69
	v_lshl_add_u64 v[218:219], s[42:43], 0, v[178:179]
	s_add_i32 m0, s55, 0xc000
	ds_read_b128 v[160:163], v210
	ds_read_b128 v[164:167], v210 offset:1024
	ds_read_b128 v[186:189], v210 offset:2048
	ds_read_b128 v[190:193], v210 offset:3072
	ds_read_b128 v[194:197], v210 offset:4096
	ds_read_b128 v[198:201], v210 offset:5120
	ds_read_b128 v[202:205], v210 offset:6144
	ds_read_b128 v[214:217], v210 offset:7168
	global_load_lds_dwordx4 v[218:219], off
	v_lshl_add_u64 v[218:219], s[42:43], 0, v[180:181]
	s_add_i32 m0, s55, 0xe000
	s_nop 0
	global_load_lds_dwordx4 v[218:219], off
	s_waitcnt vmcnt(8)
	s_waitcnt lgkmcnt(0)
	s_barrier
; #define PG8_STAGE(bufoff, gbase, voff) do { _Pragma("unroll") for (int _i = 0; _i < 2; ++_i) \
;         __builtin_amdgcn_global_load_lds((const unsigned*)((const char*)(gbase) + (voff)[_i]), (LAS unsigned*)(lds + (bufoff) + ldsw + _i * 8192), 16, 0, 0); } while (0)
; #define PG8_LDA(dst, b, h) do { _Pragma("unroll") for (int m = 0; m < 4; ++m) _Pragma("unroll") for (int k = 0; k < 2; ++k) dst[m][k] = *(const LAS bf16x8*)(lds + PG8_SA(b, h) + aoff + m * 2048 + k * 1024); } while (0)
; #define PG8_LDB(dst, b, h) do { _Pragma("unroll") for (int n = 0; n < 2; ++n) _Pragma("unroll") for (int k = 0; k < 2; ++k) dst[n][k] = *(const LAS bf16x8*)(lds + PG8_SB(b, h) + boff + n * 2048 + k * 1024); } while (0)
; #define PG8_MMA(ai, bj, At, Bt) do { __builtin_amdgcn_s_setprio(1); _Pragma("unroll") for (int m = 0; m < 4; ++m) _Pragma("unroll") for (int n = 0; n < 2; ++n) _Pragma("unroll") for (int k = 0; k < 2; ++k) \
;         acc[ai][bj][m][n] = __builtin_amdgcn_mfma_f32_16x16x32_bf16(Bt[n][k], At[m][k], acc[ai][bj][m][n], 0, 0, 0); __builtin_amdgcn_s_setprio(0); } while (0)
; #define PG8_WAIT_V(n) asm volatile("s_waitcnt vmcnt(" #n ")" ::: "memory")
; #define PG8_WAIT_L(n) asm volatile("s_waitcnt lgkmcnt(" #n ")" ::: "memory")
; #define PG8_BAR __builtin_amdgcn_s_barrier()
; #define PG8_SCHED __builtin_amdgcn_sched_barrier(0)
; template <class Epi>
; __device__ __forceinline__ void gemm_phase(LAS unsigned char* lds, const Gemm g, const StaticOrder& S, const Epi& E) {
;     ...
;             PG8_WAIT_V(8); PG8_WAIT_L(0); PG8_BAR; PG8_MMA(0, 0, At, B0); PG8_MMA(0, 1, At, B1); PG8_BAR; PG8_SCHED;
;             PG8_LDA(At, 0, 1); PG8_STAGE(PG8_SB(0, 0), b2, voffB); PG8_STAGE(PG8_SB(0, 1), b2 + hstepB, voffB); PG8_STAGE(PG8_SA(0, 0), a2, voffA);
;             PG8_WAIT_V(8); PG8_WAIT_L(0); PG8_BAR; PG8_MMA(1, 0, At, B0); PG8_MMA(1, 1, At, B1); PG8_BAR; PG8_SCHED;
;             PG8_LDB(B0, 1, 0); PG8_LDB(B1, 1, 1); PG8_SCHED; PG8_LDA(At, 1, 0); PG8_STAGE(PG8_SA(0, 1), a2 + hstepA, voffA);
;             PG8_WAIT_V(8); PG8_WAIT_L(0); PG8_BAR; PG8_MMA(0, 0, At, B0); PG8_MMA(0, 1, At, B1); PG8_BAR; PG8_SCHED;
	s_setprio 1
	s_waitcnt lgkmcnt(0)
	v_mfma_f32_16x16x32_bf16 v[140:143], v[40:43], v[160:163], v[140:143]
	v_mfma_f32_16x16x32_bf16 v[136:139], v[56:59], v[160:163], v[136:139]
	v_mfma_f32_16x16x32_bf16 v[124:127], v[40:43], v[186:189], v[124:127]
	v_mfma_f32_16x16x32_bf16 v[120:123], v[56:59], v[186:189], v[120:123]
	v_mfma_f32_16x16x32_bf16 v[108:111], v[40:43], v[194:197], v[108:111]
	v_mfma_f32_16x16x32_bf16 v[104:107], v[56:59], v[194:197], v[104:107]
	v_mfma_f32_16x16x32_bf16 v[92:95], v[40:43], v[202:205], v[92:95]
	v_mfma_f32_16x16x32_bf16 v[88:91], v[56:59], v[202:205], v[88:91]
	v_mfma_f32_16x16x32_bf16 v[140:143], v[44:47], v[164:167], v[140:143]
	v_mfma_f32_16x16x32_bf16 v[136:139], v[60:63], v[164:167], v[136:139]
	v_mfma_f32_16x16x32_bf16 v[124:127], v[44:47], v[190:193], v[124:127]
	v_mfma_f32_16x16x32_bf16 v[120:123], v[60:63], v[190:193], v[120:123]
	v_mfma_f32_16x16x32_bf16 v[108:111], v[44:47], v[198:201], v[108:111]
	v_mfma_f32_16x16x32_bf16 v[104:107], v[60:63], v[198:201], v[104:107]
	v_mfma_f32_16x16x32_bf16 v[92:95], v[44:47], v[214:217], v[92:95]
	v_mfma_f32_16x16x32_bf16 v[88:91], v[60:63], v[214:217], v[88:91]
	v_mfma_f32_16x16x32_bf16 v[132:135], v[144:147], v[160:163], v[132:135]
	v_mfma_f32_16x16x32_bf16 v[128:131], v[152:155], v[160:163], v[128:131]
	v_mfma_f32_16x16x32_bf16 v[116:119], v[144:147], v[186:189], v[116:119]
	v_mfma_f32_16x16x32_bf16 v[112:115], v[152:155], v[186:189], v[112:115]
	v_mfma_f32_16x16x32_bf16 v[100:103], v[144:147], v[194:197], v[100:103]
	v_mfma_f32_16x16x32_bf16 v[96:99], v[152:155], v[194:197], v[96:99]
	v_mfma_f32_16x16x32_bf16 v[84:87], v[144:147], v[202:205], v[84:87]
	v_mfma_f32_16x16x32_bf16 v[80:83], v[152:155], v[202:205], v[80:83]
	v_mfma_f32_16x16x32_bf16 v[132:135], v[148:151], v[164:167], v[132:135]
	v_mfma_f32_16x16x32_bf16 v[128:131], v[156:159], v[164:167], v[128:131]
	v_mfma_f32_16x16x32_bf16 v[116:119], v[148:151], v[190:193], v[116:119]
	v_mfma_f32_16x16x32_bf16 v[112:115], v[156:159], v[190:193], v[112:115]
	v_mfma_f32_16x16x32_bf16 v[100:103], v[148:151], v[198:201], v[100:103]
	v_mfma_f32_16x16x32_bf16 v[96:99], v[156:159], v[198:201], v[96:99]
	v_mfma_f32_16x16x32_bf16 v[84:87], v[148:151], v[214:217], v[84:87]
	v_mfma_f32_16x16x32_bf16 v[80:83], v[156:159], v[214:217], v[80:83]
	s_setprio 0
	s_barrier
	s_add_i32 s72, s67, s54
	v_lshl_add_u64 v[218:219], s[44:45], 0, v[170:171]
	s_mov_b32 m0, s72
	ds_read_b128 v[160:163], v210 offset:16384
	ds_read_b128 v[164:167], v210 offset:17408
	ds_read_b128 v[186:189], v210 offset:18432
	ds_read_b128 v[190:193], v210 offset:19456
	ds_read_b128 v[194:197], v210 offset:20480
	ds_read_b128 v[198:201], v210 offset:21504
	ds_read_b128 v[202:205], v210 offset:22528
	ds_read_b128 v[214:217], v210 offset:23552
	global_load_lds_dwordx4 v[218:219], off
	s_add_i32 m0, s72, 0x2000
	s_add_u32 s72, s44, 0x40000
	v_lshl_add_u64 v[220:221], s[44:45], 0, v[174:175]
	s_addc_u32 s73, s45, 0
	s_add_i32 s74, s68, s54
	global_load_lds_dwordx4 v[220:221], off
	v_lshl_add_u64 v[222:223], s[72:73], 0, v[170:171]
	s_mov_b32 m0, s74
	v_lshl_add_u64 v[224:225], s[52:53], 0, v[172:173]
	global_load_lds_dwordx4 v[222:223], off
	v_lshl_add_u64 v[222:223], s[72:73], 0, v[174:175]
	s_add_i32 m0, s74, 0x2000
	s_nop 0
	global_load_lds_dwordx4 v[222:223], off
	v_lshl_add_u64 v[222:223], s[52:53], 0, v[168:169]
	s_mov_b32 m0, s55
	s_nop 0
	global_load_lds_dwordx4 v[222:223], off
	s_mov_b32 m0, s56
	s_nop 0
	global_load_lds_dwordx4 v[224:225], off
	s_waitcnt vmcnt(8)
	s_waitcnt lgkmcnt(0)
	s_barrier
	s_setprio 1
	s_waitcnt lgkmcnt(0)
	v_mfma_f32_16x16x32_bf16 v[76:79], v[40:43], v[160:163], v[76:79]
	v_mfma_f32_16x16x32_bf16 v[72:75], v[56:59], v[160:163], v[72:75]
	v_mfma_f32_16x16x32_bf16 v[52:55], v[40:43], v[186:189], v[52:55]
	v_mfma_f32_16x16x32_bf16 v[48:51], v[56:59], v[186:189], v[48:51]
	v_mfma_f32_16x16x32_bf16 v[28:31], v[40:43], v[194:197], v[28:31]
	v_mfma_f32_16x16x32_bf16 v[24:27], v[56:59], v[194:197], v[24:27]
	v_mfma_f32_16x16x32_bf16 v[12:15], v[40:43], v[202:205], v[12:15]
	v_mfma_f32_16x16x32_bf16 v[8:11], v[56:59], v[202:205], v[8:11]
	v_mfma_f32_16x16x32_bf16 v[76:79], v[44:47], v[164:167], v[76:79]
	v_mfma_f32_16x16x32_bf16 v[72:75], v[60:63], v[164:167], v[72:75]
	v_mfma_f32_16x16x32_bf16 v[52:55], v[44:47], v[190:193], v[52:55]
	v_mfma_f32_16x16x32_bf16 v[48:51], v[60:63], v[190:193], v[48:51]
	v_mfma_f32_16x16x32_bf16 v[28:31], v[44:47], v[198:201], v[28:31]
	v_mfma_f32_16x16x32_bf16 v[24:27], v[60:63], v[198:201], v[24:27]
	v_mfma_f32_16x16x32_bf16 v[12:15], v[44:47], v[214:217], v[12:15]
	v_mfma_f32_16x16x32_bf16 v[8:11], v[60:63], v[214:217], v[8:11]
	v_mfma_f32_16x16x32_bf16 v[36:39], v[144:147], v[186:189], v[36:39]
	v_mfma_f32_16x16x32_bf16 v[32:35], v[152:155], v[186:189], v[32:35]
	v_mfma_f32_16x16x32_bf16 v[20:23], v[144:147], v[194:197], v[20:23]
	v_mfma_f32_16x16x32_bf16 v[16:19], v[152:155], v[194:197], v[16:19]
	v_mfma_f32_16x16x32_bf16 v[4:7], v[144:147], v[202:205], v[4:7]
	v_mfma_f32_16x16x32_bf16 v[0:3], v[152:155], v[202:205], v[0:3]
	v_mfma_f32_16x16x32_bf16 v[40:43], v[144:147], v[160:163], v[68:71]
	v_mfma_f32_16x16x32_bf16 v[44:47], v[152:155], v[160:163], v[64:67]
	v_mfma_f32_16x16x32_bf16 v[36:39], v[148:151], v[190:193], v[36:39]
	v_mfma_f32_16x16x32_bf16 v[32:35], v[156:159], v[190:193], v[32:35]
	v_mfma_f32_16x16x32_bf16 v[20:23], v[148:151], v[198:201], v[20:23]
	v_mfma_f32_16x16x32_bf16 v[16:19], v[156:159], v[198:201], v[16:19]
	v_mfma_f32_16x16x32_bf16 v[4:7], v[148:151], v[214:217], v[4:7]
	v_mfma_f32_16x16x32_bf16 v[0:3], v[156:159], v[214:217], v[0:3]
	v_mfma_f32_16x16x32_bf16 v[40:43], v[148:151], v[164:167], v[40:43]
	v_mfma_f32_16x16x32_bf16 v[44:47], v[156:159], v[164:167], v[44:47]
	s_setprio 0
	s_barrier
; #define PG8_STAGE(bufoff, gbase, voff) do { _Pragma("unroll") for (int _i = 0; _i < 2; ++_i) \
;         __builtin_amdgcn_global_load_lds((const unsigned*)((const char*)(gbase) + (voff)[_i]), (LAS unsigned*)(lds + (bufoff) + ldsw + _i * 8192), 16, 0, 0); } while (0)
; #define PG8_LDA(dst, b, h) do { _Pragma("unroll") for (int m = 0; m < 4; ++m) _Pragma("unroll") for (int k = 0; k < 2; ++k) dst[m][k] = *(const LAS bf16x8*)(lds + PG8_SA(b, h) + aoff + m * 2048 + k * 1024); } while (0)
; #define PG8_MMA(ai, bj, At, Bt) do { __builtin_amdgcn_s_setprio(1); _Pragma("unroll") for (int m = 0; m < 4; ++m) _Pragma("unroll") for (int n = 0; n < 2; ++n) _Pragma("unroll") for (int k = 0; k < 2; ++k) \
;         acc[ai][bj][m][n] = __builtin_amdgcn_mfma_f32_16x16x32_bf16(Bt[n][k], At[m][k], acc[ai][bj][m][n], 0, 0, 0); __builtin_amdgcn_s_setprio(0); } while (0)
; #define PG8_WAIT_V(n) asm volatile("s_waitcnt vmcnt(" #n ")" ::: "memory")
; #define PG8_WAIT_L(n) asm volatile("s_waitcnt lgkmcnt(" #n ")" ::: "memory")
; #define PG8_BAR __builtin_amdgcn_s_barrier()
; #define PG8_SCHED __builtin_amdgcn_sched_barrier(0)
; template <class Epi>
; __device__ __forceinline__ void gemm_phase(LAS unsigned char* lds, const Gemm g, const StaticOrder& S, const Epi& E) {
;     ...
;             PG8_LDA(At, 1, 1); PG8_STAGE(PG8_SB(1, 0), b3, voffB); PG8_STAGE(PG8_SB(1, 1), b3 + hstepB, voffB); PG8_STAGE(PG8_SA(1, 0), a3, voffA);
;             PG8_WAIT_V(8); PG8_WAIT_L(0); PG8_BAR; PG8_MMA(1, 0, At, B0); PG8_MMA(1, 1, At, B1); PG8_BAR; PG8_SCHED;
	s_add_i32 s72, 0, 0x18000
	s_add_i32 s73, 0, 0x1c000
	v_add_u32_e32 v68, s72, v207
	v_add_u32_e32 v156, s73, v207
	ds_read_b128 v[56:59], v68
	ds_read_b128 v[60:63], v68 offset:1024
	ds_read_b128 v[64:67], v68 offset:2048
	ds_read_b128 v[68:71], v68 offset:3072
	ds_read_b128 v[144:147], v156
	ds_read_b128 v[148:151], v156 offset:1024
	ds_read_b128 v[152:155], v156 offset:2048
	ds_read_b128 v[156:159], v156 offset:3072
	s_add_u32 s52, s52, 0x40000
	s_addc_u32 s53, s53, 0
	s_mov_b32 m0, s57
	v_lshl_add_u64 v[226:227], s[52:53], 0, v[168:169]
	ds_read_b128 v[160:163], v210 offset:32768
	ds_read_b128 v[164:167], v210 offset:33792
	ds_read_b128 v[186:189], v210 offset:34816
	ds_read_b128 v[190:193], v210 offset:35840
	ds_read_b128 v[194:197], v210 offset:36864
	ds_read_b128 v[198:201], v210 offset:37888
	ds_read_b128 v[202:205], v210 offset:38912
	ds_read_b128 v[214:217], v210 offset:39936
	global_load_lds_dwordx4 v[226:227], off
	v_lshl_add_u64 v[226:227], s[52:53], 0, v[172:173]
	s_mov_b32 m0, s58
	s_nop 0
	global_load_lds_dwordx4 v[226:227], off
	s_waitcnt vmcnt(8)
	s_waitcnt lgkmcnt(0)
	s_barrier
	s_setprio 1
	s_waitcnt lgkmcnt(0)
	v_mfma_f32_16x16x32_bf16 v[140:143], v[56:59], v[160:163], v[140:143]
	v_mfma_f32_16x16x32_bf16 v[136:139], v[64:67], v[160:163], v[136:139]
	v_mfma_f32_16x16x32_bf16 v[124:127], v[56:59], v[186:189], v[124:127]
	v_mfma_f32_16x16x32_bf16 v[120:123], v[64:67], v[186:189], v[120:123]
	v_mfma_f32_16x16x32_bf16 v[108:111], v[56:59], v[194:197], v[108:111]
	v_mfma_f32_16x16x32_bf16 v[104:107], v[64:67], v[194:197], v[104:107]
	v_mfma_f32_16x16x32_bf16 v[92:95], v[56:59], v[202:205], v[92:95]
	v_mfma_f32_16x16x32_bf16 v[88:91], v[64:67], v[202:205], v[88:91]
	v_mfma_f32_16x16x32_bf16 v[140:143], v[60:63], v[164:167], v[140:143]
	v_mfma_f32_16x16x32_bf16 v[136:139], v[68:71], v[164:167], v[136:139]
	v_mfma_f32_16x16x32_bf16 v[124:127], v[60:63], v[190:193], v[124:127]
	v_mfma_f32_16x16x32_bf16 v[120:123], v[68:71], v[190:193], v[120:123]
	v_mfma_f32_16x16x32_bf16 v[108:111], v[60:63], v[198:201], v[108:111]
	v_mfma_f32_16x16x32_bf16 v[104:107], v[68:71], v[198:201], v[104:107]
	v_mfma_f32_16x16x32_bf16 v[92:95], v[60:63], v[214:217], v[92:95]
	v_mfma_f32_16x16x32_bf16 v[88:91], v[68:71], v[214:217], v[88:91]
	v_mfma_f32_16x16x32_bf16 v[132:135], v[144:147], v[160:163], v[132:135]
	v_mfma_f32_16x16x32_bf16 v[128:131], v[152:155], v[160:163], v[128:131]
	v_mfma_f32_16x16x32_bf16 v[116:119], v[144:147], v[186:189], v[116:119]
	v_mfma_f32_16x16x32_bf16 v[112:115], v[152:155], v[186:189], v[112:115]
	v_mfma_f32_16x16x32_bf16 v[100:103], v[144:147], v[194:197], v[100:103]
	v_mfma_f32_16x16x32_bf16 v[96:99], v[152:155], v[194:197], v[96:99]
	v_mfma_f32_16x16x32_bf16 v[84:87], v[144:147], v[202:205], v[84:87]
	v_mfma_f32_16x16x32_bf16 v[80:83], v[152:155], v[202:205], v[80:83]
	v_mfma_f32_16x16x32_bf16 v[132:135], v[148:151], v[164:167], v[132:135]
	v_mfma_f32_16x16x32_bf16 v[128:131], v[156:159], v[164:167], v[128:131]
	v_mfma_f32_16x16x32_bf16 v[116:119], v[148:151], v[190:193], v[116:119]
	v_mfma_f32_16x16x32_bf16 v[112:115], v[156:159], v[190:193], v[112:115]
	v_mfma_f32_16x16x32_bf16 v[100:103], v[148:151], v[198:201], v[100:103]
	v_mfma_f32_16x16x32_bf16 v[96:99], v[156:159], v[198:201], v[96:99]
	v_mfma_f32_16x16x32_bf16 v[84:87], v[148:151], v[214:217], v[84:87]
	v_mfma_f32_16x16x32_bf16 v[80:83], v[156:159], v[214:217], v[80:83]
	s_setprio 0
	s_barrier
; #define PG8_STAGE(bufoff, gbase, voff) do { _Pragma("unroll") for (int _i = 0; _i < 2; ++_i) \
;         __builtin_amdgcn_global_load_lds((const unsigned*)((const char*)(gbase) + (voff)[_i]), (LAS unsigned*)(lds + (bufoff) + ldsw + _i * 8192), 16, 0, 0); } while (0)
; #define PG8_LDA(dst, b, h) do { _Pragma("unroll") for (int m = 0; m < 4; ++m) _Pragma("unroll") for (int k = 0; k < 2; ++k) dst[m][k] = *(const LAS bf16x8*)(lds + PG8_SA(b, h) + aoff + m * 2048 + k * 1024); } while (0)
; #define PG8_MMA(ai, bj, At, Bt) do { __builtin_amdgcn_s_setprio(1); _Pragma("unroll") for (int m = 0; m < 4; ++m) _Pragma("unroll") for (int n = 0; n < 2; ++n) _Pragma("unroll") for (int k = 0; k < 2; ++k) \
;         acc[ai][bj][m][n] = __builtin_amdgcn_mfma_f32_16x16x32_bf16(Bt[n][k], At[m][k], acc[ai][bj][m][n], 0, 0, 0); __builtin_amdgcn_s_setprio(0); } while (0)
; #define PG8_WAIT_V(n) asm volatile("s_waitcnt vmcnt(" #n ")" ::: "memory")
; #define PG8_WAIT_L(n) asm volatile("s_waitcnt lgkmcnt(" #n ")" ::: "memory")
; #define PG8_BAR __builtin_amdgcn_s_barrier()
; #define PG8_SCHED __builtin_amdgcn_sched_barrier(0)
; template <class Epi>
; __device__ __forceinline__ void gemm_phase(LAS unsigned char* lds, const Gemm g, const StaticOrder& S, const Epi& E) {
;     ...
;             PG8_LDA(At, 1, 1); PG8_STAGE(PG8_SB(1, 0), b3, voffB); PG8_STAGE(PG8_SB(1, 1), b3 + hstepB, voffB); PG8_STAGE(PG8_SA(1, 0), a3, voffA);
;             PG8_WAIT_V(8); PG8_WAIT_L(0); PG8_BAR; PG8_MMA(1, 0, At, B0); PG8_MMA(1, 1, At, B1); PG8_BAR; PG8_SCHED;
;         }
	s_add_i32 s52, s72, s54
	v_lshl_add_u64 v[218:219], v[218:219], 0, s[20:21]
	s_mov_b32 m0, s52
	ds_read_b128 v[160:163], v210 offset:49152
	ds_read_b128 v[164:167], v210 offset:50176
	ds_read_b128 v[186:189], v210 offset:51200
	ds_read_b128 v[190:193], v210 offset:52224
	ds_read_b128 v[194:197], v210 offset:53248
	ds_read_b128 v[198:201], v210 offset:54272
	ds_read_b128 v[202:205], v210 offset:55296
	ds_read_b128 v[214:217], v210 offset:56320
	global_load_lds_dwordx4 v[218:219], off
	s_add_i32 m0, s52, 0x2000
	s_add_u32 s44, s44, 0x40080
	v_lshl_add_u64 v[218:219], v[220:221], 0, s[20:21]
	s_addc_u32 s45, s45, 0
	s_add_i32 s52, s73, s54
	global_load_lds_dwordx4 v[218:219], off
	v_lshl_add_u64 v[218:219], s[44:45], 0, v[170:171]
	s_mov_b32 m0, s52
	s_nop 0
	global_load_lds_dwordx4 v[218:219], off
	v_lshl_add_u64 v[218:219], s[44:45], 0, v[174:175]
	s_add_i32 m0, s52, 0x2000
	s_nop 0
	global_load_lds_dwordx4 v[218:219], off
	v_lshl_add_u64 v[218:219], v[222:223], 0, s[20:21]
	s_mov_b32 m0, s62
	s_nop 0
	global_load_lds_dwordx4 v[218:219], off
	v_lshl_add_u64 v[218:219], v[224:225], 0, s[20:21]
	s_mov_b32 m0, s63
	s_nop 0
	global_load_lds_dwordx4 v[218:219], off
	s_waitcnt vmcnt(8)
	s_waitcnt lgkmcnt(0)
	s_barrier
	s_setprio 1
	s_waitcnt lgkmcnt(0)
	v_mfma_f32_16x16x32_bf16 v[76:79], v[56:59], v[160:163], v[76:79]
	v_mfma_f32_16x16x32_bf16 v[72:75], v[64:67], v[160:163], v[72:75]
	v_mfma_f32_16x16x32_bf16 v[52:55], v[56:59], v[186:189], v[52:55]
	v_mfma_f32_16x16x32_bf16 v[48:51], v[64:67], v[186:189], v[48:51]
	v_mfma_f32_16x16x32_bf16 v[28:31], v[56:59], v[194:197], v[28:31]
	v_mfma_f32_16x16x32_bf16 v[24:27], v[64:67], v[194:197], v[24:27]
	v_mfma_f32_16x16x32_bf16 v[12:15], v[56:59], v[202:205], v[12:15]
	v_mfma_f32_16x16x32_bf16 v[8:11], v[64:67], v[202:205], v[8:11]
	v_mfma_f32_16x16x32_bf16 v[76:79], v[60:63], v[164:167], v[76:79]
	v_mfma_f32_16x16x32_bf16 v[72:75], v[68:71], v[164:167], v[72:75]
	v_mfma_f32_16x16x32_bf16 v[52:55], v[60:63], v[190:193], v[52:55]
	v_mfma_f32_16x16x32_bf16 v[48:51], v[68:71], v[190:193], v[48:51]
	v_mfma_f32_16x16x32_bf16 v[28:31], v[60:63], v[198:201], v[28:31]
	v_mfma_f32_16x16x32_bf16 v[24:27], v[68:71], v[198:201], v[24:27]
	v_mfma_f32_16x16x32_bf16 v[12:15], v[60:63], v[214:217], v[12:15]
	v_mfma_f32_16x16x32_bf16 v[8:11], v[68:71], v[214:217], v[8:11]
	v_mfma_f32_16x16x32_bf16 v[40:43], v[144:147], v[160:163], v[40:43]
	v_mfma_f32_16x16x32_bf16 v[68:71], v[148:151], v[164:167], v[40:43]
	v_mfma_f32_16x16x32_bf16 v[40:43], v[152:155], v[160:163], v[44:47]
	v_mfma_f32_16x16x32_bf16 v[36:39], v[144:147], v[186:189], v[36:39]
	v_mfma_f32_16x16x32_bf16 v[32:35], v[152:155], v[186:189], v[32:35]
	v_mfma_f32_16x16x32_bf16 v[20:23], v[144:147], v[194:197], v[20:23]
	v_mfma_f32_16x16x32_bf16 v[16:19], v[152:155], v[194:197], v[16:19]
	v_mfma_f32_16x16x32_bf16 v[4:7], v[144:147], v[202:205], v[4:7]
	v_mfma_f32_16x16x32_bf16 v[0:3], v[152:155], v[202:205], v[0:3]
	v_mfma_f32_16x16x32_bf16 v[64:67], v[156:159], v[164:167], v[40:43]
	v_mfma_f32_16x16x32_bf16 v[36:39], v[148:151], v[190:193], v[36:39]
	v_mfma_f32_16x16x32_bf16 v[32:35], v[156:159], v[190:193], v[32:35]
	v_mfma_f32_16x16x32_bf16 v[20:23], v[148:151], v[198:201], v[20:23]
	v_mfma_f32_16x16x32_bf16 v[16:19], v[156:159], v[198:201], v[16:19]
	v_mfma_f32_16x16x32_bf16 v[4:7], v[148:151], v[214:217], v[4:7]
	v_mfma_f32_16x16x32_bf16 v[0:3], v[156:159], v[214:217], v[0:3]
	s_setprio 0
	s_barrier
	s_add_i32 s71, s71, 2
	s_add_u32 s42, s42, 0x100
	s_addc_u32 s43, s43, 0
	s_add_u32 s69, s69, 0x100
	s_addc_u32 s70, s70, 0
	s_cmp_gt_u32 s71, 13
	s_cbranch_scc0 .LBB0_1746
	s_and_b64 vcc, exec, s[22:23]
	s_cbranch_vccz .LBB0_1749
	s_barrier
